# weight converter: LDS read-back pipelined 8 deep with counted lgkmcnt (was one blocking read per pair)
# baseline (speedup 1.0000x reference)
; #define LAS __attribute__((address_space(3)))
; __device__ __forceinline__ void p0_item_store(const f32x4 (&v)[8], int K, int nblk, int nb0, bf16* __restrict__ WT, int mode, LAS float* scr, int item, int lane) {
;     const int kb = item / nblk, nb = nb0 + item % nblk, k0 = 64 * kb, n0 = 32 * nb;
; #pragma unroll
;     for (int i = 0; i < 8; ++i) { LAS float* d = scr + (8 * i + (lane >> 3)) * 33 + 4 * (lane & 7); d[0] = v[i].x; d[1] = v[i].y; d[2] = v[i].z; d[3] = v[i].w; }
;     LDS_WAIT(); asm volatile("" ::: "memory");
;     const int c = lane & 7, r0 = map_row(n0, mode);
;     const float wsc = mode == 1 ? 1.44269504089f : (mode == 2 ? 0.69314718056f : 1.0f);
; #pragma unroll
;     for (int j = 0; j < 4; ++j) { const int n = (lane >> 3) + 8 * j; const LAS float* s = scr + (8 * c) * 33 + n;
;         v4u o; o.x = cvt_pk_bf16(s[0 * 33] * wsc, s[1 * 33] * wsc); o.y = cvt_pk_bf16(s[2 * 33] * wsc, s[3 * 33] * wsc); o.z = cvt_pk_bf16(s[4 * 33] * wsc, s[5 * 33] * wsc); o.w = cvt_pk_bf16(s[6 * 33] * wsc, s[7 * 33] * wsc);
;         *(v4u*)(WT + (size_t)(r0 + n) * K + k0 + 8 * c) = o; }
;     LDS_WAIT(); asm volatile("" ::: "memory");
; }
;     LAS float* scr = (LAS float*)(F.lds + RING_OFF + F.wave * 16384);
;     const int nblk = nbn ? nbn : N / 32, nall = (K / 64) * nblk, nitems = (int)((long)nall * f1 / 16);
;     int it = (int)((long)nall * f0 / 16) + w0; if (it >= nitems) return;
;     f32x4 va[8], vb[8], vc[8];
;     __builtin_amdgcn_s_waitcnt(0x0F70);
;     const int last = nitems - 1, ntri = ((nitems - it + nw - 1) / nw + 2) / 3;
;     int i1 = min(it + nw, last);
;     p0_item_load(W, N, nblk, nb0, it, F.lane, va);
;     p0_item_load(W, N, nblk, nb0, i1, F.lane, vb); __builtin_amdgcn_sched_barrier(0);
;     for (int p = 0; p < ntri; ++p) {
;         const int i2 = min(i1 + nw, last), i3 = min(i2 + nw, last), i4 = min(i3 + nw, last);
;         p0_item_load(W, N, nblk, nb0, i2, F.lane, vc); __builtin_amdgcn_sched_barrier(0);
;         p0_item_store(va, K, nblk, nb0, WT, mode, scr, it, F.lane); __builtin_amdgcn_sched_barrier(0);
;         p0_item_load(W, N, nblk, nb0, i3, F.lane, va); __builtin_amdgcn_sched_barrier(0);
;         p0_item_store(vb, K, nblk, nb0, WT, mode, scr, i1, F.lane); __builtin_amdgcn_sched_barrier(0);
;         p0_item_load(W, N, nblk, nb0, i4, F.lane, vb); __builtin_amdgcn_sched_barrier(0);
.LBB0_22:
	s_add_i32 s8, s25, s90
	s_min_i32 s24, s8, 0xdff
	s_mul_hi_i32 s8, s24, 0x92492493
	s_add_i32 s8, s8, s24
	s_lshr_b32 s9, s8, 31
	s_ashr_i32 s8, s8, 5
	s_add_i32 s8, s8, s9
	s_mul_i32 s9, s8, 56
	s_lshl_b32 s8, s8, 6
	v_or_b32_e32 v66, s8, v1
	v_mov_b64_e32 v[106:107], s[82:83]
	s_sub_i32 s9, s24, s9
	v_mad_i64_i32 v[66:67], s[10:11], v66, s14, v[106:107]
	s_lshl_b32 s10, s9, 5
	s_ashr_i32 s11, s10, 31
	v_lshl_add_u64 v[66:67], s[10:11], 2, v[66:67]
	v_lshl_add_u64 v[90:91], v[66:67], 0, v[98:99]
	v_add_co_u32_e32 v70, vcc, s17, v90
	s_add_i32 s24, s24, s90
	s_nop 0
	v_addc_co_u32_e32 v71, vcc, 0, v91, vcc
	v_add_co_u32_e32 v74, vcc, s15, v90
	global_load_dwordx4 v[66:69], v[90:91], off nt
	s_nop 0
	global_load_dwordx4 v[70:73], v[70:71], off nt
	v_addc_co_u32_e32 v75, vcc, 0, v91, vcc
	v_add_co_u32_e32 v78, vcc, s18, v90
	s_min_i32 s11, s24, 0xdff
	s_nop 0
	v_addc_co_u32_e32 v79, vcc, 0, v91, vcc
	v_add_co_u32_e32 v82, vcc, s16, v90
	global_load_dwordx4 v[74:77], v[74:75], off nt
	s_nop 0
	global_load_dwordx4 v[78:81], v[78:79], off nt
	v_addc_co_u32_e32 v83, vcc, 0, v91, vcc
	v_add_co_u32_e32 v86, vcc, s19, v90
	s_add_i32 s24, s11, s90
	s_nop 0
	v_addc_co_u32_e32 v87, vcc, 0, v91, vcc
	v_add_co_u32_e32 v92, vcc, s21, v90
	global_load_dwordx4 v[82:85], v[82:83], off nt
	s_nop 0
	global_load_dwordx4 v[86:89], v[86:87], off nt
	v_addc_co_u32_e32 v93, vcc, 0, v91, vcc
	v_add_co_u32_e32 v94, vcc, s22, v90
	s_min_i32 s24, s24, 0xdff
	s_nop 0
	v_addc_co_u32_e32 v95, vcc, 0, v91, vcc
	global_load_dwordx4 v[90:93], v[92:93], off nt
	s_nop 0
	global_load_dwordx4 v[94:97], v[94:95], off nt
	v_add_u32_e32 v115, v108, v109
	v_add_u32_e32 v116, 0x420, v115
	v_add_u32_e32 v117, 0x428, v115
	v_add_u32_e32 v118, 0x840, v115
	v_add_u32_e32 v119, 0x848, v115
	v_add_u32_e32 v120, 0xc60, v115
	v_add_u32_e32 v121, 0xc68, v115
	v_add_u32_e32 v122, 0x1080, v115
	v_add_u32_e32 v123, 0x1088, v115
	v_add_u32_e32 v124, 0x14a0, v115
	v_add_u32_e32 v125, 0x14a8, v115
	v_add_u32_e32 v126, 0x18c0, v115
	v_add_u32_e32 v127, 0x18c8, v115
	v_add_u32_e32 v128, 0x1ce0, v115
	v_add_u32_e32 v129, 0x1ce8, v115
	s_waitcnt vmcnt(17)
	ds_write2_b32 v115, v30, v31 offset1:1
	ds_write2_b32 v115, v32, v33 offset0:2 offset1:3
	ds_write2_b32 v116, v2, v3 offset1:1
	ds_write2_b32 v117, v4, v5 offset1:1
	ds_write2_b32 v118, v6, v7 offset1:1
	ds_write2_b32 v119, v8, v9 offset1:1
	ds_write2_b32 v120, v10, v11 offset1:1
	ds_write2_b32 v121, v12, v13 offset1:1
	ds_write2_b32 v122, v14, v15 offset1:1
	ds_write2_b32 v123, v16, v17 offset1:1
	ds_write2_b32 v124, v26, v27 offset1:1
	ds_write2_b32 v125, v28, v29 offset1:1
	ds_write2_b32 v126, v34, v35 offset1:1
	ds_write2_b32 v127, v36, v37 offset1:1
	s_waitcnt vmcnt(15)
	ds_write2_b32 v128, v42, v43 offset1:1
	ds_write2_b32 v129, v44, v45 offset1:1
	s_waitcnt lgkmcnt(0)
	ds_read2_b32 v[240:241], v113 offset1:33
	ds_read2_b32 v[242:243], v113 offset0:66 offset1:99
	ds_read2_b32 v[244:245], v113 offset0:132 offset1:165
	ds_read2_b32 v[246:247], v113 offset0:198 offset1:231
	ds_read2_b32 v[248:249], v113 offset0:8 offset1:41
	ds_read2_b32 v[250:251], v113 offset0:74 offset1:107
	ds_read2_b32 v[252:253], v113 offset0:140 offset1:173
	ds_read2_b32 v[254:255], v113 offset0:206 offset1:239
	s_mul_hi_i32 s27, s26, 0x92492493
	s_add_i32 s27, s27, s26
	s_lshr_b32 s28, s27, 31
	s_ashr_i32 s27, s27, 5
	s_waitcnt lgkmcnt(7)
	v_mul_f32_e32 v2, 0x3fb8aa3b, v240
	v_mul_f32_e32 v3, 0x3fb8aa3b, v241
	v_cvt_pk_bf16_f32 v2, v2, v3
	ds_read2_b32 v[240:241], v113 offset0:16 offset1:49
	s_add_i32 s27, s27, s28
	s_mul_i32 s28, s27, 56
	s_sub_i32 s26, s26, s28
	s_lshl_b32 s28, s26, 5
	s_waitcnt lgkmcnt(7)
	v_mul_f32_e32 v3, 0x3fb8aa3b, v242
	v_mul_f32_e32 v4, 0x3fb8aa3b, v243
	v_cvt_pk_bf16_f32 v3, v3, v4
	ds_read2_b32 v[242:243], v113 offset0:82 offset1:115
	s_lshl_b32 s26, s26, 6
	s_and_b32 s26, s26, 0xffffff00
	s_and_b32 s28, s28, 0x60
	s_or_b32 s28, s28, s26
	s_waitcnt lgkmcnt(7)
	v_mul_f32_e32 v4, 0x3fb8aa3b, v244
	v_mul_f32_e32 v5, 0x3fb8aa3b, v245
	v_cvt_pk_bf16_f32 v4, v4, v5
	ds_read2_b32 v[244:245], v113 offset0:148 offset1:181
	s_lshl_b32 s26, s27, 6
	s_ashr_i32 s27, s26, 31
	v_lshl_add_u64 v[8:9], s[26:27], 1, v[100:101]
	s_waitcnt lgkmcnt(7)
	v_mul_f32_e32 v5, 0x3fb8aa3b, v246
	v_mul_f32_e32 v6, 0x3fb8aa3b, v247
	v_cvt_pk_bf16_f32 v5, v5, v6
	ds_read2_b32 v[246:247], v113 offset0:214 offset1:247
	v_or_b32_e32 v6, s28, v1
	v_ashrrev_i32_e32 v7, 31, v6
	v_lshlrev_b64 v[6:7], 13, v[6:7]
	v_lshl_add_u64 v[6:7], v[8:9], 0, v[6:7]
	global_store_dwordx4 v[6:7], v[2:5], off
	s_waitcnt lgkmcnt(7)
	s_nop 0
	v_mul_f32_e32 v2, 0x3fb8aa3b, v248
	v_mul_f32_e32 v3, 0x3fb8aa3b, v249
	v_cvt_pk_bf16_f32 v2, v2, v3
	ds_read2_b32 v[248:249], v113 offset0:24 offset1:57
	s_waitcnt lgkmcnt(7)
	v_mul_f32_e32 v3, 0x3fb8aa3b, v250
	v_mul_f32_e32 v4, 0x3fb8aa3b, v251
	v_cvt_pk_bf16_f32 v3, v3, v4
	ds_read2_b32 v[250:251], v113 offset0:90 offset1:123
	s_waitcnt lgkmcnt(7)
	v_mul_f32_e32 v4, 0x3fb8aa3b, v252
	v_mul_f32_e32 v5, 0x3fb8aa3b, v253
	v_cvt_pk_bf16_f32 v4, v4, v5
	ds_read2_b32 v[252:253], v113 offset0:156 offset1:189
	s_waitcnt lgkmcnt(7)
	v_mul_f32_e32 v5, 0x3fb8aa3b, v254
	v_mul_f32_e32 v6, 0x3fb8aa3b, v255
	v_cvt_pk_bf16_f32 v5, v5, v6
	ds_read2_b32 v[254:255], v113 offset0:222 offset1:255
	v_or_b32_e32 v6, s28, v110
	v_ashrrev_i32_e32 v7, 31, v6
	v_lshlrev_b64 v[6:7], 13, v[6:7]
	v_lshl_add_u64 v[6:7], v[8:9], 0, v[6:7]
	global_store_dwordx4 v[6:7], v[2:5], off
	s_waitcnt lgkmcnt(7)
	s_nop 0
	v_mul_f32_e32 v2, 0x3fb8aa3b, v240
	v_mul_f32_e32 v3, 0x3fb8aa3b, v241
	v_cvt_pk_bf16_f32 v2, v2, v3
	s_waitcnt lgkmcnt(6)
; __device__ __forceinline__ unsigned cvt_pk_bf16(float lo, float hi) { unsigned r; asm volatile("v_cvt_pk_bf16_f32 %0, %1, %2" : "=v"(r) : "v"(lo), "v"(hi)); return r; }
; #define LAS __attribute__((address_space(3)))
; #define LDS_WAIT() asm volatile("s_waitcnt lgkmcnt(0)" ::: "memory")
; __device__ __forceinline__ void p0_item_load(const float* __restrict__ W, int N, int nblk, int nb0, int item, int lane, f32x4 (&v)[8]) {
;     const int kb = item / nblk, nb = nb0 + item % nblk;
;     const float* src = W + (size_t)(64 * kb + (lane >> 3)) * N + 32 * nb + 4 * (lane & 7);
; #pragma unroll
;     for (int i = 0; i < 8; ++i) v[i] = __builtin_nontemporal_load((const f32x4*)(src + (size_t)(8 * i) * N));
; }
; __device__ __forceinline__ void p0_item_store(const f32x4 (&v)[8], int K, int nblk, int nb0, bf16* __restrict__ WT, int mode, LAS float* scr, int item, int lane) {
;     const int kb = item / nblk, nb = nb0 + item % nblk, k0 = 64 * kb, n0 = 32 * nb;
; #pragma unroll
;     for (int i = 0; i < 8; ++i) { LAS float* d = scr + (8 * i + (lane >> 3)) * 33 + 4 * (lane & 7); d[0] = v[i].x; d[1] = v[i].y; d[2] = v[i].z; d[3] = v[i].w; }
;     LDS_WAIT(); asm volatile("" ::: "memory");
;     const int c = lane & 7, r0 = map_row(n0, mode);
;     const float wsc = mode == 1 ? 1.44269504089f : (mode == 2 ? 0.69314718056f : 1.0f);
; #pragma unroll
;     for (int j = 0; j < 4; ++j) { const int n = (lane >> 3) + 8 * j; const LAS float* s = scr + (8 * c) * 33 + n;
;         v4u o; o.x = cvt_pk_bf16(s[0 * 33] * wsc, s[1 * 33] * wsc); o.y = cvt_pk_bf16(s[2 * 33] * wsc, s[3 * 33] * wsc); o.z = cvt_pk_bf16(s[4 * 33] * wsc, s[5 * 33] * wsc); o.w = cvt_pk_bf16(s[6 * 33] * wsc, s[7 * 33] * wsc);
;         *(v4u*)(WT + (size_t)(r0 + n) * K + k0 + 8 * c) = o; }
;     LDS_WAIT(); asm volatile("" ::: "memory");
; }
	v_mul_f32_e32 v3, 0x3fb8aa3b, v242
	v_mul_f32_e32 v4, 0x3fb8aa3b, v243
	v_cvt_pk_bf16_f32 v3, v3, v4
	s_waitcnt lgkmcnt(5)
	v_mul_f32_e32 v4, 0x3fb8aa3b, v244
	v_mul_f32_e32 v5, 0x3fb8aa3b, v245
	v_cvt_pk_bf16_f32 v4, v4, v5
	s_waitcnt lgkmcnt(4)
	v_mul_f32_e32 v5, 0x3fb8aa3b, v246
	v_mul_f32_e32 v6, 0x3fb8aa3b, v247
	v_cvt_pk_bf16_f32 v5, v5, v6
	v_or_b32_e32 v6, s28, v111
	v_ashrrev_i32_e32 v7, 31, v6
	v_lshlrev_b64 v[6:7], 13, v[6:7]
	v_lshl_add_u64 v[6:7], v[8:9], 0, v[6:7]
	global_store_dwordx4 v[6:7], v[2:5], off
	s_waitcnt lgkmcnt(3)
	s_nop 0
	v_mul_f32_e32 v2, 0x3fb8aa3b, v248
	v_mul_f32_e32 v3, 0x3fb8aa3b, v249
	v_cvt_pk_bf16_f32 v2, v2, v3
	s_waitcnt lgkmcnt(2)
	v_mul_f32_e32 v3, 0x3fb8aa3b, v250
	v_mul_f32_e32 v4, 0x3fb8aa3b, v251
	v_cvt_pk_bf16_f32 v3, v3, v4
	s_waitcnt lgkmcnt(1)
	v_mul_f32_e32 v4, 0x3fb8aa3b, v252
	v_mul_f32_e32 v5, 0x3fb8aa3b, v253
	v_cvt_pk_bf16_f32 v4, v4, v5
	s_waitcnt lgkmcnt(0)
	v_mul_f32_e32 v5, 0x3fb8aa3b, v254
	v_mul_f32_e32 v6, 0x3fb8aa3b, v255
	v_cvt_pk_bf16_f32 v5, v5, v6
	v_or_b32_e32 v6, s28, v112
	v_ashrrev_i32_e32 v7, 31, v6
	v_lshlrev_b64 v[6:7], 13, v[6:7]
	v_lshl_add_u64 v[6:7], v[8:9], 0, v[6:7]
	global_store_dwordx4 v[6:7], v[2:5], off
	s_waitcnt lgkmcnt(0)
	s_mul_hi_i32 s26, s11, 0x92492493
	s_add_i32 s26, s26, s11
	s_lshr_b32 s27, s26, 31
	s_ashr_i32 s26, s26, 5
	s_add_i32 s26, s26, s27
	s_mul_i32 s27, s26, 56
	v_lshl_or_b32 v2, s26, 6, v1
	s_sub_i32 s28, s11, s27
	v_mad_i64_i32 v[2:3], s[26:27], v2, s14, v[106:107]
	s_lshl_b32 s26, s28, 5
	s_ashr_i32 s27, s26, 31
	v_lshl_add_u64 v[2:3], s[26:27], 2, v[2:3]
	v_lshl_add_u64 v[34:35], v[2:3], 0, v[98:99]
	v_add_co_u32_e32 v2, vcc, s17, v34
	s_nop 1
	v_addc_co_u32_e32 v3, vcc, 0, v35, vcc
	v_add_co_u32_e32 v6, vcc, s15, v34
	global_load_dwordx4 v[30:33], v[34:35], off nt
	s_nop 0
	global_load_dwordx4 v[2:5], v[2:3], off nt
	v_addc_co_u32_e32 v7, vcc, 0, v35, vcc
	v_add_co_u32_e32 v10, vcc, s18, v34
	s_nop 1
	v_addc_co_u32_e32 v11, vcc, 0, v35, vcc
	v_add_co_u32_e32 v14, vcc, s16, v34
	global_load_dwordx4 v[6:9], v[6:7], off nt
	s_nop 0
	global_load_dwordx4 v[10:13], v[10:11], off nt
	v_addc_co_u32_e32 v15, vcc, 0, v35, vcc
	v_add_co_u32_e32 v26, vcc, s19, v34
	s_nop 1
	v_addc_co_u32_e32 v27, vcc, 0, v35, vcc
	v_add_co_u32_e32 v36, vcc, s21, v34
	global_load_dwordx4 v[14:17], v[14:15], off nt
	s_nop 0
	global_load_dwordx4 v[26:29], v[26:27], off nt
	v_addc_co_u32_e32 v37, vcc, 0, v35, vcc
	v_add_co_u32_e32 v42, vcc, s22, v34
	s_nop 1
	v_addc_co_u32_e32 v43, vcc, 0, v35, vcc
	global_load_dwordx4 v[34:37], v[36:37], off nt
	s_nop 0
	global_load_dwordx4 v[42:45], v[42:43], off nt
	ds_write2_b32 v115, v18, v19 offset1:1
	ds_write2_b32 v115, v20, v21 offset0:2 offset1:3
	s_waitcnt vmcnt(26)
	ds_write2_b32 v116, v22, v23 offset1:1
	ds_write2_b32 v117, v24, v25 offset1:1
	s_waitcnt vmcnt(25)
	ds_write2_b32 v118, v38, v39 offset1:1
	ds_write2_b32 v119, v40, v41 offset1:1
	s_waitcnt vmcnt(24)
	ds_write2_b32 v120, v46, v47 offset1:1
	ds_write2_b32 v121, v48, v49 offset1:1
	s_waitcnt vmcnt(23)
	ds_write2_b32 v122, v50, v51 offset1:1
	ds_write2_b32 v123, v52, v53 offset1:1
	s_waitcnt vmcnt(22)
	ds_write2_b32 v124, v54, v55 offset1:1
	ds_write2_b32 v125, v56, v57 offset1:1
	s_waitcnt vmcnt(21)
	ds_write2_b32 v126, v58, v59 offset1:1
	ds_write2_b32 v127, v60, v61 offset1:1
	s_waitcnt vmcnt(20)
	ds_write2_b32 v128, v62, v63 offset1:1
	ds_write2_b32 v129, v64, v65 offset1:1
	s_waitcnt lgkmcnt(0)
	ds_read2_b32 v[240:241], v113 offset1:33
	ds_read2_b32 v[242:243], v113 offset0:66 offset1:99
	ds_read2_b32 v[244:245], v113 offset0:132 offset1:165
	ds_read2_b32 v[246:247], v113 offset0:198 offset1:231
	ds_read2_b32 v[248:249], v113 offset0:8 offset1:41
	ds_read2_b32 v[250:251], v113 offset0:74 offset1:107
	ds_read2_b32 v[252:253], v113 offset0:140 offset1:173
	ds_read2_b32 v[254:255], v113 offset0:206 offset1:239
	s_mul_hi_i32 s26, s25, 0x92492493
	s_add_i32 s26, s26, s25
	s_lshr_b32 s27, s26, 31
	s_ashr_i32 s26, s26, 5
	s_waitcnt lgkmcnt(7)
	v_mul_f32_e32 v18, 0x3fb8aa3b, v240
	v_mul_f32_e32 v19, 0x3fb8aa3b, v241
	v_cvt_pk_bf16_f32 v18, v18, v19
	ds_read2_b32 v[240:241], v113 offset0:16 offset1:49
	s_add_i32 s26, s26, s27
	s_mul_i32 s27, s26, 56
	s_sub_i32 s25, s25, s27
	s_lshl_b32 s27, s25, 5
	s_waitcnt lgkmcnt(7)
	v_mul_f32_e32 v19, 0x3fb8aa3b, v242
	v_mul_f32_e32 v20, 0x3fb8aa3b, v243
	v_cvt_pk_bf16_f32 v19, v19, v20
	ds_read2_b32 v[242:243], v113 offset0:82 offset1:115
	s_lshl_b32 s25, s25, 6
	s_and_b32 s25, s25, 0xffffff00
	s_and_b32 s27, s27, 0x60
	s_or_b32 s25, s27, s25
	s_waitcnt lgkmcnt(7)
	v_mul_f32_e32 v20, 0x3fb8aa3b, v244
	v_mul_f32_e32 v21, 0x3fb8aa3b, v245
	v_cvt_pk_bf16_f32 v20, v20, v21
	ds_read2_b32 v[244:245], v113 offset0:148 offset1:181
	s_lshl_b32 s26, s26, 6
	s_ashr_i32 s27, s26, 31
	v_lshl_add_u64 v[24:25], s[26:27], 1, v[100:101]
	s_waitcnt lgkmcnt(7)
	v_mul_f32_e32 v21, 0x3fb8aa3b, v246
	v_mul_f32_e32 v22, 0x3fb8aa3b, v247
	v_cvt_pk_bf16_f32 v21, v21, v22
	ds_read2_b32 v[246:247], v113 offset0:214 offset1:247
	v_or_b32_e32 v22, s25, v1
	v_ashrrev_i32_e32 v23, 31, v22
	v_lshlrev_b64 v[22:23], 13, v[22:23]
	v_lshl_add_u64 v[22:23], v[24:25], 0, v[22:23]
	global_store_dwordx4 v[22:23], v[18:21], off
	s_waitcnt lgkmcnt(7)
	s_nop 0
	v_mul_f32_e32 v18, 0x3fb8aa3b, v248
	v_mul_f32_e32 v19, 0x3fb8aa3b, v249
	v_cvt_pk_bf16_f32 v18, v18, v19
	ds_read2_b32 v[248:249], v113 offset0:24 offset1:57
	s_waitcnt lgkmcnt(7)
	v_mul_f32_e32 v19, 0x3fb8aa3b, v250
	v_mul_f32_e32 v20, 0x3fb8aa3b, v251
	v_cvt_pk_bf16_f32 v19, v19, v20
	ds_read2_b32 v[250:251], v113 offset0:90 offset1:123
	s_waitcnt lgkmcnt(7)
; __device__ __forceinline__ unsigned cvt_pk_bf16(float lo, float hi) { unsigned r; asm volatile("v_cvt_pk_bf16_f32 %0, %1, %2" : "=v"(r) : "v"(lo), "v"(hi)); return r; }
; #define LAS __attribute__((address_space(3)))
; #define LDS_WAIT() asm volatile("s_waitcnt lgkmcnt(0)" ::: "memory")
; __device__ __forceinline__ void p0_item_load(const float* __restrict__ W, int N, int nblk, int nb0, int item, int lane, f32x4 (&v)[8]) {
;     const int kb = item / nblk, nb = nb0 + item % nblk;
;     const float* src = W + (size_t)(64 * kb + (lane >> 3)) * N + 32 * nb + 4 * (lane & 7);
; #pragma unroll
;     for (int i = 0; i < 8; ++i) v[i] = __builtin_nontemporal_load((const f32x4*)(src + (size_t)(8 * i) * N));
; }
; __device__ __forceinline__ void p0_item_store(const f32x4 (&v)[8], int K, int nblk, int nb0, bf16* __restrict__ WT, int mode, LAS float* scr, int item, int lane) {
;     const int kb = item / nblk, nb = nb0 + item % nblk, k0 = 64 * kb, n0 = 32 * nb;
; #pragma unroll
;     for (int i = 0; i < 8; ++i) { LAS float* d = scr + (8 * i + (lane >> 3)) * 33 + 4 * (lane & 7); d[0] = v[i].x; d[1] = v[i].y; d[2] = v[i].z; d[3] = v[i].w; }
;     LDS_WAIT(); asm volatile("" ::: "memory");
;     const int c = lane & 7, r0 = map_row(n0, mode);
;     const float wsc = mode == 1 ? 1.44269504089f : (mode == 2 ? 0.69314718056f : 1.0f);
; #pragma unroll
;     for (int j = 0; j < 4; ++j) { const int n = (lane >> 3) + 8 * j; const LAS float* s = scr + (8 * c) * 33 + n;
;         v4u o; o.x = cvt_pk_bf16(s[0 * 33] * wsc, s[1 * 33] * wsc); o.y = cvt_pk_bf16(s[2 * 33] * wsc, s[3 * 33] * wsc); o.z = cvt_pk_bf16(s[4 * 33] * wsc, s[5 * 33] * wsc); o.w = cvt_pk_bf16(s[6 * 33] * wsc, s[7 * 33] * wsc);
;         *(v4u*)(WT + (size_t)(r0 + n) * K + k0 + 8 * c) = o; }
;     LDS_WAIT(); asm volatile("" ::: "memory");
; }
	v_mul_f32_e32 v20, 0x3fb8aa3b, v252
	v_mul_f32_e32 v21, 0x3fb8aa3b, v253
	v_cvt_pk_bf16_f32 v20, v20, v21
	ds_read2_b32 v[252:253], v113 offset0:156 offset1:189
	s_waitcnt lgkmcnt(7)
	v_mul_f32_e32 v21, 0x3fb8aa3b, v254
	v_mul_f32_e32 v22, 0x3fb8aa3b, v255
	v_cvt_pk_bf16_f32 v21, v21, v22
	ds_read2_b32 v[254:255], v113 offset0:222 offset1:255
	v_or_b32_e32 v22, s25, v110
	v_ashrrev_i32_e32 v23, 31, v22
	v_lshlrev_b64 v[22:23], 13, v[22:23]
	v_lshl_add_u64 v[22:23], v[24:25], 0, v[22:23]
	global_store_dwordx4 v[22:23], v[18:21], off
	s_waitcnt lgkmcnt(7)
	s_nop 0
	v_mul_f32_e32 v18, 0x3fb8aa3b, v240
	v_mul_f32_e32 v19, 0x3fb8aa3b, v241
	v_cvt_pk_bf16_f32 v18, v18, v19
	s_waitcnt lgkmcnt(6)
	v_mul_f32_e32 v19, 0x3fb8aa3b, v242
	v_mul_f32_e32 v20, 0x3fb8aa3b, v243
	v_cvt_pk_bf16_f32 v19, v19, v20
	s_waitcnt lgkmcnt(5)
	v_mul_f32_e32 v20, 0x3fb8aa3b, v244
	v_mul_f32_e32 v21, 0x3fb8aa3b, v245
	v_cvt_pk_bf16_f32 v20, v20, v21
	s_waitcnt lgkmcnt(4)
	v_mul_f32_e32 v21, 0x3fb8aa3b, v246
	v_mul_f32_e32 v22, 0x3fb8aa3b, v247
	v_cvt_pk_bf16_f32 v21, v21, v22
	v_or_b32_e32 v22, s25, v111
	v_ashrrev_i32_e32 v23, 31, v22
	v_lshlrev_b64 v[22:23], 13, v[22:23]
	v_lshl_add_u64 v[22:23], v[24:25], 0, v[22:23]
	global_store_dwordx4 v[22:23], v[18:21], off
	s_waitcnt lgkmcnt(3)
	s_nop 0
	v_mul_f32_e32 v18, 0x3fb8aa3b, v248
	v_mul_f32_e32 v19, 0x3fb8aa3b, v249
	v_cvt_pk_bf16_f32 v18, v18, v19
	s_waitcnt lgkmcnt(2)
	v_mul_f32_e32 v19, 0x3fb8aa3b, v250
	v_mul_f32_e32 v20, 0x3fb8aa3b, v251
	v_cvt_pk_bf16_f32 v19, v19, v20
	s_waitcnt lgkmcnt(1)
	v_mul_f32_e32 v20, 0x3fb8aa3b, v252
	v_mul_f32_e32 v21, 0x3fb8aa3b, v253
	v_cvt_pk_bf16_f32 v20, v20, v21
	s_waitcnt lgkmcnt(0)
	v_mul_f32_e32 v21, 0x3fb8aa3b, v254
	v_mul_f32_e32 v22, 0x3fb8aa3b, v255
	v_cvt_pk_bf16_f32 v21, v21, v22
	v_or_b32_e32 v22, s25, v112
	v_ashrrev_i32_e32 v23, 31, v22
	v_lshlrev_b64 v[22:23], 13, v[22:23]
	v_lshl_add_u64 v[22:23], v[24:25], 0, v[22:23]
	global_store_dwordx4 v[22:23], v[18:21], off
	s_waitcnt lgkmcnt(0)
	s_mul_hi_i32 s25, s24, 0x92492493
	s_add_i32 s25, s25, s24
	s_lshr_b32 s26, s25, 31
	s_ashr_i32 s25, s25, 5
	s_add_i32 s25, s25, s26
	s_mul_i32 s26, s25, 56
	v_lshl_or_b32 v18, s25, 6, v1
	s_sub_i32 s28, s24, s26
	v_mad_i64_i32 v[18:19], s[26:27], v18, s14, v[106:107]
	s_lshl_b32 s26, s28, 5
	s_ashr_i32 s27, s26, 31
	v_lshl_add_u64 v[18:19], s[26:27], 2, v[18:19]
	v_lshl_add_u64 v[58:59], v[18:19], 0, v[98:99]
	v_add_co_u32_e32 v22, vcc, s17, v58
	s_nop 1
	v_addc_co_u32_e32 v23, vcc, 0, v59, vcc
	v_add_co_u32_e32 v38, vcc, s15, v58
	global_load_dwordx4 v[18:21], v[58:59], off nt
	s_nop 0
	global_load_dwordx4 v[22:25], v[22:23], off nt
	v_addc_co_u32_e32 v39, vcc, 0, v59, vcc
	v_add_co_u32_e32 v46, vcc, s18, v58
	s_nop 1
	v_addc_co_u32_e32 v47, vcc, 0, v59, vcc
	v_add_co_u32_e32 v50, vcc, s16, v58
	global_load_dwordx4 v[38:41], v[38:39], off nt
	s_nop 0
	global_load_dwordx4 v[46:49], v[46:47], off nt
	v_addc_co_u32_e32 v51, vcc, 0, v59, vcc
	v_add_co_u32_e32 v54, vcc, s19, v58
	s_nop 1
	v_addc_co_u32_e32 v55, vcc, 0, v59, vcc
	v_add_co_u32_e32 v60, vcc, s21, v58
	global_load_dwordx4 v[50:53], v[50:51], off nt
	s_nop 0
	global_load_dwordx4 v[54:57], v[54:55], off nt
	v_addc_co_u32_e32 v61, vcc, 0, v59, vcc
	v_add_co_u32_e32 v62, vcc, s22, v58
	s_nop 1
	v_addc_co_u32_e32 v63, vcc, 0, v59, vcc
	global_load_dwordx4 v[58:61], v[60:61], off nt
	s_nop 0
	global_load_dwordx4 v[62:65], v[62:63], off nt
	s_waitcnt vmcnt(31)
	ds_write2_b32 v115, v66, v67 offset1:1
	ds_write2_b32 v115, v68, v69 offset0:2 offset1:3
	s_waitcnt vmcnt(30)
	ds_write2_b32 v116, v70, v71 offset1:1
	ds_write2_b32 v117, v72, v73 offset1:1
	s_waitcnt vmcnt(29)
	ds_write2_b32 v118, v74, v75 offset1:1
	ds_write2_b32 v119, v76, v77 offset1:1
	s_waitcnt vmcnt(28)
	ds_write2_b32 v120, v78, v79 offset1:1
	ds_write2_b32 v121, v80, v81 offset1:1
	s_waitcnt vmcnt(27)
	ds_write2_b32 v122, v82, v83 offset1:1
	ds_write2_b32 v123, v84, v85 offset1:1
	s_waitcnt vmcnt(26)
	ds_write2_b32 v124, v86, v87 offset1:1
	ds_write2_b32 v125, v88, v89 offset1:1
	s_waitcnt vmcnt(25)
	ds_write2_b32 v126, v90, v91 offset1:1
	ds_write2_b32 v127, v92, v93 offset1:1
	s_waitcnt vmcnt(24)
; #define LAS __attribute__((address_space(3)))
; __device__ __forceinline__ void p0_item_load(const float* __restrict__ W, int N, int nblk, int nb0, int item, int lane, f32x4 (&v)[8]) {
;     const int kb = item / nblk, nb = nb0 + item % nblk;
;     const float* src = W + (size_t)(64 * kb + (lane >> 3)) * N + 32 * nb + 4 * (lane & 7);
; #pragma unroll
;     for (int i = 0; i < 8; ++i) v[i] = __builtin_nontemporal_load((const f32x4*)(src + (size_t)(8 * i) * N));
; }
; __device__ __forceinline__ void p0_item_store(const f32x4 (&v)[8], int K, int nblk, int nb0, bf16* __restrict__ WT, int mode, LAS float* scr, int item, int lane) {
;     const int kb = item / nblk, nb = nb0 + item % nblk, k0 = 64 * kb, n0 = 32 * nb;
; #pragma unroll
;     for (int i = 0; i < 8; ++i) { LAS float* d = scr + (8 * i + (lane >> 3)) * 33 + 4 * (lane & 7); d[0] = v[i].x; d[1] = v[i].y; d[2] = v[i].z; d[3] = v[i].w; }
;     LDS_WAIT(); asm volatile("" ::: "memory");
;     const int c = lane & 7, r0 = map_row(n0, mode);
;     const float wsc = mode == 1 ? 1.44269504089f : (mode == 2 ? 0.69314718056f : 1.0f);
; #pragma unroll
;     for (int j = 0; j < 4; ++j) { const int n = (lane >> 3) + 8 * j; const LAS float* s = scr + (8 * c) * 33 + n;
;         v4u o; o.x = cvt_pk_bf16(s[0 * 33] * wsc, s[1 * 33] * wsc); o.y = cvt_pk_bf16(s[2 * 33] * wsc, s[3 * 33] * wsc); o.z = cvt_pk_bf16(s[4 * 33] * wsc, s[5 * 33] * wsc); o.w = cvt_pk_bf16(s[6 * 33] * wsc, s[7 * 33] * wsc);
;         *(v4u*)(WT + (size_t)(r0 + n) * K + k0 + 8 * c) = o; }
;     LDS_WAIT(); asm volatile("" ::: "memory");
; }
;     ...
;     for (int p = 0; p < ntri; ++p) {
;         const int i2 = min(i1 + nw, last), i3 = min(i2 + nw, last), i4 = min(i3 + nw, last);
;         p0_item_load(W, N, nblk, nb0, i2, F.lane, vc); __builtin_amdgcn_sched_barrier(0);
;         p0_item_store(va, K, nblk, nb0, WT, mode, scr, it, F.lane); __builtin_amdgcn_sched_barrier(0);
;         p0_item_load(W, N, nblk, nb0, i3, F.lane, va); __builtin_amdgcn_sched_barrier(0);
;         p0_item_store(vb, K, nblk, nb0, WT, mode, scr, i1, F.lane); __builtin_amdgcn_sched_barrier(0);
;         p0_item_load(W, N, nblk, nb0, i4, F.lane, vb); __builtin_amdgcn_sched_barrier(0);
;         p0_item_store(vc, K, nblk, nb0, WT, mode, scr, i2, F.lane); __builtin_amdgcn_sched_barrier(0);
;         it = i3; i1 = i4;
;     }
	ds_write2_b32 v128, v94, v95 offset1:1
	ds_write2_b32 v129, v96, v97 offset1:1
	s_waitcnt lgkmcnt(0)
	ds_read2_b32 v[240:241], v113 offset1:33
	ds_read2_b32 v[242:243], v113 offset0:66 offset1:99
	ds_read2_b32 v[244:245], v113 offset0:132 offset1:165
	ds_read2_b32 v[246:247], v113 offset0:198 offset1:231
	ds_read2_b32 v[248:249], v113 offset0:8 offset1:41
	ds_read2_b32 v[250:251], v113 offset0:74 offset1:107
	ds_read2_b32 v[252:253], v113 offset0:140 offset1:173
	ds_read2_b32 v[254:255], v113 offset0:206 offset1:239
	s_lshl_b32 s9, s9, 6
	s_and_b32 s9, s9, 0xffffff00
	s_and_b32 s10, s10, 0x60
	s_or_b32 s10, s10, s9
	s_waitcnt lgkmcnt(7)
	v_mul_f32_e32 v66, 0x3fb8aa3b, v240
	v_mul_f32_e32 v67, 0x3fb8aa3b, v241
	v_cvt_pk_bf16_f32 v66, v66, v67
	ds_read2_b32 v[240:241], v113 offset0:16 offset1:49
	s_ashr_i32 s9, s8, 31
	v_lshl_add_u64 v[72:73], s[8:9], 1, v[100:101]
	s_waitcnt lgkmcnt(7)
	v_mul_f32_e32 v67, 0x3fb8aa3b, v242
	v_mul_f32_e32 v68, 0x3fb8aa3b, v243
	v_cvt_pk_bf16_f32 v67, v67, v68
	ds_read2_b32 v[242:243], v113 offset0:82 offset1:115
	s_waitcnt lgkmcnt(7)
	v_mul_f32_e32 v68, 0x3fb8aa3b, v244
	v_mul_f32_e32 v69, 0x3fb8aa3b, v245
	v_cvt_pk_bf16_f32 v68, v68, v69
	ds_read2_b32 v[244:245], v113 offset0:148 offset1:181
	s_waitcnt lgkmcnt(7)
	v_mul_f32_e32 v69, 0x3fb8aa3b, v246
	v_mul_f32_e32 v70, 0x3fb8aa3b, v247
	v_cvt_pk_bf16_f32 v69, v69, v70
	ds_read2_b32 v[246:247], v113 offset0:214 offset1:247
	v_or_b32_e32 v70, s10, v1
	v_ashrrev_i32_e32 v71, 31, v70
	v_lshlrev_b64 v[70:71], 13, v[70:71]
	v_lshl_add_u64 v[70:71], v[72:73], 0, v[70:71]
	global_store_dwordx4 v[70:71], v[66:69], off
	s_waitcnt lgkmcnt(7)
	s_nop 0
	v_mul_f32_e32 v66, 0x3fb8aa3b, v248
	v_mul_f32_e32 v67, 0x3fb8aa3b, v249
	v_cvt_pk_bf16_f32 v66, v66, v67
	ds_read2_b32 v[248:249], v113 offset0:24 offset1:57
	s_waitcnt lgkmcnt(7)
	v_mul_f32_e32 v67, 0x3fb8aa3b, v250
	v_mul_f32_e32 v68, 0x3fb8aa3b, v251
	v_cvt_pk_bf16_f32 v67, v67, v68
	ds_read2_b32 v[250:251], v113 offset0:90 offset1:123
	s_waitcnt lgkmcnt(7)
	v_mul_f32_e32 v68, 0x3fb8aa3b, v252
	v_mul_f32_e32 v69, 0x3fb8aa3b, v253
	v_cvt_pk_bf16_f32 v68, v68, v69
	ds_read2_b32 v[252:253], v113 offset0:156 offset1:189
	s_waitcnt lgkmcnt(7)
	v_mul_f32_e32 v69, 0x3fb8aa3b, v254
	v_mul_f32_e32 v70, 0x3fb8aa3b, v255
	v_cvt_pk_bf16_f32 v69, v69, v70
	ds_read2_b32 v[254:255], v113 offset0:222 offset1:255
	v_or_b32_e32 v70, s10, v110
	v_ashrrev_i32_e32 v71, 31, v70
	v_lshlrev_b64 v[70:71], 13, v[70:71]
	v_lshl_add_u64 v[70:71], v[72:73], 0, v[70:71]
	global_store_dwordx4 v[70:71], v[66:69], off
	s_waitcnt lgkmcnt(7)
	s_nop 0
	v_mul_f32_e32 v66, 0x3fb8aa3b, v240
	v_mul_f32_e32 v67, 0x3fb8aa3b, v241
	v_cvt_pk_bf16_f32 v66, v66, v67
	s_waitcnt lgkmcnt(6)
	v_mul_f32_e32 v67, 0x3fb8aa3b, v242
	v_mul_f32_e32 v68, 0x3fb8aa3b, v243
	v_cvt_pk_bf16_f32 v67, v67, v68
	s_waitcnt lgkmcnt(5)
	v_mul_f32_e32 v68, 0x3fb8aa3b, v244
	v_mul_f32_e32 v69, 0x3fb8aa3b, v245
	v_cvt_pk_bf16_f32 v68, v68, v69
	s_waitcnt lgkmcnt(4)
	v_mul_f32_e32 v69, 0x3fb8aa3b, v246
	v_mul_f32_e32 v70, 0x3fb8aa3b, v247
	v_cvt_pk_bf16_f32 v69, v69, v70
	v_or_b32_e32 v70, s10, v111
	v_ashrrev_i32_e32 v71, 31, v70
	v_lshlrev_b64 v[70:71], 13, v[70:71]
	v_lshl_add_u64 v[70:71], v[72:73], 0, v[70:71]
	global_store_dwordx4 v[70:71], v[66:69], off
	s_waitcnt lgkmcnt(3)
	s_nop 0
	v_mul_f32_e32 v66, 0x3fb8aa3b, v248
	v_mul_f32_e32 v67, 0x3fb8aa3b, v249
	v_cvt_pk_bf16_f32 v66, v66, v67
	s_waitcnt lgkmcnt(2)
	v_mul_f32_e32 v67, 0x3fb8aa3b, v250
	v_mul_f32_e32 v68, 0x3fb8aa3b, v251
	v_cvt_pk_bf16_f32 v67, v67, v68
	s_waitcnt lgkmcnt(1)
	v_mul_f32_e32 v68, 0x3fb8aa3b, v252
	v_mul_f32_e32 v69, 0x3fb8aa3b, v253
	v_cvt_pk_bf16_f32 v68, v68, v69
	s_waitcnt lgkmcnt(0)
	v_mul_f32_e32 v69, 0x3fb8aa3b, v254
	v_mul_f32_e32 v70, 0x3fb8aa3b, v255
	v_cvt_pk_bf16_f32 v69, v69, v70
	v_or_b32_e32 v70, s10, v112
	v_ashrrev_i32_e32 v71, 31, v70
	v_lshlrev_b64 v[70:71], 13, v[70:71]
	v_lshl_add_u64 v[70:71], v[72:73], 0, v[70:71]
	global_store_dwordx4 v[70:71], v[66:69], off
	s_waitcnt lgkmcnt(0)
	s_add_i32 s23, s23, -1
	s_cmp_lg_u32 s23, 0
	s_mov_b32 s26, s11
	s_mov_b32 s25, s24
	s_cbranch_scc1 .LBB0_22

; #define LAS __attribute__((address_space(3)))
; __device__ __forceinline__ void p0_item_load(const float* __restrict__ W, int N, int nblk, int nb0, int item, int lane, f32x4 (&v)[8]) {
;     const int kb = item / nblk, nb = nb0 + item % nblk;
;     const float* src = W + (size_t)(64 * kb + (lane >> 3)) * N + 32 * nb + 4 * (lane & 7);
; #pragma unroll
;     for (int i = 0; i < 8; ++i) v[i] = __builtin_nontemporal_load((const f32x4*)(src + (size_t)(8 * i) * N));
; }
; __device__ __forceinline__ void p0_item_store(const f32x4 (&v)[8], int K, int nblk, int nb0, bf16* __restrict__ WT, int mode, LAS float* scr, int item, int lane) {
;     const int kb = item / nblk, nb = nb0 + item % nblk, k0 = 64 * kb, n0 = 32 * nb;
; #pragma unroll
;     for (int i = 0; i < 8; ++i) { LAS float* d = scr + (8 * i + (lane >> 3)) * 33 + 4 * (lane & 7); d[0] = v[i].x; d[1] = v[i].y; d[2] = v[i].z; d[3] = v[i].w; }
;     LDS_WAIT(); asm volatile("" ::: "memory");
;     const int c = lane & 7, r0 = map_row(n0, mode);
;     const float wsc = mode == 1 ? 1.44269504089f : (mode == 2 ? 0.69314718056f : 1.0f);
; #pragma unroll
;     for (int j = 0; j < 4; ++j) { const int n = (lane >> 3) + 8 * j; const LAS float* s = scr + (8 * c) * 33 + n;
;         v4u o; o.x = cvt_pk_bf16(s[0 * 33] * wsc, s[1 * 33] * wsc); o.y = cvt_pk_bf16(s[2 * 33] * wsc, s[3 * 33] * wsc); o.z = cvt_pk_bf16(s[4 * 33] * wsc, s[5 * 33] * wsc); o.w = cvt_pk_bf16(s[6 * 33] * wsc, s[7 * 33] * wsc);
;         *(v4u*)(WT + (size_t)(r0 + n) * K + k0 + 8 * c) = o; }
;     LDS_WAIT(); asm volatile("" ::: "memory");
; }
;     LAS float* scr = (LAS float*)(F.lds + RING_OFF + F.wave * 16384);
;     const int nblk = nbn ? nbn : N / 32, nall = (K / 64) * nblk, nitems = (int)((long)nall * f1 / 16);
;     int it = (int)((long)nall * f0 / 16) + w0; if (it >= nitems) return;
;     f32x4 va[8], vb[8], vc[8];
;     __builtin_amdgcn_s_waitcnt(0x0F70);
;     const int last = nitems - 1, ntri = ((nitems - it + nw - 1) / nw + 2) / 3;
;     int i1 = min(it + nw, last);
;     p0_item_load(W, N, nblk, nb0, it, F.lane, va);
;     p0_item_load(W, N, nblk, nb0, i1, F.lane, vb); __builtin_amdgcn_sched_barrier(0);
;     for (int p = 0; p < ntri; ++p) {
;         const int i2 = min(i1 + nw, last), i3 = min(i2 + nw, last), i4 = min(i3 + nw, last);
;         p0_item_load(W, N, nblk, nb0, i2, F.lane, vc); __builtin_amdgcn_sched_barrier(0);
.LBB0_25:
	s_add_i32 s2, s13, s90
	s_min_i32 s17, s2, 0xdff
	s_mul_hi_i32 s2, s17, 0x92492493
	s_add_i32 s2, s2, s17
	s_lshr_b32 s3, s2, 31
	s_ashr_i32 s2, s2, 5
	s_add_i32 s2, s2, s3
	s_mul_i32 s3, s2, 56
	s_lshl_b32 s2, s2, 6
	v_or_b32_e32 v66, s2, v1
	v_mov_b64_e32 v[102:103], s[84:85]
	s_sub_i32 s3, s17, s3
	v_mad_i64_i32 v[66:67], s[4:5], v66, s7, v[102:103]
	s_lshl_b32 s4, s3, 5
	s_ashr_i32 s5, s4, 31
	v_lshl_add_u64 v[66:67], s[4:5], 2, v[66:67]
	v_lshl_add_u64 v[90:91], v[66:67], 0, v[98:99]
	v_add_co_u32_e32 v70, vcc, s8, v90
	s_add_i32 s17, s17, s90
	s_nop 0
	v_addc_co_u32_e32 v71, vcc, 0, v91, vcc
	v_add_co_u32_e32 v74, vcc, s9, v90
	global_load_dwordx4 v[66:69], v[90:91], off nt
	s_nop 0
	global_load_dwordx4 v[70:73], v[70:71], off nt
	v_addc_co_u32_e32 v75, vcc, 0, v91, vcc
	v_add_co_u32_e32 v78, vcc, s10, v90
	s_min_i32 s5, s17, 0xdff
	s_nop 0
	v_addc_co_u32_e32 v79, vcc, 0, v91, vcc
	v_add_co_u32_e32 v82, vcc, s11, v90
	global_load_dwordx4 v[74:77], v[74:75], off nt
	s_nop 0
	global_load_dwordx4 v[78:81], v[78:79], off nt
	v_addc_co_u32_e32 v83, vcc, 0, v91, vcc
	v_add_co_u32_e32 v86, vcc, s14, v90
	s_add_i32 s17, s5, s90
	s_nop 0
	v_addc_co_u32_e32 v87, vcc, 0, v91, vcc
	v_add_co_u32_e32 v92, vcc, s15, v90
	global_load_dwordx4 v[82:85], v[82:83], off nt
	s_nop 0
	global_load_dwordx4 v[86:89], v[86:87], off nt
	v_addc_co_u32_e32 v93, vcc, 0, v91, vcc
	v_add_co_u32_e32 v94, vcc, s16, v90
	s_min_i32 s17, s17, 0xdff
	s_nop 0
	v_addc_co_u32_e32 v95, vcc, 0, v91, vcc
	global_load_dwordx4 v[90:93], v[92:93], off nt
	s_nop 0
	global_load_dwordx4 v[94:97], v[94:95], off nt
	v_add_u32_e32 v104, v108, v109
	v_add_u32_e32 v105, 0x420, v104
	v_add_u32_e32 v106, 0x428, v104
	v_add_u32_e32 v107, 0x840, v104
	v_add_u32_e32 v115, 0x848, v104
	v_add_u32_e32 v116, 0xc60, v104
	v_add_u32_e32 v117, 0xc68, v104
	v_add_u32_e32 v118, 0x1080, v104
	v_add_u32_e32 v119, 0x1088, v104
	v_add_u32_e32 v120, 0x14a0, v104
	v_add_u32_e32 v121, 0x14a8, v104
	v_add_u32_e32 v122, 0x18c0, v104
	v_add_u32_e32 v123, 0x18c8, v104
	v_add_u32_e32 v124, 0x1ce0, v104
	v_add_u32_e32 v125, 0x1ce8, v104
	s_waitcnt vmcnt(17)
	ds_write2_b32 v104, v30, v31 offset1:1
	ds_write2_b32 v104, v32, v33 offset0:2 offset1:3
	ds_write2_b32 v105, v2, v3 offset1:1
	ds_write2_b32 v106, v4, v5 offset1:1
	ds_write2_b32 v107, v6, v7 offset1:1
	ds_write2_b32 v115, v8, v9 offset1:1
	ds_write2_b32 v116, v10, v11 offset1:1
	ds_write2_b32 v117, v12, v13 offset1:1
	ds_write2_b32 v118, v14, v15 offset1:1
	ds_write2_b32 v119, v16, v17 offset1:1
	ds_write2_b32 v120, v26, v27 offset1:1
	ds_write2_b32 v121, v28, v29 offset1:1
	ds_write2_b32 v122, v34, v35 offset1:1
	ds_write2_b32 v123, v36, v37 offset1:1
	s_waitcnt vmcnt(15)
	ds_write2_b32 v124, v42, v43 offset1:1
	ds_write2_b32 v125, v44, v45 offset1:1
	s_waitcnt lgkmcnt(0)
	ds_read2_b32 v[240:241], v113 offset1:33
	ds_read2_b32 v[242:243], v113 offset0:66 offset1:99
	ds_read2_b32 v[244:245], v113 offset0:132 offset1:165
	ds_read2_b32 v[246:247], v113 offset0:198 offset1:231
	ds_read2_b32 v[248:249], v113 offset0:8 offset1:41
	ds_read2_b32 v[250:251], v113 offset0:74 offset1:107
	ds_read2_b32 v[252:253], v113 offset0:140 offset1:173
	ds_read2_b32 v[254:255], v113 offset0:206 offset1:239
	s_mul_hi_i32 s19, s18, 0x92492493
	s_add_i32 s19, s19, s18
	s_lshr_b32 s20, s19, 31
	s_ashr_i32 s19, s19, 5
	s_waitcnt lgkmcnt(7)
	v_mul_f32_e32 v2, 0x3f317218, v240
	v_mul_f32_e32 v3, 0x3f317218, v241
	v_cvt_pk_bf16_f32 v2, v2, v3
	ds_read2_b32 v[240:241], v113 offset0:16 offset1:49
	s_add_i32 s19, s19, s20
	s_mul_i32 s20, s19, 56
	s_sub_i32 s18, s18, s20
	s_lshl_b32 s20, s18, 5
	s_waitcnt lgkmcnt(7)
	v_mul_f32_e32 v3, 0x3f317218, v242
	v_mul_f32_e32 v4, 0x3f317218, v243
	v_cvt_pk_bf16_f32 v3, v3, v4
	ds_read2_b32 v[242:243], v113 offset0:82 offset1:115
	s_lshl_b32 s18, s18, 6
	s_and_b32 s18, s18, 0xffffff00
	s_or_b32 s20, s20, 0xffffff80
	s_add_i32 s18, s20, s18
	s_waitcnt lgkmcnt(7)
	v_mul_f32_e32 v4, 0x3f317218, v244
	v_mul_f32_e32 v5, 0x3f317218, v245
	v_cvt_pk_bf16_f32 v4, v4, v5
	ds_read2_b32 v[244:245], v113 offset0:148 offset1:181
	s_add_i32 s20, s18, 0x100
	s_lshl_b32 s18, s19, 6
	s_ashr_i32 s19, s18, 31
	v_lshl_add_u64 v[8:9], s[18:19], 1, v[100:101]
	s_waitcnt lgkmcnt(7)
	v_mul_f32_e32 v5, 0x3f317218, v246
	v_mul_f32_e32 v6, 0x3f317218, v247
	v_cvt_pk_bf16_f32 v5, v5, v6
	ds_read2_b32 v[246:247], v113 offset0:214 offset1:247
	v_or_b32_e32 v6, s20, v1
	v_ashrrev_i32_e32 v7, 31, v6
	v_lshlrev_b64 v[6:7], 13, v[6:7]
	v_lshl_add_u64 v[6:7], v[8:9], 0, v[6:7]
	global_store_dwordx4 v[6:7], v[2:5], off
	s_waitcnt lgkmcnt(7)
	s_nop 0
	v_mul_f32_e32 v2, 0x3f317218, v248
	v_mul_f32_e32 v3, 0x3f317218, v249
	v_cvt_pk_bf16_f32 v2, v2, v3
	ds_read2_b32 v[248:249], v113 offset0:24 offset1:57
	s_waitcnt lgkmcnt(7)
	v_mul_f32_e32 v3, 0x3f317218, v250
	v_mul_f32_e32 v4, 0x3f317218, v251
	v_cvt_pk_bf16_f32 v3, v3, v4
	ds_read2_b32 v[250:251], v113 offset0:90 offset1:123
	s_waitcnt lgkmcnt(7)
	v_mul_f32_e32 v4, 0x3f317218, v252
	v_mul_f32_e32 v5, 0x3f317218, v253
	v_cvt_pk_bf16_f32 v4, v4, v5
	ds_read2_b32 v[252:253], v113 offset0:156 offset1:189
	s_waitcnt lgkmcnt(7)
	v_mul_f32_e32 v5, 0x3f317218, v254
	v_mul_f32_e32 v6, 0x3f317218, v255
	v_cvt_pk_bf16_f32 v5, v5, v6
	ds_read2_b32 v[254:255], v113 offset0:222 offset1:255
	v_or_b32_e32 v6, s20, v110
	v_ashrrev_i32_e32 v7, 31, v6
	v_lshlrev_b64 v[6:7], 13, v[6:7]
	v_lshl_add_u64 v[6:7], v[8:9], 0, v[6:7]
	global_store_dwordx4 v[6:7], v[2:5], off
	s_waitcnt lgkmcnt(7)
	s_nop 0
	v_mul_f32_e32 v2, 0x3f317218, v240
	v_mul_f32_e32 v3, 0x3f317218, v241
	v_cvt_pk_bf16_f32 v2, v2, v3
	s_waitcnt lgkmcnt(6)
; __device__ __forceinline__ unsigned cvt_pk_bf16(float lo, float hi) { unsigned r; asm volatile("v_cvt_pk_bf16_f32 %0, %1, %2" : "=v"(r) : "v"(lo), "v"(hi)); return r; }
; #define LAS __attribute__((address_space(3)))
; #define LDS_WAIT() asm volatile("s_waitcnt lgkmcnt(0)" ::: "memory")
; __device__ __forceinline__ void p0_item_load(const float* __restrict__ W, int N, int nblk, int nb0, int item, int lane, f32x4 (&v)[8]) {
;     const int kb = item / nblk, nb = nb0 + item % nblk;
;     const float* src = W + (size_t)(64 * kb + (lane >> 3)) * N + 32 * nb + 4 * (lane & 7);
; #pragma unroll
;     for (int i = 0; i < 8; ++i) v[i] = __builtin_nontemporal_load((const f32x4*)(src + (size_t)(8 * i) * N));
; }
; __device__ __forceinline__ void p0_item_store(const f32x4 (&v)[8], int K, int nblk, int nb0, bf16* __restrict__ WT, int mode, LAS float* scr, int item, int lane) {
;     const int kb = item / nblk, nb = nb0 + item % nblk, k0 = 64 * kb, n0 = 32 * nb;
; #pragma unroll
;     for (int i = 0; i < 8; ++i) { LAS float* d = scr + (8 * i + (lane >> 3)) * 33 + 4 * (lane & 7); d[0] = v[i].x; d[1] = v[i].y; d[2] = v[i].z; d[3] = v[i].w; }
;     LDS_WAIT(); asm volatile("" ::: "memory");
;     const int c = lane & 7, r0 = map_row(n0, mode);
;     const float wsc = mode == 1 ? 1.44269504089f : (mode == 2 ? 0.69314718056f : 1.0f);
; #pragma unroll
;     for (int j = 0; j < 4; ++j) { const int n = (lane >> 3) + 8 * j; const LAS float* s = scr + (8 * c) * 33 + n;
;         v4u o; o.x = cvt_pk_bf16(s[0 * 33] * wsc, s[1 * 33] * wsc); o.y = cvt_pk_bf16(s[2 * 33] * wsc, s[3 * 33] * wsc); o.z = cvt_pk_bf16(s[4 * 33] * wsc, s[5 * 33] * wsc); o.w = cvt_pk_bf16(s[6 * 33] * wsc, s[7 * 33] * wsc);
;         *(v4u*)(WT + (size_t)(r0 + n) * K + k0 + 8 * c) = o; }
;     LDS_WAIT(); asm volatile("" ::: "memory");
; }
	v_mul_f32_e32 v3, 0x3f317218, v242
	v_mul_f32_e32 v4, 0x3f317218, v243
	v_cvt_pk_bf16_f32 v3, v3, v4
	s_waitcnt lgkmcnt(5)
	v_mul_f32_e32 v4, 0x3f317218, v244
	v_mul_f32_e32 v5, 0x3f317218, v245
	v_cvt_pk_bf16_f32 v4, v4, v5
	s_waitcnt lgkmcnt(4)
	v_mul_f32_e32 v5, 0x3f317218, v246
	v_mul_f32_e32 v6, 0x3f317218, v247
	v_cvt_pk_bf16_f32 v5, v5, v6
	v_or_b32_e32 v6, s20, v111
	v_ashrrev_i32_e32 v7, 31, v6
	v_lshlrev_b64 v[6:7], 13, v[6:7]
	v_lshl_add_u64 v[6:7], v[8:9], 0, v[6:7]
	global_store_dwordx4 v[6:7], v[2:5], off
	s_waitcnt lgkmcnt(3)
	s_nop 0
	v_mul_f32_e32 v2, 0x3f317218, v248
	v_mul_f32_e32 v3, 0x3f317218, v249
	v_cvt_pk_bf16_f32 v2, v2, v3
	s_waitcnt lgkmcnt(2)
	v_mul_f32_e32 v3, 0x3f317218, v250
	v_mul_f32_e32 v4, 0x3f317218, v251
	v_cvt_pk_bf16_f32 v3, v3, v4
	s_waitcnt lgkmcnt(1)
	v_mul_f32_e32 v4, 0x3f317218, v252
	v_mul_f32_e32 v5, 0x3f317218, v253
	v_cvt_pk_bf16_f32 v4, v4, v5
	s_waitcnt lgkmcnt(0)
	v_mul_f32_e32 v5, 0x3f317218, v254
	v_mul_f32_e32 v6, 0x3f317218, v255
	v_cvt_pk_bf16_f32 v5, v5, v6
	v_or_b32_e32 v6, s20, v112
	v_ashrrev_i32_e32 v7, 31, v6
	v_lshlrev_b64 v[6:7], 13, v[6:7]
	v_lshl_add_u64 v[6:7], v[8:9], 0, v[6:7]
	global_store_dwordx4 v[6:7], v[2:5], off
	s_waitcnt lgkmcnt(0)
	s_mul_hi_i32 s18, s5, 0x92492493
	s_add_i32 s18, s18, s5
	s_lshr_b32 s19, s18, 31
	s_ashr_i32 s18, s18, 5
	s_add_i32 s18, s18, s19
	s_mul_i32 s19, s18, 56
	v_lshl_or_b32 v2, s18, 6, v1
	s_sub_i32 s20, s5, s19
	v_mad_i64_i32 v[2:3], s[18:19], v2, s7, v[102:103]
	s_lshl_b32 s18, s20, 5
	s_ashr_i32 s19, s18, 31
	v_lshl_add_u64 v[2:3], s[18:19], 2, v[2:3]
	v_lshl_add_u64 v[34:35], v[2:3], 0, v[98:99]
	v_add_co_u32_e32 v2, vcc, s8, v34
	s_nop 1
	v_addc_co_u32_e32 v3, vcc, 0, v35, vcc
	v_add_co_u32_e32 v6, vcc, s9, v34
	global_load_dwordx4 v[30:33], v[34:35], off nt
	s_nop 0
	global_load_dwordx4 v[2:5], v[2:3], off nt
	v_addc_co_u32_e32 v7, vcc, 0, v35, vcc
	v_add_co_u32_e32 v10, vcc, s10, v34
	s_nop 1
	v_addc_co_u32_e32 v11, vcc, 0, v35, vcc
	v_add_co_u32_e32 v14, vcc, s11, v34
	global_load_dwordx4 v[6:9], v[6:7], off nt
	s_nop 0
	global_load_dwordx4 v[10:13], v[10:11], off nt
	v_addc_co_u32_e32 v15, vcc, 0, v35, vcc
	v_add_co_u32_e32 v26, vcc, s14, v34
	s_nop 1
	v_addc_co_u32_e32 v27, vcc, 0, v35, vcc
	v_add_co_u32_e32 v36, vcc, s15, v34
	global_load_dwordx4 v[14:17], v[14:15], off nt
	s_nop 0
	global_load_dwordx4 v[26:29], v[26:27], off nt
	v_addc_co_u32_e32 v37, vcc, 0, v35, vcc
	v_add_co_u32_e32 v42, vcc, s16, v34
	s_nop 1
	v_addc_co_u32_e32 v43, vcc, 0, v35, vcc
	global_load_dwordx4 v[34:37], v[36:37], off nt
	s_nop 0
	global_load_dwordx4 v[42:45], v[42:43], off nt
	ds_write2_b32 v104, v18, v19 offset1:1
	ds_write2_b32 v104, v20, v21 offset0:2 offset1:3
	s_waitcnt vmcnt(26)
	ds_write2_b32 v105, v22, v23 offset1:1
	ds_write2_b32 v106, v24, v25 offset1:1
	s_waitcnt vmcnt(25)
	ds_write2_b32 v107, v38, v39 offset1:1
	ds_write2_b32 v115, v40, v41 offset1:1
	s_waitcnt vmcnt(24)
	ds_write2_b32 v116, v46, v47 offset1:1
	ds_write2_b32 v117, v48, v49 offset1:1
	s_waitcnt vmcnt(23)
	ds_write2_b32 v118, v50, v51 offset1:1
	ds_write2_b32 v119, v52, v53 offset1:1
	s_waitcnt vmcnt(22)
	ds_write2_b32 v120, v54, v55 offset1:1
	ds_write2_b32 v121, v56, v57 offset1:1
	s_waitcnt vmcnt(21)
	ds_write2_b32 v122, v58, v59 offset1:1
	ds_write2_b32 v123, v60, v61 offset1:1
	s_waitcnt vmcnt(20)
	ds_write2_b32 v124, v62, v63 offset1:1
	ds_write2_b32 v125, v64, v65 offset1:1
	s_waitcnt lgkmcnt(0)
	ds_read2_b32 v[240:241], v113 offset1:33
	ds_read2_b32 v[242:243], v113 offset0:66 offset1:99
	ds_read2_b32 v[244:245], v113 offset0:132 offset1:165
	ds_read2_b32 v[246:247], v113 offset0:198 offset1:231
	ds_read2_b32 v[248:249], v113 offset0:8 offset1:41
	ds_read2_b32 v[250:251], v113 offset0:74 offset1:107
	ds_read2_b32 v[252:253], v113 offset0:140 offset1:173
	ds_read2_b32 v[254:255], v113 offset0:206 offset1:239
	s_mul_hi_i32 s18, s13, 0x92492493
	s_add_i32 s18, s18, s13
	s_lshr_b32 s19, s18, 31
	s_ashr_i32 s18, s18, 5
	s_waitcnt lgkmcnt(7)
	v_mul_f32_e32 v18, 0x3f317218, v240
	v_mul_f32_e32 v19, 0x3f317218, v241
	v_cvt_pk_bf16_f32 v18, v18, v19
	ds_read2_b32 v[240:241], v113 offset0:16 offset1:49
	s_add_i32 s18, s18, s19
	s_mul_i32 s19, s18, 56
	s_sub_i32 s13, s13, s19
	s_lshl_b32 s19, s13, 5
	s_waitcnt lgkmcnt(7)
	v_mul_f32_e32 v19, 0x3f317218, v242
	v_mul_f32_e32 v20, 0x3f317218, v243
	v_cvt_pk_bf16_f32 v19, v19, v20
	ds_read2_b32 v[242:243], v113 offset0:82 offset1:115
	s_lshl_b32 s13, s13, 6
	s_and_b32 s13, s13, 0xffffff00
	s_or_b32 s19, s19, 0xffffff80
	s_add_i32 s13, s19, s13
	s_waitcnt lgkmcnt(7)
	v_mul_f32_e32 v20, 0x3f317218, v244
	v_mul_f32_e32 v21, 0x3f317218, v245
	v_cvt_pk_bf16_f32 v20, v20, v21
	ds_read2_b32 v[244:245], v113 offset0:148 offset1:181
	s_addk_i32 s13, 0x100
	s_lshl_b32 s18, s18, 6
	s_ashr_i32 s19, s18, 31
	v_lshl_add_u64 v[24:25], s[18:19], 1, v[100:101]
	s_waitcnt lgkmcnt(7)
	v_mul_f32_e32 v21, 0x3f317218, v246
	v_mul_f32_e32 v22, 0x3f317218, v247
	v_cvt_pk_bf16_f32 v21, v21, v22
	ds_read2_b32 v[246:247], v113 offset0:214 offset1:247
	v_or_b32_e32 v22, s13, v1
	v_ashrrev_i32_e32 v23, 31, v22
	v_lshlrev_b64 v[22:23], 13, v[22:23]
	v_lshl_add_u64 v[22:23], v[24:25], 0, v[22:23]
	global_store_dwordx4 v[22:23], v[18:21], off
	s_waitcnt lgkmcnt(7)
	s_nop 0
	v_mul_f32_e32 v18, 0x3f317218, v248
	v_mul_f32_e32 v19, 0x3f317218, v249
	v_cvt_pk_bf16_f32 v18, v18, v19
	ds_read2_b32 v[248:249], v113 offset0:24 offset1:57
	s_waitcnt lgkmcnt(7)
	v_mul_f32_e32 v19, 0x3f317218, v250
	v_mul_f32_e32 v20, 0x3f317218, v251
	v_cvt_pk_bf16_f32 v19, v19, v20
	ds_read2_b32 v[250:251], v113 offset0:90 offset1:123
	s_waitcnt lgkmcnt(7)
; __device__ __forceinline__ unsigned cvt_pk_bf16(float lo, float hi) { unsigned r; asm volatile("v_cvt_pk_bf16_f32 %0, %1, %2" : "=v"(r) : "v"(lo), "v"(hi)); return r; }
; #define LAS __attribute__((address_space(3)))
; #define LDS_WAIT() asm volatile("s_waitcnt lgkmcnt(0)" ::: "memory")
; __device__ __forceinline__ void p0_item_load(const float* __restrict__ W, int N, int nblk, int nb0, int item, int lane, f32x4 (&v)[8]) {
;     const int kb = item / nblk, nb = nb0 + item % nblk;
;     const float* src = W + (size_t)(64 * kb + (lane >> 3)) * N + 32 * nb + 4 * (lane & 7);
; #pragma unroll
;     for (int i = 0; i < 8; ++i) v[i] = __builtin_nontemporal_load((const f32x4*)(src + (size_t)(8 * i) * N));
; }
; __device__ __forceinline__ void p0_item_store(const f32x4 (&v)[8], int K, int nblk, int nb0, bf16* __restrict__ WT, int mode, LAS float* scr, int item, int lane) {
;     const int kb = item / nblk, nb = nb0 + item % nblk, k0 = 64 * kb, n0 = 32 * nb;
; #pragma unroll
;     for (int i = 0; i < 8; ++i) { LAS float* d = scr + (8 * i + (lane >> 3)) * 33 + 4 * (lane & 7); d[0] = v[i].x; d[1] = v[i].y; d[2] = v[i].z; d[3] = v[i].w; }
;     LDS_WAIT(); asm volatile("" ::: "memory");
;     const int c = lane & 7, r0 = map_row(n0, mode);
;     const float wsc = mode == 1 ? 1.44269504089f : (mode == 2 ? 0.69314718056f : 1.0f);
; #pragma unroll
;     for (int j = 0; j < 4; ++j) { const int n = (lane >> 3) + 8 * j; const LAS float* s = scr + (8 * c) * 33 + n;
;         v4u o; o.x = cvt_pk_bf16(s[0 * 33] * wsc, s[1 * 33] * wsc); o.y = cvt_pk_bf16(s[2 * 33] * wsc, s[3 * 33] * wsc); o.z = cvt_pk_bf16(s[4 * 33] * wsc, s[5 * 33] * wsc); o.w = cvt_pk_bf16(s[6 * 33] * wsc, s[7 * 33] * wsc);
;         *(v4u*)(WT + (size_t)(r0 + n) * K + k0 + 8 * c) = o; }
;     LDS_WAIT(); asm volatile("" ::: "memory");
; }
	v_mul_f32_e32 v20, 0x3f317218, v252
	v_mul_f32_e32 v21, 0x3f317218, v253
	v_cvt_pk_bf16_f32 v20, v20, v21
	ds_read2_b32 v[252:253], v113 offset0:156 offset1:189
	s_waitcnt lgkmcnt(7)
	v_mul_f32_e32 v21, 0x3f317218, v254
	v_mul_f32_e32 v22, 0x3f317218, v255
	v_cvt_pk_bf16_f32 v21, v21, v22
	ds_read2_b32 v[254:255], v113 offset0:222 offset1:255
	v_or_b32_e32 v22, s13, v110
	v_ashrrev_i32_e32 v23, 31, v22
	v_lshlrev_b64 v[22:23], 13, v[22:23]
	v_lshl_add_u64 v[22:23], v[24:25], 0, v[22:23]
	global_store_dwordx4 v[22:23], v[18:21], off
	s_waitcnt lgkmcnt(7)
	s_nop 0
	v_mul_f32_e32 v18, 0x3f317218, v240
	v_mul_f32_e32 v19, 0x3f317218, v241
	v_cvt_pk_bf16_f32 v18, v18, v19
	s_waitcnt lgkmcnt(6)
	v_mul_f32_e32 v19, 0x3f317218, v242
	v_mul_f32_e32 v20, 0x3f317218, v243
	v_cvt_pk_bf16_f32 v19, v19, v20
	s_waitcnt lgkmcnt(5)
	v_mul_f32_e32 v20, 0x3f317218, v244
	v_mul_f32_e32 v21, 0x3f317218, v245
	v_cvt_pk_bf16_f32 v20, v20, v21
	s_waitcnt lgkmcnt(4)
	v_mul_f32_e32 v21, 0x3f317218, v246
	v_mul_f32_e32 v22, 0x3f317218, v247
	v_cvt_pk_bf16_f32 v21, v21, v22
	v_or_b32_e32 v22, s13, v111
	v_ashrrev_i32_e32 v23, 31, v22
	v_lshlrev_b64 v[22:23], 13, v[22:23]
	v_lshl_add_u64 v[22:23], v[24:25], 0, v[22:23]
	global_store_dwordx4 v[22:23], v[18:21], off
	s_waitcnt lgkmcnt(3)
	s_nop 0
	v_mul_f32_e32 v18, 0x3f317218, v248
	v_mul_f32_e32 v19, 0x3f317218, v249
	v_cvt_pk_bf16_f32 v18, v18, v19
	s_waitcnt lgkmcnt(2)
	v_mul_f32_e32 v19, 0x3f317218, v250
	v_mul_f32_e32 v20, 0x3f317218, v251
	v_cvt_pk_bf16_f32 v19, v19, v20
	s_waitcnt lgkmcnt(1)
	v_mul_f32_e32 v20, 0x3f317218, v252
	v_mul_f32_e32 v21, 0x3f317218, v253
	v_cvt_pk_bf16_f32 v20, v20, v21
	s_waitcnt lgkmcnt(0)
	v_mul_f32_e32 v21, 0x3f317218, v254
	v_mul_f32_e32 v22, 0x3f317218, v255
	v_cvt_pk_bf16_f32 v21, v21, v22
	v_or_b32_e32 v22, s13, v112
	v_ashrrev_i32_e32 v23, 31, v22
	v_lshlrev_b64 v[22:23], 13, v[22:23]
	v_lshl_add_u64 v[22:23], v[24:25], 0, v[22:23]
	global_store_dwordx4 v[22:23], v[18:21], off
	s_waitcnt lgkmcnt(0)
	s_mul_hi_i32 s13, s17, 0x92492493
	s_add_i32 s13, s13, s17
	s_lshr_b32 s18, s13, 31
	s_ashr_i32 s13, s13, 5
	s_add_i32 s13, s13, s18
	s_mul_i32 s18, s13, 56
	v_lshl_or_b32 v18, s13, 6, v1
	s_sub_i32 s20, s17, s18
	v_mad_i64_i32 v[18:19], s[18:19], v18, s7, v[102:103]
	s_lshl_b32 s18, s20, 5
	s_ashr_i32 s19, s18, 31
	v_lshl_add_u64 v[18:19], s[18:19], 2, v[18:19]
	v_lshl_add_u64 v[58:59], v[18:19], 0, v[98:99]
	v_add_co_u32_e32 v22, vcc, s8, v58
	s_nop 1
	v_addc_co_u32_e32 v23, vcc, 0, v59, vcc
	v_add_co_u32_e32 v38, vcc, s9, v58
	global_load_dwordx4 v[18:21], v[58:59], off nt
	s_nop 0
	global_load_dwordx4 v[22:25], v[22:23], off nt
	v_addc_co_u32_e32 v39, vcc, 0, v59, vcc
	v_add_co_u32_e32 v46, vcc, s10, v58
	s_nop 1
	v_addc_co_u32_e32 v47, vcc, 0, v59, vcc
	v_add_co_u32_e32 v50, vcc, s11, v58
	global_load_dwordx4 v[38:41], v[38:39], off nt
	s_nop 0
	global_load_dwordx4 v[46:49], v[46:47], off nt
	v_addc_co_u32_e32 v51, vcc, 0, v59, vcc
	v_add_co_u32_e32 v54, vcc, s14, v58
	s_nop 1
	v_addc_co_u32_e32 v55, vcc, 0, v59, vcc
	v_add_co_u32_e32 v60, vcc, s15, v58
	global_load_dwordx4 v[50:53], v[50:51], off nt
	s_nop 0
	global_load_dwordx4 v[54:57], v[54:55], off nt
	v_addc_co_u32_e32 v61, vcc, 0, v59, vcc
	v_add_co_u32_e32 v62, vcc, s16, v58
	s_nop 1
	v_addc_co_u32_e32 v63, vcc, 0, v59, vcc
	global_load_dwordx4 v[58:61], v[60:61], off nt
	s_nop 0
	global_load_dwordx4 v[62:65], v[62:63], off nt
	s_waitcnt vmcnt(31)
	ds_write2_b32 v104, v66, v67 offset1:1
	ds_write2_b32 v104, v68, v69 offset0:2 offset1:3
	s_waitcnt vmcnt(30)
	ds_write2_b32 v105, v70, v71 offset1:1
	ds_write2_b32 v106, v72, v73 offset1:1
	s_waitcnt vmcnt(29)
	ds_write2_b32 v107, v74, v75 offset1:1
	ds_write2_b32 v115, v76, v77 offset1:1
	s_waitcnt vmcnt(28)
	ds_write2_b32 v116, v78, v79 offset1:1
	ds_write2_b32 v117, v80, v81 offset1:1
	s_waitcnt vmcnt(27)
	ds_write2_b32 v118, v82, v83 offset1:1
	ds_write2_b32 v119, v84, v85 offset1:1
	s_waitcnt vmcnt(26)
	ds_write2_b32 v120, v86, v87 offset1:1
	ds_write2_b32 v121, v88, v89 offset1:1
	s_waitcnt vmcnt(25)
	ds_write2_b32 v122, v90, v91 offset1:1
	ds_write2_b32 v123, v92, v93 offset1:1
	s_waitcnt vmcnt(24)
; #define LAS __attribute__((address_space(3)))
; __device__ __forceinline__ void p0_item_load(const float* __restrict__ W, int N, int nblk, int nb0, int item, int lane, f32x4 (&v)[8]) {
;     const int kb = item / nblk, nb = nb0 + item % nblk;
;     const float* src = W + (size_t)(64 * kb + (lane >> 3)) * N + 32 * nb + 4 * (lane & 7);
; #pragma unroll
;     for (int i = 0; i < 8; ++i) v[i] = __builtin_nontemporal_load((const f32x4*)(src + (size_t)(8 * i) * N));
; }
; __device__ __forceinline__ void p0_item_store(const f32x4 (&v)[8], int K, int nblk, int nb0, bf16* __restrict__ WT, int mode, LAS float* scr, int item, int lane) {
;     const int kb = item / nblk, nb = nb0 + item % nblk, k0 = 64 * kb, n0 = 32 * nb;
; #pragma unroll
;     for (int i = 0; i < 8; ++i) { LAS float* d = scr + (8 * i + (lane >> 3)) * 33 + 4 * (lane & 7); d[0] = v[i].x; d[1] = v[i].y; d[2] = v[i].z; d[3] = v[i].w; }
;     LDS_WAIT(); asm volatile("" ::: "memory");
;     const int c = lane & 7, r0 = map_row(n0, mode);
;     const float wsc = mode == 1 ? 1.44269504089f : (mode == 2 ? 0.69314718056f : 1.0f);
; #pragma unroll
;     for (int j = 0; j < 4; ++j) { const int n = (lane >> 3) + 8 * j; const LAS float* s = scr + (8 * c) * 33 + n;
;         v4u o; o.x = cvt_pk_bf16(s[0 * 33] * wsc, s[1 * 33] * wsc); o.y = cvt_pk_bf16(s[2 * 33] * wsc, s[3 * 33] * wsc); o.z = cvt_pk_bf16(s[4 * 33] * wsc, s[5 * 33] * wsc); o.w = cvt_pk_bf16(s[6 * 33] * wsc, s[7 * 33] * wsc);
;         *(v4u*)(WT + (size_t)(r0 + n) * K + k0 + 8 * c) = o; }
;     LDS_WAIT(); asm volatile("" ::: "memory");
; }
;     ...
;     for (int p = 0; p < ntri; ++p) {
;         const int i2 = min(i1 + nw, last), i3 = min(i2 + nw, last), i4 = min(i3 + nw, last);
;         p0_item_load(W, N, nblk, nb0, i2, F.lane, vc); __builtin_amdgcn_sched_barrier(0);
;         p0_item_store(va, K, nblk, nb0, WT, mode, scr, it, F.lane); __builtin_amdgcn_sched_barrier(0);
;         p0_item_load(W, N, nblk, nb0, i3, F.lane, va); __builtin_amdgcn_sched_barrier(0);
;         p0_item_store(vb, K, nblk, nb0, WT, mode, scr, i1, F.lane); __builtin_amdgcn_sched_barrier(0);
;         p0_item_load(W, N, nblk, nb0, i4, F.lane, vb); __builtin_amdgcn_sched_barrier(0);
;         p0_item_store(vc, K, nblk, nb0, WT, mode, scr, i2, F.lane); __builtin_amdgcn_sched_barrier(0);
;         it = i3; i1 = i4;
;     }
	ds_write2_b32 v124, v94, v95 offset1:1
	ds_write2_b32 v125, v96, v97 offset1:1
	s_waitcnt lgkmcnt(0)
	ds_read2_b32 v[240:241], v113 offset1:33
	ds_read2_b32 v[242:243], v113 offset0:66 offset1:99
	ds_read2_b32 v[244:245], v113 offset0:132 offset1:165
	ds_read2_b32 v[246:247], v113 offset0:198 offset1:231
	ds_read2_b32 v[248:249], v113 offset0:8 offset1:41
	ds_read2_b32 v[250:251], v113 offset0:74 offset1:107
	ds_read2_b32 v[252:253], v113 offset0:140 offset1:173
	ds_read2_b32 v[254:255], v113 offset0:206 offset1:239
	s_lshl_b32 s3, s3, 6
	s_and_b32 s3, s3, 0xffffff00
	s_or_b32 s4, s4, 0xffffff80
	s_add_i32 s3, s4, s3
	s_waitcnt lgkmcnt(7)
	v_mul_f32_e32 v66, 0x3f317218, v240
	v_mul_f32_e32 v67, 0x3f317218, v241
	v_cvt_pk_bf16_f32 v66, v66, v67
	ds_read2_b32 v[240:241], v113 offset0:16 offset1:49
	s_add_i32 s4, s3, 0x100
	s_ashr_i32 s3, s2, 31
	v_lshl_add_u64 v[72:73], s[2:3], 1, v[100:101]
	s_waitcnt lgkmcnt(7)
	v_mul_f32_e32 v67, 0x3f317218, v242
	v_mul_f32_e32 v68, 0x3f317218, v243
	v_cvt_pk_bf16_f32 v67, v67, v68
	ds_read2_b32 v[242:243], v113 offset0:82 offset1:115
	s_waitcnt lgkmcnt(7)
	v_mul_f32_e32 v68, 0x3f317218, v244
	v_mul_f32_e32 v69, 0x3f317218, v245
	v_cvt_pk_bf16_f32 v68, v68, v69
	ds_read2_b32 v[244:245], v113 offset0:148 offset1:181
	s_waitcnt lgkmcnt(7)
	v_mul_f32_e32 v69, 0x3f317218, v246
	v_mul_f32_e32 v70, 0x3f317218, v247
	v_cvt_pk_bf16_f32 v69, v69, v70
	ds_read2_b32 v[246:247], v113 offset0:214 offset1:247
	v_or_b32_e32 v70, s4, v1
	v_ashrrev_i32_e32 v71, 31, v70
	v_lshlrev_b64 v[70:71], 13, v[70:71]
	v_lshl_add_u64 v[70:71], v[72:73], 0, v[70:71]
	global_store_dwordx4 v[70:71], v[66:69], off
	s_waitcnt lgkmcnt(7)
	s_nop 0
	v_mul_f32_e32 v66, 0x3f317218, v248
	v_mul_f32_e32 v67, 0x3f317218, v249
	v_cvt_pk_bf16_f32 v66, v66, v67
	ds_read2_b32 v[248:249], v113 offset0:24 offset1:57
	s_waitcnt lgkmcnt(7)
	v_mul_f32_e32 v67, 0x3f317218, v250
	v_mul_f32_e32 v68, 0x3f317218, v251
	v_cvt_pk_bf16_f32 v67, v67, v68
	ds_read2_b32 v[250:251], v113 offset0:90 offset1:123
	s_waitcnt lgkmcnt(7)
	v_mul_f32_e32 v68, 0x3f317218, v252
	v_mul_f32_e32 v69, 0x3f317218, v253
	v_cvt_pk_bf16_f32 v68, v68, v69
	ds_read2_b32 v[252:253], v113 offset0:156 offset1:189
	s_waitcnt lgkmcnt(7)
	v_mul_f32_e32 v69, 0x3f317218, v254
	v_mul_f32_e32 v70, 0x3f317218, v255
	v_cvt_pk_bf16_f32 v69, v69, v70
	ds_read2_b32 v[254:255], v113 offset0:222 offset1:255
	v_or_b32_e32 v70, s4, v110
	v_ashrrev_i32_e32 v71, 31, v70
	v_lshlrev_b64 v[70:71], 13, v[70:71]
	v_lshl_add_u64 v[70:71], v[72:73], 0, v[70:71]
	global_store_dwordx4 v[70:71], v[66:69], off
	s_waitcnt lgkmcnt(7)
	s_nop 0
	v_mul_f32_e32 v66, 0x3f317218, v240
	v_mul_f32_e32 v67, 0x3f317218, v241
	v_cvt_pk_bf16_f32 v66, v66, v67
	s_waitcnt lgkmcnt(6)
	v_mul_f32_e32 v67, 0x3f317218, v242
	v_mul_f32_e32 v68, 0x3f317218, v243
	v_cvt_pk_bf16_f32 v67, v67, v68
	s_waitcnt lgkmcnt(5)
	v_mul_f32_e32 v68, 0x3f317218, v244
	v_mul_f32_e32 v69, 0x3f317218, v245
	v_cvt_pk_bf16_f32 v68, v68, v69
	s_waitcnt lgkmcnt(4)
	v_mul_f32_e32 v69, 0x3f317218, v246
	v_mul_f32_e32 v70, 0x3f317218, v247
	v_cvt_pk_bf16_f32 v69, v69, v70
	v_or_b32_e32 v70, s4, v111
	v_ashrrev_i32_e32 v71, 31, v70
	v_lshlrev_b64 v[70:71], 13, v[70:71]
	v_lshl_add_u64 v[70:71], v[72:73], 0, v[70:71]
	global_store_dwordx4 v[70:71], v[66:69], off
	s_waitcnt lgkmcnt(3)
	s_nop 0
	v_mul_f32_e32 v66, 0x3f317218, v248
	v_mul_f32_e32 v67, 0x3f317218, v249
	v_cvt_pk_bf16_f32 v66, v66, v67
	s_waitcnt lgkmcnt(2)
	v_mul_f32_e32 v67, 0x3f317218, v250
	v_mul_f32_e32 v68, 0x3f317218, v251
	v_cvt_pk_bf16_f32 v67, v67, v68
	s_waitcnt lgkmcnt(1)
	v_mul_f32_e32 v68, 0x3f317218, v252
	v_mul_f32_e32 v69, 0x3f317218, v253
	v_cvt_pk_bf16_f32 v68, v68, v69
	s_waitcnt lgkmcnt(0)
	v_mul_f32_e32 v69, 0x3f317218, v254
	v_mul_f32_e32 v70, 0x3f317218, v255
	v_cvt_pk_bf16_f32 v69, v69, v70
	v_or_b32_e32 v70, s4, v112
	v_ashrrev_i32_e32 v71, 31, v70
	v_lshlrev_b64 v[70:71], 13, v[70:71]
	v_lshl_add_u64 v[70:71], v[72:73], 0, v[70:71]
	global_store_dwordx4 v[70:71], v[66:69], off
	s_waitcnt lgkmcnt(0)
	s_add_i32 s6, s6, -1
	s_cmp_lg_u32 s6, 0
	s_mov_b32 s18, s5
	s_mov_b32 s13, s17
	s_cbranch_scc1 .LBB0_25

; #define LAS __attribute__((address_space(3)))
; __device__ __forceinline__ void p0_item_load(const float* __restrict__ W, int N, int nblk, int nb0, int item, int lane, f32x4 (&v)[8]) {
;     const int kb = item / nblk, nb = nb0 + item % nblk;
;     const float* src = W + (size_t)(64 * kb + (lane >> 3)) * N + 32 * nb + 4 * (lane & 7);
; #pragma unroll
;     for (int i = 0; i < 8; ++i) v[i] = __builtin_nontemporal_load((const f32x4*)(src + (size_t)(8 * i) * N));
; }
; __device__ __forceinline__ void p0_item_store(const f32x4 (&v)[8], int K, int nblk, int nb0, bf16* __restrict__ WT, int mode, LAS float* scr, int item, int lane) {
;     const int kb = item / nblk, nb = nb0 + item % nblk, k0 = 64 * kb, n0 = 32 * nb;
; #pragma unroll
;     for (int i = 0; i < 8; ++i) { LAS float* d = scr + (8 * i + (lane >> 3)) * 33 + 4 * (lane & 7); d[0] = v[i].x; d[1] = v[i].y; d[2] = v[i].z; d[3] = v[i].w; }
;     LDS_WAIT(); asm volatile("" ::: "memory");
;     const int c = lane & 7, r0 = map_row(n0, mode);
;     const float wsc = mode == 1 ? 1.44269504089f : (mode == 2 ? 0.69314718056f : 1.0f);
; #pragma unroll
;     for (int j = 0; j < 4; ++j) { const int n = (lane >> 3) + 8 * j; const LAS float* s = scr + (8 * c) * 33 + n;
;         v4u o; o.x = cvt_pk_bf16(s[0 * 33] * wsc, s[1 * 33] * wsc); o.y = cvt_pk_bf16(s[2 * 33] * wsc, s[3 * 33] * wsc); o.z = cvt_pk_bf16(s[4 * 33] * wsc, s[5 * 33] * wsc); o.w = cvt_pk_bf16(s[6 * 33] * wsc, s[7 * 33] * wsc);
;         *(v4u*)(WT + (size_t)(r0 + n) * K + k0 + 8 * c) = o; }
;     LDS_WAIT(); asm volatile("" ::: "memory");
; }
;     LAS float* scr = (LAS float*)(F.lds + RING_OFF + F.wave * 16384);
;     const int nblk = nbn ? nbn : N / 32, nall = (K / 64) * nblk, nitems = (int)((long)nall * f1 / 16);
;     int it = (int)((long)nall * f0 / 16) + w0; if (it >= nitems) return;
;     f32x4 va[8], vb[8], vc[8];
;     __builtin_amdgcn_s_waitcnt(0x0F70);
;     const int last = nitems - 1, ntri = ((nitems - it + nw - 1) / nw + 2) / 3;
;     int i1 = min(it + nw, last);
;     p0_item_load(W, N, nblk, nb0, it, F.lane, va);
;     p0_item_load(W, N, nblk, nb0, i1, F.lane, vb); __builtin_amdgcn_sched_barrier(0);
;     for (int p = 0; p < ntri; ++p) {
;         const int i2 = min(i1 + nw, last), i3 = min(i2 + nw, last), i4 = min(i3 + nw, last);
;         p0_item_load(W, N, nblk, nb0, i2, F.lane, vc); __builtin_amdgcn_sched_barrier(0);
.LBB0_29:
	s_add_i32 s2, s3, s90
	s_min_i32 s15, s2, 0x55ff
	s_mul_hi_i32 s2, s15, 0x2fa0be83
	s_lshr_b32 s4, s2, 31
	s_ashr_i32 s2, s2, 6
	s_add_i32 s2, s2, s4
	s_mul_i32 s4, s2, 0x158
	s_lshl_b32 s2, s2, 6
	v_or_b32_e32 v66, s2, v1
	s_waitcnt lgkmcnt(0)
	v_mov_b64_e32 v[102:103], s[24:25]
	s_sub_i32 s16, s15, s4
	v_mad_i64_i32 v[66:67], s[4:5], v66, s6, v[102:103]
	s_lshl_b32 s4, s16, 5
	s_ashr_i32 s5, s4, 31
	v_lshl_add_u64 v[66:67], s[4:5], 2, v[66:67]
	v_lshl_add_u64 v[90:91], v[66:67], 0, v[98:99]
	v_add_co_u32_e32 v70, vcc, s7, v90
	s_add_i32 s15, s15, s90
	s_nop 0
	v_addc_co_u32_e32 v71, vcc, 0, v91, vcc
	v_add_co_u32_e32 v74, vcc, s8, v90
	global_load_dwordx4 v[66:69], v[90:91], off nt
	s_nop 0
	global_load_dwordx4 v[70:73], v[70:71], off nt
	v_addc_co_u32_e32 v75, vcc, 0, v91, vcc
	v_add_co_u32_e32 v78, vcc, s9, v90
	s_min_i32 s5, s15, 0x55ff
	s_nop 0
	v_addc_co_u32_e32 v79, vcc, 0, v91, vcc
	v_add_co_u32_e32 v82, vcc, s10, v90
	global_load_dwordx4 v[74:77], v[74:75], off nt
	s_nop 0
	global_load_dwordx4 v[78:81], v[78:79], off nt
	v_addc_co_u32_e32 v83, vcc, 0, v91, vcc
	v_add_co_u32_e32 v86, vcc, s11, v90
	s_add_i32 s15, s5, s90
	s_nop 0
	v_addc_co_u32_e32 v87, vcc, 0, v91, vcc
	v_add_co_u32_e32 v92, vcc, s13, v90
	global_load_dwordx4 v[82:85], v[82:83], off nt
	s_nop 0
	global_load_dwordx4 v[86:89], v[86:87], off nt
	v_addc_co_u32_e32 v93, vcc, 0, v91, vcc
	v_add_co_u32_e32 v94, vcc, s14, v90
	s_min_i32 s15, s15, 0x55ff
	s_nop 0
	v_addc_co_u32_e32 v95, vcc, 0, v91, vcc
	global_load_dwordx4 v[90:93], v[92:93], off nt
	s_nop 0
	global_load_dwordx4 v[94:97], v[94:95], off nt
	v_add_u32_e32 v104, v108, v109
	v_add_u32_e32 v105, 0x420, v104
	v_add_u32_e32 v106, 0x428, v104
	v_add_u32_e32 v107, 0x840, v104
	v_add_u32_e32 v114, 0x848, v104
	v_add_u32_e32 v115, 0xc60, v104
	v_add_u32_e32 v116, 0xc68, v104
	v_add_u32_e32 v117, 0x1080, v104
	v_add_u32_e32 v118, 0x1088, v104
	v_add_u32_e32 v119, 0x14a0, v104
	v_add_u32_e32 v120, 0x14a8, v104
	v_add_u32_e32 v121, 0x18c0, v104
	v_add_u32_e32 v122, 0x18c8, v104
	v_add_u32_e32 v123, 0x1ce0, v104
	v_add_u32_e32 v124, 0x1ce8, v104
	s_waitcnt vmcnt(17)
	ds_write2_b32 v104, v30, v31 offset1:1
	ds_write2_b32 v104, v32, v33 offset0:2 offset1:3
	ds_write2_b32 v105, v2, v3 offset1:1
	ds_write2_b32 v106, v4, v5 offset1:1
	ds_write2_b32 v107, v6, v7 offset1:1
	ds_write2_b32 v114, v8, v9 offset1:1
	ds_write2_b32 v115, v10, v11 offset1:1
	ds_write2_b32 v116, v12, v13 offset1:1
	ds_write2_b32 v117, v14, v15 offset1:1
	ds_write2_b32 v118, v16, v17 offset1:1
	ds_write2_b32 v119, v26, v27 offset1:1
	ds_write2_b32 v120, v28, v29 offset1:1
	ds_write2_b32 v121, v34, v35 offset1:1
	ds_write2_b32 v122, v36, v37 offset1:1
	s_waitcnt vmcnt(15)
	ds_write2_b32 v123, v42, v43 offset1:1
	ds_write2_b32 v124, v44, v45 offset1:1
	s_waitcnt lgkmcnt(0)
	ds_read2_b32 v[240:241], v113 offset1:33
	ds_read2_b32 v[242:243], v113 offset0:66 offset1:99
	ds_read2_b32 v[244:245], v113 offset0:132 offset1:165
	ds_read2_b32 v[246:247], v113 offset0:198 offset1:231
	ds_read2_b32 v[248:249], v113 offset0:8 offset1:41
	ds_read2_b32 v[250:251], v113 offset0:74 offset1:107
	ds_read2_b32 v[252:253], v113 offset0:140 offset1:173
	ds_read2_b32 v[254:255], v113 offset0:206 offset1:239
	s_mul_hi_i32 s18, s17, 0x2fa0be83
	s_lshr_b32 s19, s18, 31
	s_ashr_i32 s18, s18, 6
	s_add_i32 s18, s18, s19
	s_waitcnt lgkmcnt(7)
	v_mul_f32_e32 v2, 0x3f317218, v240
	v_mul_f32_e32 v3, 0x3f317218, v241
	v_cvt_pk_bf16_f32 v2, v2, v3
	ds_read2_b32 v[240:241], v113 offset0:16 offset1:49
	s_mul_i32 s19, s18, 0x158
	s_sub_i32 s17, s17, s19
	s_lshl_b32 s19, s17, 5
	s_lshl_b32 s17, s17, 6
	s_waitcnt lgkmcnt(7)
	v_mul_f32_e32 v3, 0x3f317218, v242
	v_mul_f32_e32 v4, 0x3f317218, v243
	v_cvt_pk_bf16_f32 v3, v3, v4
	ds_read2_b32 v[242:243], v113 offset0:82 offset1:115
	s_and_b32 s17, s17, 0xffffff00
	s_or_b32 s19, s19, 0xffffff80
	s_add_i32 s17, s19, s17
	s_addk_i32 s17, 0x100
	s_waitcnt lgkmcnt(7)
	v_mul_f32_e32 v4, 0x3f317218, v244
	v_mul_f32_e32 v5, 0x3f317218, v245
	v_cvt_pk_bf16_f32 v4, v4, v5
	ds_read2_b32 v[244:245], v113 offset0:148 offset1:181
	s_lshl_b32 s18, s18, 6
	s_ashr_i32 s19, s18, 31
	v_lshl_add_u64 v[8:9], s[18:19], 1, v[100:101]
	s_waitcnt lgkmcnt(7)
	v_mul_f32_e32 v5, 0x3f317218, v246
	v_mul_f32_e32 v6, 0x3f317218, v247
	v_cvt_pk_bf16_f32 v5, v5, v6
	ds_read2_b32 v[246:247], v113 offset0:214 offset1:247
	v_or_b32_e32 v6, s17, v1
	v_ashrrev_i32_e32 v7, 31, v6
	v_lshlrev_b64 v[6:7], 13, v[6:7]
	v_lshl_add_u64 v[6:7], v[8:9], 0, v[6:7]
	global_store_dwordx4 v[6:7], v[2:5], off
	s_waitcnt lgkmcnt(7)
	s_nop 0
	v_mul_f32_e32 v2, 0x3f317218, v248
	v_mul_f32_e32 v3, 0x3f317218, v249
	v_cvt_pk_bf16_f32 v2, v2, v3
	ds_read2_b32 v[248:249], v113 offset0:24 offset1:57
	s_waitcnt lgkmcnt(7)
	v_mul_f32_e32 v3, 0x3f317218, v250
	v_mul_f32_e32 v4, 0x3f317218, v251
	v_cvt_pk_bf16_f32 v3, v3, v4
	ds_read2_b32 v[250:251], v113 offset0:90 offset1:123
	s_waitcnt lgkmcnt(7)
	v_mul_f32_e32 v4, 0x3f317218, v252
	v_mul_f32_e32 v5, 0x3f317218, v253
	v_cvt_pk_bf16_f32 v4, v4, v5
	ds_read2_b32 v[252:253], v113 offset0:156 offset1:189
	s_waitcnt lgkmcnt(7)
	v_mul_f32_e32 v5, 0x3f317218, v254
	v_mul_f32_e32 v6, 0x3f317218, v255
	v_cvt_pk_bf16_f32 v5, v5, v6
	ds_read2_b32 v[254:255], v113 offset0:222 offset1:255
	v_or_b32_e32 v6, s17, v110
	v_ashrrev_i32_e32 v7, 31, v6
	v_lshlrev_b64 v[6:7], 13, v[6:7]
	v_lshl_add_u64 v[6:7], v[8:9], 0, v[6:7]
	global_store_dwordx4 v[6:7], v[2:5], off
	s_waitcnt lgkmcnt(7)
	s_nop 0
	v_mul_f32_e32 v2, 0x3f317218, v240
	v_mul_f32_e32 v3, 0x3f317218, v241
	v_cvt_pk_bf16_f32 v2, v2, v3
	s_waitcnt lgkmcnt(6)
; __device__ __forceinline__ unsigned cvt_pk_bf16(float lo, float hi) { unsigned r; asm volatile("v_cvt_pk_bf16_f32 %0, %1, %2" : "=v"(r) : "v"(lo), "v"(hi)); return r; }
; #define LAS __attribute__((address_space(3)))
; #define LDS_WAIT() asm volatile("s_waitcnt lgkmcnt(0)" ::: "memory")
; __device__ __forceinline__ void p0_item_load(const float* __restrict__ W, int N, int nblk, int nb0, int item, int lane, f32x4 (&v)[8]) {
;     const int kb = item / nblk, nb = nb0 + item % nblk;
;     const float* src = W + (size_t)(64 * kb + (lane >> 3)) * N + 32 * nb + 4 * (lane & 7);
; #pragma unroll
;     for (int i = 0; i < 8; ++i) v[i] = __builtin_nontemporal_load((const f32x4*)(src + (size_t)(8 * i) * N));
; }
; __device__ __forceinline__ void p0_item_store(const f32x4 (&v)[8], int K, int nblk, int nb0, bf16* __restrict__ WT, int mode, LAS float* scr, int item, int lane) {
;     const int kb = item / nblk, nb = nb0 + item % nblk, k0 = 64 * kb, n0 = 32 * nb;
; #pragma unroll
;     for (int i = 0; i < 8; ++i) { LAS float* d = scr + (8 * i + (lane >> 3)) * 33 + 4 * (lane & 7); d[0] = v[i].x; d[1] = v[i].y; d[2] = v[i].z; d[3] = v[i].w; }
;     LDS_WAIT(); asm volatile("" ::: "memory");
;     const int c = lane & 7, r0 = map_row(n0, mode);
;     const float wsc = mode == 1 ? 1.44269504089f : (mode == 2 ? 0.69314718056f : 1.0f);
; #pragma unroll
;     for (int j = 0; j < 4; ++j) { const int n = (lane >> 3) + 8 * j; const LAS float* s = scr + (8 * c) * 33 + n;
;         v4u o; o.x = cvt_pk_bf16(s[0 * 33] * wsc, s[1 * 33] * wsc); o.y = cvt_pk_bf16(s[2 * 33] * wsc, s[3 * 33] * wsc); o.z = cvt_pk_bf16(s[4 * 33] * wsc, s[5 * 33] * wsc); o.w = cvt_pk_bf16(s[6 * 33] * wsc, s[7 * 33] * wsc);
;         *(v4u*)(WT + (size_t)(r0 + n) * K + k0 + 8 * c) = o; }
;     LDS_WAIT(); asm volatile("" ::: "memory");
; }
	v_mul_f32_e32 v3, 0x3f317218, v242
	v_mul_f32_e32 v4, 0x3f317218, v243
	v_cvt_pk_bf16_f32 v3, v3, v4
	s_waitcnt lgkmcnt(5)
	v_mul_f32_e32 v4, 0x3f317218, v244
	v_mul_f32_e32 v5, 0x3f317218, v245
	v_cvt_pk_bf16_f32 v4, v4, v5
	s_waitcnt lgkmcnt(4)
	v_mul_f32_e32 v5, 0x3f317218, v246
	v_mul_f32_e32 v6, 0x3f317218, v247
	v_cvt_pk_bf16_f32 v5, v5, v6
	v_or_b32_e32 v6, s17, v111
	v_ashrrev_i32_e32 v7, 31, v6
	v_lshlrev_b64 v[6:7], 13, v[6:7]
	v_lshl_add_u64 v[6:7], v[8:9], 0, v[6:7]
	global_store_dwordx4 v[6:7], v[2:5], off
	s_waitcnt lgkmcnt(3)
	s_nop 0
	v_mul_f32_e32 v2, 0x3f317218, v248
	v_mul_f32_e32 v3, 0x3f317218, v249
	v_cvt_pk_bf16_f32 v2, v2, v3
	s_waitcnt lgkmcnt(2)
	v_mul_f32_e32 v3, 0x3f317218, v250
	v_mul_f32_e32 v4, 0x3f317218, v251
	v_cvt_pk_bf16_f32 v3, v3, v4
	s_waitcnt lgkmcnt(1)
	v_mul_f32_e32 v4, 0x3f317218, v252
	v_mul_f32_e32 v5, 0x3f317218, v253
	v_cvt_pk_bf16_f32 v4, v4, v5
	s_waitcnt lgkmcnt(0)
	v_mul_f32_e32 v5, 0x3f317218, v254
	v_mul_f32_e32 v6, 0x3f317218, v255
	v_cvt_pk_bf16_f32 v5, v5, v6
	v_or_b32_e32 v6, s17, v112
	v_ashrrev_i32_e32 v7, 31, v6
	v_lshlrev_b64 v[6:7], 13, v[6:7]
	v_lshl_add_u64 v[6:7], v[8:9], 0, v[6:7]
	global_store_dwordx4 v[6:7], v[2:5], off
	s_waitcnt lgkmcnt(0)
	s_mul_hi_i32 s17, s5, 0x2fa0be83
	s_lshr_b32 s18, s17, 31
	s_ashr_i32 s17, s17, 6
	s_add_i32 s17, s17, s18
	s_mul_i32 s18, s17, 0x158
	v_lshl_or_b32 v2, s17, 6, v1
	s_sub_i32 s20, s5, s18
	v_mad_i64_i32 v[2:3], s[18:19], v2, s6, v[102:103]
	s_lshl_b32 s18, s20, 5
	s_ashr_i32 s19, s18, 31
	v_lshl_add_u64 v[2:3], s[18:19], 2, v[2:3]
	v_lshl_add_u64 v[34:35], v[2:3], 0, v[98:99]
	v_add_co_u32_e32 v2, vcc, s7, v34
	s_nop 1
	v_addc_co_u32_e32 v3, vcc, 0, v35, vcc
	v_add_co_u32_e32 v6, vcc, s8, v34
	global_load_dwordx4 v[30:33], v[34:35], off nt
	s_nop 0
	global_load_dwordx4 v[2:5], v[2:3], off nt
	v_addc_co_u32_e32 v7, vcc, 0, v35, vcc
	v_add_co_u32_e32 v10, vcc, s9, v34
	s_nop 1
	v_addc_co_u32_e32 v11, vcc, 0, v35, vcc
	v_add_co_u32_e32 v14, vcc, s10, v34
	global_load_dwordx4 v[6:9], v[6:7], off nt
	s_nop 0
	global_load_dwordx4 v[10:13], v[10:11], off nt
	v_addc_co_u32_e32 v15, vcc, 0, v35, vcc
	v_add_co_u32_e32 v26, vcc, s11, v34
	s_nop 1
	v_addc_co_u32_e32 v27, vcc, 0, v35, vcc
	v_add_co_u32_e32 v36, vcc, s13, v34
	global_load_dwordx4 v[14:17], v[14:15], off nt
	s_nop 0
	global_load_dwordx4 v[26:29], v[26:27], off nt
	v_addc_co_u32_e32 v37, vcc, 0, v35, vcc
	v_add_co_u32_e32 v42, vcc, s14, v34
	s_nop 1
	v_addc_co_u32_e32 v43, vcc, 0, v35, vcc
	global_load_dwordx4 v[34:37], v[36:37], off nt
	s_nop 0
	global_load_dwordx4 v[42:45], v[42:43], off nt
	ds_write2_b32 v104, v18, v19 offset1:1
	ds_write2_b32 v104, v20, v21 offset0:2 offset1:3
	s_waitcnt vmcnt(26)
	ds_write2_b32 v105, v22, v23 offset1:1
	ds_write2_b32 v106, v24, v25 offset1:1
	s_waitcnt vmcnt(25)
	ds_write2_b32 v107, v38, v39 offset1:1
	ds_write2_b32 v114, v40, v41 offset1:1
	s_waitcnt vmcnt(24)
	ds_write2_b32 v115, v46, v47 offset1:1
	ds_write2_b32 v116, v48, v49 offset1:1
	s_waitcnt vmcnt(23)
	ds_write2_b32 v117, v50, v51 offset1:1
	ds_write2_b32 v118, v52, v53 offset1:1
	s_waitcnt vmcnt(22)
	ds_write2_b32 v119, v54, v55 offset1:1
	ds_write2_b32 v120, v56, v57 offset1:1
	s_waitcnt vmcnt(21)
	ds_write2_b32 v121, v58, v59 offset1:1
	ds_write2_b32 v122, v60, v61 offset1:1
	s_waitcnt vmcnt(20)
	ds_write2_b32 v123, v62, v63 offset1:1
	ds_write2_b32 v124, v64, v65 offset1:1
	s_waitcnt lgkmcnt(0)
	ds_read2_b32 v[240:241], v113 offset1:33
	ds_read2_b32 v[242:243], v113 offset0:66 offset1:99
	ds_read2_b32 v[244:245], v113 offset0:132 offset1:165
	ds_read2_b32 v[246:247], v113 offset0:198 offset1:231
	ds_read2_b32 v[248:249], v113 offset0:8 offset1:41
	ds_read2_b32 v[250:251], v113 offset0:74 offset1:107
	ds_read2_b32 v[252:253], v113 offset0:140 offset1:173
	ds_read2_b32 v[254:255], v113 offset0:206 offset1:239
	s_mul_hi_i32 s17, s3, 0x2fa0be83
	s_lshr_b32 s18, s17, 31
	s_ashr_i32 s17, s17, 6
	s_add_i32 s17, s17, s18
	s_waitcnt lgkmcnt(7)
	v_mul_f32_e32 v18, 0x3f317218, v240
	v_mul_f32_e32 v19, 0x3f317218, v241
	v_cvt_pk_bf16_f32 v18, v18, v19
	ds_read2_b32 v[240:241], v113 offset0:16 offset1:49
	s_mul_i32 s18, s17, 0x158
	s_sub_i32 s3, s3, s18
	s_lshl_b32 s18, s3, 5
	s_lshl_b32 s3, s3, 6
	s_waitcnt lgkmcnt(7)
	v_mul_f32_e32 v19, 0x3f317218, v242
	v_mul_f32_e32 v20, 0x3f317218, v243
	v_cvt_pk_bf16_f32 v19, v19, v20
	ds_read2_b32 v[242:243], v113 offset0:82 offset1:115
	s_and_b32 s3, s3, 0xffffff00
	s_or_b32 s18, s18, 0xffffff80
	s_add_i32 s3, s18, s3
	s_addk_i32 s3, 0x100
	s_waitcnt lgkmcnt(7)
	v_mul_f32_e32 v20, 0x3f317218, v244
	v_mul_f32_e32 v21, 0x3f317218, v245
	v_cvt_pk_bf16_f32 v20, v20, v21
	ds_read2_b32 v[244:245], v113 offset0:148 offset1:181
	s_lshl_b32 s18, s17, 6
	s_ashr_i32 s19, s18, 31
	v_lshl_add_u64 v[24:25], s[18:19], 1, v[100:101]
	s_waitcnt lgkmcnt(7)
	v_mul_f32_e32 v21, 0x3f317218, v246
	v_mul_f32_e32 v22, 0x3f317218, v247
	v_cvt_pk_bf16_f32 v21, v21, v22
	ds_read2_b32 v[246:247], v113 offset0:214 offset1:247
	v_or_b32_e32 v22, s3, v1
	v_ashrrev_i32_e32 v23, 31, v22
	v_lshlrev_b64 v[22:23], 13, v[22:23]
	v_lshl_add_u64 v[22:23], v[24:25], 0, v[22:23]
	global_store_dwordx4 v[22:23], v[18:21], off
	s_waitcnt lgkmcnt(7)
	s_nop 0
	v_mul_f32_e32 v18, 0x3f317218, v248
	v_mul_f32_e32 v19, 0x3f317218, v249
	v_cvt_pk_bf16_f32 v18, v18, v19
	ds_read2_b32 v[248:249], v113 offset0:24 offset1:57
	s_waitcnt lgkmcnt(7)
	v_mul_f32_e32 v19, 0x3f317218, v250
	v_mul_f32_e32 v20, 0x3f317218, v251
	v_cvt_pk_bf16_f32 v19, v19, v20
	ds_read2_b32 v[250:251], v113 offset0:90 offset1:123
	s_waitcnt lgkmcnt(7)
; __device__ __forceinline__ unsigned cvt_pk_bf16(float lo, float hi) { unsigned r; asm volatile("v_cvt_pk_bf16_f32 %0, %1, %2" : "=v"(r) : "v"(lo), "v"(hi)); return r; }
; #define LAS __attribute__((address_space(3)))
; #define LDS_WAIT() asm volatile("s_waitcnt lgkmcnt(0)" ::: "memory")
; __device__ __forceinline__ void p0_item_load(const float* __restrict__ W, int N, int nblk, int nb0, int item, int lane, f32x4 (&v)[8]) {
;     const int kb = item / nblk, nb = nb0 + item % nblk;
;     const float* src = W + (size_t)(64 * kb + (lane >> 3)) * N + 32 * nb + 4 * (lane & 7);
; #pragma unroll
;     for (int i = 0; i < 8; ++i) v[i] = __builtin_nontemporal_load((const f32x4*)(src + (size_t)(8 * i) * N));
; }
; __device__ __forceinline__ void p0_item_store(const f32x4 (&v)[8], int K, int nblk, int nb0, bf16* __restrict__ WT, int mode, LAS float* scr, int item, int lane) {
;     const int kb = item / nblk, nb = nb0 + item % nblk, k0 = 64 * kb, n0 = 32 * nb;
; #pragma unroll
;     for (int i = 0; i < 8; ++i) { LAS float* d = scr + (8 * i + (lane >> 3)) * 33 + 4 * (lane & 7); d[0] = v[i].x; d[1] = v[i].y; d[2] = v[i].z; d[3] = v[i].w; }
;     LDS_WAIT(); asm volatile("" ::: "memory");
;     const int c = lane & 7, r0 = map_row(n0, mode);
;     const float wsc = mode == 1 ? 1.44269504089f : (mode == 2 ? 0.69314718056f : 1.0f);
; #pragma unroll
;     for (int j = 0; j < 4; ++j) { const int n = (lane >> 3) + 8 * j; const LAS float* s = scr + (8 * c) * 33 + n;
;         v4u o; o.x = cvt_pk_bf16(s[0 * 33] * wsc, s[1 * 33] * wsc); o.y = cvt_pk_bf16(s[2 * 33] * wsc, s[3 * 33] * wsc); o.z = cvt_pk_bf16(s[4 * 33] * wsc, s[5 * 33] * wsc); o.w = cvt_pk_bf16(s[6 * 33] * wsc, s[7 * 33] * wsc);
;         *(v4u*)(WT + (size_t)(r0 + n) * K + k0 + 8 * c) = o; }
;     LDS_WAIT(); asm volatile("" ::: "memory");
; }
	v_mul_f32_e32 v20, 0x3f317218, v252
	v_mul_f32_e32 v21, 0x3f317218, v253
	v_cvt_pk_bf16_f32 v20, v20, v21
	ds_read2_b32 v[252:253], v113 offset0:156 offset1:189
	s_waitcnt lgkmcnt(7)
	v_mul_f32_e32 v21, 0x3f317218, v254
	v_mul_f32_e32 v22, 0x3f317218, v255
	v_cvt_pk_bf16_f32 v21, v21, v22
	ds_read2_b32 v[254:255], v113 offset0:222 offset1:255
	v_or_b32_e32 v22, s3, v110
	v_ashrrev_i32_e32 v23, 31, v22
	v_lshlrev_b64 v[22:23], 13, v[22:23]
	v_lshl_add_u64 v[22:23], v[24:25], 0, v[22:23]
	global_store_dwordx4 v[22:23], v[18:21], off
	s_waitcnt lgkmcnt(7)
	s_nop 0
	v_mul_f32_e32 v18, 0x3f317218, v240
	v_mul_f32_e32 v19, 0x3f317218, v241
	v_cvt_pk_bf16_f32 v18, v18, v19
	s_waitcnt lgkmcnt(6)
	v_mul_f32_e32 v19, 0x3f317218, v242
	v_mul_f32_e32 v20, 0x3f317218, v243
	v_cvt_pk_bf16_f32 v19, v19, v20
	s_waitcnt lgkmcnt(5)
	v_mul_f32_e32 v20, 0x3f317218, v244
	v_mul_f32_e32 v21, 0x3f317218, v245
	v_cvt_pk_bf16_f32 v20, v20, v21
	s_waitcnt lgkmcnt(4)
	v_mul_f32_e32 v21, 0x3f317218, v246
	v_mul_f32_e32 v22, 0x3f317218, v247
	v_cvt_pk_bf16_f32 v21, v21, v22
	v_or_b32_e32 v22, s3, v111
	v_ashrrev_i32_e32 v23, 31, v22
	v_lshlrev_b64 v[22:23], 13, v[22:23]
	v_lshl_add_u64 v[22:23], v[24:25], 0, v[22:23]
	global_store_dwordx4 v[22:23], v[18:21], off
	s_waitcnt lgkmcnt(3)
	s_nop 0
	v_mul_f32_e32 v18, 0x3f317218, v248
	v_mul_f32_e32 v19, 0x3f317218, v249
	v_cvt_pk_bf16_f32 v18, v18, v19
	s_waitcnt lgkmcnt(2)
	v_mul_f32_e32 v19, 0x3f317218, v250
	v_mul_f32_e32 v20, 0x3f317218, v251
	v_cvt_pk_bf16_f32 v19, v19, v20
	s_waitcnt lgkmcnt(1)
	v_mul_f32_e32 v20, 0x3f317218, v252
	v_mul_f32_e32 v21, 0x3f317218, v253
	v_cvt_pk_bf16_f32 v20, v20, v21
	s_waitcnt lgkmcnt(0)
	v_mul_f32_e32 v21, 0x3f317218, v254
	v_mul_f32_e32 v22, 0x3f317218, v255
	v_cvt_pk_bf16_f32 v21, v21, v22
	v_or_b32_e32 v22, s3, v112
	v_ashrrev_i32_e32 v23, 31, v22
	v_lshlrev_b64 v[22:23], 13, v[22:23]
	v_lshl_add_u64 v[22:23], v[24:25], 0, v[22:23]
	global_store_dwordx4 v[22:23], v[18:21], off
	s_waitcnt lgkmcnt(0)
	s_mul_hi_i32 s3, s15, 0x2fa0be83
	s_lshr_b32 s17, s3, 31
	s_ashr_i32 s3, s3, 6
	s_add_i32 s3, s3, s17
	s_mul_i32 s17, s3, 0x158
	v_lshl_or_b32 v18, s3, 6, v1
	s_sub_i32 s17, s15, s17
	v_mad_i64_i32 v[18:19], s[18:19], v18, s6, v[102:103]
	s_lshl_b32 s18, s17, 5
	s_ashr_i32 s19, s18, 31
	v_lshl_add_u64 v[18:19], s[18:19], 2, v[18:19]
	v_lshl_add_u64 v[58:59], v[18:19], 0, v[98:99]
	v_add_co_u32_e32 v22, vcc, s7, v58
	s_nop 1
	v_addc_co_u32_e32 v23, vcc, 0, v59, vcc
	v_add_co_u32_e32 v38, vcc, s8, v58
	global_load_dwordx4 v[18:21], v[58:59], off nt
	s_nop 0
	global_load_dwordx4 v[22:25], v[22:23], off nt
	v_addc_co_u32_e32 v39, vcc, 0, v59, vcc
	v_add_co_u32_e32 v46, vcc, s9, v58
	s_nop 1
	v_addc_co_u32_e32 v47, vcc, 0, v59, vcc
	v_add_co_u32_e32 v50, vcc, s10, v58
	global_load_dwordx4 v[38:41], v[38:39], off nt
	s_nop 0
	global_load_dwordx4 v[46:49], v[46:47], off nt
	v_addc_co_u32_e32 v51, vcc, 0, v59, vcc
	v_add_co_u32_e32 v54, vcc, s11, v58
	s_nop 1
	v_addc_co_u32_e32 v55, vcc, 0, v59, vcc
	v_add_co_u32_e32 v60, vcc, s13, v58
	global_load_dwordx4 v[50:53], v[50:51], off nt
	s_nop 0
	global_load_dwordx4 v[54:57], v[54:55], off nt
	v_addc_co_u32_e32 v61, vcc, 0, v59, vcc
	v_add_co_u32_e32 v62, vcc, s14, v58
	s_nop 1
	v_addc_co_u32_e32 v63, vcc, 0, v59, vcc
	global_load_dwordx4 v[58:61], v[60:61], off nt
	s_nop 0
	global_load_dwordx4 v[62:65], v[62:63], off nt
	s_waitcnt vmcnt(31)
	ds_write2_b32 v104, v66, v67 offset1:1
	ds_write2_b32 v104, v68, v69 offset0:2 offset1:3
	s_waitcnt vmcnt(30)
	ds_write2_b32 v105, v70, v71 offset1:1
	ds_write2_b32 v106, v72, v73 offset1:1
	s_waitcnt vmcnt(29)
	ds_write2_b32 v107, v74, v75 offset1:1
	ds_write2_b32 v114, v76, v77 offset1:1
	s_waitcnt vmcnt(28)
	ds_write2_b32 v115, v78, v79 offset1:1
	ds_write2_b32 v116, v80, v81 offset1:1
	s_waitcnt vmcnt(27)
	ds_write2_b32 v117, v82, v83 offset1:1
	ds_write2_b32 v118, v84, v85 offset1:1
	s_waitcnt vmcnt(26)
	ds_write2_b32 v119, v86, v87 offset1:1
	ds_write2_b32 v120, v88, v89 offset1:1
	s_waitcnt vmcnt(25)
	ds_write2_b32 v121, v90, v91 offset1:1
	ds_write2_b32 v122, v92, v93 offset1:1
	s_waitcnt vmcnt(24)
; #define LAS __attribute__((address_space(3)))
; __device__ __forceinline__ void p0_item_load(const float* __restrict__ W, int N, int nblk, int nb0, int item, int lane, f32x4 (&v)[8]) {
;     const int kb = item / nblk, nb = nb0 + item % nblk;
;     const float* src = W + (size_t)(64 * kb + (lane >> 3)) * N + 32 * nb + 4 * (lane & 7);
; #pragma unroll
;     for (int i = 0; i < 8; ++i) v[i] = __builtin_nontemporal_load((const f32x4*)(src + (size_t)(8 * i) * N));
; }
; __device__ __forceinline__ void p0_item_store(const f32x4 (&v)[8], int K, int nblk, int nb0, bf16* __restrict__ WT, int mode, LAS float* scr, int item, int lane) {
;     const int kb = item / nblk, nb = nb0 + item % nblk, k0 = 64 * kb, n0 = 32 * nb;
; #pragma unroll
;     for (int i = 0; i < 8; ++i) { LAS float* d = scr + (8 * i + (lane >> 3)) * 33 + 4 * (lane & 7); d[0] = v[i].x; d[1] = v[i].y; d[2] = v[i].z; d[3] = v[i].w; }
;     LDS_WAIT(); asm volatile("" ::: "memory");
;     const int c = lane & 7, r0 = map_row(n0, mode);
;     const float wsc = mode == 1 ? 1.44269504089f : (mode == 2 ? 0.69314718056f : 1.0f);
; #pragma unroll
;     for (int j = 0; j < 4; ++j) { const int n = (lane >> 3) + 8 * j; const LAS float* s = scr + (8 * c) * 33 + n;
;         v4u o; o.x = cvt_pk_bf16(s[0 * 33] * wsc, s[1 * 33] * wsc); o.y = cvt_pk_bf16(s[2 * 33] * wsc, s[3 * 33] * wsc); o.z = cvt_pk_bf16(s[4 * 33] * wsc, s[5 * 33] * wsc); o.w = cvt_pk_bf16(s[6 * 33] * wsc, s[7 * 33] * wsc);
;         *(v4u*)(WT + (size_t)(r0 + n) * K + k0 + 8 * c) = o; }
;     LDS_WAIT(); asm volatile("" ::: "memory");
; }
;     ...
;     for (int p = 0; p < ntri; ++p) {
;         const int i2 = min(i1 + nw, last), i3 = min(i2 + nw, last), i4 = min(i3 + nw, last);
;         p0_item_load(W, N, nblk, nb0, i2, F.lane, vc); __builtin_amdgcn_sched_barrier(0);
;         p0_item_store(va, K, nblk, nb0, WT, mode, scr, it, F.lane); __builtin_amdgcn_sched_barrier(0);
;         p0_item_load(W, N, nblk, nb0, i3, F.lane, va); __builtin_amdgcn_sched_barrier(0);
;         p0_item_store(vb, K, nblk, nb0, WT, mode, scr, i1, F.lane); __builtin_amdgcn_sched_barrier(0);
;         p0_item_load(W, N, nblk, nb0, i4, F.lane, vb); __builtin_amdgcn_sched_barrier(0);
;         p0_item_store(vc, K, nblk, nb0, WT, mode, scr, i2, F.lane); __builtin_amdgcn_sched_barrier(0);
;         it = i3; i1 = i4;
;     }
	ds_write2_b32 v123, v94, v95 offset1:1
	ds_write2_b32 v124, v96, v97 offset1:1
	s_waitcnt lgkmcnt(0)
	ds_read2_b32 v[240:241], v113 offset1:33
	ds_read2_b32 v[242:243], v113 offset0:66 offset1:99
	ds_read2_b32 v[244:245], v113 offset0:132 offset1:165
	ds_read2_b32 v[246:247], v113 offset0:198 offset1:231
	ds_read2_b32 v[248:249], v113 offset0:8 offset1:41
	ds_read2_b32 v[250:251], v113 offset0:74 offset1:107
	ds_read2_b32 v[252:253], v113 offset0:140 offset1:173
	ds_read2_b32 v[254:255], v113 offset0:206 offset1:239
	s_lshl_b32 s3, s16, 6
	s_and_b32 s3, s3, 0xffffff00
	s_or_b32 s4, s4, 0xffffff80
	s_add_i32 s3, s4, s3
	s_waitcnt lgkmcnt(7)
	v_mul_f32_e32 v66, 0x3f317218, v240
	v_mul_f32_e32 v67, 0x3f317218, v241
	v_cvt_pk_bf16_f32 v66, v66, v67
	ds_read2_b32 v[240:241], v113 offset0:16 offset1:49
	s_add_i32 s4, s3, 0x100
	s_ashr_i32 s3, s2, 31
	v_lshl_add_u64 v[72:73], s[2:3], 1, v[100:101]
	s_waitcnt lgkmcnt(7)
	v_mul_f32_e32 v67, 0x3f317218, v242
	v_mul_f32_e32 v68, 0x3f317218, v243
	v_cvt_pk_bf16_f32 v67, v67, v68
	ds_read2_b32 v[242:243], v113 offset0:82 offset1:115
	s_waitcnt lgkmcnt(7)
	v_mul_f32_e32 v68, 0x3f317218, v244
	v_mul_f32_e32 v69, 0x3f317218, v245
	v_cvt_pk_bf16_f32 v68, v68, v69
	ds_read2_b32 v[244:245], v113 offset0:148 offset1:181
	s_waitcnt lgkmcnt(7)
	v_mul_f32_e32 v69, 0x3f317218, v246
	v_mul_f32_e32 v70, 0x3f317218, v247
	v_cvt_pk_bf16_f32 v69, v69, v70
	ds_read2_b32 v[246:247], v113 offset0:214 offset1:247
	v_or_b32_e32 v70, s4, v1
	v_ashrrev_i32_e32 v71, 31, v70
	v_lshlrev_b64 v[70:71], 13, v[70:71]
	v_lshl_add_u64 v[70:71], v[72:73], 0, v[70:71]
	global_store_dwordx4 v[70:71], v[66:69], off
	s_waitcnt lgkmcnt(7)
	s_nop 0
	v_mul_f32_e32 v66, 0x3f317218, v248
	v_mul_f32_e32 v67, 0x3f317218, v249
	v_cvt_pk_bf16_f32 v66, v66, v67
	ds_read2_b32 v[248:249], v113 offset0:24 offset1:57
	s_waitcnt lgkmcnt(7)
	v_mul_f32_e32 v67, 0x3f317218, v250
	v_mul_f32_e32 v68, 0x3f317218, v251
	v_cvt_pk_bf16_f32 v67, v67, v68
	ds_read2_b32 v[250:251], v113 offset0:90 offset1:123
	s_waitcnt lgkmcnt(7)
	v_mul_f32_e32 v68, 0x3f317218, v252
	v_mul_f32_e32 v69, 0x3f317218, v253
	v_cvt_pk_bf16_f32 v68, v68, v69
	ds_read2_b32 v[252:253], v113 offset0:156 offset1:189
	s_waitcnt lgkmcnt(7)
	v_mul_f32_e32 v69, 0x3f317218, v254
	v_mul_f32_e32 v70, 0x3f317218, v255
	v_cvt_pk_bf16_f32 v69, v69, v70
	ds_read2_b32 v[254:255], v113 offset0:222 offset1:255
	v_or_b32_e32 v70, s4, v110
	v_ashrrev_i32_e32 v71, 31, v70
	v_lshlrev_b64 v[70:71], 13, v[70:71]
	v_lshl_add_u64 v[70:71], v[72:73], 0, v[70:71]
	global_store_dwordx4 v[70:71], v[66:69], off
	s_waitcnt lgkmcnt(7)
	s_nop 0
	v_mul_f32_e32 v66, 0x3f317218, v240
	v_mul_f32_e32 v67, 0x3f317218, v241
	v_cvt_pk_bf16_f32 v66, v66, v67
	s_waitcnt lgkmcnt(6)
	v_mul_f32_e32 v67, 0x3f317218, v242
	v_mul_f32_e32 v68, 0x3f317218, v243
	v_cvt_pk_bf16_f32 v67, v67, v68
	s_waitcnt lgkmcnt(5)
	v_mul_f32_e32 v68, 0x3f317218, v244
	v_mul_f32_e32 v69, 0x3f317218, v245
	v_cvt_pk_bf16_f32 v68, v68, v69
	s_waitcnt lgkmcnt(4)
	v_mul_f32_e32 v69, 0x3f317218, v246
	v_mul_f32_e32 v70, 0x3f317218, v247
	v_cvt_pk_bf16_f32 v69, v69, v70
	v_or_b32_e32 v70, s4, v111
	v_ashrrev_i32_e32 v71, 31, v70
	v_lshlrev_b64 v[70:71], 13, v[70:71]
	v_lshl_add_u64 v[70:71], v[72:73], 0, v[70:71]
	global_store_dwordx4 v[70:71], v[66:69], off
	s_waitcnt lgkmcnt(3)
	s_nop 0
	v_mul_f32_e32 v66, 0x3f317218, v248
	v_mul_f32_e32 v67, 0x3f317218, v249
	v_cvt_pk_bf16_f32 v66, v66, v67
	s_waitcnt lgkmcnt(2)
	v_mul_f32_e32 v67, 0x3f317218, v250
	v_mul_f32_e32 v68, 0x3f317218, v251
	v_cvt_pk_bf16_f32 v67, v67, v68
	s_waitcnt lgkmcnt(1)
	v_mul_f32_e32 v68, 0x3f317218, v252
	v_mul_f32_e32 v69, 0x3f317218, v253
	v_cvt_pk_bf16_f32 v68, v68, v69
	s_waitcnt lgkmcnt(0)
	v_mul_f32_e32 v69, 0x3f317218, v254
	v_mul_f32_e32 v70, 0x3f317218, v255
	v_cvt_pk_bf16_f32 v69, v69, v70
	v_or_b32_e32 v70, s4, v112
	v_ashrrev_i32_e32 v71, 31, v70
	v_lshlrev_b64 v[70:71], 13, v[70:71]
	v_lshl_add_u64 v[70:71], v[72:73], 0, v[70:71]
	global_store_dwordx4 v[70:71], v[66:69], off
	s_waitcnt lgkmcnt(0)
	s_add_i32 s12, s12, -1
	s_cmp_eq_u32 s12, 0
	s_mov_b32 s17, s5
	s_mov_b32 s3, s15
	s_cbranch_scc0 .LBB0_29

; __device__ __forceinline__ unsigned cvt_pk_bf16(float lo, float hi) { unsigned r; asm volatile("v_cvt_pk_bf16_f32 %0, %1, %2" : "=v"(r) : "v"(lo), "v"(hi)); return r; }
; #define LAS __attribute__((address_space(3)))
; #define LDS_WAIT() asm volatile("s_waitcnt lgkmcnt(0)" ::: "memory")
; __device__ __forceinline__ void p0_item_load(const float* __restrict__ W, int N, int nblk, int nb0, int item, int lane, f32x4 (&v)[8]) {
;     const int kb = item / nblk, nb = nb0 + item % nblk;
;     const float* src = W + (size_t)(64 * kb + (lane >> 3)) * N + 32 * nb + 4 * (lane & 7);
; #pragma unroll
;     for (int i = 0; i < 8; ++i) v[i] = __builtin_nontemporal_load((const f32x4*)(src + (size_t)(8 * i) * N));
; }
; __device__ __forceinline__ void p0_item_store(const f32x4 (&v)[8], int K, int nblk, int nb0, bf16* __restrict__ WT, int mode, LAS float* scr, int item, int lane) {
;     const int kb = item / nblk, nb = nb0 + item % nblk, k0 = 64 * kb, n0 = 32 * nb;
; #pragma unroll
;     for (int i = 0; i < 8; ++i) { LAS float* d = scr + (8 * i + (lane >> 3)) * 33 + 4 * (lane & 7); d[0] = v[i].x; d[1] = v[i].y; d[2] = v[i].z; d[3] = v[i].w; }
;     LDS_WAIT(); asm volatile("" ::: "memory");
;     const int c = lane & 7, r0 = map_row(n0, mode);
;     const float wsc = mode == 1 ? 1.44269504089f : (mode == 2 ? 0.69314718056f : 1.0f);
; #pragma unroll
;     for (int j = 0; j < 4; ++j) { const int n = (lane >> 3) + 8 * j; const LAS float* s = scr + (8 * c) * 33 + n;
;         v4u o; o.x = cvt_pk_bf16(s[0 * 33] * wsc, s[1 * 33] * wsc); o.y = cvt_pk_bf16(s[2 * 33] * wsc, s[3 * 33] * wsc); o.z = cvt_pk_bf16(s[4 * 33] * wsc, s[5 * 33] * wsc); o.w = cvt_pk_bf16(s[6 * 33] * wsc, s[7 * 33] * wsc);
;         *(v4u*)(WT + (size_t)(r0 + n) * K + k0 + 8 * c) = o; }
;     LDS_WAIT(); asm volatile("" ::: "memory");
; }
; __device__ __forceinline__ void convert_beside_ffn1(Frame& F, const Args& A, int w0, int nw) {
;     ...
;     for (int t0 = GATE_G0; t0 < NPN1; t0 += GATE_SG) { const int tn = min(GATE_SG, NPN1 - t0);
;         p0_transpose(F, A.in[5], D, DFF, (bf16*)(F.ws + WS_WGU1), 1, w0, nw, 0, 16, 4 * t0, 4 * tn);
;         p0_transpose(F, A.in[6], D, DFF, (bf16*)(F.ws + WS_WGU1), 2, w0, nw, 0, 16, 4 * t0, 4 * tn);
.LBB0_91:
	s_add_i32 s10, s43, s17
	s_min_i32 s33, s10, 0xbff
	s_mul_hi_i32 s10, s33, 0x2aaaaaab
	s_lshr_b32 s14, s10, 31
	s_ashr_i32 s10, s10, 3
	s_add_i32 s10, s10, s14
	s_mul_i32 s14, s10, 48
	s_sub_i32 s15, s33, s14
	s_lshl_b32 s14, s10, 6
	s_add_i32 s15, s15, s39
	v_or_b32_e32 v66, s14, v116
	v_mov_b64_e32 v[114:115], s[82:83]
	v_mad_i64_i32 v[66:67], s[48:49], v66, s28, v[114:115]
	s_lshl_b32 s10, s15, 5
	v_lshl_add_u64 v[66:67], s[10:11], 2, v[66:67]
	v_lshlrev_b32_e32 v102, 2, v100
	v_lshl_add_u64 v[90:91], v[66:67], 0, v[102:103]
	v_add_co_u32_e32 v70, vcc, s30, v90
	s_add_i32 s33, s33, s17
	s_nop 0
	v_addc_co_u32_e32 v71, vcc, 0, v91, vcc
	v_add_co_u32_e32 v74, vcc, s31, v90
	global_load_dwordx4 v[66:69], v[90:91], off nt
	s_nop 0
	global_load_dwordx4 v[70:73], v[70:71], off nt
	v_addc_co_u32_e32 v75, vcc, 0, v91, vcc
	v_add_co_u32_e32 v78, vcc, s34, v90
	s_min_i32 s41, s33, 0xbff
	s_nop 0
	v_addc_co_u32_e32 v79, vcc, 0, v91, vcc
	v_add_co_u32_e32 v82, vcc, s35, v90
	global_load_dwordx4 v[74:77], v[74:75], off nt
	s_nop 0
	global_load_dwordx4 v[78:81], v[78:79], off nt
	v_addc_co_u32_e32 v83, vcc, 0, v91, vcc
	v_add_co_u32_e32 v86, vcc, s36, v90
	s_add_i32 s33, s41, s17
	s_nop 0
	v_addc_co_u32_e32 v87, vcc, 0, v91, vcc
	v_add_co_u32_e32 v92, vcc, s37, v90
	global_load_dwordx4 v[82:85], v[82:83], off nt
	s_nop 0
	global_load_dwordx4 v[86:89], v[86:87], off nt
	v_addc_co_u32_e32 v93, vcc, 0, v91, vcc
	v_add_co_u32_e32 v94, vcc, s38, v90
	s_min_i32 s42, s33, 0xbff
	s_nop 0
	v_addc_co_u32_e32 v95, vcc, 0, v91, vcc
	global_load_dwordx4 v[90:93], v[92:93], off nt
	s_nop 0
	global_load_dwordx4 v[94:97], v[94:95], off nt
	v_add_u32_e32 v99, v117, v118
	v_add_u32_e32 v101, 0x420, v99
	v_add_u32_e32 v123, 0x428, v99
	v_add_u32_e32 v124, 0x840, v99
	v_add_u32_e32 v125, 0x848, v99
	v_add_u32_e32 v126, 0xc60, v99
	v_add_u32_e32 v127, 0xc68, v99
	v_add_u32_e32 v128, 0x1080, v99
	v_add_u32_e32 v129, 0x1088, v99
	v_add_u32_e32 v130, 0x14a0, v99
	v_add_u32_e32 v131, 0x14a8, v99
	v_add_u32_e32 v132, 0x18c0, v99
	v_add_u32_e32 v133, 0x18c8, v99
	v_add_u32_e32 v134, 0x1ce0, v99
	v_add_u32_e32 v135, 0x1ce8, v99
	s_waitcnt vmcnt(23)
	ds_write2_b32 v99, v2, v3 offset1:1
	ds_write2_b32 v99, v4, v5 offset0:2 offset1:3
	s_waitcnt vmcnt(22)
	ds_write2_b32 v101, v6, v7 offset1:1
	ds_write2_b32 v123, v8, v9 offset1:1
	s_waitcnt vmcnt(21)
	ds_write2_b32 v124, v10, v11 offset1:1
	ds_write2_b32 v125, v12, v13 offset1:1
	s_waitcnt vmcnt(20)
	ds_write2_b32 v126, v14, v15 offset1:1
	ds_write2_b32 v127, v16, v17 offset1:1
	s_waitcnt vmcnt(19)
	ds_write2_b32 v128, v18, v19 offset1:1
	ds_write2_b32 v129, v20, v21 offset1:1
	s_waitcnt vmcnt(18)
	ds_write2_b32 v130, v22, v23 offset1:1
	ds_write2_b32 v131, v24, v25 offset1:1
	s_waitcnt vmcnt(17)
	ds_write2_b32 v132, v34, v35 offset1:1
	ds_write2_b32 v133, v36, v37 offset1:1
	s_waitcnt vmcnt(16)
	ds_write2_b32 v134, v38, v39 offset1:1
	ds_write2_b32 v135, v40, v41 offset1:1
	s_waitcnt lgkmcnt(0)
	ds_read2_b32 v[240:241], v122 offset1:33
	ds_read2_b32 v[242:243], v122 offset0:66 offset1:99
	ds_read2_b32 v[244:245], v122 offset0:132 offset1:165
	ds_read2_b32 v[246:247], v122 offset0:198 offset1:231
	ds_read2_b32 v[248:249], v122 offset0:8 offset1:41
	ds_read2_b32 v[250:251], v122 offset0:74 offset1:107
	ds_read2_b32 v[252:253], v122 offset0:140 offset1:173
	ds_read2_b32 v[254:255], v122 offset0:206 offset1:239
	s_mul_hi_i32 s33, s44, 0x2aaaaaab
	s_lshr_b32 s45, s33, 31
	s_ashr_i32 s33, s33, 3
	s_add_i32 s33, s33, s45
	s_waitcnt lgkmcnt(7)
	v_mul_f32_e32 v2, 0x3fb8aa3b, v240
	v_mul_f32_e32 v3, 0x3fb8aa3b, v241
	v_cvt_pk_bf16_f32 v2, v2, v3
	ds_read2_b32 v[240:241], v122 offset0:16 offset1:49
	s_mul_i32 s45, s33, 48
	s_sub_i32 s44, s44, s45
	s_add_i32 s44, s44, s39
	s_lshl_b32 s45, s44, 5
	s_waitcnt lgkmcnt(7)
	v_mul_f32_e32 v3, 0x3fb8aa3b, v242
	v_mul_f32_e32 v4, 0x3fb8aa3b, v243
	v_cvt_pk_bf16_f32 v3, v3, v4
	ds_read2_b32 v[242:243], v122 offset0:82 offset1:115
	s_lshl_b32 s44, s44, 6
	s_and_b32 s44, s44, 0x7fffff00
	s_and_b32 s45, s45, 0x60
	s_or_b32 s47, s45, s44
	s_waitcnt lgkmcnt(7)
	v_mul_f32_e32 v4, 0x3fb8aa3b, v244
	v_mul_f32_e32 v5, 0x3fb8aa3b, v245
	v_cvt_pk_bf16_f32 v4, v4, v5
	ds_read2_b32 v[244:245], v122 offset0:148 offset1:181
	s_lshl_b32 s44, s33, 6
	s_ashr_i32 s45, s44, 31
	v_lshl_add_u64 v[8:9], s[44:45], 1, v[108:109]
	s_waitcnt lgkmcnt(7)
	v_mul_f32_e32 v5, 0x3fb8aa3b, v246
	v_mul_f32_e32 v6, 0x3fb8aa3b, v247
	v_cvt_pk_bf16_f32 v5, v5, v6
	ds_read2_b32 v[246:247], v122 offset0:214 offset1:247
	v_or_b32_e32 v6, s47, v116
	v_mov_b32_e32 v7, v103
	v_lshlrev_b64 v[6:7], 13, v[6:7]
	v_lshl_add_u64 v[6:7], v[8:9], 0, v[6:7]
	global_store_dwordx4 v[6:7], v[2:5], off
	s_waitcnt lgkmcnt(7)
	s_nop 0
	v_mul_f32_e32 v2, 0x3fb8aa3b, v248
	v_mul_f32_e32 v3, 0x3fb8aa3b, v249
	v_cvt_pk_bf16_f32 v2, v2, v3
	ds_read2_b32 v[248:249], v122 offset0:24 offset1:57
	s_waitcnt lgkmcnt(7)
	v_mul_f32_e32 v3, 0x3fb8aa3b, v250
	v_mul_f32_e32 v4, 0x3fb8aa3b, v251
	v_cvt_pk_bf16_f32 v3, v3, v4
	ds_read2_b32 v[250:251], v122 offset0:90 offset1:123
	s_waitcnt lgkmcnt(7)
	v_mul_f32_e32 v4, 0x3fb8aa3b, v252
	v_mul_f32_e32 v5, 0x3fb8aa3b, v253
	v_cvt_pk_bf16_f32 v4, v4, v5
	ds_read2_b32 v[252:253], v122 offset0:156 offset1:189
	s_waitcnt lgkmcnt(7)
	v_mul_f32_e32 v5, 0x3fb8aa3b, v254
	v_mul_f32_e32 v6, 0x3fb8aa3b, v255
	v_cvt_pk_bf16_f32 v5, v5, v6
	ds_read2_b32 v[254:255], v122 offset0:222 offset1:255
	v_or_b32_e32 v6, s47, v119
	v_mov_b32_e32 v7, v103
	v_lshlrev_b64 v[6:7], 13, v[6:7]
	v_lshl_add_u64 v[6:7], v[8:9], 0, v[6:7]
	global_store_dwordx4 v[6:7], v[2:5], off
	s_waitcnt lgkmcnt(7)
; __device__ __forceinline__ unsigned cvt_pk_bf16(float lo, float hi) { unsigned r; asm volatile("v_cvt_pk_bf16_f32 %0, %1, %2" : "=v"(r) : "v"(lo), "v"(hi)); return r; }
; #define LAS __attribute__((address_space(3)))
; #define LDS_WAIT() asm volatile("s_waitcnt lgkmcnt(0)" ::: "memory")
; __device__ __forceinline__ void p0_item_load(const float* __restrict__ W, int N, int nblk, int nb0, int item, int lane, f32x4 (&v)[8]) {
;     const int kb = item / nblk, nb = nb0 + item % nblk;
;     const float* src = W + (size_t)(64 * kb + (lane >> 3)) * N + 32 * nb + 4 * (lane & 7);
; #pragma unroll
;     for (int i = 0; i < 8; ++i) v[i] = __builtin_nontemporal_load((const f32x4*)(src + (size_t)(8 * i) * N));
; }
; __device__ __forceinline__ void p0_item_store(const f32x4 (&v)[8], int K, int nblk, int nb0, bf16* __restrict__ WT, int mode, LAS float* scr, int item, int lane) {
;     const int kb = item / nblk, nb = nb0 + item % nblk, k0 = 64 * kb, n0 = 32 * nb;
; #pragma unroll
;     for (int i = 0; i < 8; ++i) { LAS float* d = scr + (8 * i + (lane >> 3)) * 33 + 4 * (lane & 7); d[0] = v[i].x; d[1] = v[i].y; d[2] = v[i].z; d[3] = v[i].w; }
;     LDS_WAIT(); asm volatile("" ::: "memory");
;     const int c = lane & 7, r0 = map_row(n0, mode);
;     const float wsc = mode == 1 ? 1.44269504089f : (mode == 2 ? 0.69314718056f : 1.0f);
; #pragma unroll
;     for (int j = 0; j < 4; ++j) { const int n = (lane >> 3) + 8 * j; const LAS float* s = scr + (8 * c) * 33 + n;
;         v4u o; o.x = cvt_pk_bf16(s[0 * 33] * wsc, s[1 * 33] * wsc); o.y = cvt_pk_bf16(s[2 * 33] * wsc, s[3 * 33] * wsc); o.z = cvt_pk_bf16(s[4 * 33] * wsc, s[5 * 33] * wsc); o.w = cvt_pk_bf16(s[6 * 33] * wsc, s[7 * 33] * wsc);
;         *(v4u*)(WT + (size_t)(r0 + n) * K + k0 + 8 * c) = o; }
;     LDS_WAIT(); asm volatile("" ::: "memory");
; }
	s_nop 0
	v_mul_f32_e32 v2, 0x3fb8aa3b, v240
	v_mul_f32_e32 v3, 0x3fb8aa3b, v241
	v_cvt_pk_bf16_f32 v2, v2, v3
	s_waitcnt lgkmcnt(6)
	v_mul_f32_e32 v3, 0x3fb8aa3b, v242
	v_mul_f32_e32 v4, 0x3fb8aa3b, v243
	v_cvt_pk_bf16_f32 v3, v3, v4
	s_waitcnt lgkmcnt(5)
	v_mul_f32_e32 v4, 0x3fb8aa3b, v244
	v_mul_f32_e32 v5, 0x3fb8aa3b, v245
	v_cvt_pk_bf16_f32 v4, v4, v5
	s_waitcnt lgkmcnt(4)
	v_mul_f32_e32 v5, 0x3fb8aa3b, v246
	v_mul_f32_e32 v6, 0x3fb8aa3b, v247
	v_cvt_pk_bf16_f32 v5, v5, v6
	v_or_b32_e32 v6, s47, v120
	v_mov_b32_e32 v7, v103
	v_lshlrev_b64 v[6:7], 13, v[6:7]
	v_lshl_add_u64 v[6:7], v[8:9], 0, v[6:7]
	global_store_dwordx4 v[6:7], v[2:5], off
	s_waitcnt lgkmcnt(3)
	s_nop 0
	v_mul_f32_e32 v2, 0x3fb8aa3b, v248
	v_mul_f32_e32 v3, 0x3fb8aa3b, v249
	v_cvt_pk_bf16_f32 v2, v2, v3
	s_waitcnt lgkmcnt(2)
	v_mul_f32_e32 v3, 0x3fb8aa3b, v250
	v_mul_f32_e32 v4, 0x3fb8aa3b, v251
	v_cvt_pk_bf16_f32 v3, v3, v4
	s_waitcnt lgkmcnt(1)
	v_mul_f32_e32 v4, 0x3fb8aa3b, v252
	v_mul_f32_e32 v5, 0x3fb8aa3b, v253
	v_cvt_pk_bf16_f32 v4, v4, v5
	s_waitcnt lgkmcnt(0)
	v_mul_f32_e32 v5, 0x3fb8aa3b, v254
	v_mul_f32_e32 v6, 0x3fb8aa3b, v255
	v_cvt_pk_bf16_f32 v5, v5, v6
	v_or_b32_e32 v6, s47, v121
	v_mov_b32_e32 v7, v103
	v_lshlrev_b64 v[6:7], 13, v[6:7]
	v_lshl_add_u64 v[6:7], v[8:9], 0, v[6:7]
	global_store_dwordx4 v[6:7], v[2:5], off
	s_waitcnt lgkmcnt(0)
	s_mul_hi_i32 s33, s41, 0x2aaaaaab
	s_lshr_b32 s44, s33, 31
	s_ashr_i32 s33, s33, 3
	s_add_i32 s33, s33, s44
	s_mul_i32 s44, s33, 48
	s_sub_i32 s44, s41, s44
	v_lshl_or_b32 v2, s33, 6, v116
	s_add_i32 s47, s44, s39
	v_mad_i64_i32 v[2:3], s[44:45], v2, s28, v[114:115]
	s_lshl_b32 s44, s47, 5
	s_mov_b32 s45, s11
	v_lshl_add_u64 v[2:3], s[44:45], 2, v[2:3]
	v_lshl_add_u64 v[34:35], v[2:3], 0, v[102:103]
	v_add_co_u32_e32 v6, vcc, s30, v34
	s_nop 1
	v_addc_co_u32_e32 v7, vcc, 0, v35, vcc
	v_add_co_u32_e32 v10, vcc, s31, v34
	global_load_dwordx4 v[2:5], v[34:35], off nt
	s_nop 0
	global_load_dwordx4 v[6:9], v[6:7], off nt
	v_addc_co_u32_e32 v11, vcc, 0, v35, vcc
	v_add_co_u32_e32 v14, vcc, s34, v34
	s_nop 1
	v_addc_co_u32_e32 v15, vcc, 0, v35, vcc
	v_add_co_u32_e32 v18, vcc, s35, v34
	global_load_dwordx4 v[10:13], v[10:11], off nt
	s_nop 0
	global_load_dwordx4 v[14:17], v[14:15], off nt
	v_addc_co_u32_e32 v19, vcc, 0, v35, vcc
	v_add_co_u32_e32 v22, vcc, s36, v34
	s_nop 1
	v_addc_co_u32_e32 v23, vcc, 0, v35, vcc
	v_add_co_u32_e32 v36, vcc, s37, v34
	global_load_dwordx4 v[18:21], v[18:19], off nt
	s_nop 0
	global_load_dwordx4 v[22:25], v[22:23], off nt
	v_addc_co_u32_e32 v37, vcc, 0, v35, vcc
	v_add_co_u32_e32 v38, vcc, s38, v34
	s_nop 1
	v_addc_co_u32_e32 v39, vcc, 0, v35, vcc
	global_load_dwordx4 v[34:37], v[36:37], off nt
	s_nop 0
	global_load_dwordx4 v[38:41], v[38:39], off nt
	s_waitcnt vmcnt(27)
	ds_write2_b32 v99, v26, v27 offset1:1
	ds_write2_b32 v99, v28, v29 offset0:2 offset1:3
	s_waitcnt vmcnt(26)
	ds_write2_b32 v101, v30, v31 offset1:1
	ds_write2_b32 v123, v32, v33 offset1:1
	s_waitcnt vmcnt(25)
	ds_write2_b32 v124, v42, v43 offset1:1
	ds_write2_b32 v125, v44, v45 offset1:1
	s_waitcnt vmcnt(24)
	ds_write2_b32 v126, v46, v47 offset1:1
	ds_write2_b32 v127, v48, v49 offset1:1
	s_waitcnt vmcnt(23)
	ds_write2_b32 v128, v50, v51 offset1:1
	ds_write2_b32 v129, v52, v53 offset1:1
	s_waitcnt vmcnt(22)
	ds_write2_b32 v130, v54, v55 offset1:1
	ds_write2_b32 v131, v56, v57 offset1:1
	s_waitcnt vmcnt(21)
	ds_write2_b32 v132, v58, v59 offset1:1
	ds_write2_b32 v133, v60, v61 offset1:1
	s_waitcnt vmcnt(20)
	ds_write2_b32 v134, v62, v63 offset1:1
	ds_write2_b32 v135, v64, v65 offset1:1
	s_waitcnt lgkmcnt(0)
	ds_read2_b32 v[240:241], v122 offset1:33
	ds_read2_b32 v[242:243], v122 offset0:66 offset1:99
	ds_read2_b32 v[244:245], v122 offset0:132 offset1:165
	ds_read2_b32 v[246:247], v122 offset0:198 offset1:231
	ds_read2_b32 v[248:249], v122 offset0:8 offset1:41
	ds_read2_b32 v[250:251], v122 offset0:74 offset1:107
	ds_read2_b32 v[252:253], v122 offset0:140 offset1:173
	ds_read2_b32 v[254:255], v122 offset0:206 offset1:239
	s_mul_hi_i32 s33, s43, 0x2aaaaaab
	s_lshr_b32 s44, s33, 31
	s_ashr_i32 s33, s33, 3
	s_add_i32 s33, s33, s44
	s_waitcnt lgkmcnt(7)
	v_mul_f32_e32 v26, 0x3fb8aa3b, v240
	v_mul_f32_e32 v27, 0x3fb8aa3b, v241
	v_cvt_pk_bf16_f32 v26, v26, v27
	ds_read2_b32 v[240:241], v122 offset0:16 offset1:49
	s_mul_i32 s44, s33, 48
	s_sub_i32 s43, s43, s44
	s_add_i32 s43, s43, s39
	s_lshl_b32 s44, s43, 5
	s_waitcnt lgkmcnt(7)
	v_mul_f32_e32 v27, 0x3fb8aa3b, v242
	v_mul_f32_e32 v28, 0x3fb8aa3b, v243
	v_cvt_pk_bf16_f32 v27, v27, v28
	ds_read2_b32 v[242:243], v122 offset0:82 offset1:115
	s_lshl_b32 s43, s43, 6
	s_and_b32 s43, s43, 0x7fffff00
	s_and_b32 s44, s44, 0x60
	s_or_b32 s43, s44, s43
	s_waitcnt lgkmcnt(7)
	v_mul_f32_e32 v28, 0x3fb8aa3b, v244
	v_mul_f32_e32 v29, 0x3fb8aa3b, v245
	v_cvt_pk_bf16_f32 v28, v28, v29
	ds_read2_b32 v[244:245], v122 offset0:148 offset1:181
	s_lshl_b32 s44, s33, 6
	s_ashr_i32 s45, s44, 31
	v_lshl_add_u64 v[32:33], s[44:45], 1, v[108:109]
	s_waitcnt lgkmcnt(7)
	v_mul_f32_e32 v29, 0x3fb8aa3b, v246
	v_mul_f32_e32 v30, 0x3fb8aa3b, v247
	v_cvt_pk_bf16_f32 v29, v29, v30
	ds_read2_b32 v[246:247], v122 offset0:214 offset1:247
	v_or_b32_e32 v30, s43, v116
	v_mov_b32_e32 v31, v103
	v_lshlrev_b64 v[30:31], 13, v[30:31]
	v_lshl_add_u64 v[30:31], v[32:33], 0, v[30:31]
	global_store_dwordx4 v[30:31], v[26:29], off
	s_waitcnt lgkmcnt(7)
	s_nop 0
	v_mul_f32_e32 v26, 0x3fb8aa3b, v248
	v_mul_f32_e32 v27, 0x3fb8aa3b, v249
	v_cvt_pk_bf16_f32 v26, v26, v27
	ds_read2_b32 v[248:249], v122 offset0:24 offset1:57
	s_waitcnt lgkmcnt(7)
; __device__ __forceinline__ unsigned cvt_pk_bf16(float lo, float hi) { unsigned r; asm volatile("v_cvt_pk_bf16_f32 %0, %1, %2" : "=v"(r) : "v"(lo), "v"(hi)); return r; }
; #define LAS __attribute__((address_space(3)))
; #define LDS_WAIT() asm volatile("s_waitcnt lgkmcnt(0)" ::: "memory")
; __device__ __forceinline__ void p0_item_load(const float* __restrict__ W, int N, int nblk, int nb0, int item, int lane, f32x4 (&v)[8]) {
;     const int kb = item / nblk, nb = nb0 + item % nblk;
;     const float* src = W + (size_t)(64 * kb + (lane >> 3)) * N + 32 * nb + 4 * (lane & 7);
; #pragma unroll
;     for (int i = 0; i < 8; ++i) v[i] = __builtin_nontemporal_load((const f32x4*)(src + (size_t)(8 * i) * N));
; }
; __device__ __forceinline__ void p0_item_store(const f32x4 (&v)[8], int K, int nblk, int nb0, bf16* __restrict__ WT, int mode, LAS float* scr, int item, int lane) {
;     const int kb = item / nblk, nb = nb0 + item % nblk, k0 = 64 * kb, n0 = 32 * nb;
; #pragma unroll
;     for (int i = 0; i < 8; ++i) { LAS float* d = scr + (8 * i + (lane >> 3)) * 33 + 4 * (lane & 7); d[0] = v[i].x; d[1] = v[i].y; d[2] = v[i].z; d[3] = v[i].w; }
;     LDS_WAIT(); asm volatile("" ::: "memory");
;     const int c = lane & 7, r0 = map_row(n0, mode);
;     const float wsc = mode == 1 ? 1.44269504089f : (mode == 2 ? 0.69314718056f : 1.0f);
; #pragma unroll
;     for (int j = 0; j < 4; ++j) { const int n = (lane >> 3) + 8 * j; const LAS float* s = scr + (8 * c) * 33 + n;
;         v4u o; o.x = cvt_pk_bf16(s[0 * 33] * wsc, s[1 * 33] * wsc); o.y = cvt_pk_bf16(s[2 * 33] * wsc, s[3 * 33] * wsc); o.z = cvt_pk_bf16(s[4 * 33] * wsc, s[5 * 33] * wsc); o.w = cvt_pk_bf16(s[6 * 33] * wsc, s[7 * 33] * wsc);
;         *(v4u*)(WT + (size_t)(r0 + n) * K + k0 + 8 * c) = o; }
;     LDS_WAIT(); asm volatile("" ::: "memory");
; }
	v_mul_f32_e32 v27, 0x3fb8aa3b, v250
	v_mul_f32_e32 v28, 0x3fb8aa3b, v251
	v_cvt_pk_bf16_f32 v27, v27, v28
	ds_read2_b32 v[250:251], v122 offset0:90 offset1:123
	s_waitcnt lgkmcnt(7)
	v_mul_f32_e32 v28, 0x3fb8aa3b, v252
	v_mul_f32_e32 v29, 0x3fb8aa3b, v253
	v_cvt_pk_bf16_f32 v28, v28, v29
	ds_read2_b32 v[252:253], v122 offset0:156 offset1:189
	s_waitcnt lgkmcnt(7)
	v_mul_f32_e32 v29, 0x3fb8aa3b, v254
	v_mul_f32_e32 v30, 0x3fb8aa3b, v255
	v_cvt_pk_bf16_f32 v29, v29, v30
	ds_read2_b32 v[254:255], v122 offset0:222 offset1:255
	v_or_b32_e32 v30, s43, v119
	v_mov_b32_e32 v31, v103
	v_lshlrev_b64 v[30:31], 13, v[30:31]
	v_lshl_add_u64 v[30:31], v[32:33], 0, v[30:31]
	global_store_dwordx4 v[30:31], v[26:29], off
	s_waitcnt lgkmcnt(7)
	s_nop 0
	v_mul_f32_e32 v26, 0x3fb8aa3b, v240
	v_mul_f32_e32 v27, 0x3fb8aa3b, v241
	v_cvt_pk_bf16_f32 v26, v26, v27
	s_waitcnt lgkmcnt(6)
	v_mul_f32_e32 v27, 0x3fb8aa3b, v242
	v_mul_f32_e32 v28, 0x3fb8aa3b, v243
	v_cvt_pk_bf16_f32 v27, v27, v28
	s_waitcnt lgkmcnt(5)
	v_mul_f32_e32 v28, 0x3fb8aa3b, v244
	v_mul_f32_e32 v29, 0x3fb8aa3b, v245
	v_cvt_pk_bf16_f32 v28, v28, v29
	s_waitcnt lgkmcnt(4)
	v_mul_f32_e32 v29, 0x3fb8aa3b, v246
	v_mul_f32_e32 v30, 0x3fb8aa3b, v247
	v_cvt_pk_bf16_f32 v29, v29, v30
	v_or_b32_e32 v30, s43, v120
	v_mov_b32_e32 v31, v103
	v_lshlrev_b64 v[30:31], 13, v[30:31]
	v_lshl_add_u64 v[30:31], v[32:33], 0, v[30:31]
	global_store_dwordx4 v[30:31], v[26:29], off
	s_waitcnt lgkmcnt(3)
	s_nop 0
	v_mul_f32_e32 v26, 0x3fb8aa3b, v248
	v_mul_f32_e32 v27, 0x3fb8aa3b, v249
	v_cvt_pk_bf16_f32 v26, v26, v27
	s_waitcnt lgkmcnt(2)
	v_mul_f32_e32 v27, 0x3fb8aa3b, v250
	v_mul_f32_e32 v28, 0x3fb8aa3b, v251
	v_cvt_pk_bf16_f32 v27, v27, v28
	s_waitcnt lgkmcnt(1)
	v_mul_f32_e32 v28, 0x3fb8aa3b, v252
	v_mul_f32_e32 v29, 0x3fb8aa3b, v253
	v_cvt_pk_bf16_f32 v28, v28, v29
	s_waitcnt lgkmcnt(0)
	v_mul_f32_e32 v29, 0x3fb8aa3b, v254
	v_mul_f32_e32 v30, 0x3fb8aa3b, v255
	v_cvt_pk_bf16_f32 v29, v29, v30
	v_or_b32_e32 v30, s43, v121
	v_mov_b32_e32 v31, v103
	v_lshlrev_b64 v[30:31], 13, v[30:31]
	v_lshl_add_u64 v[30:31], v[32:33], 0, v[30:31]
	global_store_dwordx4 v[30:31], v[26:29], off
	s_waitcnt lgkmcnt(0)
	s_mul_hi_i32 s33, s42, 0x2aaaaaab
	s_lshr_b32 s43, s33, 31
	s_ashr_i32 s33, s33, 3
	s_add_i32 s33, s33, s43
	s_mul_i32 s43, s33, 48
	s_sub_i32 s43, s42, s43
	v_lshl_or_b32 v26, s33, 6, v116
	s_add_i32 s43, s43, s39
	v_mad_i64_i32 v[26:27], s[44:45], v26, s28, v[114:115]
	s_lshl_b32 s44, s43, 5
	s_mov_b32 s45, s11
	v_lshl_add_u64 v[26:27], s[44:45], 2, v[26:27]
	v_lshl_add_u64 v[58:59], v[26:27], 0, v[102:103]
	v_add_co_u32_e32 v30, vcc, s30, v58
	s_nop 1
	v_addc_co_u32_e32 v31, vcc, 0, v59, vcc
	v_add_co_u32_e32 v42, vcc, s31, v58
	global_load_dwordx4 v[26:29], v[58:59], off nt
	s_nop 0
	global_load_dwordx4 v[30:33], v[30:31], off nt
	v_addc_co_u32_e32 v43, vcc, 0, v59, vcc
	v_add_co_u32_e32 v46, vcc, s34, v58
	s_nop 1
	v_addc_co_u32_e32 v47, vcc, 0, v59, vcc
	v_add_co_u32_e32 v50, vcc, s35, v58
	global_load_dwordx4 v[42:45], v[42:43], off nt
	s_nop 0
	global_load_dwordx4 v[46:49], v[46:47], off nt
	v_addc_co_u32_e32 v51, vcc, 0, v59, vcc
	v_add_co_u32_e32 v54, vcc, s36, v58
	s_nop 1
	v_addc_co_u32_e32 v55, vcc, 0, v59, vcc
	v_add_co_u32_e32 v60, vcc, s37, v58
	global_load_dwordx4 v[50:53], v[50:51], off nt
	s_nop 0
	global_load_dwordx4 v[54:57], v[54:55], off nt
	v_addc_co_u32_e32 v61, vcc, 0, v59, vcc
	v_add_co_u32_e32 v62, vcc, s38, v58
	s_nop 1
	v_addc_co_u32_e32 v63, vcc, 0, v59, vcc
	global_load_dwordx4 v[58:61], v[60:61], off nt
	s_nop 0
	global_load_dwordx4 v[62:65], v[62:63], off nt
	s_waitcnt vmcnt(31)
	ds_write2_b32 v99, v66, v67 offset1:1
	ds_write2_b32 v99, v68, v69 offset0:2 offset1:3
	s_waitcnt vmcnt(30)
	ds_write2_b32 v101, v70, v71 offset1:1
	ds_write2_b32 v123, v72, v73 offset1:1
	s_waitcnt vmcnt(29)
	ds_write2_b32 v124, v74, v75 offset1:1
	ds_write2_b32 v125, v76, v77 offset1:1
	s_waitcnt vmcnt(28)
	ds_write2_b32 v126, v78, v79 offset1:1
	ds_write2_b32 v127, v80, v81 offset1:1
	s_waitcnt vmcnt(27)
	ds_write2_b32 v128, v82, v83 offset1:1
	ds_write2_b32 v129, v84, v85 offset1:1
	s_waitcnt vmcnt(26)
; #define LAS __attribute__((address_space(3)))
; __device__ __forceinline__ void p0_item_load(const float* __restrict__ W, int N, int nblk, int nb0, int item, int lane, f32x4 (&v)[8]) {
;     const int kb = item / nblk, nb = nb0 + item % nblk;
;     const float* src = W + (size_t)(64 * kb + (lane >> 3)) * N + 32 * nb + 4 * (lane & 7);
; #pragma unroll
;     for (int i = 0; i < 8; ++i) v[i] = __builtin_nontemporal_load((const f32x4*)(src + (size_t)(8 * i) * N));
; }
; __device__ __forceinline__ void p0_item_store(const f32x4 (&v)[8], int K, int nblk, int nb0, bf16* __restrict__ WT, int mode, LAS float* scr, int item, int lane) {
;     const int kb = item / nblk, nb = nb0 + item % nblk, k0 = 64 * kb, n0 = 32 * nb;
; #pragma unroll
;     for (int i = 0; i < 8; ++i) { LAS float* d = scr + (8 * i + (lane >> 3)) * 33 + 4 * (lane & 7); d[0] = v[i].x; d[1] = v[i].y; d[2] = v[i].z; d[3] = v[i].w; }
;     LDS_WAIT(); asm volatile("" ::: "memory");
;     const int c = lane & 7, r0 = map_row(n0, mode);
;     const float wsc = mode == 1 ? 1.44269504089f : (mode == 2 ? 0.69314718056f : 1.0f);
; #pragma unroll
;     for (int j = 0; j < 4; ++j) { const int n = (lane >> 3) + 8 * j; const LAS float* s = scr + (8 * c) * 33 + n;
;         v4u o; o.x = cvt_pk_bf16(s[0 * 33] * wsc, s[1 * 33] * wsc); o.y = cvt_pk_bf16(s[2 * 33] * wsc, s[3 * 33] * wsc); o.z = cvt_pk_bf16(s[4 * 33] * wsc, s[5 * 33] * wsc); o.w = cvt_pk_bf16(s[6 * 33] * wsc, s[7 * 33] * wsc);
;         *(v4u*)(WT + (size_t)(r0 + n) * K + k0 + 8 * c) = o; }
;     LDS_WAIT(); asm volatile("" ::: "memory");
; }
;     ...
;     for (int p = 0; p < ntri; ++p) {
;         const int i2 = min(i1 + nw, last), i3 = min(i2 + nw, last), i4 = min(i3 + nw, last);
;         p0_item_load(W, N, nblk, nb0, i2, F.lane, vc); __builtin_amdgcn_sched_barrier(0);
;         p0_item_store(va, K, nblk, nb0, WT, mode, scr, it, F.lane); __builtin_amdgcn_sched_barrier(0);
;         p0_item_load(W, N, nblk, nb0, i3, F.lane, va); __builtin_amdgcn_sched_barrier(0);
;         p0_item_store(vb, K, nblk, nb0, WT, mode, scr, i1, F.lane); __builtin_amdgcn_sched_barrier(0);
;         p0_item_load(W, N, nblk, nb0, i4, F.lane, vb); __builtin_amdgcn_sched_barrier(0);
;         p0_item_store(vc, K, nblk, nb0, WT, mode, scr, i2, F.lane); __builtin_amdgcn_sched_barrier(0);
;         it = i3; i1 = i4;
;     }
	ds_write2_b32 v130, v86, v87 offset1:1
	ds_write2_b32 v131, v88, v89 offset1:1
	s_waitcnt vmcnt(25)
	ds_write2_b32 v132, v90, v91 offset1:1
	ds_write2_b32 v133, v92, v93 offset1:1
	s_waitcnt vmcnt(24)
	ds_write2_b32 v134, v94, v95 offset1:1
	ds_write2_b32 v135, v96, v97 offset1:1
	s_waitcnt lgkmcnt(0)
	ds_read2_b32 v[240:241], v122 offset1:33
	ds_read2_b32 v[242:243], v122 offset0:66 offset1:99
	ds_read2_b32 v[244:245], v122 offset0:132 offset1:165
	ds_read2_b32 v[246:247], v122 offset0:198 offset1:231
	ds_read2_b32 v[248:249], v122 offset0:8 offset1:41
	ds_read2_b32 v[250:251], v122 offset0:74 offset1:107
	ds_read2_b32 v[252:253], v122 offset0:140 offset1:173
	ds_read2_b32 v[254:255], v122 offset0:206 offset1:239
	s_lshl_b32 s15, s15, 6
	s_and_b32 s15, s15, 0x7fffff00
	s_and_b32 s10, s10, 0x60
	s_or_b32 s10, s10, s15
	s_waitcnt lgkmcnt(7)
	v_mul_f32_e32 v66, 0x3fb8aa3b, v240
	v_mul_f32_e32 v67, 0x3fb8aa3b, v241
	v_cvt_pk_bf16_f32 v66, v66, v67
	ds_read2_b32 v[240:241], v122 offset0:16 offset1:49
	s_ashr_i32 s15, s14, 31
	v_or_b32_e32 v102, s10, v116
	v_lshl_add_u64 v[72:73], s[14:15], 1, v[108:109]
	v_lshlrev_b64 v[74:75], 13, v[102:103]
	s_waitcnt lgkmcnt(7)
	v_mul_f32_e32 v67, 0x3fb8aa3b, v242
	v_mul_f32_e32 v68, 0x3fb8aa3b, v243
	v_cvt_pk_bf16_f32 v67, v67, v68
	ds_read2_b32 v[242:243], v122 offset0:82 offset1:115
	v_lshl_add_u64 v[74:75], v[72:73], 0, v[74:75]
	v_or_b32_e32 v102, s10, v119
	s_waitcnt lgkmcnt(7)
	v_mul_f32_e32 v68, 0x3fb8aa3b, v244
	v_mul_f32_e32 v69, 0x3fb8aa3b, v245
	v_cvt_pk_bf16_f32 v68, v68, v69
	ds_read2_b32 v[244:245], v122 offset0:148 offset1:181
	s_waitcnt lgkmcnt(7)
	v_mul_f32_e32 v69, 0x3fb8aa3b, v246
	v_mul_f32_e32 v70, 0x3fb8aa3b, v247
	v_cvt_pk_bf16_f32 v69, v69, v70
	ds_read2_b32 v[246:247], v122 offset0:214 offset1:247
	global_store_dwordx4 v[74:75], v[66:69], off
	v_lshlrev_b64 v[74:75], 13, v[102:103]
	v_lshl_add_u64 v[74:75], v[72:73], 0, v[74:75]
	v_or_b32_e32 v102, s10, v120
	s_waitcnt lgkmcnt(7)
	v_mul_f32_e32 v66, 0x3fb8aa3b, v248
	v_mul_f32_e32 v67, 0x3fb8aa3b, v249
	v_cvt_pk_bf16_f32 v66, v66, v67
	ds_read2_b32 v[248:249], v122 offset0:24 offset1:57
	s_waitcnt lgkmcnt(7)
	v_mul_f32_e32 v67, 0x3fb8aa3b, v250
	v_mul_f32_e32 v68, 0x3fb8aa3b, v251
	v_cvt_pk_bf16_f32 v67, v67, v68
	ds_read2_b32 v[250:251], v122 offset0:90 offset1:123
	s_waitcnt lgkmcnt(7)
	v_mul_f32_e32 v68, 0x3fb8aa3b, v252
	v_mul_f32_e32 v69, 0x3fb8aa3b, v253
	v_cvt_pk_bf16_f32 v68, v68, v69
	ds_read2_b32 v[252:253], v122 offset0:156 offset1:189
	s_waitcnt lgkmcnt(7)
	v_mul_f32_e32 v69, 0x3fb8aa3b, v254
	v_mul_f32_e32 v70, 0x3fb8aa3b, v255
	v_cvt_pk_bf16_f32 v69, v69, v70
	ds_read2_b32 v[254:255], v122 offset0:222 offset1:255
	global_store_dwordx4 v[74:75], v[66:69], off
	v_lshlrev_b64 v[74:75], 13, v[102:103]
	v_lshl_add_u64 v[74:75], v[72:73], 0, v[74:75]
	v_or_b32_e32 v102, s10, v121
	s_waitcnt lgkmcnt(7)
	v_mul_f32_e32 v66, 0x3fb8aa3b, v240
	v_mul_f32_e32 v67, 0x3fb8aa3b, v241
	v_cvt_pk_bf16_f32 v66, v66, v67
	s_waitcnt lgkmcnt(6)
	v_mul_f32_e32 v67, 0x3fb8aa3b, v242
	v_mul_f32_e32 v68, 0x3fb8aa3b, v243
	v_cvt_pk_bf16_f32 v67, v67, v68
	s_waitcnt lgkmcnt(5)
	v_mul_f32_e32 v68, 0x3fb8aa3b, v244
	v_mul_f32_e32 v69, 0x3fb8aa3b, v245
	v_cvt_pk_bf16_f32 v68, v68, v69
	s_waitcnt lgkmcnt(4)
	v_mul_f32_e32 v69, 0x3fb8aa3b, v246
	v_mul_f32_e32 v70, 0x3fb8aa3b, v247
	v_cvt_pk_bf16_f32 v69, v69, v70
	global_store_dwordx4 v[74:75], v[66:69], off
	s_waitcnt lgkmcnt(3)
	s_nop 0
	v_mul_f32_e32 v66, 0x3fb8aa3b, v248
	v_mul_f32_e32 v67, 0x3fb8aa3b, v249
	v_cvt_pk_bf16_f32 v66, v66, v67
	s_waitcnt lgkmcnt(2)
	v_mul_f32_e32 v67, 0x3fb8aa3b, v250
	v_mul_f32_e32 v68, 0x3fb8aa3b, v251
	v_cvt_pk_bf16_f32 v67, v67, v68
	s_waitcnt lgkmcnt(1)
	v_mul_f32_e32 v68, 0x3fb8aa3b, v252
	v_mul_f32_e32 v69, 0x3fb8aa3b, v253
	v_cvt_pk_bf16_f32 v68, v68, v69
	s_waitcnt lgkmcnt(0)
	v_mul_f32_e32 v69, 0x3fb8aa3b, v254
	v_mul_f32_e32 v70, 0x3fb8aa3b, v255
	v_cvt_pk_bf16_f32 v69, v69, v70
	v_lshlrev_b64 v[70:71], 13, v[102:103]
	v_lshl_add_u64 v[70:71], v[72:73], 0, v[70:71]
	global_store_dwordx4 v[70:71], v[66:69], off
	s_waitcnt lgkmcnt(0)
	s_add_i32 s40, s40, -1
	s_cmp_lg_u32 s40, 0
	s_mov_b32 s44, s41
	s_mov_b32 s43, s42
	s_cbranch_scc1 .LBB0_91

; __device__ __forceinline__ unsigned cvt_pk_bf16(float lo, float hi) { unsigned r; asm volatile("v_cvt_pk_bf16_f32 %0, %1, %2" : "=v"(r) : "v"(lo), "v"(hi)); return r; }
; #define LAS __attribute__((address_space(3)))
; #define LDS_WAIT() asm volatile("s_waitcnt lgkmcnt(0)" ::: "memory")
; __device__ __forceinline__ void p0_item_load(const float* __restrict__ W, int N, int nblk, int nb0, int item, int lane, f32x4 (&v)[8]) {
;     const int kb = item / nblk, nb = nb0 + item % nblk;
;     const float* src = W + (size_t)(64 * kb + (lane >> 3)) * N + 32 * nb + 4 * (lane & 7);
; #pragma unroll
;     for (int i = 0; i < 8; ++i) v[i] = __builtin_nontemporal_load((const f32x4*)(src + (size_t)(8 * i) * N));
; }
; __device__ __forceinline__ void p0_item_store(const f32x4 (&v)[8], int K, int nblk, int nb0, bf16* __restrict__ WT, int mode, LAS float* scr, int item, int lane) {
;     const int kb = item / nblk, nb = nb0 + item % nblk, k0 = 64 * kb, n0 = 32 * nb;
; #pragma unroll
;     for (int i = 0; i < 8; ++i) { LAS float* d = scr + (8 * i + (lane >> 3)) * 33 + 4 * (lane & 7); d[0] = v[i].x; d[1] = v[i].y; d[2] = v[i].z; d[3] = v[i].w; }
;     LDS_WAIT(); asm volatile("" ::: "memory");
;     const int c = lane & 7, r0 = map_row(n0, mode);
;     const float wsc = mode == 1 ? 1.44269504089f : (mode == 2 ? 0.69314718056f : 1.0f);
; #pragma unroll
;     for (int j = 0; j < 4; ++j) { const int n = (lane >> 3) + 8 * j; const LAS float* s = scr + (8 * c) * 33 + n;
;         v4u o; o.x = cvt_pk_bf16(s[0 * 33] * wsc, s[1 * 33] * wsc); o.y = cvt_pk_bf16(s[2 * 33] * wsc, s[3 * 33] * wsc); o.z = cvt_pk_bf16(s[4 * 33] * wsc, s[5 * 33] * wsc); o.w = cvt_pk_bf16(s[6 * 33] * wsc, s[7 * 33] * wsc);
;         *(v4u*)(WT + (size_t)(r0 + n) * K + k0 + 8 * c) = o; }
;     LDS_WAIT(); asm volatile("" ::: "memory");
; }
; __device__ __forceinline__ void convert_beside_ffn1(Frame& F, const Args& A, int w0, int nw) {
;     ...
;     for (int t0 = GATE_G0; t0 < NPN1; t0 += GATE_SG) { const int tn = min(GATE_SG, NPN1 - t0);
;         p0_transpose(F, A.in[5], D, DFF, (bf16*)(F.ws + WS_WGU1), 1, w0, nw, 0, 16, 4 * t0, 4 * tn);
;         p0_transpose(F, A.in[6], D, DFF, (bf16*)(F.ws + WS_WGU1), 2, w0, nw, 0, 16, 4 * t0, 4 * tn);
.LBB0_94:
	s_add_i32 s2, s15, s17
	s_min_i32 s13, s2, 0xbff
	s_mul_hi_i32 s2, s13, 0x2aaaaaab
	s_lshr_b32 s3, s2, 31
	s_ashr_i32 s2, s2, 3
	s_add_i32 s2, s2, s3
	s_mul_i32 s3, s2, 48
	s_sub_i32 s3, s13, s3
	s_lshl_b32 s2, s2, 6
	s_add_i32 s3, s3, s39
	v_or_b32_e32 v66, s2, v116
	v_mov_b64_e32 v[114:115], s[84:85]
	v_mad_i64_i32 v[66:67], s[42:43], v66, s28, v[114:115]
	s_lshl_b32 s10, s3, 5
	v_lshl_add_u64 v[66:67], s[10:11], 2, v[66:67]
	v_lshlrev_b32_e32 v102, 2, v100
	v_lshl_add_u64 v[90:91], v[66:67], 0, v[102:103]
	v_add_co_u32_e32 v70, vcc, s30, v90
	s_add_i32 s13, s13, s17
	s_nop 0
	v_addc_co_u32_e32 v71, vcc, 0, v91, vcc
	v_add_co_u32_e32 v74, vcc, s31, v90
	global_load_dwordx4 v[66:69], v[90:91], off nt
	s_nop 0
	global_load_dwordx4 v[70:73], v[70:71], off nt
	v_addc_co_u32_e32 v75, vcc, 0, v91, vcc
	v_add_co_u32_e32 v78, vcc, s34, v90
	s_min_i32 s13, s13, 0xbff
	s_nop 0
	v_addc_co_u32_e32 v79, vcc, 0, v91, vcc
	v_add_co_u32_e32 v82, vcc, s35, v90
	global_load_dwordx4 v[74:77], v[74:75], off nt
	s_nop 0
	global_load_dwordx4 v[78:81], v[78:79], off nt
	v_addc_co_u32_e32 v83, vcc, 0, v91, vcc
	v_add_co_u32_e32 v86, vcc, s36, v90
	s_add_i32 s14, s13, s17
	s_nop 0
	v_addc_co_u32_e32 v87, vcc, 0, v91, vcc
	v_add_co_u32_e32 v92, vcc, s37, v90
	global_load_dwordx4 v[82:85], v[82:83], off nt
	s_nop 0
	global_load_dwordx4 v[86:89], v[86:87], off nt
	v_addc_co_u32_e32 v93, vcc, 0, v91, vcc
	v_add_co_u32_e32 v94, vcc, s38, v90
	s_min_i32 s14, s14, 0xbff
	s_nop 0
	v_addc_co_u32_e32 v95, vcc, 0, v91, vcc
	global_load_dwordx4 v[90:93], v[92:93], off nt
	s_nop 0
	global_load_dwordx4 v[94:97], v[94:95], off nt
	v_add_u32_e32 v99, v117, v118
	v_add_u32_e32 v101, 0x420, v99
	v_add_u32_e32 v123, 0x428, v99
	v_add_u32_e32 v124, 0x840, v99
	v_add_u32_e32 v125, 0x848, v99
	v_add_u32_e32 v126, 0xc60, v99
	v_add_u32_e32 v127, 0xc68, v99
	v_add_u32_e32 v128, 0x1080, v99
	v_add_u32_e32 v129, 0x1088, v99
	v_add_u32_e32 v130, 0x14a0, v99
	v_add_u32_e32 v131, 0x14a8, v99
	v_add_u32_e32 v132, 0x18c0, v99
	v_add_u32_e32 v133, 0x18c8, v99
	v_add_u32_e32 v134, 0x1ce0, v99
	v_add_u32_e32 v135, 0x1ce8, v99
	s_waitcnt vmcnt(23)
	ds_write2_b32 v99, v2, v3 offset1:1
	ds_write2_b32 v99, v4, v5 offset0:2 offset1:3
	s_waitcnt vmcnt(22)
	ds_write2_b32 v101, v6, v7 offset1:1
	ds_write2_b32 v123, v8, v9 offset1:1
	s_waitcnt vmcnt(21)
	ds_write2_b32 v124, v10, v11 offset1:1
	ds_write2_b32 v125, v12, v13 offset1:1
	s_waitcnt vmcnt(20)
	ds_write2_b32 v126, v14, v15 offset1:1
	ds_write2_b32 v127, v16, v17 offset1:1
	s_waitcnt vmcnt(19)
	ds_write2_b32 v128, v18, v19 offset1:1
	ds_write2_b32 v129, v20, v21 offset1:1
	s_waitcnt vmcnt(18)
	ds_write2_b32 v130, v22, v23 offset1:1
	ds_write2_b32 v131, v24, v25 offset1:1
	s_waitcnt vmcnt(17)
	ds_write2_b32 v132, v34, v35 offset1:1
	ds_write2_b32 v133, v36, v37 offset1:1
	s_waitcnt vmcnt(16)
	ds_write2_b32 v134, v38, v39 offset1:1
	ds_write2_b32 v135, v40, v41 offset1:1
	s_waitcnt lgkmcnt(0)
	ds_read2_b32 v[240:241], v122 offset1:33
	ds_read2_b32 v[242:243], v122 offset0:66 offset1:99
	ds_read2_b32 v[244:245], v122 offset0:132 offset1:165
	ds_read2_b32 v[246:247], v122 offset0:198 offset1:231
	ds_read2_b32 v[248:249], v122 offset0:8 offset1:41
	ds_read2_b32 v[250:251], v122 offset0:74 offset1:107
	ds_read2_b32 v[252:253], v122 offset0:140 offset1:173
	ds_read2_b32 v[254:255], v122 offset0:206 offset1:239
	s_mul_hi_i32 s33, s40, 0x2aaaaaab
	s_lshr_b32 s41, s33, 31
	s_ashr_i32 s33, s33, 3
	s_add_i32 s33, s33, s41
	s_waitcnt lgkmcnt(7)
	v_mul_f32_e32 v2, 0x3f317218, v240
	v_mul_f32_e32 v3, 0x3f317218, v241
	v_cvt_pk_bf16_f32 v2, v2, v3
	ds_read2_b32 v[240:241], v122 offset0:16 offset1:49
	s_mul_i32 s41, s33, 48
	s_sub_i32 s40, s40, s41
	s_add_i32 s40, s40, s39
	s_lshl_b32 s41, s40, 5
	s_waitcnt lgkmcnt(7)
	v_mul_f32_e32 v3, 0x3f317218, v242
	v_mul_f32_e32 v4, 0x3f317218, v243
	v_cvt_pk_bf16_f32 v3, v3, v4
	ds_read2_b32 v[242:243], v122 offset0:82 offset1:115
	s_lshl_b32 s40, s40, 6
	s_and_b32 s40, s40, 0x7fffff00
	s_or_b32 s41, s41, 0xffffff80
	s_add_i32 s40, s41, s40
	s_waitcnt lgkmcnt(7)
	v_mul_f32_e32 v4, 0x3f317218, v244
	v_mul_f32_e32 v5, 0x3f317218, v245
	v_cvt_pk_bf16_f32 v4, v4, v5
	ds_read2_b32 v[244:245], v122 offset0:148 offset1:181
	s_add_i32 s42, s40, 0x100
	s_lshl_b32 s40, s33, 6
	s_ashr_i32 s41, s40, 31
	v_lshl_add_u64 v[8:9], s[40:41], 1, v[108:109]
	s_waitcnt lgkmcnt(7)
	v_mul_f32_e32 v5, 0x3f317218, v246
	v_mul_f32_e32 v6, 0x3f317218, v247
	v_cvt_pk_bf16_f32 v5, v5, v6
	ds_read2_b32 v[246:247], v122 offset0:214 offset1:247
	v_or_b32_e32 v6, s42, v116
	v_mov_b32_e32 v7, v103
	v_lshlrev_b64 v[6:7], 13, v[6:7]
	v_lshl_add_u64 v[6:7], v[8:9], 0, v[6:7]
	global_store_dwordx4 v[6:7], v[2:5], off
	s_waitcnt lgkmcnt(7)
	s_nop 0
	v_mul_f32_e32 v2, 0x3f317218, v248
	v_mul_f32_e32 v3, 0x3f317218, v249
	v_cvt_pk_bf16_f32 v2, v2, v3
	ds_read2_b32 v[248:249], v122 offset0:24 offset1:57
	s_waitcnt lgkmcnt(7)
	v_mul_f32_e32 v3, 0x3f317218, v250
	v_mul_f32_e32 v4, 0x3f317218, v251
	v_cvt_pk_bf16_f32 v3, v3, v4
	ds_read2_b32 v[250:251], v122 offset0:90 offset1:123
	s_waitcnt lgkmcnt(7)
	v_mul_f32_e32 v4, 0x3f317218, v252
	v_mul_f32_e32 v5, 0x3f317218, v253
	v_cvt_pk_bf16_f32 v4, v4, v5
	ds_read2_b32 v[252:253], v122 offset0:156 offset1:189
	s_waitcnt lgkmcnt(7)
	v_mul_f32_e32 v5, 0x3f317218, v254
	v_mul_f32_e32 v6, 0x3f317218, v255
	v_cvt_pk_bf16_f32 v5, v5, v6
	ds_read2_b32 v[254:255], v122 offset0:222 offset1:255
	v_or_b32_e32 v6, s42, v119
	v_mov_b32_e32 v7, v103
	v_lshlrev_b64 v[6:7], 13, v[6:7]
	v_lshl_add_u64 v[6:7], v[8:9], 0, v[6:7]
	global_store_dwordx4 v[6:7], v[2:5], off
	s_waitcnt lgkmcnt(7)
; __device__ __forceinline__ unsigned cvt_pk_bf16(float lo, float hi) { unsigned r; asm volatile("v_cvt_pk_bf16_f32 %0, %1, %2" : "=v"(r) : "v"(lo), "v"(hi)); return r; }
; #define LAS __attribute__((address_space(3)))
; #define LDS_WAIT() asm volatile("s_waitcnt lgkmcnt(0)" ::: "memory")
; __device__ __forceinline__ void p0_item_load(const float* __restrict__ W, int N, int nblk, int nb0, int item, int lane, f32x4 (&v)[8]) {
;     const int kb = item / nblk, nb = nb0 + item % nblk;
;     const float* src = W + (size_t)(64 * kb + (lane >> 3)) * N + 32 * nb + 4 * (lane & 7);
; #pragma unroll
;     for (int i = 0; i < 8; ++i) v[i] = __builtin_nontemporal_load((const f32x4*)(src + (size_t)(8 * i) * N));
; }
; __device__ __forceinline__ void p0_item_store(const f32x4 (&v)[8], int K, int nblk, int nb0, bf16* __restrict__ WT, int mode, LAS float* scr, int item, int lane) {
;     const int kb = item / nblk, nb = nb0 + item % nblk, k0 = 64 * kb, n0 = 32 * nb;
; #pragma unroll
;     for (int i = 0; i < 8; ++i) { LAS float* d = scr + (8 * i + (lane >> 3)) * 33 + 4 * (lane & 7); d[0] = v[i].x; d[1] = v[i].y; d[2] = v[i].z; d[3] = v[i].w; }
;     LDS_WAIT(); asm volatile("" ::: "memory");
;     const int c = lane & 7, r0 = map_row(n0, mode);
;     const float wsc = mode == 1 ? 1.44269504089f : (mode == 2 ? 0.69314718056f : 1.0f);
; #pragma unroll
;     for (int j = 0; j < 4; ++j) { const int n = (lane >> 3) + 8 * j; const LAS float* s = scr + (8 * c) * 33 + n;
;         v4u o; o.x = cvt_pk_bf16(s[0 * 33] * wsc, s[1 * 33] * wsc); o.y = cvt_pk_bf16(s[2 * 33] * wsc, s[3 * 33] * wsc); o.z = cvt_pk_bf16(s[4 * 33] * wsc, s[5 * 33] * wsc); o.w = cvt_pk_bf16(s[6 * 33] * wsc, s[7 * 33] * wsc);
;         *(v4u*)(WT + (size_t)(r0 + n) * K + k0 + 8 * c) = o; }
;     LDS_WAIT(); asm volatile("" ::: "memory");
; }
	s_nop 0
	v_mul_f32_e32 v2, 0x3f317218, v240
	v_mul_f32_e32 v3, 0x3f317218, v241
	v_cvt_pk_bf16_f32 v2, v2, v3
	s_waitcnt lgkmcnt(6)
	v_mul_f32_e32 v3, 0x3f317218, v242
	v_mul_f32_e32 v4, 0x3f317218, v243
	v_cvt_pk_bf16_f32 v3, v3, v4
	s_waitcnt lgkmcnt(5)
	v_mul_f32_e32 v4, 0x3f317218, v244
	v_mul_f32_e32 v5, 0x3f317218, v245
	v_cvt_pk_bf16_f32 v4, v4, v5
	s_waitcnt lgkmcnt(4)
	v_mul_f32_e32 v5, 0x3f317218, v246
	v_mul_f32_e32 v6, 0x3f317218, v247
	v_cvt_pk_bf16_f32 v5, v5, v6
	v_or_b32_e32 v6, s42, v120
	v_mov_b32_e32 v7, v103
	v_lshlrev_b64 v[6:7], 13, v[6:7]
	v_lshl_add_u64 v[6:7], v[8:9], 0, v[6:7]
	global_store_dwordx4 v[6:7], v[2:5], off
	s_waitcnt lgkmcnt(3)
	s_nop 0
	v_mul_f32_e32 v2, 0x3f317218, v248
	v_mul_f32_e32 v3, 0x3f317218, v249
	v_cvt_pk_bf16_f32 v2, v2, v3
	s_waitcnt lgkmcnt(2)
	v_mul_f32_e32 v3, 0x3f317218, v250
	v_mul_f32_e32 v4, 0x3f317218, v251
	v_cvt_pk_bf16_f32 v3, v3, v4
	s_waitcnt lgkmcnt(1)
	v_mul_f32_e32 v4, 0x3f317218, v252
	v_mul_f32_e32 v5, 0x3f317218, v253
	v_cvt_pk_bf16_f32 v4, v4, v5
	s_waitcnt lgkmcnt(0)
	v_mul_f32_e32 v5, 0x3f317218, v254
	v_mul_f32_e32 v6, 0x3f317218, v255
	v_cvt_pk_bf16_f32 v5, v5, v6
	v_or_b32_e32 v6, s42, v121
	v_mov_b32_e32 v7, v103
	v_lshlrev_b64 v[6:7], 13, v[6:7]
	v_lshl_add_u64 v[6:7], v[8:9], 0, v[6:7]
	global_store_dwordx4 v[6:7], v[2:5], off
	s_waitcnt lgkmcnt(0)
	s_mul_hi_i32 s33, s13, 0x2aaaaaab
	s_lshr_b32 s40, s33, 31
	s_ashr_i32 s33, s33, 3
	s_add_i32 s33, s33, s40
	s_mul_i32 s40, s33, 48
	s_sub_i32 s40, s13, s40
	v_lshl_or_b32 v2, s33, 6, v116
	s_add_i32 s42, s40, s39
	v_mad_i64_i32 v[2:3], s[40:41], v2, s28, v[114:115]
	s_lshl_b32 s40, s42, 5
	s_mov_b32 s41, s11
	v_lshl_add_u64 v[2:3], s[40:41], 2, v[2:3]
	v_lshl_add_u64 v[34:35], v[2:3], 0, v[102:103]
	v_add_co_u32_e32 v6, vcc, s30, v34
	s_nop 1
	v_addc_co_u32_e32 v7, vcc, 0, v35, vcc
	v_add_co_u32_e32 v10, vcc, s31, v34
	global_load_dwordx4 v[2:5], v[34:35], off nt
	s_nop 0
	global_load_dwordx4 v[6:9], v[6:7], off nt
	v_addc_co_u32_e32 v11, vcc, 0, v35, vcc
	v_add_co_u32_e32 v14, vcc, s34, v34
	s_nop 1
	v_addc_co_u32_e32 v15, vcc, 0, v35, vcc
	v_add_co_u32_e32 v18, vcc, s35, v34
	global_load_dwordx4 v[10:13], v[10:11], off nt
	s_nop 0
	global_load_dwordx4 v[14:17], v[14:15], off nt
	v_addc_co_u32_e32 v19, vcc, 0, v35, vcc
	v_add_co_u32_e32 v22, vcc, s36, v34
	s_nop 1
	v_addc_co_u32_e32 v23, vcc, 0, v35, vcc
	v_add_co_u32_e32 v36, vcc, s37, v34
	global_load_dwordx4 v[18:21], v[18:19], off nt
	s_nop 0
	global_load_dwordx4 v[22:25], v[22:23], off nt
	v_addc_co_u32_e32 v37, vcc, 0, v35, vcc
	v_add_co_u32_e32 v38, vcc, s38, v34
	s_nop 1
	v_addc_co_u32_e32 v39, vcc, 0, v35, vcc
	global_load_dwordx4 v[34:37], v[36:37], off nt
	s_nop 0
	global_load_dwordx4 v[38:41], v[38:39], off nt
	s_waitcnt vmcnt(27)
	ds_write2_b32 v99, v26, v27 offset1:1
	ds_write2_b32 v99, v28, v29 offset0:2 offset1:3
	s_waitcnt vmcnt(26)
	ds_write2_b32 v101, v30, v31 offset1:1
	ds_write2_b32 v123, v32, v33 offset1:1
	s_waitcnt vmcnt(25)
	ds_write2_b32 v124, v42, v43 offset1:1
	ds_write2_b32 v125, v44, v45 offset1:1
	s_waitcnt vmcnt(24)
	ds_write2_b32 v126, v46, v47 offset1:1
	ds_write2_b32 v127, v48, v49 offset1:1
	s_waitcnt vmcnt(23)
	ds_write2_b32 v128, v50, v51 offset1:1
	ds_write2_b32 v129, v52, v53 offset1:1
	s_waitcnt vmcnt(22)
	ds_write2_b32 v130, v54, v55 offset1:1
	ds_write2_b32 v131, v56, v57 offset1:1
	s_waitcnt vmcnt(21)
	ds_write2_b32 v132, v58, v59 offset1:1
	ds_write2_b32 v133, v60, v61 offset1:1
	s_waitcnt vmcnt(20)
	ds_write2_b32 v134, v62, v63 offset1:1
	ds_write2_b32 v135, v64, v65 offset1:1
	s_waitcnt lgkmcnt(0)
	ds_read2_b32 v[240:241], v122 offset1:33
	ds_read2_b32 v[242:243], v122 offset0:66 offset1:99
	ds_read2_b32 v[244:245], v122 offset0:132 offset1:165
	ds_read2_b32 v[246:247], v122 offset0:198 offset1:231
	ds_read2_b32 v[248:249], v122 offset0:8 offset1:41
	ds_read2_b32 v[250:251], v122 offset0:74 offset1:107
	ds_read2_b32 v[252:253], v122 offset0:140 offset1:173
	ds_read2_b32 v[254:255], v122 offset0:206 offset1:239
	s_mul_hi_i32 s33, s15, 0x2aaaaaab
	s_lshr_b32 s40, s33, 31
	s_ashr_i32 s33, s33, 3
	s_add_i32 s33, s33, s40
	s_waitcnt lgkmcnt(7)
	v_mul_f32_e32 v26, 0x3f317218, v240
	v_mul_f32_e32 v27, 0x3f317218, v241
	v_cvt_pk_bf16_f32 v26, v26, v27
	ds_read2_b32 v[240:241], v122 offset0:16 offset1:49
	s_mul_i32 s40, s33, 48
	s_sub_i32 s15, s15, s40
	s_add_i32 s15, s15, s39
	s_lshl_b32 s40, s15, 5
	s_waitcnt lgkmcnt(7)
	v_mul_f32_e32 v27, 0x3f317218, v242
	v_mul_f32_e32 v28, 0x3f317218, v243
	v_cvt_pk_bf16_f32 v27, v27, v28
	ds_read2_b32 v[242:243], v122 offset0:82 offset1:115
	s_lshl_b32 s15, s15, 6
	s_and_b32 s15, s15, 0x7fffff00
	s_or_b32 s40, s40, 0xffffff80
	s_add_i32 s15, s40, s15
	s_waitcnt lgkmcnt(7)
	v_mul_f32_e32 v28, 0x3f317218, v244
	v_mul_f32_e32 v29, 0x3f317218, v245
	v_cvt_pk_bf16_f32 v28, v28, v29
	ds_read2_b32 v[244:245], v122 offset0:148 offset1:181
	s_addk_i32 s15, 0x100
	s_lshl_b32 s40, s33, 6
	s_ashr_i32 s41, s40, 31
	v_lshl_add_u64 v[32:33], s[40:41], 1, v[108:109]
	s_waitcnt lgkmcnt(7)
	v_mul_f32_e32 v29, 0x3f317218, v246
	v_mul_f32_e32 v30, 0x3f317218, v247
	v_cvt_pk_bf16_f32 v29, v29, v30
	ds_read2_b32 v[246:247], v122 offset0:214 offset1:247
	v_or_b32_e32 v30, s15, v116
	v_mov_b32_e32 v31, v103
	v_lshlrev_b64 v[30:31], 13, v[30:31]
	v_lshl_add_u64 v[30:31], v[32:33], 0, v[30:31]
	global_store_dwordx4 v[30:31], v[26:29], off
	s_waitcnt lgkmcnt(7)
	s_nop 0
	v_mul_f32_e32 v26, 0x3f317218, v248
	v_mul_f32_e32 v27, 0x3f317218, v249
	v_cvt_pk_bf16_f32 v26, v26, v27
	ds_read2_b32 v[248:249], v122 offset0:24 offset1:57
	s_waitcnt lgkmcnt(7)
; __device__ __forceinline__ unsigned cvt_pk_bf16(float lo, float hi) { unsigned r; asm volatile("v_cvt_pk_bf16_f32 %0, %1, %2" : "=v"(r) : "v"(lo), "v"(hi)); return r; }
; #define LAS __attribute__((address_space(3)))
; #define LDS_WAIT() asm volatile("s_waitcnt lgkmcnt(0)" ::: "memory")
; __device__ __forceinline__ void p0_item_load(const float* __restrict__ W, int N, int nblk, int nb0, int item, int lane, f32x4 (&v)[8]) {
;     const int kb = item / nblk, nb = nb0 + item % nblk;
;     const float* src = W + (size_t)(64 * kb + (lane >> 3)) * N + 32 * nb + 4 * (lane & 7);
; #pragma unroll
;     for (int i = 0; i < 8; ++i) v[i] = __builtin_nontemporal_load((const f32x4*)(src + (size_t)(8 * i) * N));
; }
; __device__ __forceinline__ void p0_item_store(const f32x4 (&v)[8], int K, int nblk, int nb0, bf16* __restrict__ WT, int mode, LAS float* scr, int item, int lane) {
;     const int kb = item / nblk, nb = nb0 + item % nblk, k0 = 64 * kb, n0 = 32 * nb;
; #pragma unroll
;     for (int i = 0; i < 8; ++i) { LAS float* d = scr + (8 * i + (lane >> 3)) * 33 + 4 * (lane & 7); d[0] = v[i].x; d[1] = v[i].y; d[2] = v[i].z; d[3] = v[i].w; }
;     LDS_WAIT(); asm volatile("" ::: "memory");
;     const int c = lane & 7, r0 = map_row(n0, mode);
;     const float wsc = mode == 1 ? 1.44269504089f : (mode == 2 ? 0.69314718056f : 1.0f);
; #pragma unroll
;     for (int j = 0; j < 4; ++j) { const int n = (lane >> 3) + 8 * j; const LAS float* s = scr + (8 * c) * 33 + n;
;         v4u o; o.x = cvt_pk_bf16(s[0 * 33] * wsc, s[1 * 33] * wsc); o.y = cvt_pk_bf16(s[2 * 33] * wsc, s[3 * 33] * wsc); o.z = cvt_pk_bf16(s[4 * 33] * wsc, s[5 * 33] * wsc); o.w = cvt_pk_bf16(s[6 * 33] * wsc, s[7 * 33] * wsc);
;         *(v4u*)(WT + (size_t)(r0 + n) * K + k0 + 8 * c) = o; }
;     LDS_WAIT(); asm volatile("" ::: "memory");
; }
	v_mul_f32_e32 v27, 0x3f317218, v250
	v_mul_f32_e32 v28, 0x3f317218, v251
	v_cvt_pk_bf16_f32 v27, v27, v28
	ds_read2_b32 v[250:251], v122 offset0:90 offset1:123
	s_waitcnt lgkmcnt(7)
	v_mul_f32_e32 v28, 0x3f317218, v252
	v_mul_f32_e32 v29, 0x3f317218, v253
	v_cvt_pk_bf16_f32 v28, v28, v29
	ds_read2_b32 v[252:253], v122 offset0:156 offset1:189
	s_waitcnt lgkmcnt(7)
	v_mul_f32_e32 v29, 0x3f317218, v254
	v_mul_f32_e32 v30, 0x3f317218, v255
	v_cvt_pk_bf16_f32 v29, v29, v30
	ds_read2_b32 v[254:255], v122 offset0:222 offset1:255
	v_or_b32_e32 v30, s15, v119
	v_mov_b32_e32 v31, v103
	v_lshlrev_b64 v[30:31], 13, v[30:31]
	v_lshl_add_u64 v[30:31], v[32:33], 0, v[30:31]
	global_store_dwordx4 v[30:31], v[26:29], off
	s_waitcnt lgkmcnt(7)
	s_nop 0
	v_mul_f32_e32 v26, 0x3f317218, v240
	v_mul_f32_e32 v27, 0x3f317218, v241
	v_cvt_pk_bf16_f32 v26, v26, v27
	s_waitcnt lgkmcnt(6)
	v_mul_f32_e32 v27, 0x3f317218, v242
	v_mul_f32_e32 v28, 0x3f317218, v243
	v_cvt_pk_bf16_f32 v27, v27, v28
	s_waitcnt lgkmcnt(5)
	v_mul_f32_e32 v28, 0x3f317218, v244
	v_mul_f32_e32 v29, 0x3f317218, v245
	v_cvt_pk_bf16_f32 v28, v28, v29
	s_waitcnt lgkmcnt(4)
	v_mul_f32_e32 v29, 0x3f317218, v246
	v_mul_f32_e32 v30, 0x3f317218, v247
	v_cvt_pk_bf16_f32 v29, v29, v30
	v_or_b32_e32 v30, s15, v120
	v_mov_b32_e32 v31, v103
	v_lshlrev_b64 v[30:31], 13, v[30:31]
	v_lshl_add_u64 v[30:31], v[32:33], 0, v[30:31]
	global_store_dwordx4 v[30:31], v[26:29], off
	s_waitcnt lgkmcnt(3)
	s_nop 0
	v_mul_f32_e32 v26, 0x3f317218, v248
	v_mul_f32_e32 v27, 0x3f317218, v249
	v_cvt_pk_bf16_f32 v26, v26, v27
	s_waitcnt lgkmcnt(2)
	v_mul_f32_e32 v27, 0x3f317218, v250
	v_mul_f32_e32 v28, 0x3f317218, v251
	v_cvt_pk_bf16_f32 v27, v27, v28
	s_waitcnt lgkmcnt(1)
	v_mul_f32_e32 v28, 0x3f317218, v252
	v_mul_f32_e32 v29, 0x3f317218, v253
	v_cvt_pk_bf16_f32 v28, v28, v29
	s_waitcnt lgkmcnt(0)
	v_mul_f32_e32 v29, 0x3f317218, v254
	v_mul_f32_e32 v30, 0x3f317218, v255
	v_cvt_pk_bf16_f32 v29, v29, v30
	v_or_b32_e32 v30, s15, v121
	v_mov_b32_e32 v31, v103
	v_lshlrev_b64 v[30:31], 13, v[30:31]
	v_lshl_add_u64 v[30:31], v[32:33], 0, v[30:31]
	global_store_dwordx4 v[30:31], v[26:29], off
	s_waitcnt lgkmcnt(0)
	s_mul_hi_i32 s15, s14, 0x2aaaaaab
	s_lshr_b32 s33, s15, 31
	s_ashr_i32 s15, s15, 3
	s_add_i32 s15, s15, s33
	s_mul_i32 s33, s15, 48
	s_sub_i32 s33, s14, s33
	v_lshl_or_b32 v26, s15, 6, v116
	s_add_i32 s33, s33, s39
	v_mad_i64_i32 v[26:27], s[40:41], v26, s28, v[114:115]
	s_lshl_b32 s40, s33, 5
	s_mov_b32 s41, s11
	v_lshl_add_u64 v[26:27], s[40:41], 2, v[26:27]
	v_lshl_add_u64 v[58:59], v[26:27], 0, v[102:103]
	v_add_co_u32_e32 v30, vcc, s30, v58
	s_nop 1
	v_addc_co_u32_e32 v31, vcc, 0, v59, vcc
	v_add_co_u32_e32 v42, vcc, s31, v58
	global_load_dwordx4 v[26:29], v[58:59], off nt
	s_nop 0
	global_load_dwordx4 v[30:33], v[30:31], off nt
	v_addc_co_u32_e32 v43, vcc, 0, v59, vcc
	v_add_co_u32_e32 v46, vcc, s34, v58
	s_nop 1
	v_addc_co_u32_e32 v47, vcc, 0, v59, vcc
	v_add_co_u32_e32 v50, vcc, s35, v58
	global_load_dwordx4 v[42:45], v[42:43], off nt
	s_nop 0
	global_load_dwordx4 v[46:49], v[46:47], off nt
	v_addc_co_u32_e32 v51, vcc, 0, v59, vcc
	v_add_co_u32_e32 v54, vcc, s36, v58
	s_nop 1
	v_addc_co_u32_e32 v55, vcc, 0, v59, vcc
	v_add_co_u32_e32 v60, vcc, s37, v58
	global_load_dwordx4 v[50:53], v[50:51], off nt
	s_nop 0
	global_load_dwordx4 v[54:57], v[54:55], off nt
	v_addc_co_u32_e32 v61, vcc, 0, v59, vcc
	v_add_co_u32_e32 v62, vcc, s38, v58
	s_nop 1
	v_addc_co_u32_e32 v63, vcc, 0, v59, vcc
	global_load_dwordx4 v[58:61], v[60:61], off nt
	s_nop 0
	global_load_dwordx4 v[62:65], v[62:63], off nt
	s_waitcnt vmcnt(31)
	ds_write2_b32 v99, v66, v67 offset1:1
	ds_write2_b32 v99, v68, v69 offset0:2 offset1:3
	s_waitcnt vmcnt(30)
	ds_write2_b32 v101, v70, v71 offset1:1
	ds_write2_b32 v123, v72, v73 offset1:1
	s_waitcnt vmcnt(29)
	ds_write2_b32 v124, v74, v75 offset1:1
	ds_write2_b32 v125, v76, v77 offset1:1
	s_waitcnt vmcnt(28)
	ds_write2_b32 v126, v78, v79 offset1:1
	ds_write2_b32 v127, v80, v81 offset1:1
	s_waitcnt vmcnt(27)
	ds_write2_b32 v128, v82, v83 offset1:1
	ds_write2_b32 v129, v84, v85 offset1:1
	s_waitcnt vmcnt(26)
	ds_write2_b32 v130, v86, v87 offset1:1
	ds_write2_b32 v131, v88, v89 offset1:1
	s_waitcnt vmcnt(25)
; __device__ __forceinline__ unsigned cvt_pk_bf16(float lo, float hi) { unsigned r; asm volatile("v_cvt_pk_bf16_f32 %0, %1, %2" : "=v"(r) : "v"(lo), "v"(hi)); return r; }
; #define LAS __attribute__((address_space(3)))
; #define LDS_WAIT() asm volatile("s_waitcnt lgkmcnt(0)" ::: "memory")
; __device__ __forceinline__ void p0_item_store(const f32x4 (&v)[8], int K, int nblk, int nb0, bf16* __restrict__ WT, int mode, LAS float* scr, int item, int lane) {
;     const int kb = item / nblk, nb = nb0 + item % nblk, k0 = 64 * kb, n0 = 32 * nb;
; #pragma unroll
;     for (int i = 0; i < 8; ++i) { LAS float* d = scr + (8 * i + (lane >> 3)) * 33 + 4 * (lane & 7); d[0] = v[i].x; d[1] = v[i].y; d[2] = v[i].z; d[3] = v[i].w; }
;     LDS_WAIT(); asm volatile("" ::: "memory");
;     const int c = lane & 7, r0 = map_row(n0, mode);
;     const float wsc = mode == 1 ? 1.44269504089f : (mode == 2 ? 0.69314718056f : 1.0f);
; #pragma unroll
;     for (int j = 0; j < 4; ++j) { const int n = (lane >> 3) + 8 * j; const LAS float* s = scr + (8 * c) * 33 + n;
;         v4u o; o.x = cvt_pk_bf16(s[0 * 33] * wsc, s[1 * 33] * wsc); o.y = cvt_pk_bf16(s[2 * 33] * wsc, s[3 * 33] * wsc); o.z = cvt_pk_bf16(s[4 * 33] * wsc, s[5 * 33] * wsc); o.w = cvt_pk_bf16(s[6 * 33] * wsc, s[7 * 33] * wsc);
;         *(v4u*)(WT + (size_t)(r0 + n) * K + k0 + 8 * c) = o; }
;     LDS_WAIT(); asm volatile("" ::: "memory");
; }
	ds_write2_b32 v132, v90, v91 offset1:1
	ds_write2_b32 v133, v92, v93 offset1:1
	s_waitcnt vmcnt(24)
	ds_write2_b32 v134, v94, v95 offset1:1
	ds_write2_b32 v135, v96, v97 offset1:1
	s_waitcnt lgkmcnt(0)
	ds_read2_b32 v[240:241], v122 offset1:33
	ds_read2_b32 v[242:243], v122 offset0:66 offset1:99
	ds_read2_b32 v[244:245], v122 offset0:132 offset1:165
	ds_read2_b32 v[246:247], v122 offset0:198 offset1:231
	ds_read2_b32 v[248:249], v122 offset0:8 offset1:41
	ds_read2_b32 v[250:251], v122 offset0:74 offset1:107
	ds_read2_b32 v[252:253], v122 offset0:140 offset1:173
	ds_read2_b32 v[254:255], v122 offset0:206 offset1:239
	s_lshl_b32 s3, s3, 6
	s_and_b32 s3, s3, 0x7fffff00
	s_or_b32 s10, s10, 0xffffff80
	s_add_i32 s3, s10, s3
	s_waitcnt lgkmcnt(7)
	v_mul_f32_e32 v66, 0x3f317218, v240
	v_mul_f32_e32 v67, 0x3f317218, v241
	v_cvt_pk_bf16_f32 v66, v66, v67
	ds_read2_b32 v[240:241], v122 offset0:16 offset1:49
	s_add_i32 s10, s3, 0x100
	s_ashr_i32 s3, s2, 31
	v_or_b32_e32 v102, s10, v116
	v_lshl_add_u64 v[72:73], s[2:3], 1, v[108:109]
	s_waitcnt lgkmcnt(7)
	v_mul_f32_e32 v67, 0x3f317218, v242
	v_mul_f32_e32 v68, 0x3f317218, v243
	v_cvt_pk_bf16_f32 v67, v67, v68
	ds_read2_b32 v[242:243], v122 offset0:82 offset1:115
	v_lshlrev_b64 v[74:75], 13, v[102:103]
	v_lshl_add_u64 v[74:75], v[72:73], 0, v[74:75]
	v_or_b32_e32 v102, s10, v119
	s_waitcnt lgkmcnt(7)
	v_mul_f32_e32 v68, 0x3f317218, v244
	v_mul_f32_e32 v69, 0x3f317218, v245
	v_cvt_pk_bf16_f32 v68, v68, v69
	ds_read2_b32 v[244:245], v122 offset0:148 offset1:181
	s_waitcnt lgkmcnt(7)
	v_mul_f32_e32 v69, 0x3f317218, v246
	v_mul_f32_e32 v70, 0x3f317218, v247
	v_cvt_pk_bf16_f32 v69, v69, v70
	ds_read2_b32 v[246:247], v122 offset0:214 offset1:247
	global_store_dwordx4 v[74:75], v[66:69], off
	v_lshlrev_b64 v[74:75], 13, v[102:103]
	v_lshl_add_u64 v[74:75], v[72:73], 0, v[74:75]
	v_or_b32_e32 v102, s10, v120
	s_waitcnt lgkmcnt(7)
	v_mul_f32_e32 v66, 0x3f317218, v248
	v_mul_f32_e32 v67, 0x3f317218, v249
	v_cvt_pk_bf16_f32 v66, v66, v67
	ds_read2_b32 v[248:249], v122 offset0:24 offset1:57
	s_waitcnt lgkmcnt(7)
	v_mul_f32_e32 v67, 0x3f317218, v250
	v_mul_f32_e32 v68, 0x3f317218, v251
	v_cvt_pk_bf16_f32 v67, v67, v68
	ds_read2_b32 v[250:251], v122 offset0:90 offset1:123
	s_waitcnt lgkmcnt(7)
	v_mul_f32_e32 v68, 0x3f317218, v252
	v_mul_f32_e32 v69, 0x3f317218, v253
	v_cvt_pk_bf16_f32 v68, v68, v69
	ds_read2_b32 v[252:253], v122 offset0:156 offset1:189
	s_waitcnt lgkmcnt(7)
	v_mul_f32_e32 v69, 0x3f317218, v254
	v_mul_f32_e32 v70, 0x3f317218, v255
	v_cvt_pk_bf16_f32 v69, v69, v70
	ds_read2_b32 v[254:255], v122 offset0:222 offset1:255
	global_store_dwordx4 v[74:75], v[66:69], off
	v_lshlrev_b64 v[74:75], 13, v[102:103]
	v_lshl_add_u64 v[74:75], v[72:73], 0, v[74:75]
	v_or_b32_e32 v102, s10, v121
	s_waitcnt lgkmcnt(7)
	v_mul_f32_e32 v66, 0x3f317218, v240
	v_mul_f32_e32 v67, 0x3f317218, v241
	v_cvt_pk_bf16_f32 v66, v66, v67
	s_waitcnt lgkmcnt(6)
	v_mul_f32_e32 v67, 0x3f317218, v242
	v_mul_f32_e32 v68, 0x3f317218, v243
	v_cvt_pk_bf16_f32 v67, v67, v68
	s_waitcnt lgkmcnt(5)
	v_mul_f32_e32 v68, 0x3f317218, v244
	v_mul_f32_e32 v69, 0x3f317218, v245
	v_cvt_pk_bf16_f32 v68, v68, v69
	s_waitcnt lgkmcnt(4)
	v_mul_f32_e32 v69, 0x3f317218, v246
	v_mul_f32_e32 v70, 0x3f317218, v247
	v_cvt_pk_bf16_f32 v69, v69, v70
	global_store_dwordx4 v[74:75], v[66:69], off
	s_waitcnt lgkmcnt(3)
	s_nop 0
	v_mul_f32_e32 v66, 0x3f317218, v248
	v_mul_f32_e32 v67, 0x3f317218, v249
	v_cvt_pk_bf16_f32 v66, v66, v67
	s_waitcnt lgkmcnt(2)
	v_mul_f32_e32 v67, 0x3f317218, v250
	v_mul_f32_e32 v68, 0x3f317218, v251
	v_cvt_pk_bf16_f32 v67, v67, v68
	s_waitcnt lgkmcnt(1)
	v_mul_f32_e32 v68, 0x3f317218, v252
	v_mul_f32_e32 v69, 0x3f317218, v253
	v_cvt_pk_bf16_f32 v68, v68, v69
	s_waitcnt lgkmcnt(0)
	v_mul_f32_e32 v69, 0x3f317218, v254
	v_mul_f32_e32 v70, 0x3f317218, v255
	v_cvt_pk_bf16_f32 v69, v69, v70
	v_lshlrev_b64 v[70:71], 13, v[102:103]
	v_lshl_add_u64 v[70:71], v[72:73], 0, v[70:71]
	global_store_dwordx4 v[70:71], v[66:69], off
	s_waitcnt lgkmcnt(0)
	s_add_i32 s12, s12, -1
	s_cmp_lg_u32 s12, 0
	s_mov_b32 s40, s13
	s_mov_b32 s15, s14
	s_cbranch_scc1 .LBB0_94

; __device__ __forceinline__ unsigned cvt_pk_bf16(float lo, float hi) { unsigned r; asm volatile("v_cvt_pk_bf16_f32 %0, %1, %2" : "=v"(r) : "v"(lo), "v"(hi)); return r; }
; #define LAS __attribute__((address_space(3)))
; #define LDS_WAIT() asm volatile("s_waitcnt lgkmcnt(0)" ::: "memory")
; __device__ __forceinline__ void p0_item_load(const float* __restrict__ W, int N, int nblk, int nb0, int item, int lane, f32x4 (&v)[8]) {
;     const int kb = item / nblk, nb = nb0 + item % nblk;
;     const float* src = W + (size_t)(64 * kb + (lane >> 3)) * N + 32 * nb + 4 * (lane & 7);
; #pragma unroll
;     for (int i = 0; i < 8; ++i) v[i] = __builtin_nontemporal_load((const f32x4*)(src + (size_t)(8 * i) * N));
; }
; __device__ __forceinline__ void p0_item_store(const f32x4 (&v)[8], int K, int nblk, int nb0, bf16* __restrict__ WT, int mode, LAS float* scr, int item, int lane) {
;     const int kb = item / nblk, nb = nb0 + item % nblk, k0 = 64 * kb, n0 = 32 * nb;
; #pragma unroll
;     for (int i = 0; i < 8; ++i) { LAS float* d = scr + (8 * i + (lane >> 3)) * 33 + 4 * (lane & 7); d[0] = v[i].x; d[1] = v[i].y; d[2] = v[i].z; d[3] = v[i].w; }
;     LDS_WAIT(); asm volatile("" ::: "memory");
;     const int c = lane & 7, r0 = map_row(n0, mode);
;     const float wsc = mode == 1 ? 1.44269504089f : (mode == 2 ? 0.69314718056f : 1.0f);
; #pragma unroll
;     for (int j = 0; j < 4; ++j) { const int n = (lane >> 3) + 8 * j; const LAS float* s = scr + (8 * c) * 33 + n;
;         v4u o; o.x = cvt_pk_bf16(s[0 * 33] * wsc, s[1 * 33] * wsc); o.y = cvt_pk_bf16(s[2 * 33] * wsc, s[3 * 33] * wsc); o.z = cvt_pk_bf16(s[4 * 33] * wsc, s[5 * 33] * wsc); o.w = cvt_pk_bf16(s[6 * 33] * wsc, s[7 * 33] * wsc);
;         *(v4u*)(WT + (size_t)(r0 + n) * K + k0 + 8 * c) = o; }
;     LDS_WAIT(); asm volatile("" ::: "memory");
; }
.LBB0_101:
	s_add_i32 s2, s5, s17
	s_min_i32 s27, s2, 0x55ff
	s_ashr_i32 s2, s27, 31
	s_lshr_b32 s2, s2, 25
	s_add_i32 s2, s27, s2
	s_ashr_i32 s3, s2, 7
	s_lshl_b32 s4, s3, 6
	s_and_b32 s2, s2, 0x7ffff80
	v_or_b32_e32 v66, s4, v116
	s_sub_i32 s2, s27, s2
	v_ashrrev_i32_e32 v67, 31, v66
	v_lshlrev_b64 v[66:67], 14, v[66:67]
	s_lshl_b32 s2, s2, 5
	v_lshl_add_u64 v[66:67], s[86:87], 0, v[66:67]
	s_ashr_i32 s3, s2, 31
	v_lshl_add_u64 v[66:67], s[2:3], 2, v[66:67]
	v_lshl_add_u64 v[90:91], v[66:67], 0, v[100:101]
	v_add_co_u32_e32 v70, vcc, s10, v90
	s_add_i32 s27, s27, s17
	s_nop 0
	v_addc_co_u32_e32 v71, vcc, 0, v91, vcc
	v_add_co_u32_e32 v74, vcc, s11, v90
	global_load_dwordx4 v[66:69], v[90:91], off nt
	s_nop 0
	global_load_dwordx4 v[70:73], v[70:71], off nt
	v_addc_co_u32_e32 v75, vcc, 0, v91, vcc
	v_add_co_u32_e32 v78, vcc, s12, v90
	s_min_i32 s3, s27, 0x55ff
	s_nop 0
	v_addc_co_u32_e32 v79, vcc, 0, v91, vcc
	v_add_co_u32_e32 v82, vcc, s13, v90
	global_load_dwordx4 v[74:77], v[74:75], off nt
	s_nop 0
	global_load_dwordx4 v[78:81], v[78:79], off nt
	v_addc_co_u32_e32 v83, vcc, 0, v91, vcc
	v_add_co_u32_e32 v86, vcc, s14, v90
	s_add_i32 s27, s3, s17
	s_nop 0
	v_addc_co_u32_e32 v87, vcc, 0, v91, vcc
	v_add_co_u32_e32 v92, vcc, s15, v90
	global_load_dwordx4 v[82:85], v[82:83], off nt
	s_nop 0
	global_load_dwordx4 v[86:89], v[86:87], off nt
	v_addc_co_u32_e32 v93, vcc, 0, v91, vcc
	v_add_co_u32_e32 v94, vcc, s24, v90
	s_min_i32 s27, s27, 0x55ff
	s_nop 0
	v_addc_co_u32_e32 v95, vcc, 0, v91, vcc
	global_load_dwordx4 v[90:93], v[92:93], off nt
	s_nop 0
	global_load_dwordx4 v[94:97], v[94:95], off nt
	s_ashr_i32 s29, s28, 31
	s_lshr_b32 s29, s29, 25
	v_add_u32_e32 v99, v117, v118
	s_add_i32 s29, s28, s29
	v_add_u32_e32 v106, 0x420, v99
	v_add_u32_e32 v107, 0x428, v99
	v_add_u32_e32 v108, 0x840, v99
	v_add_u32_e32 v109, 0x848, v99
	v_add_u32_e32 v110, 0xc60, v99
	v_add_u32_e32 v111, 0xc68, v99
	v_add_u32_e32 v112, 0x1080, v99
	v_add_u32_e32 v113, 0x1088, v99
	v_add_u32_e32 v114, 0x14a0, v99
	v_add_u32_e32 v115, 0x14a8, v99
	v_add_u32_e32 v123, 0x18c0, v99
	v_add_u32_e32 v124, 0x18c8, v99
	v_add_u32_e32 v125, 0x1ce0, v99
	v_add_u32_e32 v126, 0x1ce8, v99
	s_ashr_i32 s30, s29, 7
	s_and_b32 s29, s29, 0x7ffff80
	s_waitcnt vmcnt(17)
	ds_write2_b32 v99, v30, v31 offset1:1
	ds_write2_b32 v99, v32, v33 offset0:2 offset1:3
	ds_write2_b32 v106, v2, v3 offset1:1
	ds_write2_b32 v107, v4, v5 offset1:1
	ds_write2_b32 v108, v6, v7 offset1:1
	ds_write2_b32 v109, v8, v9 offset1:1
	ds_write2_b32 v110, v10, v11 offset1:1
	ds_write2_b32 v111, v12, v13 offset1:1
	ds_write2_b32 v112, v14, v15 offset1:1
	ds_write2_b32 v113, v16, v17 offset1:1
	ds_write2_b32 v114, v22, v23 offset1:1
	ds_write2_b32 v115, v24, v25 offset1:1
	ds_write2_b32 v123, v34, v35 offset1:1
	ds_write2_b32 v124, v36, v37 offset1:1
	s_waitcnt vmcnt(15)
	ds_write2_b32 v125, v42, v43 offset1:1
	ds_write2_b32 v126, v44, v45 offset1:1
	s_sub_i32 s28, s28, s29
	s_waitcnt lgkmcnt(0)
	s_lshl_b32 s31, s28, 5
	s_lshl_b32 s28, s30, 6
	v_or_b32_e32 v10, s31, v116
	ds_read2_b32 v[240:241], v122 offset1:33
	ds_read2_b32 v[242:243], v122 offset0:66 offset1:99
	ds_read2_b32 v[244:245], v122 offset0:132 offset1:165
	ds_read2_b32 v[246:247], v122 offset0:198 offset1:231
	ds_read2_b32 v[248:249], v122 offset0:8 offset1:41
	ds_read2_b32 v[250:251], v122 offset0:74 offset1:107
	ds_read2_b32 v[252:253], v122 offset0:140 offset1:173
	ds_read2_b32 v[254:255], v122 offset0:206 offset1:239
	s_ashr_i32 s29, s28, 31
	v_mul_lo_u32 v10, v10, s26
	s_waitcnt lgkmcnt(7)
	v_cvt_pk_bf16_f32 v2, v240, v241
	ds_read2_b32 v[240:241], v122 offset0:16 offset1:49
	v_lshl_add_u64 v[8:9], s[28:29], 1, v[104:105]
	v_ashrrev_i32_e32 v11, 31, v10
	s_waitcnt lgkmcnt(7)
	v_cvt_pk_bf16_f32 v3, v242, v243
	ds_read2_b32 v[242:243], v122 offset0:82 offset1:115
	v_lshl_add_u64 v[10:11], v[8:9], 0, v[10:11]
	s_waitcnt lgkmcnt(7)
	v_cvt_pk_bf16_f32 v4, v244, v245
	ds_read2_b32 v[244:245], v122 offset0:148 offset1:181
	s_waitcnt lgkmcnt(7)
	v_cvt_pk_bf16_f32 v5, v246, v247
	ds_read2_b32 v[246:247], v122 offset0:214 offset1:247
	global_store_dwordx4 v[10:11], v[2:5], off
	v_or_b32_e32 v10, s31, v119
	v_mul_lo_u32 v10, v10, s26
	s_waitcnt lgkmcnt(7)
	v_cvt_pk_bf16_f32 v2, v248, v249
	ds_read2_b32 v[248:249], v122 offset0:24 offset1:57
	v_ashrrev_i32_e32 v11, 31, v10
	s_waitcnt lgkmcnt(7)
	v_cvt_pk_bf16_f32 v3, v250, v251
	ds_read2_b32 v[250:251], v122 offset0:90 offset1:123
	v_lshl_add_u64 v[10:11], v[8:9], 0, v[10:11]
	s_waitcnt lgkmcnt(7)
	v_cvt_pk_bf16_f32 v4, v252, v253
	ds_read2_b32 v[252:253], v122 offset0:156 offset1:189
	s_waitcnt lgkmcnt(7)
	v_cvt_pk_bf16_f32 v5, v254, v255
	ds_read2_b32 v[254:255], v122 offset0:222 offset1:255
	global_store_dwordx4 v[10:11], v[2:5], off
	v_or_b32_e32 v10, s31, v120
	s_waitcnt lgkmcnt(7)
	v_cvt_pk_bf16_f32 v2, v240, v241
	v_mul_lo_u32 v10, v10, s26
	s_waitcnt lgkmcnt(6)
	v_cvt_pk_bf16_f32 v3, v242, v243
	v_ashrrev_i32_e32 v11, 31, v10
	s_waitcnt lgkmcnt(5)
	v_cvt_pk_bf16_f32 v4, v244, v245
	s_waitcnt lgkmcnt(4)
	v_cvt_pk_bf16_f32 v5, v246, v247
	v_lshl_add_u64 v[10:11], v[8:9], 0, v[10:11]
	global_store_dwordx4 v[10:11], v[2:5], off
	s_waitcnt lgkmcnt(3)
	s_nop 0
	v_cvt_pk_bf16_f32 v2, v248, v249
	s_waitcnt lgkmcnt(2)
	v_cvt_pk_bf16_f32 v3, v250, v251
	s_waitcnt lgkmcnt(1)
	v_cvt_pk_bf16_f32 v4, v252, v253
	s_waitcnt lgkmcnt(0)
	v_cvt_pk_bf16_f32 v5, v254, v255
	v_or_b32_e32 v6, s31, v121
	v_mul_lo_u32 v6, v6, s26
	v_ashrrev_i32_e32 v7, 31, v6
	v_lshl_add_u64 v[6:7], v[8:9], 0, v[6:7]
	global_store_dwordx4 v[6:7], v[2:5], off
	s_waitcnt lgkmcnt(0)
; __device__ __forceinline__ unsigned cvt_pk_bf16(float lo, float hi) { unsigned r; asm volatile("v_cvt_pk_bf16_f32 %0, %1, %2" : "=v"(r) : "v"(lo), "v"(hi)); return r; }
; #define LAS __attribute__((address_space(3)))
; #define LDS_WAIT() asm volatile("s_waitcnt lgkmcnt(0)" ::: "memory")
; __device__ __forceinline__ void p0_item_load(const float* __restrict__ W, int N, int nblk, int nb0, int item, int lane, f32x4 (&v)[8]) {
;     const int kb = item / nblk, nb = nb0 + item % nblk;
;     const float* src = W + (size_t)(64 * kb + (lane >> 3)) * N + 32 * nb + 4 * (lane & 7);
; #pragma unroll
;     for (int i = 0; i < 8; ++i) v[i] = __builtin_nontemporal_load((const f32x4*)(src + (size_t)(8 * i) * N));
; }
; __device__ __forceinline__ void p0_item_store(const f32x4 (&v)[8], int K, int nblk, int nb0, bf16* __restrict__ WT, int mode, LAS float* scr, int item, int lane) {
;     const int kb = item / nblk, nb = nb0 + item % nblk, k0 = 64 * kb, n0 = 32 * nb;
; #pragma unroll
;     for (int i = 0; i < 8; ++i) { LAS float* d = scr + (8 * i + (lane >> 3)) * 33 + 4 * (lane & 7); d[0] = v[i].x; d[1] = v[i].y; d[2] = v[i].z; d[3] = v[i].w; }
;     LDS_WAIT(); asm volatile("" ::: "memory");
;     const int c = lane & 7, r0 = map_row(n0, mode);
;     const float wsc = mode == 1 ? 1.44269504089f : (mode == 2 ? 0.69314718056f : 1.0f);
; #pragma unroll
;     for (int j = 0; j < 4; ++j) { const int n = (lane >> 3) + 8 * j; const LAS float* s = scr + (8 * c) * 33 + n;
;         v4u o; o.x = cvt_pk_bf16(s[0 * 33] * wsc, s[1 * 33] * wsc); o.y = cvt_pk_bf16(s[2 * 33] * wsc, s[3 * 33] * wsc); o.z = cvt_pk_bf16(s[4 * 33] * wsc, s[5 * 33] * wsc); o.w = cvt_pk_bf16(s[6 * 33] * wsc, s[7 * 33] * wsc);
;         *(v4u*)(WT + (size_t)(r0 + n) * K + k0 + 8 * c) = o; }
;     LDS_WAIT(); asm volatile("" ::: "memory");
; }
	s_ashr_i32 s28, s3, 31
	s_lshr_b32 s28, s28, 25
	s_add_i32 s28, s3, s28
	s_ashr_i32 s29, s28, 7
	s_and_b32 s28, s28, 0x7ffff80
	v_lshl_or_b32 v2, s29, 6, v116
	s_sub_i32 s28, s3, s28
	v_ashrrev_i32_e32 v3, 31, v2
	v_lshlrev_b64 v[2:3], 14, v[2:3]
	s_lshl_b32 s28, s28, 5
	v_lshl_add_u64 v[2:3], s[86:87], 0, v[2:3]
	s_ashr_i32 s29, s28, 31
	v_lshl_add_u64 v[2:3], s[28:29], 2, v[2:3]
	v_lshl_add_u64 v[34:35], v[2:3], 0, v[100:101]
	v_add_co_u32_e32 v2, vcc, s10, v34
	s_nop 1
	v_addc_co_u32_e32 v3, vcc, 0, v35, vcc
	v_add_co_u32_e32 v6, vcc, s11, v34
	global_load_dwordx4 v[30:33], v[34:35], off nt
	s_nop 0
	global_load_dwordx4 v[2:5], v[2:3], off nt
	v_addc_co_u32_e32 v7, vcc, 0, v35, vcc
	v_add_co_u32_e32 v10, vcc, s12, v34
	s_nop 1
	v_addc_co_u32_e32 v11, vcc, 0, v35, vcc
	v_add_co_u32_e32 v14, vcc, s13, v34
	global_load_dwordx4 v[6:9], v[6:7], off nt
	s_nop 0
	global_load_dwordx4 v[10:13], v[10:11], off nt
	v_addc_co_u32_e32 v15, vcc, 0, v35, vcc
	v_add_co_u32_e32 v22, vcc, s14, v34
	s_nop 1
	v_addc_co_u32_e32 v23, vcc, 0, v35, vcc
	v_add_co_u32_e32 v36, vcc, s15, v34
	global_load_dwordx4 v[14:17], v[14:15], off nt
	s_nop 0
	global_load_dwordx4 v[22:25], v[22:23], off nt
	v_addc_co_u32_e32 v37, vcc, 0, v35, vcc
	v_add_co_u32_e32 v42, vcc, s24, v34
	s_nop 1
	v_addc_co_u32_e32 v43, vcc, 0, v35, vcc
	global_load_dwordx4 v[34:37], v[36:37], off nt
	s_nop 0
	global_load_dwordx4 v[42:45], v[42:43], off nt
	s_ashr_i32 s28, s5, 31
	s_lshr_b32 s28, s28, 25
	s_add_i32 s28, s5, s28
	s_ashr_i32 s29, s28, 7
	s_and_b32 s28, s28, 0x7ffff80
	ds_write2_b32 v99, v18, v19 offset1:1
	ds_write2_b32 v99, v20, v21 offset0:2 offset1:3
	s_waitcnt vmcnt(26)
	ds_write2_b32 v106, v26, v27 offset1:1
	ds_write2_b32 v107, v28, v29 offset1:1
	s_waitcnt vmcnt(25)
	ds_write2_b32 v108, v38, v39 offset1:1
	ds_write2_b32 v109, v40, v41 offset1:1
	s_waitcnt vmcnt(24)
	ds_write2_b32 v110, v46, v47 offset1:1
	ds_write2_b32 v111, v48, v49 offset1:1
	s_waitcnt vmcnt(23)
	ds_write2_b32 v112, v50, v51 offset1:1
	ds_write2_b32 v113, v52, v53 offset1:1
	s_waitcnt vmcnt(22)
	ds_write2_b32 v114, v54, v55 offset1:1
	ds_write2_b32 v115, v56, v57 offset1:1
	s_waitcnt vmcnt(21)
	ds_write2_b32 v123, v58, v59 offset1:1
	ds_write2_b32 v124, v60, v61 offset1:1
	s_waitcnt vmcnt(20)
	ds_write2_b32 v125, v62, v63 offset1:1
	ds_write2_b32 v126, v64, v65 offset1:1
	s_sub_i32 s5, s5, s28
	s_waitcnt lgkmcnt(0)
	s_lshl_b32 s5, s5, 5
	s_lshl_b32 s28, s29, 6
	v_or_b32_e32 v38, s5, v116
	ds_read2_b32 v[240:241], v122 offset1:33
	ds_read2_b32 v[242:243], v122 offset0:66 offset1:99
	ds_read2_b32 v[244:245], v122 offset0:132 offset1:165
	ds_read2_b32 v[246:247], v122 offset0:198 offset1:231
	ds_read2_b32 v[248:249], v122 offset0:8 offset1:41
	ds_read2_b32 v[250:251], v122 offset0:74 offset1:107
	ds_read2_b32 v[252:253], v122 offset0:140 offset1:173
	ds_read2_b32 v[254:255], v122 offset0:206 offset1:239
	s_ashr_i32 s29, s28, 31
	v_mul_lo_u32 v38, v38, s26
	s_waitcnt lgkmcnt(7)
	v_cvt_pk_bf16_f32 v18, v240, v241
	ds_read2_b32 v[240:241], v122 offset0:16 offset1:49
	v_lshl_add_u64 v[28:29], s[28:29], 1, v[104:105]
	v_ashrrev_i32_e32 v39, 31, v38
	s_waitcnt lgkmcnt(7)
	v_cvt_pk_bf16_f32 v19, v242, v243
	ds_read2_b32 v[242:243], v122 offset0:82 offset1:115
	v_lshl_add_u64 v[38:39], v[28:29], 0, v[38:39]
	s_waitcnt lgkmcnt(7)
	v_cvt_pk_bf16_f32 v20, v244, v245
	ds_read2_b32 v[244:245], v122 offset0:148 offset1:181
	s_waitcnt lgkmcnt(7)
	v_cvt_pk_bf16_f32 v21, v246, v247
	ds_read2_b32 v[246:247], v122 offset0:214 offset1:247
	global_store_dwordx4 v[38:39], v[18:21], off
	v_or_b32_e32 v38, s5, v119
	v_mul_lo_u32 v38, v38, s26
	s_waitcnt lgkmcnt(7)
	v_cvt_pk_bf16_f32 v18, v248, v249
	ds_read2_b32 v[248:249], v122 offset0:24 offset1:57
	v_ashrrev_i32_e32 v39, 31, v38
	s_waitcnt lgkmcnt(7)
	v_cvt_pk_bf16_f32 v19, v250, v251
	ds_read2_b32 v[250:251], v122 offset0:90 offset1:123
	v_lshl_add_u64 v[38:39], v[28:29], 0, v[38:39]
	s_waitcnt lgkmcnt(7)
	v_cvt_pk_bf16_f32 v20, v252, v253
	ds_read2_b32 v[252:253], v122 offset0:156 offset1:189
	s_waitcnt lgkmcnt(7)
	v_cvt_pk_bf16_f32 v21, v254, v255
	ds_read2_b32 v[254:255], v122 offset0:222 offset1:255
	global_store_dwordx4 v[38:39], v[18:21], off
	v_or_b32_e32 v38, s5, v120
	s_waitcnt lgkmcnt(7)
	v_cvt_pk_bf16_f32 v18, v240, v241
	v_mul_lo_u32 v38, v38, s26
	s_waitcnt lgkmcnt(6)
	v_cvt_pk_bf16_f32 v19, v242, v243
	v_ashrrev_i32_e32 v39, 31, v38
	s_waitcnt lgkmcnt(5)
	v_cvt_pk_bf16_f32 v20, v244, v245
	s_waitcnt lgkmcnt(4)
	v_cvt_pk_bf16_f32 v21, v246, v247
	v_lshl_add_u64 v[38:39], v[28:29], 0, v[38:39]
	global_store_dwordx4 v[38:39], v[18:21], off
	s_waitcnt lgkmcnt(3)
	s_nop 0
	v_cvt_pk_bf16_f32 v18, v248, v249
	s_waitcnt lgkmcnt(2)
	v_cvt_pk_bf16_f32 v19, v250, v251
	s_waitcnt lgkmcnt(1)
	v_cvt_pk_bf16_f32 v20, v252, v253
	v_or_b32_e32 v21, s5, v121
	v_mul_lo_u32 v38, v21, s26
	v_ashrrev_i32_e32 v39, 31, v38
	s_waitcnt lgkmcnt(0)
	v_cvt_pk_bf16_f32 v21, v254, v255
	v_lshl_add_u64 v[26:27], v[28:29], 0, v[38:39]
	global_store_dwordx4 v[26:27], v[18:21], off
	s_waitcnt lgkmcnt(0)
; __device__ __forceinline__ unsigned cvt_pk_bf16(float lo, float hi) { unsigned r; asm volatile("v_cvt_pk_bf16_f32 %0, %1, %2" : "=v"(r) : "v"(lo), "v"(hi)); return r; }
; #define LAS __attribute__((address_space(3)))
; #define LDS_WAIT() asm volatile("s_waitcnt lgkmcnt(0)" ::: "memory")
; __device__ __forceinline__ void p0_item_load(const float* __restrict__ W, int N, int nblk, int nb0, int item, int lane, f32x4 (&v)[8]) {
;     const int kb = item / nblk, nb = nb0 + item % nblk;
;     const float* src = W + (size_t)(64 * kb + (lane >> 3)) * N + 32 * nb + 4 * (lane & 7);
; #pragma unroll
;     for (int i = 0; i < 8; ++i) v[i] = __builtin_nontemporal_load((const f32x4*)(src + (size_t)(8 * i) * N));
; }
; __device__ __forceinline__ void p0_item_store(const f32x4 (&v)[8], int K, int nblk, int nb0, bf16* __restrict__ WT, int mode, LAS float* scr, int item, int lane) {
;     const int kb = item / nblk, nb = nb0 + item % nblk, k0 = 64 * kb, n0 = 32 * nb;
; #pragma unroll
;     for (int i = 0; i < 8; ++i) { LAS float* d = scr + (8 * i + (lane >> 3)) * 33 + 4 * (lane & 7); d[0] = v[i].x; d[1] = v[i].y; d[2] = v[i].z; d[3] = v[i].w; }
;     LDS_WAIT(); asm volatile("" ::: "memory");
;     const int c = lane & 7, r0 = map_row(n0, mode);
;     const float wsc = mode == 1 ? 1.44269504089f : (mode == 2 ? 0.69314718056f : 1.0f);
; #pragma unroll
;     for (int j = 0; j < 4; ++j) { const int n = (lane >> 3) + 8 * j; const LAS float* s = scr + (8 * c) * 33 + n;
;         v4u o; o.x = cvt_pk_bf16(s[0 * 33] * wsc, s[1 * 33] * wsc); o.y = cvt_pk_bf16(s[2 * 33] * wsc, s[3 * 33] * wsc); o.z = cvt_pk_bf16(s[4 * 33] * wsc, s[5 * 33] * wsc); o.w = cvt_pk_bf16(s[6 * 33] * wsc, s[7 * 33] * wsc);
;         *(v4u*)(WT + (size_t)(r0 + n) * K + k0 + 8 * c) = o; }
;     LDS_WAIT(); asm volatile("" ::: "memory");
; }
	s_ashr_i32 s5, s27, 31
	s_lshr_b32 s5, s5, 25
	s_add_i32 s5, s27, s5
	s_ashr_i32 s28, s5, 7
	s_and_b32 s5, s5, 0x7ffff80
	v_lshl_or_b32 v18, s28, 6, v116
	s_sub_i32 s5, s27, s5
	v_ashrrev_i32_e32 v19, 31, v18
	v_lshlrev_b64 v[18:19], 14, v[18:19]
	s_lshl_b32 s28, s5, 5
	v_lshl_add_u64 v[18:19], s[86:87], 0, v[18:19]
	s_ashr_i32 s29, s28, 31
	v_lshl_add_u64 v[18:19], s[28:29], 2, v[18:19]
	v_lshl_add_u64 v[58:59], v[18:19], 0, v[100:101]
	v_add_co_u32_e32 v26, vcc, s10, v58
	s_nop 1
	v_addc_co_u32_e32 v27, vcc, 0, v59, vcc
	v_add_co_u32_e32 v38, vcc, s11, v58
	global_load_dwordx4 v[18:21], v[58:59], off nt
	s_nop 0
	global_load_dwordx4 v[26:29], v[26:27], off nt
	v_addc_co_u32_e32 v39, vcc, 0, v59, vcc
	v_add_co_u32_e32 v46, vcc, s12, v58
	s_nop 1
	v_addc_co_u32_e32 v47, vcc, 0, v59, vcc
	v_add_co_u32_e32 v50, vcc, s13, v58
	global_load_dwordx4 v[38:41], v[38:39], off nt
	s_nop 0
	global_load_dwordx4 v[46:49], v[46:47], off nt
	v_addc_co_u32_e32 v51, vcc, 0, v59, vcc
	v_add_co_u32_e32 v54, vcc, s14, v58
	s_nop 1
	v_addc_co_u32_e32 v55, vcc, 0, v59, vcc
	v_add_co_u32_e32 v60, vcc, s15, v58
	global_load_dwordx4 v[50:53], v[50:51], off nt
	s_nop 0
	global_load_dwordx4 v[54:57], v[54:55], off nt
	v_addc_co_u32_e32 v61, vcc, 0, v59, vcc
	v_add_co_u32_e32 v62, vcc, s24, v58
	s_nop 1
	v_addc_co_u32_e32 v63, vcc, 0, v59, vcc
	global_load_dwordx4 v[58:61], v[60:61], off nt
	s_nop 0
	global_load_dwordx4 v[62:65], v[62:63], off nt
	s_waitcnt vmcnt(31)
	ds_write2_b32 v99, v66, v67 offset1:1
	ds_write2_b32 v99, v68, v69 offset0:2 offset1:3
	s_waitcnt vmcnt(30)
	ds_write2_b32 v106, v70, v71 offset1:1
	ds_write2_b32 v107, v72, v73 offset1:1
	s_waitcnt vmcnt(29)
	ds_write2_b32 v108, v74, v75 offset1:1
	ds_write2_b32 v109, v76, v77 offset1:1
	s_waitcnt vmcnt(28)
	ds_write2_b32 v110, v78, v79 offset1:1
	ds_write2_b32 v111, v80, v81 offset1:1
	s_waitcnt vmcnt(27)
	ds_write2_b32 v112, v82, v83 offset1:1
	ds_write2_b32 v113, v84, v85 offset1:1
	s_waitcnt vmcnt(26)
	ds_write2_b32 v114, v86, v87 offset1:1
	ds_write2_b32 v115, v88, v89 offset1:1
	s_waitcnt vmcnt(25)
	ds_write2_b32 v123, v90, v91 offset1:1
	ds_write2_b32 v124, v92, v93 offset1:1
	s_waitcnt vmcnt(24)
	ds_write2_b32 v125, v94, v95 offset1:1
	ds_write2_b32 v126, v96, v97 offset1:1
	s_waitcnt lgkmcnt(0)
	v_or_b32_e32 v74, s2, v116
	ds_read2_b32 v[240:241], v122 offset1:33
	ds_read2_b32 v[242:243], v122 offset0:66 offset1:99
	ds_read2_b32 v[244:245], v122 offset0:132 offset1:165
	ds_read2_b32 v[246:247], v122 offset0:198 offset1:231
	ds_read2_b32 v[248:249], v122 offset0:8 offset1:41
	ds_read2_b32 v[250:251], v122 offset0:74 offset1:107
	ds_read2_b32 v[252:253], v122 offset0:140 offset1:173
	ds_read2_b32 v[254:255], v122 offset0:206 offset1:239
	s_ashr_i32 s5, s4, 31
	v_mul_lo_u32 v74, v74, s26
	s_waitcnt lgkmcnt(7)
	v_cvt_pk_bf16_f32 v66, v240, v241
	ds_read2_b32 v[240:241], v122 offset0:16 offset1:49
	v_lshl_add_u64 v[72:73], s[4:5], 1, v[104:105]
	v_ashrrev_i32_e32 v75, 31, v74
	s_waitcnt lgkmcnt(7)
	v_cvt_pk_bf16_f32 v67, v242, v243
	ds_read2_b32 v[242:243], v122 offset0:82 offset1:115
	v_lshl_add_u64 v[74:75], v[72:73], 0, v[74:75]
	s_waitcnt lgkmcnt(7)
	v_cvt_pk_bf16_f32 v68, v244, v245
	ds_read2_b32 v[244:245], v122 offset0:148 offset1:181
	s_waitcnt lgkmcnt(7)
	v_cvt_pk_bf16_f32 v69, v246, v247
	ds_read2_b32 v[246:247], v122 offset0:214 offset1:247
	global_store_dwordx4 v[74:75], v[66:69], off
	v_or_b32_e32 v74, s2, v119
	v_mul_lo_u32 v74, v74, s26
	s_waitcnt lgkmcnt(7)
	v_cvt_pk_bf16_f32 v66, v248, v249
	ds_read2_b32 v[248:249], v122 offset0:24 offset1:57
	v_ashrrev_i32_e32 v75, 31, v74
	s_waitcnt lgkmcnt(7)
	v_cvt_pk_bf16_f32 v67, v250, v251
	ds_read2_b32 v[250:251], v122 offset0:90 offset1:123
	v_lshl_add_u64 v[74:75], v[72:73], 0, v[74:75]
	s_waitcnt lgkmcnt(7)
	v_cvt_pk_bf16_f32 v68, v252, v253
	ds_read2_b32 v[252:253], v122 offset0:156 offset1:189
	s_waitcnt lgkmcnt(7)
	v_cvt_pk_bf16_f32 v69, v254, v255
	ds_read2_b32 v[254:255], v122 offset0:222 offset1:255
	global_store_dwordx4 v[74:75], v[66:69], off
	v_or_b32_e32 v74, s2, v120
	s_waitcnt lgkmcnt(7)
	v_cvt_pk_bf16_f32 v66, v240, v241
	v_mul_lo_u32 v74, v74, s26
	s_waitcnt lgkmcnt(6)
	v_cvt_pk_bf16_f32 v67, v242, v243
	v_ashrrev_i32_e32 v75, 31, v74
	s_waitcnt lgkmcnt(5)
	v_cvt_pk_bf16_f32 v68, v244, v245
	s_waitcnt lgkmcnt(4)
	v_cvt_pk_bf16_f32 v69, v246, v247
	v_lshl_add_u64 v[74:75], v[72:73], 0, v[74:75]
	global_store_dwordx4 v[74:75], v[66:69], off
	s_waitcnt lgkmcnt(3)
	s_nop 0
	v_cvt_pk_bf16_f32 v66, v248, v249
	s_waitcnt lgkmcnt(2)
	v_cvt_pk_bf16_f32 v67, v250, v251
	s_waitcnt lgkmcnt(1)
	v_cvt_pk_bf16_f32 v68, v252, v253
	v_or_b32_e32 v69, s2, v121
	v_mul_lo_u32 v74, v69, s26
	v_ashrrev_i32_e32 v75, 31, v74
	s_waitcnt lgkmcnt(0)
	v_cvt_pk_bf16_f32 v69, v254, v255
	v_lshl_add_u64 v[70:71], v[72:73], 0, v[74:75]
	global_store_dwordx4 v[70:71], v[66:69], off
	s_waitcnt lgkmcnt(0)
	s_add_i32 s25, s25, -1
	s_cmp_lg_u32 s25, 0
	s_mov_b32 s28, s3
	s_mov_b32 s5, s27
	s_cbranch_scc1 .LBB0_101

; __device__ __forceinline__ unsigned cvt_pk_bf16(float lo, float hi) { unsigned r; asm volatile("v_cvt_pk_bf16_f32 %0, %1, %2" : "=v"(r) : "v"(lo), "v"(hi)); return r; }
; #define LAS __attribute__((address_space(3)))
; #define LDS_WAIT() asm volatile("s_waitcnt lgkmcnt(0)" ::: "memory")
; __device__ __forceinline__ void p0_item_load(const float* __restrict__ W, int N, int nblk, int nb0, int item, int lane, f32x4 (&v)[8]) {
;     const int kb = item / nblk, nb = nb0 + item % nblk;
;     const float* src = W + (size_t)(64 * kb + (lane >> 3)) * N + 32 * nb + 4 * (lane & 7);
; #pragma unroll
;     for (int i = 0; i < 8; ++i) v[i] = __builtin_nontemporal_load((const f32x4*)(src + (size_t)(8 * i) * N));
; }
; __device__ __forceinline__ void p0_item_store(const f32x4 (&v)[8], int K, int nblk, int nb0, bf16* __restrict__ WT, int mode, LAS float* scr, int item, int lane) {
;     const int kb = item / nblk, nb = nb0 + item % nblk, k0 = 64 * kb, n0 = 32 * nb;
; #pragma unroll
;     for (int i = 0; i < 8; ++i) { LAS float* d = scr + (8 * i + (lane >> 3)) * 33 + 4 * (lane & 7); d[0] = v[i].x; d[1] = v[i].y; d[2] = v[i].z; d[3] = v[i].w; }
;     LDS_WAIT(); asm volatile("" ::: "memory");
;     const int c = lane & 7, r0 = map_row(n0, mode);
;     const float wsc = mode == 1 ? 1.44269504089f : (mode == 2 ? 0.69314718056f : 1.0f);
; #pragma unroll
;     for (int j = 0; j < 4; ++j) { const int n = (lane >> 3) + 8 * j; const LAS float* s = scr + (8 * c) * 33 + n;
;         v4u o; o.x = cvt_pk_bf16(s[0 * 33] * wsc, s[1 * 33] * wsc); o.y = cvt_pk_bf16(s[2 * 33] * wsc, s[3 * 33] * wsc); o.z = cvt_pk_bf16(s[4 * 33] * wsc, s[5 * 33] * wsc); o.w = cvt_pk_bf16(s[6 * 33] * wsc, s[7 * 33] * wsc);
;         *(v4u*)(WT + (size_t)(r0 + n) * K + k0 + 8 * c) = o; }
;     LDS_WAIT(); asm volatile("" ::: "memory");
; }
.LBB0_105:
	s_add_i32 s2, s5, s17
	s_min_i32 s27, s2, 0x6fff
	s_mul_hi_i32 s2, s27, 0x92492493
	s_add_i32 s2, s2, s27
	s_lshr_b32 s3, s2, 31
	s_ashr_i32 s2, s2, 8
	s_add_i32 s2, s2, s3
	s_lshl_b32 s4, s2, 6
	s_mul_i32 s3, s2, 0x1c0
	v_or_b32_e32 v66, s4, v116
	v_mov_b64_e32 v[106:107], s[38:39]
	s_sub_i32 s29, s27, s3
	v_mad_i64_i32 v[66:67], s[2:3], v66, s10, v[106:107]
	s_lshl_b32 s2, s29, 5
	s_ashr_i32 s3, s2, 31
	v_lshl_add_u64 v[66:67], s[2:3], 2, v[66:67]
	v_lshl_add_u64 v[90:91], v[66:67], 0, v[100:101]
	v_add_co_u32_e32 v70, vcc, s11, v90
	s_add_i32 s27, s27, s17
	s_nop 0
	v_addc_co_u32_e32 v71, vcc, 0, v91, vcc
	v_add_co_u32_e32 v74, vcc, s12, v90
	global_load_dwordx4 v[66:69], v[90:91], off nt
	s_nop 0
	global_load_dwordx4 v[70:73], v[70:71], off nt
	v_addc_co_u32_e32 v75, vcc, 0, v91, vcc
	v_add_co_u32_e32 v78, vcc, s13, v90
	s_min_i32 s3, s27, 0x6fff
	s_nop 0
	v_addc_co_u32_e32 v79, vcc, 0, v91, vcc
	v_add_co_u32_e32 v82, vcc, s14, v90
	global_load_dwordx4 v[74:77], v[74:75], off nt
	s_nop 0
	global_load_dwordx4 v[78:81], v[78:79], off nt
	v_addc_co_u32_e32 v83, vcc, 0, v91, vcc
	v_add_co_u32_e32 v86, vcc, s15, v90
	s_add_i32 s27, s3, s17
	s_nop 0
	v_addc_co_u32_e32 v87, vcc, 0, v91, vcc
	v_add_co_u32_e32 v92, vcc, s24, v90
	global_load_dwordx4 v[82:85], v[82:83], off nt
	s_nop 0
	global_load_dwordx4 v[86:89], v[86:87], off nt
	v_addc_co_u32_e32 v93, vcc, 0, v91, vcc
	v_add_co_u32_e32 v94, vcc, s25, v90
	s_min_i32 s27, s27, 0x6fff
	s_nop 0
	v_addc_co_u32_e32 v95, vcc, 0, v91, vcc
	global_load_dwordx4 v[90:93], v[92:93], off nt
	s_nop 0
	global_load_dwordx4 v[94:97], v[94:95], off nt
	v_add_u32_e32 v99, v117, v118
	v_add_u32_e32 v108, 0x420, v99
	v_add_u32_e32 v109, 0x428, v99
	v_add_u32_e32 v110, 0x840, v99
	v_add_u32_e32 v111, 0x848, v99
	v_add_u32_e32 v112, 0xc60, v99
	v_add_u32_e32 v113, 0xc68, v99
	v_add_u32_e32 v114, 0x1080, v99
	v_add_u32_e32 v115, 0x1088, v99
	v_add_u32_e32 v123, 0x14a0, v99
	v_add_u32_e32 v124, 0x14a8, v99
	v_add_u32_e32 v125, 0x18c0, v99
	v_add_u32_e32 v126, 0x18c8, v99
	v_add_u32_e32 v127, 0x1ce0, v99
	v_add_u32_e32 v128, 0x1ce8, v99
	s_waitcnt vmcnt(17)
	ds_write2_b32 v99, v30, v31 offset1:1
	ds_write2_b32 v99, v32, v33 offset0:2 offset1:3
	ds_write2_b32 v108, v2, v3 offset1:1
	ds_write2_b32 v109, v4, v5 offset1:1
	ds_write2_b32 v110, v6, v7 offset1:1
	ds_write2_b32 v111, v8, v9 offset1:1
	ds_write2_b32 v112, v10, v11 offset1:1
	ds_write2_b32 v113, v12, v13 offset1:1
	ds_write2_b32 v114, v14, v15 offset1:1
	ds_write2_b32 v115, v16, v17 offset1:1
	ds_write2_b32 v123, v22, v23 offset1:1
	ds_write2_b32 v124, v24, v25 offset1:1
	ds_write2_b32 v125, v34, v35 offset1:1
	ds_write2_b32 v126, v36, v37 offset1:1
	s_waitcnt vmcnt(15)
	ds_write2_b32 v127, v42, v43 offset1:1
	ds_write2_b32 v128, v44, v45 offset1:1
	s_mul_hi_i32 s29, s28, 0x92492493
	s_waitcnt lgkmcnt(0)
	s_add_i32 s29, s29, s28
	s_lshr_b32 s30, s29, 31
	s_ashr_i32 s29, s29, 8
	ds_read2_b32 v[240:241], v122 offset1:33
	ds_read2_b32 v[242:243], v122 offset0:66 offset1:99
	ds_read2_b32 v[244:245], v122 offset0:132 offset1:165
	ds_read2_b32 v[246:247], v122 offset0:198 offset1:231
	ds_read2_b32 v[248:249], v122 offset0:8 offset1:41
	ds_read2_b32 v[250:251], v122 offset0:74 offset1:107
	ds_read2_b32 v[252:253], v122 offset0:140 offset1:173
	ds_read2_b32 v[254:255], v122 offset0:206 offset1:239
	s_add_i32 s29, s29, s30
	s_waitcnt lgkmcnt(7)
	v_cvt_pk_bf16_f32 v2, v240, v241
	ds_read2_b32 v[240:241], v122 offset0:16 offset1:49
	s_mul_i32 s30, s29, 0x1c0
	s_waitcnt lgkmcnt(7)
	v_cvt_pk_bf16_f32 v3, v242, v243
	ds_read2_b32 v[242:243], v122 offset0:82 offset1:115
	s_sub_i32 s28, s28, s30
	s_waitcnt lgkmcnt(7)
	v_cvt_pk_bf16_f32 v4, v244, v245
	ds_read2_b32 v[244:245], v122 offset0:148 offset1:181
	s_lshl_b32 s30, s28, 5
	s_lshl_b32 s28, s29, 6
	s_waitcnt lgkmcnt(7)
	v_cvt_pk_bf16_f32 v5, v246, v247
	ds_read2_b32 v[246:247], v122 offset0:214 offset1:247
	v_or_b32_e32 v6, s30, v116
	s_ashr_i32 s29, s28, 31
	v_ashrrev_i32_e32 v7, 31, v6
	v_lshl_add_u64 v[8:9], s[28:29], 1, v[104:105]
	v_lshlrev_b64 v[6:7], 13, v[6:7]
	v_lshl_add_u64 v[6:7], v[8:9], 0, v[6:7]
	global_store_dwordx4 v[6:7], v[2:5], off
	s_waitcnt lgkmcnt(7)
	s_nop 0
	v_cvt_pk_bf16_f32 v2, v248, v249
	ds_read2_b32 v[248:249], v122 offset0:24 offset1:57
	s_waitcnt lgkmcnt(7)
	v_cvt_pk_bf16_f32 v3, v250, v251
	ds_read2_b32 v[250:251], v122 offset0:90 offset1:123
	s_waitcnt lgkmcnt(7)
	v_cvt_pk_bf16_f32 v4, v252, v253
	ds_read2_b32 v[252:253], v122 offset0:156 offset1:189
	s_waitcnt lgkmcnt(7)
	v_cvt_pk_bf16_f32 v5, v254, v255
	ds_read2_b32 v[254:255], v122 offset0:222 offset1:255
	v_or_b32_e32 v6, s30, v119
	v_ashrrev_i32_e32 v7, 31, v6
	v_lshlrev_b64 v[6:7], 13, v[6:7]
	v_lshl_add_u64 v[6:7], v[8:9], 0, v[6:7]
	global_store_dwordx4 v[6:7], v[2:5], off
	s_waitcnt lgkmcnt(7)
	s_nop 0
	v_cvt_pk_bf16_f32 v2, v240, v241
	s_waitcnt lgkmcnt(6)
	v_cvt_pk_bf16_f32 v3, v242, v243
	s_waitcnt lgkmcnt(5)
	v_cvt_pk_bf16_f32 v4, v244, v245
	s_waitcnt lgkmcnt(4)
	v_cvt_pk_bf16_f32 v5, v246, v247
	v_or_b32_e32 v6, s30, v120
	v_ashrrev_i32_e32 v7, 31, v6
	v_lshlrev_b64 v[6:7], 13, v[6:7]
	v_lshl_add_u64 v[6:7], v[8:9], 0, v[6:7]
	global_store_dwordx4 v[6:7], v[2:5], off
	s_waitcnt lgkmcnt(3)
	s_nop 0
	v_cvt_pk_bf16_f32 v2, v248, v249
	s_waitcnt lgkmcnt(2)
	v_cvt_pk_bf16_f32 v3, v250, v251
	s_waitcnt lgkmcnt(1)
	v_cvt_pk_bf16_f32 v4, v252, v253
	s_waitcnt lgkmcnt(0)
	v_cvt_pk_bf16_f32 v5, v254, v255
	v_or_b32_e32 v6, s30, v121
	v_ashrrev_i32_e32 v7, 31, v6
	v_lshlrev_b64 v[6:7], 13, v[6:7]
	v_lshl_add_u64 v[6:7], v[8:9], 0, v[6:7]
	global_store_dwordx4 v[6:7], v[2:5], off
	s_waitcnt lgkmcnt(0)
; __device__ __forceinline__ unsigned cvt_pk_bf16(float lo, float hi) { unsigned r; asm volatile("v_cvt_pk_bf16_f32 %0, %1, %2" : "=v"(r) : "v"(lo), "v"(hi)); return r; }
; #define LAS __attribute__((address_space(3)))
; #define LDS_WAIT() asm volatile("s_waitcnt lgkmcnt(0)" ::: "memory")
; __device__ __forceinline__ void p0_item_load(const float* __restrict__ W, int N, int nblk, int nb0, int item, int lane, f32x4 (&v)[8]) {
;     const int kb = item / nblk, nb = nb0 + item % nblk;
;     const float* src = W + (size_t)(64 * kb + (lane >> 3)) * N + 32 * nb + 4 * (lane & 7);
; #pragma unroll
;     for (int i = 0; i < 8; ++i) v[i] = __builtin_nontemporal_load((const f32x4*)(src + (size_t)(8 * i) * N));
; }
; __device__ __forceinline__ void p0_item_store(const f32x4 (&v)[8], int K, int nblk, int nb0, bf16* __restrict__ WT, int mode, LAS float* scr, int item, int lane) {
;     const int kb = item / nblk, nb = nb0 + item % nblk, k0 = 64 * kb, n0 = 32 * nb;
; #pragma unroll
;     for (int i = 0; i < 8; ++i) { LAS float* d = scr + (8 * i + (lane >> 3)) * 33 + 4 * (lane & 7); d[0] = v[i].x; d[1] = v[i].y; d[2] = v[i].z; d[3] = v[i].w; }
;     LDS_WAIT(); asm volatile("" ::: "memory");
;     const int c = lane & 7, r0 = map_row(n0, mode);
;     const float wsc = mode == 1 ? 1.44269504089f : (mode == 2 ? 0.69314718056f : 1.0f);
; #pragma unroll
;     for (int j = 0; j < 4; ++j) { const int n = (lane >> 3) + 8 * j; const LAS float* s = scr + (8 * c) * 33 + n;
;         v4u o; o.x = cvt_pk_bf16(s[0 * 33] * wsc, s[1 * 33] * wsc); o.y = cvt_pk_bf16(s[2 * 33] * wsc, s[3 * 33] * wsc); o.z = cvt_pk_bf16(s[4 * 33] * wsc, s[5 * 33] * wsc); o.w = cvt_pk_bf16(s[6 * 33] * wsc, s[7 * 33] * wsc);
;         *(v4u*)(WT + (size_t)(r0 + n) * K + k0 + 8 * c) = o; }
;     LDS_WAIT(); asm volatile("" ::: "memory");
; }
	s_mul_hi_i32 s28, s3, 0x92492493
	s_add_i32 s28, s28, s3
	s_lshr_b32 s29, s28, 31
	s_ashr_i32 s28, s28, 8
	s_add_i32 s28, s28, s29
	s_mul_i32 s29, s28, 0x1c0
	v_lshl_or_b32 v2, s28, 6, v116
	s_sub_i32 s30, s3, s29
	v_mad_i64_i32 v[2:3], s[28:29], v2, s10, v[106:107]
	s_lshl_b32 s28, s30, 5
	s_ashr_i32 s29, s28, 31
	v_lshl_add_u64 v[2:3], s[28:29], 2, v[2:3]
	v_lshl_add_u64 v[34:35], v[2:3], 0, v[100:101]
	v_add_co_u32_e32 v2, vcc, s11, v34
	s_nop 1
	v_addc_co_u32_e32 v3, vcc, 0, v35, vcc
	v_add_co_u32_e32 v6, vcc, s12, v34
	global_load_dwordx4 v[30:33], v[34:35], off nt
	s_nop 0
	global_load_dwordx4 v[2:5], v[2:3], off nt
	v_addc_co_u32_e32 v7, vcc, 0, v35, vcc
	v_add_co_u32_e32 v10, vcc, s13, v34
	s_nop 1
	v_addc_co_u32_e32 v11, vcc, 0, v35, vcc
	v_add_co_u32_e32 v14, vcc, s14, v34
	global_load_dwordx4 v[6:9], v[6:7], off nt
	s_nop 0
	global_load_dwordx4 v[10:13], v[10:11], off nt
	v_addc_co_u32_e32 v15, vcc, 0, v35, vcc
	v_add_co_u32_e32 v22, vcc, s15, v34
	s_nop 1
	v_addc_co_u32_e32 v23, vcc, 0, v35, vcc
	v_add_co_u32_e32 v36, vcc, s24, v34
	global_load_dwordx4 v[14:17], v[14:15], off nt
	s_nop 0
	global_load_dwordx4 v[22:25], v[22:23], off nt
	v_addc_co_u32_e32 v37, vcc, 0, v35, vcc
	v_add_co_u32_e32 v42, vcc, s25, v34
	s_nop 1
	v_addc_co_u32_e32 v43, vcc, 0, v35, vcc
	global_load_dwordx4 v[34:37], v[36:37], off nt
	s_nop 0
	global_load_dwordx4 v[42:45], v[42:43], off nt
	ds_write2_b32 v99, v18, v19 offset1:1
	ds_write2_b32 v99, v20, v21 offset0:2 offset1:3
	s_waitcnt vmcnt(26)
	ds_write2_b32 v108, v26, v27 offset1:1
	ds_write2_b32 v109, v28, v29 offset1:1
	s_waitcnt vmcnt(25)
	ds_write2_b32 v110, v38, v39 offset1:1
	ds_write2_b32 v111, v40, v41 offset1:1
	s_waitcnt vmcnt(24)
	ds_write2_b32 v112, v46, v47 offset1:1
	ds_write2_b32 v113, v48, v49 offset1:1
	s_waitcnt vmcnt(23)
	ds_write2_b32 v114, v50, v51 offset1:1
	ds_write2_b32 v115, v52, v53 offset1:1
	s_waitcnt vmcnt(22)
	ds_write2_b32 v123, v54, v55 offset1:1
	ds_write2_b32 v124, v56, v57 offset1:1
	s_waitcnt vmcnt(21)
	ds_write2_b32 v125, v58, v59 offset1:1
	ds_write2_b32 v126, v60, v61 offset1:1
	s_waitcnt vmcnt(20)
	ds_write2_b32 v127, v62, v63 offset1:1
	ds_write2_b32 v128, v64, v65 offset1:1
	s_mul_hi_i32 s28, s5, 0x92492493
	s_waitcnt lgkmcnt(0)
	s_add_i32 s28, s28, s5
	s_lshr_b32 s29, s28, 31
	s_ashr_i32 s28, s28, 8
	ds_read2_b32 v[240:241], v122 offset1:33
	ds_read2_b32 v[242:243], v122 offset0:66 offset1:99
	ds_read2_b32 v[244:245], v122 offset0:132 offset1:165
	ds_read2_b32 v[246:247], v122 offset0:198 offset1:231
	ds_read2_b32 v[248:249], v122 offset0:8 offset1:41
	ds_read2_b32 v[250:251], v122 offset0:74 offset1:107
	ds_read2_b32 v[252:253], v122 offset0:140 offset1:173
	ds_read2_b32 v[254:255], v122 offset0:206 offset1:239
	s_add_i32 s28, s28, s29
	s_waitcnt lgkmcnt(7)
	v_cvt_pk_bf16_f32 v18, v240, v241
	ds_read2_b32 v[240:241], v122 offset0:16 offset1:49
	s_mul_i32 s29, s28, 0x1c0
	s_waitcnt lgkmcnt(7)
	v_cvt_pk_bf16_f32 v19, v242, v243
	ds_read2_b32 v[242:243], v122 offset0:82 offset1:115
	s_sub_i32 s5, s5, s29
	s_waitcnt lgkmcnt(7)
	v_cvt_pk_bf16_f32 v20, v244, v245
	ds_read2_b32 v[244:245], v122 offset0:148 offset1:181
	s_lshl_b32 s5, s5, 5
	s_lshl_b32 s28, s28, 6
	s_waitcnt lgkmcnt(7)
	v_cvt_pk_bf16_f32 v21, v246, v247
	ds_read2_b32 v[246:247], v122 offset0:214 offset1:247
	v_or_b32_e32 v26, s5, v116
	s_ashr_i32 s29, s28, 31
	v_ashrrev_i32_e32 v27, 31, v26
	v_lshl_add_u64 v[28:29], s[28:29], 1, v[104:105]
	v_lshlrev_b64 v[26:27], 13, v[26:27]
	v_lshl_add_u64 v[26:27], v[28:29], 0, v[26:27]
	global_store_dwordx4 v[26:27], v[18:21], off
	s_waitcnt lgkmcnt(7)
	s_nop 0
	v_cvt_pk_bf16_f32 v18, v248, v249
	ds_read2_b32 v[248:249], v122 offset0:24 offset1:57
	s_waitcnt lgkmcnt(7)
	v_cvt_pk_bf16_f32 v19, v250, v251
	ds_read2_b32 v[250:251], v122 offset0:90 offset1:123
	s_waitcnt lgkmcnt(7)
	v_cvt_pk_bf16_f32 v20, v252, v253
	ds_read2_b32 v[252:253], v122 offset0:156 offset1:189
	s_waitcnt lgkmcnt(7)
	v_cvt_pk_bf16_f32 v21, v254, v255
	ds_read2_b32 v[254:255], v122 offset0:222 offset1:255
	v_or_b32_e32 v26, s5, v119
	v_ashrrev_i32_e32 v27, 31, v26
	v_lshlrev_b64 v[26:27], 13, v[26:27]
	v_lshl_add_u64 v[26:27], v[28:29], 0, v[26:27]
	global_store_dwordx4 v[26:27], v[18:21], off
	s_waitcnt lgkmcnt(7)
	s_nop 0
	v_cvt_pk_bf16_f32 v18, v240, v241
	v_or_b32_e32 v38, s5, v120
	v_ashrrev_i32_e32 v39, 31, v38
	s_waitcnt lgkmcnt(6)
	v_cvt_pk_bf16_f32 v19, v242, v243
	v_lshlrev_b64 v[38:39], 13, v[38:39]
	s_waitcnt lgkmcnt(5)
	v_cvt_pk_bf16_f32 v20, v244, v245
	s_waitcnt lgkmcnt(4)
	v_cvt_pk_bf16_f32 v21, v246, v247
	v_lshl_add_u64 v[38:39], v[28:29], 0, v[38:39]
	global_store_dwordx4 v[38:39], v[18:21], off
	v_or_b32_e32 v38, s5, v121
	v_ashrrev_i32_e32 v39, 31, v38
	s_waitcnt lgkmcnt(3)
	v_cvt_pk_bf16_f32 v18, v248, v249
	s_waitcnt lgkmcnt(2)
	v_cvt_pk_bf16_f32 v19, v250, v251
	s_waitcnt lgkmcnt(1)
	v_cvt_pk_bf16_f32 v20, v252, v253
	v_lshlrev_b64 v[38:39], 13, v[38:39]
	s_waitcnt lgkmcnt(0)
	v_cvt_pk_bf16_f32 v21, v254, v255
	v_lshl_add_u64 v[26:27], v[28:29], 0, v[38:39]
	global_store_dwordx4 v[26:27], v[18:21], off
	s_waitcnt lgkmcnt(0)
; __device__ __forceinline__ unsigned cvt_pk_bf16(float lo, float hi) { unsigned r; asm volatile("v_cvt_pk_bf16_f32 %0, %1, %2" : "=v"(r) : "v"(lo), "v"(hi)); return r; }
; #define LAS __attribute__((address_space(3)))
; #define LDS_WAIT() asm volatile("s_waitcnt lgkmcnt(0)" ::: "memory")
; __device__ __forceinline__ void p0_item_load(const float* __restrict__ W, int N, int nblk, int nb0, int item, int lane, f32x4 (&v)[8]) {
;     const int kb = item / nblk, nb = nb0 + item % nblk;
;     const float* src = W + (size_t)(64 * kb + (lane >> 3)) * N + 32 * nb + 4 * (lane & 7);
; #pragma unroll
;     for (int i = 0; i < 8; ++i) v[i] = __builtin_nontemporal_load((const f32x4*)(src + (size_t)(8 * i) * N));
; }
; __device__ __forceinline__ void p0_item_store(const f32x4 (&v)[8], int K, int nblk, int nb0, bf16* __restrict__ WT, int mode, LAS float* scr, int item, int lane) {
;     const int kb = item / nblk, nb = nb0 + item % nblk, k0 = 64 * kb, n0 = 32 * nb;
; #pragma unroll
;     for (int i = 0; i < 8; ++i) { LAS float* d = scr + (8 * i + (lane >> 3)) * 33 + 4 * (lane & 7); d[0] = v[i].x; d[1] = v[i].y; d[2] = v[i].z; d[3] = v[i].w; }
;     LDS_WAIT(); asm volatile("" ::: "memory");
;     const int c = lane & 7, r0 = map_row(n0, mode);
;     const float wsc = mode == 1 ? 1.44269504089f : (mode == 2 ? 0.69314718056f : 1.0f);
; #pragma unroll
;     for (int j = 0; j < 4; ++j) { const int n = (lane >> 3) + 8 * j; const LAS float* s = scr + (8 * c) * 33 + n;
;         v4u o; o.x = cvt_pk_bf16(s[0 * 33] * wsc, s[1 * 33] * wsc); o.y = cvt_pk_bf16(s[2 * 33] * wsc, s[3 * 33] * wsc); o.z = cvt_pk_bf16(s[4 * 33] * wsc, s[5 * 33] * wsc); o.w = cvt_pk_bf16(s[6 * 33] * wsc, s[7 * 33] * wsc);
;         *(v4u*)(WT + (size_t)(r0 + n) * K + k0 + 8 * c) = o; }
;     LDS_WAIT(); asm volatile("" ::: "memory");
; }
	s_mul_hi_i32 s5, s27, 0x92492493
	s_add_i32 s5, s5, s27
	s_lshr_b32 s28, s5, 31
	s_ashr_i32 s5, s5, 8
	s_add_i32 s5, s5, s28
	s_mul_i32 s28, s5, 0x1c0
	v_lshl_or_b32 v18, s5, 6, v116
	s_sub_i32 s30, s27, s28
	v_mad_i64_i32 v[18:19], s[28:29], v18, s10, v[106:107]
	s_lshl_b32 s28, s30, 5
	s_ashr_i32 s29, s28, 31
	v_lshl_add_u64 v[18:19], s[28:29], 2, v[18:19]
	v_lshl_add_u64 v[58:59], v[18:19], 0, v[100:101]
	v_add_co_u32_e32 v26, vcc, s11, v58
	s_nop 1
	v_addc_co_u32_e32 v27, vcc, 0, v59, vcc
	v_add_co_u32_e32 v38, vcc, s12, v58
	global_load_dwordx4 v[18:21], v[58:59], off nt
	s_nop 0
	global_load_dwordx4 v[26:29], v[26:27], off nt
	v_addc_co_u32_e32 v39, vcc, 0, v59, vcc
	v_add_co_u32_e32 v46, vcc, s13, v58
	s_nop 1
	v_addc_co_u32_e32 v47, vcc, 0, v59, vcc
	v_add_co_u32_e32 v50, vcc, s14, v58
	global_load_dwordx4 v[38:41], v[38:39], off nt
	s_nop 0
	global_load_dwordx4 v[46:49], v[46:47], off nt
	v_addc_co_u32_e32 v51, vcc, 0, v59, vcc
	v_add_co_u32_e32 v54, vcc, s15, v58
	s_nop 1
	v_addc_co_u32_e32 v55, vcc, 0, v59, vcc
	v_add_co_u32_e32 v60, vcc, s24, v58
	global_load_dwordx4 v[50:53], v[50:51], off nt
	s_nop 0
	global_load_dwordx4 v[54:57], v[54:55], off nt
	v_addc_co_u32_e32 v61, vcc, 0, v59, vcc
	v_add_co_u32_e32 v62, vcc, s25, v58
	s_nop 1
	v_addc_co_u32_e32 v63, vcc, 0, v59, vcc
	global_load_dwordx4 v[58:61], v[60:61], off nt
	s_nop 0
	global_load_dwordx4 v[62:65], v[62:63], off nt
	s_waitcnt vmcnt(31)
	ds_write2_b32 v99, v66, v67 offset1:1
	ds_write2_b32 v99, v68, v69 offset0:2 offset1:3
	s_waitcnt vmcnt(30)
	ds_write2_b32 v108, v70, v71 offset1:1
	ds_write2_b32 v109, v72, v73 offset1:1
	s_waitcnt vmcnt(29)
	ds_write2_b32 v110, v74, v75 offset1:1
	ds_write2_b32 v111, v76, v77 offset1:1
	s_waitcnt vmcnt(28)
	ds_write2_b32 v112, v78, v79 offset1:1
	ds_write2_b32 v113, v80, v81 offset1:1
	s_waitcnt vmcnt(27)
	ds_write2_b32 v114, v82, v83 offset1:1
	ds_write2_b32 v115, v84, v85 offset1:1
	s_waitcnt vmcnt(26)
	ds_write2_b32 v123, v86, v87 offset1:1
	ds_write2_b32 v124, v88, v89 offset1:1
	s_waitcnt vmcnt(25)
	ds_write2_b32 v125, v90, v91 offset1:1
	ds_write2_b32 v126, v92, v93 offset1:1
	s_waitcnt vmcnt(24)
	ds_write2_b32 v127, v94, v95 offset1:1
	ds_write2_b32 v128, v96, v97 offset1:1
	s_waitcnt lgkmcnt(0)
	ds_read2_b32 v[240:241], v122 offset1:33
	ds_read2_b32 v[242:243], v122 offset0:66 offset1:99
	ds_read2_b32 v[244:245], v122 offset0:132 offset1:165
	ds_read2_b32 v[246:247], v122 offset0:198 offset1:231
	ds_read2_b32 v[248:249], v122 offset0:8 offset1:41
	ds_read2_b32 v[250:251], v122 offset0:74 offset1:107
	ds_read2_b32 v[252:253], v122 offset0:140 offset1:173
	ds_read2_b32 v[254:255], v122 offset0:206 offset1:239
	s_waitcnt lgkmcnt(7)
	v_cvt_pk_bf16_f32 v66, v240, v241
	ds_read2_b32 v[240:241], v122 offset0:16 offset1:49
	s_waitcnt lgkmcnt(7)
	v_cvt_pk_bf16_f32 v67, v242, v243
	ds_read2_b32 v[242:243], v122 offset0:82 offset1:115
	s_waitcnt lgkmcnt(7)
	v_cvt_pk_bf16_f32 v68, v244, v245
	ds_read2_b32 v[244:245], v122 offset0:148 offset1:181
	s_waitcnt lgkmcnt(7)
	v_cvt_pk_bf16_f32 v69, v246, v247
	ds_read2_b32 v[246:247], v122 offset0:214 offset1:247
	v_or_b32_e32 v70, s2, v116
	s_ashr_i32 s5, s4, 31
	v_ashrrev_i32_e32 v71, 31, v70
	v_lshl_add_u64 v[72:73], s[4:5], 1, v[104:105]
	v_lshlrev_b64 v[70:71], 13, v[70:71]
	v_lshl_add_u64 v[70:71], v[72:73], 0, v[70:71]
	global_store_dwordx4 v[70:71], v[66:69], off
	s_waitcnt lgkmcnt(7)
	s_nop 0
	v_cvt_pk_bf16_f32 v66, v248, v249
	ds_read2_b32 v[248:249], v122 offset0:24 offset1:57
	v_or_b32_e32 v74, s2, v119
	v_ashrrev_i32_e32 v75, 31, v74
	v_lshlrev_b64 v[74:75], 13, v[74:75]
	s_waitcnt lgkmcnt(7)
	v_cvt_pk_bf16_f32 v67, v250, v251
	ds_read2_b32 v[250:251], v122 offset0:90 offset1:123
	v_lshl_add_u64 v[74:75], v[72:73], 0, v[74:75]
	s_waitcnt lgkmcnt(7)
	v_cvt_pk_bf16_f32 v68, v252, v253
	ds_read2_b32 v[252:253], v122 offset0:156 offset1:189
	s_waitcnt lgkmcnt(7)
	v_cvt_pk_bf16_f32 v69, v254, v255
	ds_read2_b32 v[254:255], v122 offset0:222 offset1:255
	global_store_dwordx4 v[74:75], v[66:69], off
	v_or_b32_e32 v74, s2, v120
	s_waitcnt lgkmcnt(7)
	v_cvt_pk_bf16_f32 v66, v240, v241
	v_ashrrev_i32_e32 v75, 31, v74
	s_waitcnt lgkmcnt(6)
	v_cvt_pk_bf16_f32 v67, v242, v243
	v_lshlrev_b64 v[74:75], 13, v[74:75]
	s_waitcnt lgkmcnt(5)
	v_cvt_pk_bf16_f32 v68, v244, v245
	s_waitcnt lgkmcnt(4)
	v_cvt_pk_bf16_f32 v69, v246, v247
	v_lshl_add_u64 v[74:75], v[72:73], 0, v[74:75]
	global_store_dwordx4 v[74:75], v[66:69], off
	v_or_b32_e32 v74, s2, v121
	v_ashrrev_i32_e32 v75, 31, v74
	s_waitcnt lgkmcnt(3)
	v_cvt_pk_bf16_f32 v66, v248, v249
	s_waitcnt lgkmcnt(2)
	v_cvt_pk_bf16_f32 v67, v250, v251
	s_waitcnt lgkmcnt(1)
	v_cvt_pk_bf16_f32 v68, v252, v253
	v_lshlrev_b64 v[74:75], 13, v[74:75]
	s_waitcnt lgkmcnt(0)
	v_cvt_pk_bf16_f32 v69, v254, v255
	v_lshl_add_u64 v[70:71], v[72:73], 0, v[74:75]
	global_store_dwordx4 v[70:71], v[66:69], off
	s_waitcnt lgkmcnt(0)
	s_add_i32 s26, s26, -1
	s_cmp_lg_u32 s26, 0
	s_mov_b32 s28, s3
	s_mov_b32 s5, s27
	s_cbranch_scc1 .LBB0_105

; __device__ __forceinline__ unsigned cvt_pk_bf16(float lo, float hi) { unsigned r; asm volatile("v_cvt_pk_bf16_f32 %0, %1, %2" : "=v"(r) : "v"(lo), "v"(hi)); return r; }
; #define LAS __attribute__((address_space(3)))
; #define LDS_WAIT() asm volatile("s_waitcnt lgkmcnt(0)" ::: "memory")
; __device__ __forceinline__ void p0_item_load(const float* __restrict__ W, int N, int nblk, int nb0, int item, int lane, f32x4 (&v)[8]) {
;     const int kb = item / nblk, nb = nb0 + item % nblk;
;     const float* src = W + (size_t)(64 * kb + (lane >> 3)) * N + 32 * nb + 4 * (lane & 7);
; #pragma unroll
;     for (int i = 0; i < 8; ++i) v[i] = __builtin_nontemporal_load((const f32x4*)(src + (size_t)(8 * i) * N));
; }
; __device__ __forceinline__ void p0_item_store(const f32x4 (&v)[8], int K, int nblk, int nb0, bf16* __restrict__ WT, int mode, LAS float* scr, int item, int lane) {
;     const int kb = item / nblk, nb = nb0 + item % nblk, k0 = 64 * kb, n0 = 32 * nb;
; #pragma unroll
;     for (int i = 0; i < 8; ++i) { LAS float* d = scr + (8 * i + (lane >> 3)) * 33 + 4 * (lane & 7); d[0] = v[i].x; d[1] = v[i].y; d[2] = v[i].z; d[3] = v[i].w; }
;     LDS_WAIT(); asm volatile("" ::: "memory");
;     const int c = lane & 7, r0 = map_row(n0, mode);
;     const float wsc = mode == 1 ? 1.44269504089f : (mode == 2 ? 0.69314718056f : 1.0f);
; #pragma unroll
;     for (int j = 0; j < 4; ++j) { const int n = (lane >> 3) + 8 * j; const LAS float* s = scr + (8 * c) * 33 + n;
;         v4u o; o.x = cvt_pk_bf16(s[0 * 33] * wsc, s[1 * 33] * wsc); o.y = cvt_pk_bf16(s[2 * 33] * wsc, s[3 * 33] * wsc); o.z = cvt_pk_bf16(s[4 * 33] * wsc, s[5 * 33] * wsc); o.w = cvt_pk_bf16(s[6 * 33] * wsc, s[7 * 33] * wsc);
;         *(v4u*)(WT + (size_t)(r0 + n) * K + k0 + 8 * c) = o; }
;     LDS_WAIT(); asm volatile("" ::: "memory");
; }
.LBB0_109:
	s_add_i32 s0, s3, s17
	s_min_i32 s19, s0, 0xfff
	s_ashr_i32 s0, s19, 31
	s_lshr_b32 s0, s0, 25
	s_add_i32 s0, s19, s0
	s_ashr_i32 s1, s0, 7
	s_lshl_b32 s2, s1, 6
	s_and_b32 s0, s0, 0x7ffff80
	v_or_b32_e32 v66, s2, v116
	s_sub_i32 s0, s19, s0
	v_ashrrev_i32_e32 v67, 31, v66
	v_lshlrev_b64 v[66:67], 14, v[66:67]
	s_lshl_b32 s0, s0, 5
	v_lshl_add_u64 v[66:67], s[60:61], 0, v[66:67]
	s_ashr_i32 s1, s0, 31
	v_lshl_add_u64 v[66:67], s[0:1], 2, v[66:67]
	v_lshl_add_u64 v[90:91], v[66:67], 0, v[100:101]
	v_add_co_u32_e32 v70, vcc, s4, v90
	s_add_i32 s19, s19, s17
	s_nop 0
	v_addc_co_u32_e32 v71, vcc, 0, v91, vcc
	v_add_co_u32_e32 v74, vcc, s5, v90
	global_load_dwordx4 v[66:69], v[90:91], off nt
	s_nop 0
	global_load_dwordx4 v[70:73], v[70:71], off nt
	v_addc_co_u32_e32 v75, vcc, 0, v91, vcc
	v_add_co_u32_e32 v78, vcc, s10, v90
	s_min_i32 s1, s19, 0xfff
	s_nop 0
	v_addc_co_u32_e32 v79, vcc, 0, v91, vcc
	v_add_co_u32_e32 v82, vcc, s11, v90
	global_load_dwordx4 v[74:77], v[74:75], off nt
	s_nop 0
	global_load_dwordx4 v[78:81], v[78:79], off nt
	v_addc_co_u32_e32 v83, vcc, 0, v91, vcc
	v_add_co_u32_e32 v86, vcc, s12, v90
	s_add_i32 s19, s1, s17
	s_nop 0
	v_addc_co_u32_e32 v87, vcc, 0, v91, vcc
	v_add_co_u32_e32 v92, vcc, s13, v90
	global_load_dwordx4 v[82:85], v[82:83], off nt
	s_nop 0
	global_load_dwordx4 v[86:89], v[86:87], off nt
	v_addc_co_u32_e32 v93, vcc, 0, v91, vcc
	v_add_co_u32_e32 v94, vcc, s14, v90
	s_min_i32 s19, s19, 0xfff
	s_nop 0
	v_addc_co_u32_e32 v95, vcc, 0, v91, vcc
	global_load_dwordx4 v[90:93], v[92:93], off nt
	s_nop 0
	global_load_dwordx4 v[94:97], v[94:95], off nt
	v_add_u32_e32 v102, v117, v118
	v_add_u32_e32 v103, 0x420, v102
	v_add_u32_e32 v104, 0x428, v102
	v_add_u32_e32 v105, 0x840, v102
	v_add_u32_e32 v106, 0x848, v102
	v_add_u32_e32 v107, 0xc60, v102
	v_add_u32_e32 v108, 0xc68, v102
	v_add_u32_e32 v109, 0x1080, v102
	v_add_u32_e32 v110, 0x1088, v102
	v_add_u32_e32 v111, 0x14a0, v102
	v_add_u32_e32 v112, 0x14a8, v102
	v_add_u32_e32 v113, 0x18c0, v102
	v_add_u32_e32 v114, 0x18c8, v102
	v_add_u32_e32 v115, 0x1ce0, v102
	v_add_u32_e32 v123, 0x1ce8, v102
	s_waitcnt vmcnt(17)
	ds_write2_b32 v102, v30, v31 offset1:1
	ds_write2_b32 v102, v32, v33 offset0:2 offset1:3
	ds_write2_b32 v103, v2, v3 offset1:1
	ds_write2_b32 v104, v4, v5 offset1:1
	ds_write2_b32 v105, v6, v7 offset1:1
	ds_write2_b32 v106, v8, v9 offset1:1
	ds_write2_b32 v107, v10, v11 offset1:1
	ds_write2_b32 v108, v12, v13 offset1:1
	ds_write2_b32 v109, v14, v15 offset1:1
	ds_write2_b32 v110, v16, v17 offset1:1
	ds_write2_b32 v111, v22, v23 offset1:1
	ds_write2_b32 v112, v24, v25 offset1:1
	ds_write2_b32 v113, v34, v35 offset1:1
	ds_write2_b32 v114, v36, v37 offset1:1
	s_waitcnt vmcnt(15)
	ds_write2_b32 v115, v42, v43 offset1:1
	ds_write2_b32 v123, v44, v45 offset1:1
	s_waitcnt lgkmcnt(0)
	s_ashr_i32 s20, s18, 31
	s_lshr_b32 s20, s20, 25
	ds_read2_b32 v[240:241], v122 offset1:33
	ds_read2_b32 v[242:243], v122 offset0:66 offset1:99
	ds_read2_b32 v[244:245], v122 offset0:132 offset1:165
	ds_read2_b32 v[246:247], v122 offset0:198 offset1:231
	ds_read2_b32 v[248:249], v122 offset0:8 offset1:41
	ds_read2_b32 v[250:251], v122 offset0:74 offset1:107
	ds_read2_b32 v[252:253], v122 offset0:140 offset1:173
	ds_read2_b32 v[254:255], v122 offset0:206 offset1:239
	s_add_i32 s20, s18, s20
	s_waitcnt lgkmcnt(7)
	v_cvt_pk_bf16_f32 v2, v240, v241
	ds_read2_b32 v[240:241], v122 offset0:16 offset1:49
	s_ashr_i32 s21, s20, 7
	s_and_b32 s20, s20, 0x7ffff80
	s_waitcnt lgkmcnt(7)
	v_cvt_pk_bf16_f32 v3, v242, v243
	ds_read2_b32 v[242:243], v122 offset0:82 offset1:115
	s_sub_i32 s18, s18, s20
	s_waitcnt lgkmcnt(7)
	v_cvt_pk_bf16_f32 v4, v244, v245
	ds_read2_b32 v[244:245], v122 offset0:148 offset1:181
	s_lshl_b32 s18, s18, 5
	s_lshl_b32 s20, s21, 6
	s_waitcnt lgkmcnt(7)
	v_cvt_pk_bf16_f32 v5, v246, v247
	ds_read2_b32 v[246:247], v122 offset0:214 offset1:247
	v_or_b32_e32 v6, s18, v116
	s_ashr_i32 s21, s20, 31
	v_ashrrev_i32_e32 v7, 31, v6
	v_lshl_add_u64 v[8:9], s[20:21], 1, v[98:99]
	v_lshlrev_b64 v[6:7], 12, v[6:7]
	v_lshl_add_u64 v[6:7], v[8:9], 0, v[6:7]
	global_store_dwordx4 v[6:7], v[2:5], off
	s_waitcnt lgkmcnt(7)
	s_nop 0
	v_cvt_pk_bf16_f32 v2, v248, v249
	ds_read2_b32 v[248:249], v122 offset0:24 offset1:57
	s_waitcnt lgkmcnt(7)
	v_cvt_pk_bf16_f32 v3, v250, v251
	ds_read2_b32 v[250:251], v122 offset0:90 offset1:123
	s_waitcnt lgkmcnt(7)
	v_cvt_pk_bf16_f32 v4, v252, v253
	ds_read2_b32 v[252:253], v122 offset0:156 offset1:189
	s_waitcnt lgkmcnt(7)
	v_cvt_pk_bf16_f32 v5, v254, v255
	ds_read2_b32 v[254:255], v122 offset0:222 offset1:255
	v_or_b32_e32 v6, s18, v119
	v_ashrrev_i32_e32 v7, 31, v6
	v_lshlrev_b64 v[6:7], 12, v[6:7]
	v_lshl_add_u64 v[6:7], v[8:9], 0, v[6:7]
	global_store_dwordx4 v[6:7], v[2:5], off
	s_waitcnt lgkmcnt(7)
	s_nop 0
	v_cvt_pk_bf16_f32 v2, v240, v241
	s_waitcnt lgkmcnt(6)
	v_cvt_pk_bf16_f32 v3, v242, v243
	s_waitcnt lgkmcnt(5)
	v_cvt_pk_bf16_f32 v4, v244, v245
	s_waitcnt lgkmcnt(4)
	v_cvt_pk_bf16_f32 v5, v246, v247
	v_or_b32_e32 v6, s18, v120
	v_ashrrev_i32_e32 v7, 31, v6
	v_lshlrev_b64 v[6:7], 12, v[6:7]
	v_lshl_add_u64 v[6:7], v[8:9], 0, v[6:7]
	global_store_dwordx4 v[6:7], v[2:5], off
	s_waitcnt lgkmcnt(3)
	s_nop 0
	v_cvt_pk_bf16_f32 v2, v248, v249
	s_waitcnt lgkmcnt(2)
	v_cvt_pk_bf16_f32 v3, v250, v251
	s_waitcnt lgkmcnt(1)
	v_cvt_pk_bf16_f32 v4, v252, v253
	s_waitcnt lgkmcnt(0)
	v_cvt_pk_bf16_f32 v5, v254, v255
	v_or_b32_e32 v6, s18, v121
	v_ashrrev_i32_e32 v7, 31, v6
	v_lshlrev_b64 v[6:7], 12, v[6:7]
	v_lshl_add_u64 v[6:7], v[8:9], 0, v[6:7]
	global_store_dwordx4 v[6:7], v[2:5], off
	s_waitcnt lgkmcnt(0)
; __device__ __forceinline__ unsigned cvt_pk_bf16(float lo, float hi) { unsigned r; asm volatile("v_cvt_pk_bf16_f32 %0, %1, %2" : "=v"(r) : "v"(lo), "v"(hi)); return r; }
; #define LAS __attribute__((address_space(3)))
; #define LDS_WAIT() asm volatile("s_waitcnt lgkmcnt(0)" ::: "memory")
; __device__ __forceinline__ void p0_item_load(const float* __restrict__ W, int N, int nblk, int nb0, int item, int lane, f32x4 (&v)[8]) {
;     const int kb = item / nblk, nb = nb0 + item % nblk;
;     const float* src = W + (size_t)(64 * kb + (lane >> 3)) * N + 32 * nb + 4 * (lane & 7);
; #pragma unroll
;     for (int i = 0; i < 8; ++i) v[i] = __builtin_nontemporal_load((const f32x4*)(src + (size_t)(8 * i) * N));
; }
; __device__ __forceinline__ void p0_item_store(const f32x4 (&v)[8], int K, int nblk, int nb0, bf16* __restrict__ WT, int mode, LAS float* scr, int item, int lane) {
;     const int kb = item / nblk, nb = nb0 + item % nblk, k0 = 64 * kb, n0 = 32 * nb;
; #pragma unroll
;     for (int i = 0; i < 8; ++i) { LAS float* d = scr + (8 * i + (lane >> 3)) * 33 + 4 * (lane & 7); d[0] = v[i].x; d[1] = v[i].y; d[2] = v[i].z; d[3] = v[i].w; }
;     LDS_WAIT(); asm volatile("" ::: "memory");
;     const int c = lane & 7, r0 = map_row(n0, mode);
;     const float wsc = mode == 1 ? 1.44269504089f : (mode == 2 ? 0.69314718056f : 1.0f);
; #pragma unroll
;     for (int j = 0; j < 4; ++j) { const int n = (lane >> 3) + 8 * j; const LAS float* s = scr + (8 * c) * 33 + n;
;         v4u o; o.x = cvt_pk_bf16(s[0 * 33] * wsc, s[1 * 33] * wsc); o.y = cvt_pk_bf16(s[2 * 33] * wsc, s[3 * 33] * wsc); o.z = cvt_pk_bf16(s[4 * 33] * wsc, s[5 * 33] * wsc); o.w = cvt_pk_bf16(s[6 * 33] * wsc, s[7 * 33] * wsc);
;         *(v4u*)(WT + (size_t)(r0 + n) * K + k0 + 8 * c) = o; }
;     LDS_WAIT(); asm volatile("" ::: "memory");
; }
	s_ashr_i32 s18, s1, 31
	s_lshr_b32 s18, s18, 25
	s_add_i32 s18, s1, s18
	s_ashr_i32 s20, s18, 7
	s_and_b32 s18, s18, 0x7ffff80
	v_lshl_or_b32 v2, s20, 6, v116
	s_sub_i32 s18, s1, s18
	v_ashrrev_i32_e32 v3, 31, v2
	v_lshlrev_b64 v[2:3], 14, v[2:3]
	s_lshl_b32 s20, s18, 5
	v_lshl_add_u64 v[2:3], s[60:61], 0, v[2:3]
	s_ashr_i32 s21, s20, 31
	v_lshl_add_u64 v[2:3], s[20:21], 2, v[2:3]
	v_lshl_add_u64 v[34:35], v[2:3], 0, v[100:101]
	v_add_co_u32_e32 v2, vcc, s4, v34
	s_nop 1
	v_addc_co_u32_e32 v3, vcc, 0, v35, vcc
	v_add_co_u32_e32 v6, vcc, s5, v34
	global_load_dwordx4 v[30:33], v[34:35], off nt
	s_nop 0
	global_load_dwordx4 v[2:5], v[2:3], off nt
	v_addc_co_u32_e32 v7, vcc, 0, v35, vcc
	v_add_co_u32_e32 v10, vcc, s10, v34
	s_nop 1
	v_addc_co_u32_e32 v11, vcc, 0, v35, vcc
	v_add_co_u32_e32 v14, vcc, s11, v34
	global_load_dwordx4 v[6:9], v[6:7], off nt
	s_nop 0
	global_load_dwordx4 v[10:13], v[10:11], off nt
	v_addc_co_u32_e32 v15, vcc, 0, v35, vcc
	v_add_co_u32_e32 v22, vcc, s12, v34
	s_nop 1
	v_addc_co_u32_e32 v23, vcc, 0, v35, vcc
	v_add_co_u32_e32 v36, vcc, s13, v34
	global_load_dwordx4 v[14:17], v[14:15], off nt
	s_nop 0
	global_load_dwordx4 v[22:25], v[22:23], off nt
	v_addc_co_u32_e32 v37, vcc, 0, v35, vcc
	v_add_co_u32_e32 v42, vcc, s14, v34
	s_nop 1
	v_addc_co_u32_e32 v43, vcc, 0, v35, vcc
	global_load_dwordx4 v[34:37], v[36:37], off nt
	s_nop 0
	global_load_dwordx4 v[42:45], v[42:43], off nt
	ds_write2_b32 v102, v18, v19 offset1:1
	ds_write2_b32 v102, v20, v21 offset0:2 offset1:3
	s_waitcnt vmcnt(26)
	ds_write2_b32 v103, v26, v27 offset1:1
	ds_write2_b32 v104, v28, v29 offset1:1
	s_waitcnt vmcnt(25)
	ds_write2_b32 v105, v38, v39 offset1:1
	ds_write2_b32 v106, v40, v41 offset1:1
	s_waitcnt vmcnt(24)
	ds_write2_b32 v107, v46, v47 offset1:1
	ds_write2_b32 v108, v48, v49 offset1:1
	s_waitcnt vmcnt(23)
	ds_write2_b32 v109, v50, v51 offset1:1
	ds_write2_b32 v110, v52, v53 offset1:1
	s_waitcnt vmcnt(22)
	ds_write2_b32 v111, v54, v55 offset1:1
	ds_write2_b32 v112, v56, v57 offset1:1
	s_waitcnt vmcnt(21)
	ds_write2_b32 v113, v58, v59 offset1:1
	ds_write2_b32 v114, v60, v61 offset1:1
	s_waitcnt vmcnt(20)
	ds_write2_b32 v115, v62, v63 offset1:1
	ds_write2_b32 v123, v64, v65 offset1:1
	s_waitcnt lgkmcnt(0)
	s_ashr_i32 s18, s3, 31
	s_lshr_b32 s18, s18, 25
	ds_read2_b32 v[240:241], v122 offset1:33
	ds_read2_b32 v[242:243], v122 offset0:66 offset1:99
	ds_read2_b32 v[244:245], v122 offset0:132 offset1:165
	ds_read2_b32 v[246:247], v122 offset0:198 offset1:231
	ds_read2_b32 v[248:249], v122 offset0:8 offset1:41
	ds_read2_b32 v[250:251], v122 offset0:74 offset1:107
	ds_read2_b32 v[252:253], v122 offset0:140 offset1:173
	ds_read2_b32 v[254:255], v122 offset0:206 offset1:239
	s_add_i32 s18, s3, s18
	s_waitcnt lgkmcnt(7)
	v_cvt_pk_bf16_f32 v18, v240, v241
	ds_read2_b32 v[240:241], v122 offset0:16 offset1:49
	s_ashr_i32 s20, s18, 7
	s_and_b32 s18, s18, 0x7ffff80
	s_waitcnt lgkmcnt(7)
	v_cvt_pk_bf16_f32 v19, v242, v243
	ds_read2_b32 v[242:243], v122 offset0:82 offset1:115
	s_sub_i32 s3, s3, s18
	s_waitcnt lgkmcnt(7)
	v_cvt_pk_bf16_f32 v20, v244, v245
	ds_read2_b32 v[244:245], v122 offset0:148 offset1:181
	s_lshl_b32 s3, s3, 5
	s_lshl_b32 s20, s20, 6
	s_waitcnt lgkmcnt(7)
	v_cvt_pk_bf16_f32 v21, v246, v247
	ds_read2_b32 v[246:247], v122 offset0:214 offset1:247
	v_or_b32_e32 v26, s3, v116
	s_ashr_i32 s21, s20, 31
	v_ashrrev_i32_e32 v27, 31, v26
	v_lshl_add_u64 v[28:29], s[20:21], 1, v[98:99]
	v_lshlrev_b64 v[26:27], 12, v[26:27]
	v_lshl_add_u64 v[26:27], v[28:29], 0, v[26:27]
	global_store_dwordx4 v[26:27], v[18:21], off
	s_waitcnt lgkmcnt(7)
	s_nop 0
	v_cvt_pk_bf16_f32 v18, v248, v249
	ds_read2_b32 v[248:249], v122 offset0:24 offset1:57
	s_waitcnt lgkmcnt(7)
	v_cvt_pk_bf16_f32 v19, v250, v251
	ds_read2_b32 v[250:251], v122 offset0:90 offset1:123
	s_waitcnt lgkmcnt(7)
	v_cvt_pk_bf16_f32 v20, v252, v253
	ds_read2_b32 v[252:253], v122 offset0:156 offset1:189
	s_waitcnt lgkmcnt(7)
	v_cvt_pk_bf16_f32 v21, v254, v255
	ds_read2_b32 v[254:255], v122 offset0:222 offset1:255
	v_or_b32_e32 v26, s3, v119
	v_ashrrev_i32_e32 v27, 31, v26
	v_lshlrev_b64 v[26:27], 12, v[26:27]
	v_lshl_add_u64 v[26:27], v[28:29], 0, v[26:27]
	global_store_dwordx4 v[26:27], v[18:21], off
	s_waitcnt lgkmcnt(7)
	s_nop 0
	v_cvt_pk_bf16_f32 v18, v240, v241
	v_or_b32_e32 v38, s3, v120
	v_ashrrev_i32_e32 v39, 31, v38
	s_waitcnt lgkmcnt(6)
	v_cvt_pk_bf16_f32 v19, v242, v243
	v_lshlrev_b64 v[38:39], 12, v[38:39]
	s_waitcnt lgkmcnt(5)
	v_cvt_pk_bf16_f32 v20, v244, v245
	s_waitcnt lgkmcnt(4)
	v_cvt_pk_bf16_f32 v21, v246, v247
	v_lshl_add_u64 v[38:39], v[28:29], 0, v[38:39]
	global_store_dwordx4 v[38:39], v[18:21], off
	v_or_b32_e32 v38, s3, v121
	v_ashrrev_i32_e32 v39, 31, v38
	s_waitcnt lgkmcnt(3)
	v_cvt_pk_bf16_f32 v18, v248, v249
	s_waitcnt lgkmcnt(2)
	v_cvt_pk_bf16_f32 v19, v250, v251
	s_waitcnt lgkmcnt(1)
	v_cvt_pk_bf16_f32 v20, v252, v253
	v_lshlrev_b64 v[38:39], 12, v[38:39]
	s_waitcnt lgkmcnt(0)
	v_cvt_pk_bf16_f32 v21, v254, v255
	v_lshl_add_u64 v[26:27], v[28:29], 0, v[38:39]
	global_store_dwordx4 v[26:27], v[18:21], off
	s_waitcnt lgkmcnt(0)
; __device__ __forceinline__ unsigned cvt_pk_bf16(float lo, float hi) { unsigned r; asm volatile("v_cvt_pk_bf16_f32 %0, %1, %2" : "=v"(r) : "v"(lo), "v"(hi)); return r; }
; #define LAS __attribute__((address_space(3)))
; #define LDS_WAIT() asm volatile("s_waitcnt lgkmcnt(0)" ::: "memory")
; __device__ __forceinline__ void p0_item_load(const float* __restrict__ W, int N, int nblk, int nb0, int item, int lane, f32x4 (&v)[8]) {
;     const int kb = item / nblk, nb = nb0 + item % nblk;
;     const float* src = W + (size_t)(64 * kb + (lane >> 3)) * N + 32 * nb + 4 * (lane & 7);
; #pragma unroll
;     for (int i = 0; i < 8; ++i) v[i] = __builtin_nontemporal_load((const f32x4*)(src + (size_t)(8 * i) * N));
; }
; __device__ __forceinline__ void p0_item_store(const f32x4 (&v)[8], int K, int nblk, int nb0, bf16* __restrict__ WT, int mode, LAS float* scr, int item, int lane) {
;     const int kb = item / nblk, nb = nb0 + item % nblk, k0 = 64 * kb, n0 = 32 * nb;
; #pragma unroll
;     for (int i = 0; i < 8; ++i) { LAS float* d = scr + (8 * i + (lane >> 3)) * 33 + 4 * (lane & 7); d[0] = v[i].x; d[1] = v[i].y; d[2] = v[i].z; d[3] = v[i].w; }
;     LDS_WAIT(); asm volatile("" ::: "memory");
;     const int c = lane & 7, r0 = map_row(n0, mode);
;     const float wsc = mode == 1 ? 1.44269504089f : (mode == 2 ? 0.69314718056f : 1.0f);
; #pragma unroll
;     for (int j = 0; j < 4; ++j) { const int n = (lane >> 3) + 8 * j; const LAS float* s = scr + (8 * c) * 33 + n;
;         v4u o; o.x = cvt_pk_bf16(s[0 * 33] * wsc, s[1 * 33] * wsc); o.y = cvt_pk_bf16(s[2 * 33] * wsc, s[3 * 33] * wsc); o.z = cvt_pk_bf16(s[4 * 33] * wsc, s[5 * 33] * wsc); o.w = cvt_pk_bf16(s[6 * 33] * wsc, s[7 * 33] * wsc);
;         *(v4u*)(WT + (size_t)(r0 + n) * K + k0 + 8 * c) = o; }
;     LDS_WAIT(); asm volatile("" ::: "memory");
; }
	s_ashr_i32 s3, s19, 31
	s_lshr_b32 s3, s3, 25
	s_add_i32 s3, s19, s3
	s_ashr_i32 s18, s3, 7
	s_and_b32 s3, s3, 0x7ffff80
	v_lshl_or_b32 v18, s18, 6, v116
	s_sub_i32 s3, s19, s3
	v_ashrrev_i32_e32 v19, 31, v18
	v_lshlrev_b64 v[18:19], 14, v[18:19]
	s_lshl_b32 s20, s3, 5
	v_lshl_add_u64 v[18:19], s[60:61], 0, v[18:19]
	s_ashr_i32 s21, s20, 31
	v_lshl_add_u64 v[18:19], s[20:21], 2, v[18:19]
	v_lshl_add_u64 v[58:59], v[18:19], 0, v[100:101]
	v_add_co_u32_e32 v26, vcc, s4, v58
	s_nop 1
	v_addc_co_u32_e32 v27, vcc, 0, v59, vcc
	v_add_co_u32_e32 v38, vcc, s5, v58
	global_load_dwordx4 v[18:21], v[58:59], off nt
	s_nop 0
	global_load_dwordx4 v[26:29], v[26:27], off nt
	v_addc_co_u32_e32 v39, vcc, 0, v59, vcc
	v_add_co_u32_e32 v46, vcc, s10, v58
	s_nop 1
	v_addc_co_u32_e32 v47, vcc, 0, v59, vcc
	v_add_co_u32_e32 v50, vcc, s11, v58
	global_load_dwordx4 v[38:41], v[38:39], off nt
	s_nop 0
	global_load_dwordx4 v[46:49], v[46:47], off nt
	v_addc_co_u32_e32 v51, vcc, 0, v59, vcc
	v_add_co_u32_e32 v54, vcc, s12, v58
	s_nop 1
	v_addc_co_u32_e32 v55, vcc, 0, v59, vcc
	v_add_co_u32_e32 v60, vcc, s13, v58
	global_load_dwordx4 v[50:53], v[50:51], off nt
	s_nop 0
	global_load_dwordx4 v[54:57], v[54:55], off nt
	v_addc_co_u32_e32 v61, vcc, 0, v59, vcc
	v_add_co_u32_e32 v62, vcc, s14, v58
	s_nop 1
	v_addc_co_u32_e32 v63, vcc, 0, v59, vcc
	global_load_dwordx4 v[58:61], v[60:61], off nt
	s_nop 0
	global_load_dwordx4 v[62:65], v[62:63], off nt
	s_waitcnt vmcnt(31)
	ds_write2_b32 v102, v66, v67 offset1:1
	ds_write2_b32 v102, v68, v69 offset0:2 offset1:3
	s_waitcnt vmcnt(30)
	ds_write2_b32 v103, v70, v71 offset1:1
	ds_write2_b32 v104, v72, v73 offset1:1
	s_waitcnt vmcnt(29)
	ds_write2_b32 v105, v74, v75 offset1:1
	ds_write2_b32 v106, v76, v77 offset1:1
	s_waitcnt vmcnt(28)
	ds_write2_b32 v107, v78, v79 offset1:1
	ds_write2_b32 v108, v80, v81 offset1:1
	s_waitcnt vmcnt(27)
	ds_write2_b32 v109, v82, v83 offset1:1
	ds_write2_b32 v110, v84, v85 offset1:1
	s_waitcnt vmcnt(26)
	ds_write2_b32 v111, v86, v87 offset1:1
	ds_write2_b32 v112, v88, v89 offset1:1
	s_waitcnt vmcnt(25)
	ds_write2_b32 v113, v90, v91 offset1:1
	ds_write2_b32 v114, v92, v93 offset1:1
	s_waitcnt vmcnt(24)
	ds_write2_b32 v115, v94, v95 offset1:1
	ds_write2_b32 v123, v96, v97 offset1:1
	s_waitcnt lgkmcnt(0)
	ds_read2_b32 v[240:241], v122 offset1:33
	ds_read2_b32 v[242:243], v122 offset0:66 offset1:99
	ds_read2_b32 v[244:245], v122 offset0:132 offset1:165
	ds_read2_b32 v[246:247], v122 offset0:198 offset1:231
	ds_read2_b32 v[248:249], v122 offset0:8 offset1:41
	ds_read2_b32 v[250:251], v122 offset0:74 offset1:107
	ds_read2_b32 v[252:253], v122 offset0:140 offset1:173
	ds_read2_b32 v[254:255], v122 offset0:206 offset1:239
	s_waitcnt lgkmcnt(7)
	v_cvt_pk_bf16_f32 v66, v240, v241
	ds_read2_b32 v[240:241], v122 offset0:16 offset1:49
	s_waitcnt lgkmcnt(7)
	v_cvt_pk_bf16_f32 v67, v242, v243
	ds_read2_b32 v[242:243], v122 offset0:82 offset1:115
	s_waitcnt lgkmcnt(7)
	v_cvt_pk_bf16_f32 v68, v244, v245
	ds_read2_b32 v[244:245], v122 offset0:148 offset1:181
	s_waitcnt lgkmcnt(7)
	v_cvt_pk_bf16_f32 v69, v246, v247
	ds_read2_b32 v[246:247], v122 offset0:214 offset1:247
	v_or_b32_e32 v70, s0, v116
	s_ashr_i32 s3, s2, 31
	v_ashrrev_i32_e32 v71, 31, v70
	v_lshl_add_u64 v[72:73], s[2:3], 1, v[98:99]
	v_lshlrev_b64 v[70:71], 12, v[70:71]
	v_lshl_add_u64 v[70:71], v[72:73], 0, v[70:71]
	global_store_dwordx4 v[70:71], v[66:69], off
	s_waitcnt lgkmcnt(7)
	s_nop 0
	v_cvt_pk_bf16_f32 v66, v248, v249
	ds_read2_b32 v[248:249], v122 offset0:24 offset1:57
	v_or_b32_e32 v74, s0, v119
	v_ashrrev_i32_e32 v75, 31, v74
	v_lshlrev_b64 v[74:75], 12, v[74:75]
	s_waitcnt lgkmcnt(7)
	v_cvt_pk_bf16_f32 v67, v250, v251
	ds_read2_b32 v[250:251], v122 offset0:90 offset1:123
	v_lshl_add_u64 v[74:75], v[72:73], 0, v[74:75]
	s_waitcnt lgkmcnt(7)
	v_cvt_pk_bf16_f32 v68, v252, v253
	ds_read2_b32 v[252:253], v122 offset0:156 offset1:189
	s_waitcnt lgkmcnt(7)
	v_cvt_pk_bf16_f32 v69, v254, v255
	ds_read2_b32 v[254:255], v122 offset0:222 offset1:255
	global_store_dwordx4 v[74:75], v[66:69], off
	v_or_b32_e32 v74, s0, v120
	s_waitcnt lgkmcnt(7)
	v_cvt_pk_bf16_f32 v66, v240, v241
	v_ashrrev_i32_e32 v75, 31, v74
	s_waitcnt lgkmcnt(6)
	v_cvt_pk_bf16_f32 v67, v242, v243
	v_lshlrev_b64 v[74:75], 12, v[74:75]
	s_waitcnt lgkmcnt(5)
	v_cvt_pk_bf16_f32 v68, v244, v245
	s_waitcnt lgkmcnt(4)
	v_cvt_pk_bf16_f32 v69, v246, v247
	v_lshl_add_u64 v[74:75], v[72:73], 0, v[74:75]
	global_store_dwordx4 v[74:75], v[66:69], off
	v_or_b32_e32 v74, s0, v121
	v_ashrrev_i32_e32 v75, 31, v74
	s_waitcnt lgkmcnt(3)
	v_cvt_pk_bf16_f32 v66, v248, v249
	s_waitcnt lgkmcnt(2)
	v_cvt_pk_bf16_f32 v67, v250, v251
	s_waitcnt lgkmcnt(1)
	v_cvt_pk_bf16_f32 v68, v252, v253
	v_lshlrev_b64 v[74:75], 12, v[74:75]
	s_waitcnt lgkmcnt(0)
	v_cvt_pk_bf16_f32 v69, v254, v255
	v_lshl_add_u64 v[70:71], v[72:73], 0, v[74:75]
	global_store_dwordx4 v[70:71], v[66:69], off
	s_waitcnt lgkmcnt(0)
	s_add_i32 s15, s15, -1
	s_cmp_eq_u32 s15, 0
	s_mov_b32 s18, s1
	s_mov_b32 s3, s19
	s_cbranch_scc0 .LBB0_109

; __device__ __forceinline__ unsigned cvt_pk_bf16(float lo, float hi) { unsigned r; asm volatile("v_cvt_pk_bf16_f32 %0, %1, %2" : "=v"(r) : "v"(lo), "v"(hi)); return r; }
; #define LAS __attribute__((address_space(3)))
; #define LDS_WAIT() asm volatile("s_waitcnt lgkmcnt(0)" ::: "memory")
; __device__ __forceinline__ void p0_item_load(const float* __restrict__ W, int N, int nblk, int nb0, int item, int lane, f32x4 (&v)[8]) {
;     const int kb = item / nblk, nb = nb0 + item % nblk;
;     const float* src = W + (size_t)(64 * kb + (lane >> 3)) * N + 32 * nb + 4 * (lane & 7);
; #pragma unroll
;     for (int i = 0; i < 8; ++i) v[i] = __builtin_nontemporal_load((const f32x4*)(src + (size_t)(8 * i) * N));
; }
; __device__ __forceinline__ void p0_item_store(const f32x4 (&v)[8], int K, int nblk, int nb0, bf16* __restrict__ WT, int mode, LAS float* scr, int item, int lane) {
;     const int kb = item / nblk, nb = nb0 + item % nblk, k0 = 64 * kb, n0 = 32 * nb;
; #pragma unroll
;     for (int i = 0; i < 8; ++i) { LAS float* d = scr + (8 * i + (lane >> 3)) * 33 + 4 * (lane & 7); d[0] = v[i].x; d[1] = v[i].y; d[2] = v[i].z; d[3] = v[i].w; }
;     LDS_WAIT(); asm volatile("" ::: "memory");
;     const int c = lane & 7, r0 = map_row(n0, mode);
;     const float wsc = mode == 1 ? 1.44269504089f : (mode == 2 ? 0.69314718056f : 1.0f);
; #pragma unroll
;     for (int j = 0; j < 4; ++j) { const int n = (lane >> 3) + 8 * j; const LAS float* s = scr + (8 * c) * 33 + n;
;         v4u o; o.x = cvt_pk_bf16(s[0 * 33] * wsc, s[1 * 33] * wsc); o.y = cvt_pk_bf16(s[2 * 33] * wsc, s[3 * 33] * wsc); o.z = cvt_pk_bf16(s[4 * 33] * wsc, s[5 * 33] * wsc); o.w = cvt_pk_bf16(s[6 * 33] * wsc, s[7 * 33] * wsc);
;         *(v4u*)(WT + (size_t)(r0 + n) * K + k0 + 8 * c) = o; }
;     LDS_WAIT(); asm volatile("" ::: "memory");
; }
.LBB0_473:
	s_add_i32 s2, s3, s8
	s_min_i32 s21, s2, 0x55ff
	s_mul_hi_i32 s2, s21, 0x2fa0be83
	s_lshr_b32 s4, s2, 31
	s_ashr_i32 s2, s2, 6
	s_add_i32 s2, s2, s4
	s_mul_i32 s4, s2, 0x158
	s_lshl_b32 s2, s2, 6
	v_or_b32_e32 v66, s2, v108
	v_mov_b64_e32 v[106:107], s[38:39]
	s_sub_i32 s22, s21, s4
	v_mad_i64_i32 v[66:67], s[4:5], v66, s20, v[106:107]
	s_lshl_b32 s4, s22, 5
	s_ashr_i32 s5, s4, 31
	v_lshl_add_u64 v[66:67], s[4:5], 2, v[66:67]
	v_lshl_add_u64 v[90:91], v[66:67], 0, v[98:99]
	v_add_co_u32_e32 v70, vcc, s12, v90
	s_add_i32 s21, s21, s8
	s_nop 0
	v_addc_co_u32_e32 v71, vcc, 0, v91, vcc
	v_add_co_u32_e32 v74, vcc, s13, v90
	global_load_dwordx4 v[66:69], v[90:91], off nt
	s_nop 0
	global_load_dwordx4 v[70:73], v[70:71], off nt
	v_addc_co_u32_e32 v75, vcc, 0, v91, vcc
	v_add_co_u32_e32 v78, vcc, s14, v90
	s_min_i32 s5, s21, 0x55ff
	s_nop 0
	v_addc_co_u32_e32 v79, vcc, 0, v91, vcc
	v_add_co_u32_e32 v82, vcc, s15, v90
	global_load_dwordx4 v[74:77], v[74:75], off nt
	s_nop 0
	global_load_dwordx4 v[78:81], v[78:79], off nt
	v_addc_co_u32_e32 v83, vcc, 0, v91, vcc
	v_add_co_u32_e32 v86, vcc, s16, v90
	s_add_i32 s21, s5, s8
	s_nop 0
	v_addc_co_u32_e32 v87, vcc, 0, v91, vcc
	v_add_co_u32_e32 v92, vcc, s17, v90
	global_load_dwordx4 v[82:85], v[82:83], off nt
	s_nop 0
	global_load_dwordx4 v[86:89], v[86:87], off nt
	v_addc_co_u32_e32 v93, vcc, 0, v91, vcc
	v_add_co_u32_e32 v94, vcc, s18, v90
	s_min_i32 s21, s21, 0x55ff
	s_nop 0
	v_addc_co_u32_e32 v95, vcc, 0, v91, vcc
	global_load_dwordx4 v[90:93], v[92:93], off nt
	s_nop 0
	global_load_dwordx4 v[94:97], v[94:95], off nt
	v_add_u32_e32 v101, v109, v110
	v_add_u32_e32 v115, 0x420, v101
	v_add_u32_e32 v116, 0x428, v101
	v_add_u32_e32 v117, 0x840, v101
	v_add_u32_e32 v118, 0x848, v101
	v_add_u32_e32 v119, 0xc60, v101
	v_add_u32_e32 v120, 0xc68, v101
	v_add_u32_e32 v121, 0x1080, v101
	v_add_u32_e32 v122, 0x1088, v101
	v_add_u32_e32 v123, 0x14a0, v101
	v_add_u32_e32 v124, 0x14a8, v101
	v_add_u32_e32 v125, 0x18c0, v101
	v_add_u32_e32 v126, 0x18c8, v101
	v_add_u32_e32 v127, 0x1ce0, v101
	v_add_u32_e32 v128, 0x1ce8, v101
	s_waitcnt vmcnt(0)
	ds_write2_b32 v101, v30, v31 offset1:1
	ds_write2_b32 v101, v32, v33 offset0:2 offset1:3
	ds_write2_b32 v115, v2, v3 offset1:1
	ds_write2_b32 v116, v4, v5 offset1:1
	ds_write2_b32 v117, v6, v7 offset1:1
	ds_write2_b32 v118, v8, v9 offset1:1
	ds_write2_b32 v119, v10, v11 offset1:1
	ds_write2_b32 v120, v12, v13 offset1:1
	ds_write2_b32 v121, v14, v15 offset1:1
	ds_write2_b32 v122, v16, v17 offset1:1
	ds_write2_b32 v123, v26, v27 offset1:1
	ds_write2_b32 v124, v28, v29 offset1:1
	ds_write2_b32 v125, v34, v35 offset1:1
	ds_write2_b32 v126, v36, v37 offset1:1
	ds_write2_b32 v127, v42, v43 offset1:1
	ds_write2_b32 v128, v44, v45 offset1:1
	s_waitcnt lgkmcnt(0)
	ds_read2_b32 v[240:241], v114 offset1:33
	ds_read2_b32 v[242:243], v114 offset0:66 offset1:99
	ds_read2_b32 v[244:245], v114 offset0:132 offset1:165
	ds_read2_b32 v[246:247], v114 offset0:198 offset1:231
	ds_read2_b32 v[248:249], v114 offset0:8 offset1:41
	ds_read2_b32 v[250:251], v114 offset0:74 offset1:107
	ds_read2_b32 v[252:253], v114 offset0:140 offset1:173
	ds_read2_b32 v[254:255], v114 offset0:206 offset1:239
	s_mul_hi_i32 s24, s23, 0x2fa0be83
	s_lshr_b32 s25, s24, 31
	s_ashr_i32 s24, s24, 6
	s_add_i32 s24, s24, s25
	s_waitcnt lgkmcnt(7)
	v_mul_f32_e32 v2, 0x3fb8aa3b, v240
	v_mul_f32_e32 v3, 0x3fb8aa3b, v241
	v_cvt_pk_bf16_f32 v2, v2, v3
	ds_read2_b32 v[240:241], v114 offset0:16 offset1:49
	s_mul_i32 s25, s24, 0x158
	s_sub_i32 s23, s23, s25
	s_lshl_b32 s25, s23, 5
	s_lshl_b32 s23, s23, 6
	s_waitcnt lgkmcnt(7)
	v_mul_f32_e32 v3, 0x3fb8aa3b, v242
	v_mul_f32_e32 v4, 0x3fb8aa3b, v243
	v_cvt_pk_bf16_f32 v3, v3, v4
	ds_read2_b32 v[242:243], v114 offset0:82 offset1:115
	s_and_b32 s23, s23, 0xffffff00
	s_and_b32 s25, s25, 0x60
	s_or_b32 s23, s25, s23
	s_lshl_b32 s24, s24, 6
	s_waitcnt lgkmcnt(7)
	v_mul_f32_e32 v4, 0x3fb8aa3b, v244
	v_mul_f32_e32 v5, 0x3fb8aa3b, v245
	v_cvt_pk_bf16_f32 v4, v4, v5
	ds_read2_b32 v[244:245], v114 offset0:148 offset1:181
	s_ashr_i32 s25, s24, 31
	v_lshl_add_u64 v[8:9], s[24:25], 1, v[102:103]
	s_waitcnt lgkmcnt(7)
	v_mul_f32_e32 v5, 0x3fb8aa3b, v246
	v_mul_f32_e32 v6, 0x3fb8aa3b, v247
	v_cvt_pk_bf16_f32 v5, v5, v6
	ds_read2_b32 v[246:247], v114 offset0:214 offset1:247
	v_or_b32_e32 v6, s23, v108
	v_ashrrev_i32_e32 v7, 31, v6
	v_lshlrev_b64 v[6:7], 13, v[6:7]
	v_lshl_add_u64 v[6:7], v[8:9], 0, v[6:7]
	global_store_dwordx4 v[6:7], v[2:5], off
	s_waitcnt lgkmcnt(7)
	s_nop 0
	v_mul_f32_e32 v2, 0x3fb8aa3b, v248
	v_mul_f32_e32 v3, 0x3fb8aa3b, v249
	v_cvt_pk_bf16_f32 v2, v2, v3
	ds_read2_b32 v[248:249], v114 offset0:24 offset1:57
	s_waitcnt lgkmcnt(7)
	v_mul_f32_e32 v3, 0x3fb8aa3b, v250
	v_mul_f32_e32 v4, 0x3fb8aa3b, v251
	v_cvt_pk_bf16_f32 v3, v3, v4
	ds_read2_b32 v[250:251], v114 offset0:90 offset1:123
	s_waitcnt lgkmcnt(7)
	v_mul_f32_e32 v4, 0x3fb8aa3b, v252
	v_mul_f32_e32 v5, 0x3fb8aa3b, v253
	v_cvt_pk_bf16_f32 v4, v4, v5
	ds_read2_b32 v[252:253], v114 offset0:156 offset1:189
	s_waitcnt lgkmcnt(7)
	v_mul_f32_e32 v5, 0x3fb8aa3b, v254
	v_mul_f32_e32 v6, 0x3fb8aa3b, v255
	v_cvt_pk_bf16_f32 v5, v5, v6
	ds_read2_b32 v[254:255], v114 offset0:222 offset1:255
	v_or_b32_e32 v6, s23, v111
	v_ashrrev_i32_e32 v7, 31, v6
	v_lshlrev_b64 v[6:7], 13, v[6:7]
	v_lshl_add_u64 v[6:7], v[8:9], 0, v[6:7]
	global_store_dwordx4 v[6:7], v[2:5], off
	s_waitcnt lgkmcnt(7)
	s_nop 0
	v_mul_f32_e32 v2, 0x3fb8aa3b, v240
	v_mul_f32_e32 v3, 0x3fb8aa3b, v241
	v_cvt_pk_bf16_f32 v2, v2, v3
	s_waitcnt lgkmcnt(6)
	v_mul_f32_e32 v3, 0x3fb8aa3b, v242
	v_mul_f32_e32 v4, 0x3fb8aa3b, v243
	v_cvt_pk_bf16_f32 v3, v3, v4
	s_waitcnt lgkmcnt(5)
; __device__ __forceinline__ unsigned cvt_pk_bf16(float lo, float hi) { unsigned r; asm volatile("v_cvt_pk_bf16_f32 %0, %1, %2" : "=v"(r) : "v"(lo), "v"(hi)); return r; }
; #define LAS __attribute__((address_space(3)))
; #define LDS_WAIT() asm volatile("s_waitcnt lgkmcnt(0)" ::: "memory")
; __device__ __forceinline__ void p0_item_load(const float* __restrict__ W, int N, int nblk, int nb0, int item, int lane, f32x4 (&v)[8]) {
;     const int kb = item / nblk, nb = nb0 + item % nblk;
;     const float* src = W + (size_t)(64 * kb + (lane >> 3)) * N + 32 * nb + 4 * (lane & 7);
; #pragma unroll
;     for (int i = 0; i < 8; ++i) v[i] = __builtin_nontemporal_load((const f32x4*)(src + (size_t)(8 * i) * N));
; }
; __device__ __forceinline__ void p0_item_store(const f32x4 (&v)[8], int K, int nblk, int nb0, bf16* __restrict__ WT, int mode, LAS float* scr, int item, int lane) {
;     const int kb = item / nblk, nb = nb0 + item % nblk, k0 = 64 * kb, n0 = 32 * nb;
; #pragma unroll
;     for (int i = 0; i < 8; ++i) { LAS float* d = scr + (8 * i + (lane >> 3)) * 33 + 4 * (lane & 7); d[0] = v[i].x; d[1] = v[i].y; d[2] = v[i].z; d[3] = v[i].w; }
;     LDS_WAIT(); asm volatile("" ::: "memory");
;     const int c = lane & 7, r0 = map_row(n0, mode);
;     const float wsc = mode == 1 ? 1.44269504089f : (mode == 2 ? 0.69314718056f : 1.0f);
; #pragma unroll
;     for (int j = 0; j < 4; ++j) { const int n = (lane >> 3) + 8 * j; const LAS float* s = scr + (8 * c) * 33 + n;
;         v4u o; o.x = cvt_pk_bf16(s[0 * 33] * wsc, s[1 * 33] * wsc); o.y = cvt_pk_bf16(s[2 * 33] * wsc, s[3 * 33] * wsc); o.z = cvt_pk_bf16(s[4 * 33] * wsc, s[5 * 33] * wsc); o.w = cvt_pk_bf16(s[6 * 33] * wsc, s[7 * 33] * wsc);
;         *(v4u*)(WT + (size_t)(r0 + n) * K + k0 + 8 * c) = o; }
;     LDS_WAIT(); asm volatile("" ::: "memory");
; }
	v_mul_f32_e32 v4, 0x3fb8aa3b, v244
	v_mul_f32_e32 v5, 0x3fb8aa3b, v245
	v_cvt_pk_bf16_f32 v4, v4, v5
	s_waitcnt lgkmcnt(4)
	v_mul_f32_e32 v5, 0x3fb8aa3b, v246
	v_mul_f32_e32 v6, 0x3fb8aa3b, v247
	v_cvt_pk_bf16_f32 v5, v5, v6
	v_or_b32_e32 v6, s23, v112
	v_ashrrev_i32_e32 v7, 31, v6
	v_lshlrev_b64 v[6:7], 13, v[6:7]
	v_lshl_add_u64 v[6:7], v[8:9], 0, v[6:7]
	global_store_dwordx4 v[6:7], v[2:5], off
	s_waitcnt lgkmcnt(3)
	s_nop 0
	v_mul_f32_e32 v2, 0x3fb8aa3b, v248
	v_mul_f32_e32 v3, 0x3fb8aa3b, v249
	v_cvt_pk_bf16_f32 v2, v2, v3
	s_waitcnt lgkmcnt(2)
	v_mul_f32_e32 v3, 0x3fb8aa3b, v250
	v_mul_f32_e32 v4, 0x3fb8aa3b, v251
	v_cvt_pk_bf16_f32 v3, v3, v4
	s_waitcnt lgkmcnt(1)
	v_mul_f32_e32 v4, 0x3fb8aa3b, v252
	v_mul_f32_e32 v5, 0x3fb8aa3b, v253
	v_cvt_pk_bf16_f32 v4, v4, v5
	s_waitcnt lgkmcnt(0)
	v_mul_f32_e32 v5, 0x3fb8aa3b, v254
	v_mul_f32_e32 v6, 0x3fb8aa3b, v255
	v_cvt_pk_bf16_f32 v5, v5, v6
	v_or_b32_e32 v6, s23, v113
	v_ashrrev_i32_e32 v7, 31, v6
	v_lshlrev_b64 v[6:7], 13, v[6:7]
	v_lshl_add_u64 v[6:7], v[8:9], 0, v[6:7]
	global_store_dwordx4 v[6:7], v[2:5], off
	s_waitcnt lgkmcnt(0)
	s_mul_hi_i32 s23, s5, 0x2fa0be83
	s_lshr_b32 s24, s23, 31
	s_ashr_i32 s23, s23, 6
	s_add_i32 s23, s23, s24
	s_mul_i32 s24, s23, 0x158
	v_lshl_or_b32 v2, s23, 6, v108
	s_sub_i32 s26, s5, s24
	v_mad_i64_i32 v[2:3], s[24:25], v2, s20, v[106:107]
	s_lshl_b32 s24, s26, 5
	s_ashr_i32 s25, s24, 31
	v_lshl_add_u64 v[2:3], s[24:25], 2, v[2:3]
	v_lshl_add_u64 v[34:35], v[2:3], 0, v[98:99]
	v_add_co_u32_e32 v2, vcc, s12, v34
	s_nop 1
	v_addc_co_u32_e32 v3, vcc, 0, v35, vcc
	v_add_co_u32_e32 v6, vcc, s13, v34
	global_load_dwordx4 v[30:33], v[34:35], off nt
	s_nop 0
	global_load_dwordx4 v[2:5], v[2:3], off nt
	v_addc_co_u32_e32 v7, vcc, 0, v35, vcc
	v_add_co_u32_e32 v10, vcc, s14, v34
	s_nop 1
	v_addc_co_u32_e32 v11, vcc, 0, v35, vcc
	v_add_co_u32_e32 v14, vcc, s15, v34
	global_load_dwordx4 v[6:9], v[6:7], off nt
	s_nop 0
	global_load_dwordx4 v[10:13], v[10:11], off nt
	v_addc_co_u32_e32 v15, vcc, 0, v35, vcc
	v_add_co_u32_e32 v26, vcc, s16, v34
	s_nop 1
	v_addc_co_u32_e32 v27, vcc, 0, v35, vcc
	v_add_co_u32_e32 v36, vcc, s17, v34
	global_load_dwordx4 v[14:17], v[14:15], off nt
	s_nop 0
	global_load_dwordx4 v[26:29], v[26:27], off nt
	v_addc_co_u32_e32 v37, vcc, 0, v35, vcc
	v_add_co_u32_e32 v42, vcc, s18, v34
	s_nop 1
	v_addc_co_u32_e32 v43, vcc, 0, v35, vcc
	global_load_dwordx4 v[34:37], v[36:37], off nt
	s_nop 0
	global_load_dwordx4 v[42:45], v[42:43], off nt
	ds_write2_b32 v101, v18, v19 offset1:1
	ds_write2_b32 v101, v20, v21 offset0:2 offset1:3
	ds_write2_b32 v115, v22, v23 offset1:1
	ds_write2_b32 v116, v24, v25 offset1:1
	ds_write2_b32 v117, v38, v39 offset1:1
	ds_write2_b32 v118, v40, v41 offset1:1
	ds_write2_b32 v119, v46, v47 offset1:1
	ds_write2_b32 v120, v48, v49 offset1:1
	ds_write2_b32 v121, v50, v51 offset1:1
	ds_write2_b32 v122, v52, v53 offset1:1
	ds_write2_b32 v123, v54, v55 offset1:1
	ds_write2_b32 v124, v56, v57 offset1:1
	ds_write2_b32 v125, v58, v59 offset1:1
	ds_write2_b32 v126, v60, v61 offset1:1
	ds_write2_b32 v127, v62, v63 offset1:1
	ds_write2_b32 v128, v64, v65 offset1:1
	s_waitcnt lgkmcnt(0)
	ds_read2_b32 v[240:241], v114 offset1:33
	ds_read2_b32 v[242:243], v114 offset0:66 offset1:99
	ds_read2_b32 v[244:245], v114 offset0:132 offset1:165
	ds_read2_b32 v[246:247], v114 offset0:198 offset1:231
	ds_read2_b32 v[248:249], v114 offset0:8 offset1:41
	ds_read2_b32 v[250:251], v114 offset0:74 offset1:107
	ds_read2_b32 v[252:253], v114 offset0:140 offset1:173
	ds_read2_b32 v[254:255], v114 offset0:206 offset1:239
	s_mul_hi_i32 s23, s3, 0x2fa0be83
	s_lshr_b32 s24, s23, 31
	s_ashr_i32 s23, s23, 6
	s_add_i32 s23, s23, s24
	s_waitcnt lgkmcnt(7)
	v_mul_f32_e32 v18, 0x3fb8aa3b, v240
	v_mul_f32_e32 v19, 0x3fb8aa3b, v241
	v_cvt_pk_bf16_f32 v18, v18, v19
	ds_read2_b32 v[240:241], v114 offset0:16 offset1:49
	s_mul_i32 s24, s23, 0x158
	s_sub_i32 s3, s3, s24
	s_lshl_b32 s24, s3, 5
	s_lshl_b32 s3, s3, 6
	s_waitcnt lgkmcnt(7)
	v_mul_f32_e32 v19, 0x3fb8aa3b, v242
	v_mul_f32_e32 v20, 0x3fb8aa3b, v243
	v_cvt_pk_bf16_f32 v19, v19, v20
	ds_read2_b32 v[242:243], v114 offset0:82 offset1:115
	s_and_b32 s3, s3, 0xffffff00
	s_and_b32 s24, s24, 0x60
	s_or_b32 s3, s24, s3
	s_lshl_b32 s24, s23, 6
	s_waitcnt lgkmcnt(7)
	v_mul_f32_e32 v20, 0x3fb8aa3b, v244
	v_mul_f32_e32 v21, 0x3fb8aa3b, v245
	v_cvt_pk_bf16_f32 v20, v20, v21
	ds_read2_b32 v[244:245], v114 offset0:148 offset1:181
	s_ashr_i32 s25, s24, 31
	v_lshl_add_u64 v[24:25], s[24:25], 1, v[102:103]
	s_waitcnt lgkmcnt(7)
	v_mul_f32_e32 v21, 0x3fb8aa3b, v246
	v_mul_f32_e32 v22, 0x3fb8aa3b, v247
	v_cvt_pk_bf16_f32 v21, v21, v22
	ds_read2_b32 v[246:247], v114 offset0:214 offset1:247
	v_or_b32_e32 v22, s3, v108
	v_ashrrev_i32_e32 v23, 31, v22
	v_lshlrev_b64 v[22:23], 13, v[22:23]
	v_lshl_add_u64 v[22:23], v[24:25], 0, v[22:23]
	global_store_dwordx4 v[22:23], v[18:21], off
	s_waitcnt lgkmcnt(7)
	s_nop 0
	v_mul_f32_e32 v18, 0x3fb8aa3b, v248
	v_mul_f32_e32 v19, 0x3fb8aa3b, v249
	v_cvt_pk_bf16_f32 v18, v18, v19
	ds_read2_b32 v[248:249], v114 offset0:24 offset1:57
	s_waitcnt lgkmcnt(7)
	v_mul_f32_e32 v19, 0x3fb8aa3b, v250
	v_mul_f32_e32 v20, 0x3fb8aa3b, v251
	v_cvt_pk_bf16_f32 v19, v19, v20
	ds_read2_b32 v[250:251], v114 offset0:90 offset1:123
	s_waitcnt lgkmcnt(7)
	v_mul_f32_e32 v20, 0x3fb8aa3b, v252
	v_mul_f32_e32 v21, 0x3fb8aa3b, v253
	v_cvt_pk_bf16_f32 v20, v20, v21
	ds_read2_b32 v[252:253], v114 offset0:156 offset1:189
	s_waitcnt lgkmcnt(7)
; __device__ __forceinline__ unsigned cvt_pk_bf16(float lo, float hi) { unsigned r; asm volatile("v_cvt_pk_bf16_f32 %0, %1, %2" : "=v"(r) : "v"(lo), "v"(hi)); return r; }
; #define LAS __attribute__((address_space(3)))
; #define LDS_WAIT() asm volatile("s_waitcnt lgkmcnt(0)" ::: "memory")
; __device__ __forceinline__ void p0_item_load(const float* __restrict__ W, int N, int nblk, int nb0, int item, int lane, f32x4 (&v)[8]) {
;     const int kb = item / nblk, nb = nb0 + item % nblk;
;     const float* src = W + (size_t)(64 * kb + (lane >> 3)) * N + 32 * nb + 4 * (lane & 7);
; #pragma unroll
;     for (int i = 0; i < 8; ++i) v[i] = __builtin_nontemporal_load((const f32x4*)(src + (size_t)(8 * i) * N));
; }
; __device__ __forceinline__ void p0_item_store(const f32x4 (&v)[8], int K, int nblk, int nb0, bf16* __restrict__ WT, int mode, LAS float* scr, int item, int lane) {
;     const int kb = item / nblk, nb = nb0 + item % nblk, k0 = 64 * kb, n0 = 32 * nb;
; #pragma unroll
;     for (int i = 0; i < 8; ++i) { LAS float* d = scr + (8 * i + (lane >> 3)) * 33 + 4 * (lane & 7); d[0] = v[i].x; d[1] = v[i].y; d[2] = v[i].z; d[3] = v[i].w; }
;     LDS_WAIT(); asm volatile("" ::: "memory");
;     const int c = lane & 7, r0 = map_row(n0, mode);
;     const float wsc = mode == 1 ? 1.44269504089f : (mode == 2 ? 0.69314718056f : 1.0f);
; #pragma unroll
;     for (int j = 0; j < 4; ++j) { const int n = (lane >> 3) + 8 * j; const LAS float* s = scr + (8 * c) * 33 + n;
;         v4u o; o.x = cvt_pk_bf16(s[0 * 33] * wsc, s[1 * 33] * wsc); o.y = cvt_pk_bf16(s[2 * 33] * wsc, s[3 * 33] * wsc); o.z = cvt_pk_bf16(s[4 * 33] * wsc, s[5 * 33] * wsc); o.w = cvt_pk_bf16(s[6 * 33] * wsc, s[7 * 33] * wsc);
;         *(v4u*)(WT + (size_t)(r0 + n) * K + k0 + 8 * c) = o; }
;     LDS_WAIT(); asm volatile("" ::: "memory");
; }
	v_mul_f32_e32 v21, 0x3fb8aa3b, v254
	v_mul_f32_e32 v22, 0x3fb8aa3b, v255
	v_cvt_pk_bf16_f32 v21, v21, v22
	ds_read2_b32 v[254:255], v114 offset0:222 offset1:255
	v_or_b32_e32 v22, s3, v111
	v_ashrrev_i32_e32 v23, 31, v22
	v_lshlrev_b64 v[22:23], 13, v[22:23]
	v_lshl_add_u64 v[22:23], v[24:25], 0, v[22:23]
	global_store_dwordx4 v[22:23], v[18:21], off
	s_waitcnt lgkmcnt(7)
	s_nop 0
	v_mul_f32_e32 v18, 0x3fb8aa3b, v240
	v_mul_f32_e32 v19, 0x3fb8aa3b, v241
	v_cvt_pk_bf16_f32 v18, v18, v19
	s_waitcnt lgkmcnt(6)
	v_mul_f32_e32 v19, 0x3fb8aa3b, v242
	v_mul_f32_e32 v20, 0x3fb8aa3b, v243
	v_cvt_pk_bf16_f32 v19, v19, v20
	s_waitcnt lgkmcnt(5)
	v_mul_f32_e32 v20, 0x3fb8aa3b, v244
	v_mul_f32_e32 v21, 0x3fb8aa3b, v245
	v_cvt_pk_bf16_f32 v20, v20, v21
	s_waitcnt lgkmcnt(4)
	v_mul_f32_e32 v21, 0x3fb8aa3b, v246
	v_mul_f32_e32 v22, 0x3fb8aa3b, v247
	v_cvt_pk_bf16_f32 v21, v21, v22
	v_or_b32_e32 v22, s3, v112
	v_ashrrev_i32_e32 v23, 31, v22
	v_lshlrev_b64 v[22:23], 13, v[22:23]
	v_lshl_add_u64 v[22:23], v[24:25], 0, v[22:23]
	global_store_dwordx4 v[22:23], v[18:21], off
	s_waitcnt lgkmcnt(3)
	s_nop 0
	v_mul_f32_e32 v18, 0x3fb8aa3b, v248
	v_mul_f32_e32 v19, 0x3fb8aa3b, v249
	v_cvt_pk_bf16_f32 v18, v18, v19
	s_waitcnt lgkmcnt(2)
	v_mul_f32_e32 v19, 0x3fb8aa3b, v250
	v_mul_f32_e32 v20, 0x3fb8aa3b, v251
	v_cvt_pk_bf16_f32 v19, v19, v20
	s_waitcnt lgkmcnt(1)
	v_mul_f32_e32 v20, 0x3fb8aa3b, v252
	v_mul_f32_e32 v21, 0x3fb8aa3b, v253
	v_cvt_pk_bf16_f32 v20, v20, v21
	s_waitcnt lgkmcnt(0)
	v_mul_f32_e32 v21, 0x3fb8aa3b, v254
	v_mul_f32_e32 v22, 0x3fb8aa3b, v255
	v_cvt_pk_bf16_f32 v21, v21, v22
	v_or_b32_e32 v22, s3, v113
	v_ashrrev_i32_e32 v23, 31, v22
	v_lshlrev_b64 v[22:23], 13, v[22:23]
	v_lshl_add_u64 v[22:23], v[24:25], 0, v[22:23]
	global_store_dwordx4 v[22:23], v[18:21], off
	s_waitcnt lgkmcnt(0)
	s_mul_hi_i32 s3, s21, 0x2fa0be83
	s_lshr_b32 s23, s3, 31
	s_ashr_i32 s3, s3, 6
	s_add_i32 s3, s3, s23
	s_mul_i32 s23, s3, 0x158
	v_lshl_or_b32 v18, s3, 6, v108
	s_sub_i32 s23, s21, s23
	v_mad_i64_i32 v[18:19], s[24:25], v18, s20, v[106:107]
	s_lshl_b32 s24, s23, 5
	s_ashr_i32 s25, s24, 31
	v_lshl_add_u64 v[18:19], s[24:25], 2, v[18:19]
	v_lshl_add_u64 v[58:59], v[18:19], 0, v[98:99]
	v_add_co_u32_e32 v22, vcc, s12, v58
	s_nop 1
	v_addc_co_u32_e32 v23, vcc, 0, v59, vcc
	v_add_co_u32_e32 v38, vcc, s13, v58
	global_load_dwordx4 v[18:21], v[58:59], off nt
	s_nop 0
	global_load_dwordx4 v[22:25], v[22:23], off nt
	v_addc_co_u32_e32 v39, vcc, 0, v59, vcc
	v_add_co_u32_e32 v46, vcc, s14, v58
	s_nop 1
	v_addc_co_u32_e32 v47, vcc, 0, v59, vcc
	v_add_co_u32_e32 v50, vcc, s15, v58
	global_load_dwordx4 v[38:41], v[38:39], off nt
	s_nop 0
	global_load_dwordx4 v[46:49], v[46:47], off nt
	v_addc_co_u32_e32 v51, vcc, 0, v59, vcc
	v_add_co_u32_e32 v54, vcc, s16, v58
	s_nop 1
	v_addc_co_u32_e32 v55, vcc, 0, v59, vcc
	v_add_co_u32_e32 v60, vcc, s17, v58
	global_load_dwordx4 v[50:53], v[50:51], off nt
	s_nop 0
	global_load_dwordx4 v[54:57], v[54:55], off nt
	v_addc_co_u32_e32 v61, vcc, 0, v59, vcc
	v_add_co_u32_e32 v62, vcc, s18, v58
	s_nop 1
	v_addc_co_u32_e32 v63, vcc, 0, v59, vcc
	global_load_dwordx4 v[58:61], v[60:61], off nt
	s_nop 0
	global_load_dwordx4 v[62:65], v[62:63], off nt
	ds_write2_b32 v101, v66, v67 offset1:1
	ds_write2_b32 v101, v68, v69 offset0:2 offset1:3
	ds_write2_b32 v115, v70, v71 offset1:1
	ds_write2_b32 v116, v72, v73 offset1:1
	ds_write2_b32 v117, v74, v75 offset1:1
	ds_write2_b32 v118, v76, v77 offset1:1
	ds_write2_b32 v119, v78, v79 offset1:1
	ds_write2_b32 v120, v80, v81 offset1:1
	ds_write2_b32 v121, v82, v83 offset1:1
	ds_write2_b32 v122, v84, v85 offset1:1
	ds_write2_b32 v123, v86, v87 offset1:1
	ds_write2_b32 v124, v88, v89 offset1:1
	ds_write2_b32 v125, v90, v91 offset1:1
	ds_write2_b32 v126, v92, v93 offset1:1
	ds_write2_b32 v127, v94, v95 offset1:1
	ds_write2_b32 v128, v96, v97 offset1:1
	s_waitcnt lgkmcnt(0)
; __device__ __forceinline__ unsigned cvt_pk_bf16(float lo, float hi) { unsigned r; asm volatile("v_cvt_pk_bf16_f32 %0, %1, %2" : "=v"(r) : "v"(lo), "v"(hi)); return r; }
; #define LAS __attribute__((address_space(3)))
; #define LDS_WAIT() asm volatile("s_waitcnt lgkmcnt(0)" ::: "memory")
; __device__ __forceinline__ void p0_item_load(const float* __restrict__ W, int N, int nblk, int nb0, int item, int lane, f32x4 (&v)[8]) {
;     const int kb = item / nblk, nb = nb0 + item % nblk;
;     const float* src = W + (size_t)(64 * kb + (lane >> 3)) * N + 32 * nb + 4 * (lane & 7);
; #pragma unroll
;     for (int i = 0; i < 8; ++i) v[i] = __builtin_nontemporal_load((const f32x4*)(src + (size_t)(8 * i) * N));
; }
; __device__ __forceinline__ void p0_item_store(const f32x4 (&v)[8], int K, int nblk, int nb0, bf16* __restrict__ WT, int mode, LAS float* scr, int item, int lane) {
;     const int kb = item / nblk, nb = nb0 + item % nblk, k0 = 64 * kb, n0 = 32 * nb;
; #pragma unroll
;     for (int i = 0; i < 8; ++i) { LAS float* d = scr + (8 * i + (lane >> 3)) * 33 + 4 * (lane & 7); d[0] = v[i].x; d[1] = v[i].y; d[2] = v[i].z; d[3] = v[i].w; }
;     LDS_WAIT(); asm volatile("" ::: "memory");
;     const int c = lane & 7, r0 = map_row(n0, mode);
;     const float wsc = mode == 1 ? 1.44269504089f : (mode == 2 ? 0.69314718056f : 1.0f);
; #pragma unroll
;     for (int j = 0; j < 4; ++j) { const int n = (lane >> 3) + 8 * j; const LAS float* s = scr + (8 * c) * 33 + n;
;         v4u o; o.x = cvt_pk_bf16(s[0 * 33] * wsc, s[1 * 33] * wsc); o.y = cvt_pk_bf16(s[2 * 33] * wsc, s[3 * 33] * wsc); o.z = cvt_pk_bf16(s[4 * 33] * wsc, s[5 * 33] * wsc); o.w = cvt_pk_bf16(s[6 * 33] * wsc, s[7 * 33] * wsc);
;         *(v4u*)(WT + (size_t)(r0 + n) * K + k0 + 8 * c) = o; }
;     LDS_WAIT(); asm volatile("" ::: "memory");
; }
	ds_read2_b32 v[240:241], v114 offset1:33
	ds_read2_b32 v[242:243], v114 offset0:66 offset1:99
	ds_read2_b32 v[244:245], v114 offset0:132 offset1:165
	ds_read2_b32 v[246:247], v114 offset0:198 offset1:231
	ds_read2_b32 v[248:249], v114 offset0:8 offset1:41
	ds_read2_b32 v[250:251], v114 offset0:74 offset1:107
	ds_read2_b32 v[252:253], v114 offset0:140 offset1:173
	ds_read2_b32 v[254:255], v114 offset0:206 offset1:239
	s_lshl_b32 s3, s22, 6
	s_and_b32 s3, s3, 0xffffff00
	s_and_b32 s4, s4, 0x60
	s_or_b32 s4, s4, s3
	s_waitcnt lgkmcnt(7)
	v_mul_f32_e32 v66, 0x3fb8aa3b, v240
	v_mul_f32_e32 v67, 0x3fb8aa3b, v241
	v_cvt_pk_bf16_f32 v66, v66, v67
	ds_read2_b32 v[240:241], v114 offset0:16 offset1:49
	s_ashr_i32 s3, s2, 31
	v_lshl_add_u64 v[72:73], s[2:3], 1, v[102:103]
	s_waitcnt lgkmcnt(7)
	v_mul_f32_e32 v67, 0x3fb8aa3b, v242
	v_mul_f32_e32 v68, 0x3fb8aa3b, v243
	v_cvt_pk_bf16_f32 v67, v67, v68
	ds_read2_b32 v[242:243], v114 offset0:82 offset1:115
	s_waitcnt lgkmcnt(7)
	v_mul_f32_e32 v68, 0x3fb8aa3b, v244
	v_mul_f32_e32 v69, 0x3fb8aa3b, v245
	v_cvt_pk_bf16_f32 v68, v68, v69
	ds_read2_b32 v[244:245], v114 offset0:148 offset1:181
	s_waitcnt lgkmcnt(7)
	v_mul_f32_e32 v69, 0x3fb8aa3b, v246
	v_mul_f32_e32 v70, 0x3fb8aa3b, v247
	v_cvt_pk_bf16_f32 v69, v69, v70
	ds_read2_b32 v[246:247], v114 offset0:214 offset1:247
	v_or_b32_e32 v70, s4, v108
	v_ashrrev_i32_e32 v71, 31, v70
	v_lshlrev_b64 v[70:71], 13, v[70:71]
	v_lshl_add_u64 v[70:71], v[72:73], 0, v[70:71]
	global_store_dwordx4 v[70:71], v[66:69], off
	s_waitcnt lgkmcnt(7)
	s_nop 0
	v_mul_f32_e32 v66, 0x3fb8aa3b, v248
	v_mul_f32_e32 v67, 0x3fb8aa3b, v249
	v_cvt_pk_bf16_f32 v66, v66, v67
	ds_read2_b32 v[248:249], v114 offset0:24 offset1:57
	s_waitcnt lgkmcnt(7)
	v_mul_f32_e32 v67, 0x3fb8aa3b, v250
	v_mul_f32_e32 v68, 0x3fb8aa3b, v251
	v_cvt_pk_bf16_f32 v67, v67, v68
	ds_read2_b32 v[250:251], v114 offset0:90 offset1:123
	s_waitcnt lgkmcnt(7)
	v_mul_f32_e32 v68, 0x3fb8aa3b, v252
	v_mul_f32_e32 v69, 0x3fb8aa3b, v253
	v_cvt_pk_bf16_f32 v68, v68, v69
	ds_read2_b32 v[252:253], v114 offset0:156 offset1:189
	s_waitcnt lgkmcnt(7)
	v_mul_f32_e32 v69, 0x3fb8aa3b, v254
	v_mul_f32_e32 v70, 0x3fb8aa3b, v255
	v_cvt_pk_bf16_f32 v69, v69, v70
	ds_read2_b32 v[254:255], v114 offset0:222 offset1:255
	v_or_b32_e32 v70, s4, v111
	v_ashrrev_i32_e32 v71, 31, v70
	v_lshlrev_b64 v[70:71], 13, v[70:71]
	v_lshl_add_u64 v[70:71], v[72:73], 0, v[70:71]
	global_store_dwordx4 v[70:71], v[66:69], off
	s_waitcnt lgkmcnt(7)
	s_nop 0
	v_mul_f32_e32 v66, 0x3fb8aa3b, v240
	v_mul_f32_e32 v67, 0x3fb8aa3b, v241
	v_cvt_pk_bf16_f32 v66, v66, v67
	s_waitcnt lgkmcnt(6)
	v_mul_f32_e32 v67, 0x3fb8aa3b, v242
	v_mul_f32_e32 v68, 0x3fb8aa3b, v243
	v_cvt_pk_bf16_f32 v67, v67, v68
	s_waitcnt lgkmcnt(5)
	v_mul_f32_e32 v68, 0x3fb8aa3b, v244
	v_mul_f32_e32 v69, 0x3fb8aa3b, v245
	v_cvt_pk_bf16_f32 v68, v68, v69
	s_waitcnt lgkmcnt(4)
	v_mul_f32_e32 v69, 0x3fb8aa3b, v246
	v_mul_f32_e32 v70, 0x3fb8aa3b, v247
	v_cvt_pk_bf16_f32 v69, v69, v70
	v_or_b32_e32 v70, s4, v112
	v_ashrrev_i32_e32 v71, 31, v70
	v_lshlrev_b64 v[70:71], 13, v[70:71]
	v_lshl_add_u64 v[70:71], v[72:73], 0, v[70:71]
	global_store_dwordx4 v[70:71], v[66:69], off
	s_waitcnt lgkmcnt(3)
	s_nop 0
	v_mul_f32_e32 v66, 0x3fb8aa3b, v248
	v_mul_f32_e32 v67, 0x3fb8aa3b, v249
	v_cvt_pk_bf16_f32 v66, v66, v67
	s_waitcnt lgkmcnt(2)
	v_mul_f32_e32 v67, 0x3fb8aa3b, v250
	v_mul_f32_e32 v68, 0x3fb8aa3b, v251
	v_cvt_pk_bf16_f32 v67, v67, v68
	s_waitcnt lgkmcnt(1)
	v_mul_f32_e32 v68, 0x3fb8aa3b, v252
	v_mul_f32_e32 v69, 0x3fb8aa3b, v253
	v_cvt_pk_bf16_f32 v68, v68, v69
	s_waitcnt lgkmcnt(0)
	v_mul_f32_e32 v69, 0x3fb8aa3b, v254
	v_mul_f32_e32 v70, 0x3fb8aa3b, v255
	v_cvt_pk_bf16_f32 v69, v69, v70
	v_or_b32_e32 v70, s4, v113
	v_ashrrev_i32_e32 v71, 31, v70
	v_lshlrev_b64 v[70:71], 13, v[70:71]
	v_lshl_add_u64 v[70:71], v[72:73], 0, v[70:71]
	global_store_dwordx4 v[70:71], v[66:69], off
	s_waitcnt lgkmcnt(0)
	s_add_i32 s19, s19, -1
	s_cmp_lg_u32 s19, 0
	s_mov_b32 s23, s5
	s_mov_b32 s3, s21
	s_cbranch_scc1 .LBB0_473

; __device__ __forceinline__ unsigned cvt_pk_bf16(float lo, float hi) { unsigned r; asm volatile("v_cvt_pk_bf16_f32 %0, %1, %2" : "=v"(r) : "v"(lo), "v"(hi)); return r; }
; #define LAS __attribute__((address_space(3)))
; #define LDS_WAIT() asm volatile("s_waitcnt lgkmcnt(0)" ::: "memory")
; __device__ __forceinline__ void p0_item_load(const float* __restrict__ W, int N, int nblk, int nb0, int item, int lane, f32x4 (&v)[8]) {
;     const int kb = item / nblk, nb = nb0 + item % nblk;
;     const float* src = W + (size_t)(64 * kb + (lane >> 3)) * N + 32 * nb + 4 * (lane & 7);
; #pragma unroll
;     for (int i = 0; i < 8; ++i) v[i] = __builtin_nontemporal_load((const f32x4*)(src + (size_t)(8 * i) * N));
; }
; __device__ __forceinline__ void p0_item_store(const f32x4 (&v)[8], int K, int nblk, int nb0, bf16* __restrict__ WT, int mode, LAS float* scr, int item, int lane) {
;     const int kb = item / nblk, nb = nb0 + item % nblk, k0 = 64 * kb, n0 = 32 * nb;
; #pragma unroll
;     for (int i = 0; i < 8; ++i) { LAS float* d = scr + (8 * i + (lane >> 3)) * 33 + 4 * (lane & 7); d[0] = v[i].x; d[1] = v[i].y; d[2] = v[i].z; d[3] = v[i].w; }
;     LDS_WAIT(); asm volatile("" ::: "memory");
;     const int c = lane & 7, r0 = map_row(n0, mode);
;     const float wsc = mode == 1 ? 1.44269504089f : (mode == 2 ? 0.69314718056f : 1.0f);
; #pragma unroll
;     for (int j = 0; j < 4; ++j) { const int n = (lane >> 3) + 8 * j; const LAS float* s = scr + (8 * c) * 33 + n;
;         v4u o; o.x = cvt_pk_bf16(s[0 * 33] * wsc, s[1 * 33] * wsc); o.y = cvt_pk_bf16(s[2 * 33] * wsc, s[3 * 33] * wsc); o.z = cvt_pk_bf16(s[4 * 33] * wsc, s[5 * 33] * wsc); o.w = cvt_pk_bf16(s[6 * 33] * wsc, s[7 * 33] * wsc);
;         *(v4u*)(WT + (size_t)(r0 + n) * K + k0 + 8 * c) = o; }
;     LDS_WAIT(); asm volatile("" ::: "memory");
; }
.LBB0_477:
	s_add_i32 s0, s19, s8
	s_min_i32 s20, s0, 0x55ff
	s_mul_hi_i32 s0, s20, 0x2fa0be83
	s_lshr_b32 s1, s0, 31
	s_ashr_i32 s0, s0, 6
	s_add_i32 s0, s0, s1
	s_mul_i32 s1, s0, 0x158
	s_lshl_b32 s0, s0, 6
	v_or_b32_e32 v66, s0, v108
	v_mov_b64_e32 v[104:105], s[28:29]
	s_sub_i32 s1, s20, s1
	v_mad_i64_i32 v[66:67], s[2:3], v66, s4, v[104:105]
	s_lshl_b32 s2, s1, 5
	s_ashr_i32 s3, s2, 31
	v_lshl_add_u64 v[66:67], s[2:3], 2, v[66:67]
	v_lshl_add_u64 v[90:91], v[66:67], 0, v[98:99]
	v_add_co_u32_e32 v70, vcc, s5, v90
	s_add_i32 s20, s20, s8
	s_nop 0
	v_addc_co_u32_e32 v71, vcc, 0, v91, vcc
	v_add_co_u32_e32 v74, vcc, s12, v90
	global_load_dwordx4 v[66:69], v[90:91], off nt
	s_nop 0
	global_load_dwordx4 v[70:73], v[70:71], off nt
	v_addc_co_u32_e32 v75, vcc, 0, v91, vcc
	v_add_co_u32_e32 v78, vcc, s13, v90
	s_min_i32 s3, s20, 0x55ff
	s_nop 0
	v_addc_co_u32_e32 v79, vcc, 0, v91, vcc
	v_add_co_u32_e32 v82, vcc, s14, v90
	global_load_dwordx4 v[74:77], v[74:75], off nt
	s_nop 0
	global_load_dwordx4 v[78:81], v[78:79], off nt
	v_addc_co_u32_e32 v83, vcc, 0, v91, vcc
	v_add_co_u32_e32 v86, vcc, s15, v90
	s_add_i32 s20, s3, s8
	s_nop 0
	v_addc_co_u32_e32 v87, vcc, 0, v91, vcc
	v_add_co_u32_e32 v92, vcc, s16, v90
	global_load_dwordx4 v[82:85], v[82:83], off nt
	s_nop 0
	global_load_dwordx4 v[86:89], v[86:87], off nt
	v_addc_co_u32_e32 v93, vcc, 0, v91, vcc
	v_add_co_u32_e32 v94, vcc, s17, v90
	s_min_i32 s20, s20, 0x55ff
	s_nop 0
	v_addc_co_u32_e32 v95, vcc, 0, v91, vcc
	global_load_dwordx4 v[90:93], v[92:93], off nt
	s_nop 0
	global_load_dwordx4 v[94:97], v[94:95], off nt
	v_add_u32_e32 v101, v109, v110
	v_add_u32_e32 v106, 0x420, v101
	v_add_u32_e32 v107, 0x428, v101
	v_add_u32_e32 v115, 0x840, v101
	v_add_u32_e32 v116, 0x848, v101
	v_add_u32_e32 v117, 0xc60, v101
	v_add_u32_e32 v118, 0xc68, v101
	v_add_u32_e32 v119, 0x1080, v101
	v_add_u32_e32 v120, 0x1088, v101
	v_add_u32_e32 v121, 0x14a0, v101
	v_add_u32_e32 v122, 0x14a8, v101
	v_add_u32_e32 v123, 0x18c0, v101
	v_add_u32_e32 v124, 0x18c8, v101
	v_add_u32_e32 v125, 0x1ce0, v101
	v_add_u32_e32 v126, 0x1ce8, v101
	s_waitcnt vmcnt(0)
	ds_write2_b32 v101, v30, v31 offset1:1
	ds_write2_b32 v101, v32, v33 offset0:2 offset1:3
	ds_write2_b32 v106, v2, v3 offset1:1
	ds_write2_b32 v107, v4, v5 offset1:1
	ds_write2_b32 v115, v6, v7 offset1:1
	ds_write2_b32 v116, v8, v9 offset1:1
	ds_write2_b32 v117, v10, v11 offset1:1
	ds_write2_b32 v118, v12, v13 offset1:1
	ds_write2_b32 v119, v14, v15 offset1:1
	ds_write2_b32 v120, v16, v17 offset1:1
	ds_write2_b32 v121, v26, v27 offset1:1
	ds_write2_b32 v122, v28, v29 offset1:1
	ds_write2_b32 v123, v34, v35 offset1:1
	ds_write2_b32 v124, v36, v37 offset1:1
	ds_write2_b32 v125, v42, v43 offset1:1
	ds_write2_b32 v126, v44, v45 offset1:1
	s_waitcnt lgkmcnt(0)
	ds_read2_b32 v[240:241], v114 offset1:33
	ds_read2_b32 v[242:243], v114 offset0:66 offset1:99
	ds_read2_b32 v[244:245], v114 offset0:132 offset1:165
	ds_read2_b32 v[246:247], v114 offset0:198 offset1:231
	ds_read2_b32 v[248:249], v114 offset0:8 offset1:41
	ds_read2_b32 v[250:251], v114 offset0:74 offset1:107
	ds_read2_b32 v[252:253], v114 offset0:140 offset1:173
	ds_read2_b32 v[254:255], v114 offset0:206 offset1:239
	s_mul_hi_i32 s22, s21, 0x2fa0be83
	s_lshr_b32 s23, s22, 31
	s_ashr_i32 s22, s22, 6
	s_add_i32 s22, s22, s23
	s_waitcnt lgkmcnt(7)
	v_mul_f32_e32 v2, 0x3f317218, v240
	v_mul_f32_e32 v3, 0x3f317218, v241
	v_cvt_pk_bf16_f32 v2, v2, v3
	ds_read2_b32 v[240:241], v114 offset0:16 offset1:49
	s_mul_i32 s23, s22, 0x158
	s_sub_i32 s21, s21, s23
	s_lshl_b32 s23, s21, 5
	s_lshl_b32 s21, s21, 6
	s_waitcnt lgkmcnt(7)
	v_mul_f32_e32 v3, 0x3f317218, v242
	v_mul_f32_e32 v4, 0x3f317218, v243
	v_cvt_pk_bf16_f32 v3, v3, v4
	ds_read2_b32 v[242:243], v114 offset0:82 offset1:115
	s_and_b32 s21, s21, 0xffffff00
	s_or_b32 s23, s23, 0xffffff80
	s_add_i32 s21, s23, s21
	s_addk_i32 s21, 0x100
	s_waitcnt lgkmcnt(7)
	v_mul_f32_e32 v4, 0x3f317218, v244
	v_mul_f32_e32 v5, 0x3f317218, v245
	v_cvt_pk_bf16_f32 v4, v4, v5
	ds_read2_b32 v[244:245], v114 offset0:148 offset1:181
	s_lshl_b32 s22, s22, 6
	s_ashr_i32 s23, s22, 31
	v_lshl_add_u64 v[8:9], s[22:23], 1, v[102:103]
	s_waitcnt lgkmcnt(7)
	v_mul_f32_e32 v5, 0x3f317218, v246
	v_mul_f32_e32 v6, 0x3f317218, v247
	v_cvt_pk_bf16_f32 v5, v5, v6
	ds_read2_b32 v[246:247], v114 offset0:214 offset1:247
	v_or_b32_e32 v6, s21, v108
	v_ashrrev_i32_e32 v7, 31, v6
	v_lshlrev_b64 v[6:7], 13, v[6:7]
	v_lshl_add_u64 v[6:7], v[8:9], 0, v[6:7]
	global_store_dwordx4 v[6:7], v[2:5], off
	s_waitcnt lgkmcnt(7)
	s_nop 0
	v_mul_f32_e32 v2, 0x3f317218, v248
	v_mul_f32_e32 v3, 0x3f317218, v249
	v_cvt_pk_bf16_f32 v2, v2, v3
	ds_read2_b32 v[248:249], v114 offset0:24 offset1:57
	s_waitcnt lgkmcnt(7)
	v_mul_f32_e32 v3, 0x3f317218, v250
	v_mul_f32_e32 v4, 0x3f317218, v251
	v_cvt_pk_bf16_f32 v3, v3, v4
	ds_read2_b32 v[250:251], v114 offset0:90 offset1:123
	s_waitcnt lgkmcnt(7)
	v_mul_f32_e32 v4, 0x3f317218, v252
	v_mul_f32_e32 v5, 0x3f317218, v253
	v_cvt_pk_bf16_f32 v4, v4, v5
	ds_read2_b32 v[252:253], v114 offset0:156 offset1:189
	s_waitcnt lgkmcnt(7)
	v_mul_f32_e32 v5, 0x3f317218, v254
	v_mul_f32_e32 v6, 0x3f317218, v255
	v_cvt_pk_bf16_f32 v5, v5, v6
	ds_read2_b32 v[254:255], v114 offset0:222 offset1:255
	v_or_b32_e32 v6, s21, v111
	v_ashrrev_i32_e32 v7, 31, v6
	v_lshlrev_b64 v[6:7], 13, v[6:7]
	v_lshl_add_u64 v[6:7], v[8:9], 0, v[6:7]
	global_store_dwordx4 v[6:7], v[2:5], off
	s_waitcnt lgkmcnt(7)
	s_nop 0
	v_mul_f32_e32 v2, 0x3f317218, v240
	v_mul_f32_e32 v3, 0x3f317218, v241
	v_cvt_pk_bf16_f32 v2, v2, v3
	s_waitcnt lgkmcnt(6)
	v_mul_f32_e32 v3, 0x3f317218, v242
	v_mul_f32_e32 v4, 0x3f317218, v243
	v_cvt_pk_bf16_f32 v3, v3, v4
	s_waitcnt lgkmcnt(5)
; __device__ __forceinline__ unsigned cvt_pk_bf16(float lo, float hi) { unsigned r; asm volatile("v_cvt_pk_bf16_f32 %0, %1, %2" : "=v"(r) : "v"(lo), "v"(hi)); return r; }
; #define LAS __attribute__((address_space(3)))
; #define LDS_WAIT() asm volatile("s_waitcnt lgkmcnt(0)" ::: "memory")
; __device__ __forceinline__ void p0_item_load(const float* __restrict__ W, int N, int nblk, int nb0, int item, int lane, f32x4 (&v)[8]) {
;     const int kb = item / nblk, nb = nb0 + item % nblk;
;     const float* src = W + (size_t)(64 * kb + (lane >> 3)) * N + 32 * nb + 4 * (lane & 7);
; #pragma unroll
;     for (int i = 0; i < 8; ++i) v[i] = __builtin_nontemporal_load((const f32x4*)(src + (size_t)(8 * i) * N));
; }
; __device__ __forceinline__ void p0_item_store(const f32x4 (&v)[8], int K, int nblk, int nb0, bf16* __restrict__ WT, int mode, LAS float* scr, int item, int lane) {
;     const int kb = item / nblk, nb = nb0 + item % nblk, k0 = 64 * kb, n0 = 32 * nb;
; #pragma unroll
;     for (int i = 0; i < 8; ++i) { LAS float* d = scr + (8 * i + (lane >> 3)) * 33 + 4 * (lane & 7); d[0] = v[i].x; d[1] = v[i].y; d[2] = v[i].z; d[3] = v[i].w; }
;     LDS_WAIT(); asm volatile("" ::: "memory");
;     const int c = lane & 7, r0 = map_row(n0, mode);
;     const float wsc = mode == 1 ? 1.44269504089f : (mode == 2 ? 0.69314718056f : 1.0f);
; #pragma unroll
;     for (int j = 0; j < 4; ++j) { const int n = (lane >> 3) + 8 * j; const LAS float* s = scr + (8 * c) * 33 + n;
;         v4u o; o.x = cvt_pk_bf16(s[0 * 33] * wsc, s[1 * 33] * wsc); o.y = cvt_pk_bf16(s[2 * 33] * wsc, s[3 * 33] * wsc); o.z = cvt_pk_bf16(s[4 * 33] * wsc, s[5 * 33] * wsc); o.w = cvt_pk_bf16(s[6 * 33] * wsc, s[7 * 33] * wsc);
;         *(v4u*)(WT + (size_t)(r0 + n) * K + k0 + 8 * c) = o; }
;     LDS_WAIT(); asm volatile("" ::: "memory");
; }
	v_mul_f32_e32 v4, 0x3f317218, v244
	v_mul_f32_e32 v5, 0x3f317218, v245
	v_cvt_pk_bf16_f32 v4, v4, v5
	s_waitcnt lgkmcnt(4)
	v_mul_f32_e32 v5, 0x3f317218, v246
	v_mul_f32_e32 v6, 0x3f317218, v247
	v_cvt_pk_bf16_f32 v5, v5, v6
	v_or_b32_e32 v6, s21, v112
	v_ashrrev_i32_e32 v7, 31, v6
	v_lshlrev_b64 v[6:7], 13, v[6:7]
	v_lshl_add_u64 v[6:7], v[8:9], 0, v[6:7]
	global_store_dwordx4 v[6:7], v[2:5], off
	s_waitcnt lgkmcnt(3)
	s_nop 0
	v_mul_f32_e32 v2, 0x3f317218, v248
	v_mul_f32_e32 v3, 0x3f317218, v249
	v_cvt_pk_bf16_f32 v2, v2, v3
	s_waitcnt lgkmcnt(2)
	v_mul_f32_e32 v3, 0x3f317218, v250
	v_mul_f32_e32 v4, 0x3f317218, v251
	v_cvt_pk_bf16_f32 v3, v3, v4
	s_waitcnt lgkmcnt(1)
	v_mul_f32_e32 v4, 0x3f317218, v252
	v_mul_f32_e32 v5, 0x3f317218, v253
	v_cvt_pk_bf16_f32 v4, v4, v5
	s_waitcnt lgkmcnt(0)
	v_mul_f32_e32 v5, 0x3f317218, v254
	v_mul_f32_e32 v6, 0x3f317218, v255
	v_cvt_pk_bf16_f32 v5, v5, v6
	v_or_b32_e32 v6, s21, v113
	v_ashrrev_i32_e32 v7, 31, v6
	v_lshlrev_b64 v[6:7], 13, v[6:7]
	v_lshl_add_u64 v[6:7], v[8:9], 0, v[6:7]
	global_store_dwordx4 v[6:7], v[2:5], off
	s_waitcnt lgkmcnt(0)
	s_mul_hi_i32 s21, s3, 0x2fa0be83
	s_lshr_b32 s22, s21, 31
	s_ashr_i32 s21, s21, 6
	s_add_i32 s21, s21, s22
	s_mul_i32 s22, s21, 0x158
	v_lshl_or_b32 v2, s21, 6, v108
	s_sub_i32 s24, s3, s22
	v_mad_i64_i32 v[2:3], s[22:23], v2, s4, v[104:105]
	s_lshl_b32 s22, s24, 5
	s_ashr_i32 s23, s22, 31
	v_lshl_add_u64 v[2:3], s[22:23], 2, v[2:3]
	v_lshl_add_u64 v[34:35], v[2:3], 0, v[98:99]
	v_add_co_u32_e32 v2, vcc, s5, v34
	s_nop 1
	v_addc_co_u32_e32 v3, vcc, 0, v35, vcc
	v_add_co_u32_e32 v6, vcc, s12, v34
	global_load_dwordx4 v[30:33], v[34:35], off nt
	s_nop 0
	global_load_dwordx4 v[2:5], v[2:3], off nt
	v_addc_co_u32_e32 v7, vcc, 0, v35, vcc
	v_add_co_u32_e32 v10, vcc, s13, v34
	s_nop 1
	v_addc_co_u32_e32 v11, vcc, 0, v35, vcc
	v_add_co_u32_e32 v14, vcc, s14, v34
	global_load_dwordx4 v[6:9], v[6:7], off nt
	s_nop 0
	global_load_dwordx4 v[10:13], v[10:11], off nt
	v_addc_co_u32_e32 v15, vcc, 0, v35, vcc
	v_add_co_u32_e32 v26, vcc, s15, v34
	s_nop 1
	v_addc_co_u32_e32 v27, vcc, 0, v35, vcc
	v_add_co_u32_e32 v36, vcc, s16, v34
	global_load_dwordx4 v[14:17], v[14:15], off nt
	s_nop 0
	global_load_dwordx4 v[26:29], v[26:27], off nt
	v_addc_co_u32_e32 v37, vcc, 0, v35, vcc
	v_add_co_u32_e32 v42, vcc, s17, v34
	s_nop 1
	v_addc_co_u32_e32 v43, vcc, 0, v35, vcc
	global_load_dwordx4 v[34:37], v[36:37], off nt
	s_nop 0
	global_load_dwordx4 v[42:45], v[42:43], off nt
	ds_write2_b32 v101, v18, v19 offset1:1
	ds_write2_b32 v101, v20, v21 offset0:2 offset1:3
	ds_write2_b32 v106, v22, v23 offset1:1
	ds_write2_b32 v107, v24, v25 offset1:1
	ds_write2_b32 v115, v38, v39 offset1:1
	ds_write2_b32 v116, v40, v41 offset1:1
	ds_write2_b32 v117, v46, v47 offset1:1
	ds_write2_b32 v118, v48, v49 offset1:1
	ds_write2_b32 v119, v50, v51 offset1:1
	ds_write2_b32 v120, v52, v53 offset1:1
	ds_write2_b32 v121, v54, v55 offset1:1
	ds_write2_b32 v122, v56, v57 offset1:1
	ds_write2_b32 v123, v58, v59 offset1:1
	ds_write2_b32 v124, v60, v61 offset1:1
	ds_write2_b32 v125, v62, v63 offset1:1
	ds_write2_b32 v126, v64, v65 offset1:1
	s_waitcnt lgkmcnt(0)
	ds_read2_b32 v[240:241], v114 offset1:33
	ds_read2_b32 v[242:243], v114 offset0:66 offset1:99
	ds_read2_b32 v[244:245], v114 offset0:132 offset1:165
	ds_read2_b32 v[246:247], v114 offset0:198 offset1:231
	ds_read2_b32 v[248:249], v114 offset0:8 offset1:41
	ds_read2_b32 v[250:251], v114 offset0:74 offset1:107
	ds_read2_b32 v[252:253], v114 offset0:140 offset1:173
	ds_read2_b32 v[254:255], v114 offset0:206 offset1:239
	s_mul_hi_i32 s21, s19, 0x2fa0be83
	s_lshr_b32 s22, s21, 31
	s_ashr_i32 s21, s21, 6
	s_add_i32 s21, s21, s22
	s_waitcnt lgkmcnt(7)
	v_mul_f32_e32 v18, 0x3f317218, v240
	v_mul_f32_e32 v19, 0x3f317218, v241
	v_cvt_pk_bf16_f32 v18, v18, v19
	ds_read2_b32 v[240:241], v114 offset0:16 offset1:49
	s_mul_i32 s22, s21, 0x158
	s_sub_i32 s19, s19, s22
	s_lshl_b32 s22, s19, 5
	s_lshl_b32 s19, s19, 6
	s_waitcnt lgkmcnt(7)
	v_mul_f32_e32 v19, 0x3f317218, v242
	v_mul_f32_e32 v20, 0x3f317218, v243
	v_cvt_pk_bf16_f32 v19, v19, v20
	ds_read2_b32 v[242:243], v114 offset0:82 offset1:115
	s_and_b32 s19, s19, 0xffffff00
	s_or_b32 s22, s22, 0xffffff80
	s_add_i32 s19, s22, s19
	s_addk_i32 s19, 0x100
	s_waitcnt lgkmcnt(7)
	v_mul_f32_e32 v20, 0x3f317218, v244
	v_mul_f32_e32 v21, 0x3f317218, v245
	v_cvt_pk_bf16_f32 v20, v20, v21
	ds_read2_b32 v[244:245], v114 offset0:148 offset1:181
	s_lshl_b32 s22, s21, 6
	s_ashr_i32 s23, s22, 31
	v_lshl_add_u64 v[24:25], s[22:23], 1, v[102:103]
	s_waitcnt lgkmcnt(7)
	v_mul_f32_e32 v21, 0x3f317218, v246
	v_mul_f32_e32 v22, 0x3f317218, v247
	v_cvt_pk_bf16_f32 v21, v21, v22
	ds_read2_b32 v[246:247], v114 offset0:214 offset1:247
	v_or_b32_e32 v22, s19, v108
	v_ashrrev_i32_e32 v23, 31, v22
	v_lshlrev_b64 v[22:23], 13, v[22:23]
	v_lshl_add_u64 v[22:23], v[24:25], 0, v[22:23]
	global_store_dwordx4 v[22:23], v[18:21], off
	s_waitcnt lgkmcnt(7)
	s_nop 0
	v_mul_f32_e32 v18, 0x3f317218, v248
	v_mul_f32_e32 v19, 0x3f317218, v249
	v_cvt_pk_bf16_f32 v18, v18, v19
	ds_read2_b32 v[248:249], v114 offset0:24 offset1:57
	s_waitcnt lgkmcnt(7)
	v_mul_f32_e32 v19, 0x3f317218, v250
	v_mul_f32_e32 v20, 0x3f317218, v251
	v_cvt_pk_bf16_f32 v19, v19, v20
	ds_read2_b32 v[250:251], v114 offset0:90 offset1:123
	s_waitcnt lgkmcnt(7)
	v_mul_f32_e32 v20, 0x3f317218, v252
	v_mul_f32_e32 v21, 0x3f317218, v253
	v_cvt_pk_bf16_f32 v20, v20, v21
	ds_read2_b32 v[252:253], v114 offset0:156 offset1:189
	s_waitcnt lgkmcnt(7)
; __device__ __forceinline__ unsigned cvt_pk_bf16(float lo, float hi) { unsigned r; asm volatile("v_cvt_pk_bf16_f32 %0, %1, %2" : "=v"(r) : "v"(lo), "v"(hi)); return r; }
; #define LAS __attribute__((address_space(3)))
; #define LDS_WAIT() asm volatile("s_waitcnt lgkmcnt(0)" ::: "memory")
; __device__ __forceinline__ void p0_item_load(const float* __restrict__ W, int N, int nblk, int nb0, int item, int lane, f32x4 (&v)[8]) {
;     const int kb = item / nblk, nb = nb0 + item % nblk;
;     const float* src = W + (size_t)(64 * kb + (lane >> 3)) * N + 32 * nb + 4 * (lane & 7);
; #pragma unroll
;     for (int i = 0; i < 8; ++i) v[i] = __builtin_nontemporal_load((const f32x4*)(src + (size_t)(8 * i) * N));
; }
; __device__ __forceinline__ void p0_item_store(const f32x4 (&v)[8], int K, int nblk, int nb0, bf16* __restrict__ WT, int mode, LAS float* scr, int item, int lane) {
;     const int kb = item / nblk, nb = nb0 + item % nblk, k0 = 64 * kb, n0 = 32 * nb;
; #pragma unroll
;     for (int i = 0; i < 8; ++i) { LAS float* d = scr + (8 * i + (lane >> 3)) * 33 + 4 * (lane & 7); d[0] = v[i].x; d[1] = v[i].y; d[2] = v[i].z; d[3] = v[i].w; }
;     LDS_WAIT(); asm volatile("" ::: "memory");
;     const int c = lane & 7, r0 = map_row(n0, mode);
;     const float wsc = mode == 1 ? 1.44269504089f : (mode == 2 ? 0.69314718056f : 1.0f);
; #pragma unroll
;     for (int j = 0; j < 4; ++j) { const int n = (lane >> 3) + 8 * j; const LAS float* s = scr + (8 * c) * 33 + n;
;         v4u o; o.x = cvt_pk_bf16(s[0 * 33] * wsc, s[1 * 33] * wsc); o.y = cvt_pk_bf16(s[2 * 33] * wsc, s[3 * 33] * wsc); o.z = cvt_pk_bf16(s[4 * 33] * wsc, s[5 * 33] * wsc); o.w = cvt_pk_bf16(s[6 * 33] * wsc, s[7 * 33] * wsc);
;         *(v4u*)(WT + (size_t)(r0 + n) * K + k0 + 8 * c) = o; }
;     LDS_WAIT(); asm volatile("" ::: "memory");
; }
	v_mul_f32_e32 v21, 0x3f317218, v254
	v_mul_f32_e32 v22, 0x3f317218, v255
	v_cvt_pk_bf16_f32 v21, v21, v22
	ds_read2_b32 v[254:255], v114 offset0:222 offset1:255
	v_or_b32_e32 v22, s19, v111
	v_ashrrev_i32_e32 v23, 31, v22
	v_lshlrev_b64 v[22:23], 13, v[22:23]
	v_lshl_add_u64 v[22:23], v[24:25], 0, v[22:23]
	global_store_dwordx4 v[22:23], v[18:21], off
	s_waitcnt lgkmcnt(7)
	s_nop 0
	v_mul_f32_e32 v18, 0x3f317218, v240
	v_mul_f32_e32 v19, 0x3f317218, v241
	v_cvt_pk_bf16_f32 v18, v18, v19
	s_waitcnt lgkmcnt(6)
	v_mul_f32_e32 v19, 0x3f317218, v242
	v_mul_f32_e32 v20, 0x3f317218, v243
	v_cvt_pk_bf16_f32 v19, v19, v20
	s_waitcnt lgkmcnt(5)
	v_mul_f32_e32 v20, 0x3f317218, v244
	v_mul_f32_e32 v21, 0x3f317218, v245
	v_cvt_pk_bf16_f32 v20, v20, v21
	s_waitcnt lgkmcnt(4)
	v_mul_f32_e32 v21, 0x3f317218, v246
	v_mul_f32_e32 v22, 0x3f317218, v247
	v_cvt_pk_bf16_f32 v21, v21, v22
	v_or_b32_e32 v22, s19, v112
	v_ashrrev_i32_e32 v23, 31, v22
	v_lshlrev_b64 v[22:23], 13, v[22:23]
	v_lshl_add_u64 v[22:23], v[24:25], 0, v[22:23]
	global_store_dwordx4 v[22:23], v[18:21], off
	s_waitcnt lgkmcnt(3)
	s_nop 0
	v_mul_f32_e32 v18, 0x3f317218, v248
	v_mul_f32_e32 v19, 0x3f317218, v249
	v_cvt_pk_bf16_f32 v18, v18, v19
	s_waitcnt lgkmcnt(2)
	v_mul_f32_e32 v19, 0x3f317218, v250
	v_mul_f32_e32 v20, 0x3f317218, v251
	v_cvt_pk_bf16_f32 v19, v19, v20
	s_waitcnt lgkmcnt(1)
	v_mul_f32_e32 v20, 0x3f317218, v252
	v_mul_f32_e32 v21, 0x3f317218, v253
	v_cvt_pk_bf16_f32 v20, v20, v21
	s_waitcnt lgkmcnt(0)
	v_mul_f32_e32 v21, 0x3f317218, v254
	v_mul_f32_e32 v22, 0x3f317218, v255
	v_cvt_pk_bf16_f32 v21, v21, v22
	v_or_b32_e32 v22, s19, v113
	v_ashrrev_i32_e32 v23, 31, v22
	v_lshlrev_b64 v[22:23], 13, v[22:23]
	v_lshl_add_u64 v[22:23], v[24:25], 0, v[22:23]
	global_store_dwordx4 v[22:23], v[18:21], off
	s_waitcnt lgkmcnt(0)
	s_mul_hi_i32 s19, s20, 0x2fa0be83
	s_lshr_b32 s21, s19, 31
	s_ashr_i32 s19, s19, 6
	s_add_i32 s19, s19, s21
	s_mul_i32 s21, s19, 0x158
	v_lshl_or_b32 v18, s19, 6, v108
	s_sub_i32 s21, s20, s21
	v_mad_i64_i32 v[18:19], s[22:23], v18, s4, v[104:105]
	s_lshl_b32 s22, s21, 5
	s_ashr_i32 s23, s22, 31
	v_lshl_add_u64 v[18:19], s[22:23], 2, v[18:19]
	v_lshl_add_u64 v[58:59], v[18:19], 0, v[98:99]
	v_add_co_u32_e32 v22, vcc, s5, v58
	s_nop 1
	v_addc_co_u32_e32 v23, vcc, 0, v59, vcc
	v_add_co_u32_e32 v38, vcc, s12, v58
	global_load_dwordx4 v[18:21], v[58:59], off nt
	s_nop 0
	global_load_dwordx4 v[22:25], v[22:23], off nt
	v_addc_co_u32_e32 v39, vcc, 0, v59, vcc
	v_add_co_u32_e32 v46, vcc, s13, v58
	s_nop 1
	v_addc_co_u32_e32 v47, vcc, 0, v59, vcc
	v_add_co_u32_e32 v50, vcc, s14, v58
	global_load_dwordx4 v[38:41], v[38:39], off nt
	s_nop 0
	global_load_dwordx4 v[46:49], v[46:47], off nt
	v_addc_co_u32_e32 v51, vcc, 0, v59, vcc
	v_add_co_u32_e32 v54, vcc, s15, v58
	s_nop 1
	v_addc_co_u32_e32 v55, vcc, 0, v59, vcc
	v_add_co_u32_e32 v60, vcc, s16, v58
	global_load_dwordx4 v[50:53], v[50:51], off nt
	s_nop 0
	global_load_dwordx4 v[54:57], v[54:55], off nt
	v_addc_co_u32_e32 v61, vcc, 0, v59, vcc
	v_add_co_u32_e32 v62, vcc, s17, v58
	s_nop 1
	v_addc_co_u32_e32 v63, vcc, 0, v59, vcc
	global_load_dwordx4 v[58:61], v[60:61], off nt
	s_nop 0
	global_load_dwordx4 v[62:65], v[62:63], off nt
	ds_write2_b32 v101, v66, v67 offset1:1
	ds_write2_b32 v101, v68, v69 offset0:2 offset1:3
	ds_write2_b32 v106, v70, v71 offset1:1
	ds_write2_b32 v107, v72, v73 offset1:1
	ds_write2_b32 v115, v74, v75 offset1:1
	ds_write2_b32 v116, v76, v77 offset1:1
	ds_write2_b32 v117, v78, v79 offset1:1
	ds_write2_b32 v118, v80, v81 offset1:1
	ds_write2_b32 v119, v82, v83 offset1:1
	ds_write2_b32 v120, v84, v85 offset1:1
	ds_write2_b32 v121, v86, v87 offset1:1
	ds_write2_b32 v122, v88, v89 offset1:1
	ds_write2_b32 v123, v90, v91 offset1:1
	ds_write2_b32 v124, v92, v93 offset1:1
	ds_write2_b32 v125, v94, v95 offset1:1
	ds_write2_b32 v126, v96, v97 offset1:1
	s_waitcnt lgkmcnt(0)
; __device__ __forceinline__ unsigned cvt_pk_bf16(float lo, float hi) { unsigned r; asm volatile("v_cvt_pk_bf16_f32 %0, %1, %2" : "=v"(r) : "v"(lo), "v"(hi)); return r; }
; #define LAS __attribute__((address_space(3)))
; #define LDS_WAIT() asm volatile("s_waitcnt lgkmcnt(0)" ::: "memory")
; __device__ __forceinline__ void p0_item_load(const float* __restrict__ W, int N, int nblk, int nb0, int item, int lane, f32x4 (&v)[8]) {
;     const int kb = item / nblk, nb = nb0 + item % nblk;
;     const float* src = W + (size_t)(64 * kb + (lane >> 3)) * N + 32 * nb + 4 * (lane & 7);
; #pragma unroll
;     for (int i = 0; i < 8; ++i) v[i] = __builtin_nontemporal_load((const f32x4*)(src + (size_t)(8 * i) * N));
; }
; __device__ __forceinline__ void p0_item_store(const f32x4 (&v)[8], int K, int nblk, int nb0, bf16* __restrict__ WT, int mode, LAS float* scr, int item, int lane) {
;     const int kb = item / nblk, nb = nb0 + item % nblk, k0 = 64 * kb, n0 = 32 * nb;
; #pragma unroll
;     for (int i = 0; i < 8; ++i) { LAS float* d = scr + (8 * i + (lane >> 3)) * 33 + 4 * (lane & 7); d[0] = v[i].x; d[1] = v[i].y; d[2] = v[i].z; d[3] = v[i].w; }
;     LDS_WAIT(); asm volatile("" ::: "memory");
;     const int c = lane & 7, r0 = map_row(n0, mode);
;     const float wsc = mode == 1 ? 1.44269504089f : (mode == 2 ? 0.69314718056f : 1.0f);
; #pragma unroll
;     for (int j = 0; j < 4; ++j) { const int n = (lane >> 3) + 8 * j; const LAS float* s = scr + (8 * c) * 33 + n;
;         v4u o; o.x = cvt_pk_bf16(s[0 * 33] * wsc, s[1 * 33] * wsc); o.y = cvt_pk_bf16(s[2 * 33] * wsc, s[3 * 33] * wsc); o.z = cvt_pk_bf16(s[4 * 33] * wsc, s[5 * 33] * wsc); o.w = cvt_pk_bf16(s[6 * 33] * wsc, s[7 * 33] * wsc);
;         *(v4u*)(WT + (size_t)(r0 + n) * K + k0 + 8 * c) = o; }
;     LDS_WAIT(); asm volatile("" ::: "memory");
; }
	ds_read2_b32 v[240:241], v114 offset1:33
	ds_read2_b32 v[242:243], v114 offset0:66 offset1:99
	ds_read2_b32 v[244:245], v114 offset0:132 offset1:165
	ds_read2_b32 v[246:247], v114 offset0:198 offset1:231
	ds_read2_b32 v[248:249], v114 offset0:8 offset1:41
	ds_read2_b32 v[250:251], v114 offset0:74 offset1:107
	ds_read2_b32 v[252:253], v114 offset0:140 offset1:173
	ds_read2_b32 v[254:255], v114 offset0:206 offset1:239
	s_lshl_b32 s1, s1, 6
	s_and_b32 s1, s1, 0xffffff00
	s_or_b32 s2, s2, 0xffffff80
	s_add_i32 s1, s2, s1
	s_waitcnt lgkmcnt(7)
	v_mul_f32_e32 v66, 0x3f317218, v240
	v_mul_f32_e32 v67, 0x3f317218, v241
	v_cvt_pk_bf16_f32 v66, v66, v67
	ds_read2_b32 v[240:241], v114 offset0:16 offset1:49
	s_add_i32 s2, s1, 0x100
	s_ashr_i32 s1, s0, 31
	v_lshl_add_u64 v[72:73], s[0:1], 1, v[102:103]
	s_waitcnt lgkmcnt(7)
	v_mul_f32_e32 v67, 0x3f317218, v242
	v_mul_f32_e32 v68, 0x3f317218, v243
	v_cvt_pk_bf16_f32 v67, v67, v68
	ds_read2_b32 v[242:243], v114 offset0:82 offset1:115
	s_waitcnt lgkmcnt(7)
	v_mul_f32_e32 v68, 0x3f317218, v244
	v_mul_f32_e32 v69, 0x3f317218, v245
	v_cvt_pk_bf16_f32 v68, v68, v69
	ds_read2_b32 v[244:245], v114 offset0:148 offset1:181
	s_waitcnt lgkmcnt(7)
	v_mul_f32_e32 v69, 0x3f317218, v246
	v_mul_f32_e32 v70, 0x3f317218, v247
	v_cvt_pk_bf16_f32 v69, v69, v70
	ds_read2_b32 v[246:247], v114 offset0:214 offset1:247
	v_or_b32_e32 v70, s2, v108
	v_ashrrev_i32_e32 v71, 31, v70
	v_lshlrev_b64 v[70:71], 13, v[70:71]
	v_lshl_add_u64 v[70:71], v[72:73], 0, v[70:71]
	global_store_dwordx4 v[70:71], v[66:69], off
	s_waitcnt lgkmcnt(7)
	s_nop 0
	v_mul_f32_e32 v66, 0x3f317218, v248
	v_mul_f32_e32 v67, 0x3f317218, v249
	v_cvt_pk_bf16_f32 v66, v66, v67
	ds_read2_b32 v[248:249], v114 offset0:24 offset1:57
	s_waitcnt lgkmcnt(7)
	v_mul_f32_e32 v67, 0x3f317218, v250
	v_mul_f32_e32 v68, 0x3f317218, v251
	v_cvt_pk_bf16_f32 v67, v67, v68
	ds_read2_b32 v[250:251], v114 offset0:90 offset1:123
	s_waitcnt lgkmcnt(7)
	v_mul_f32_e32 v68, 0x3f317218, v252
	v_mul_f32_e32 v69, 0x3f317218, v253
	v_cvt_pk_bf16_f32 v68, v68, v69
	ds_read2_b32 v[252:253], v114 offset0:156 offset1:189
	s_waitcnt lgkmcnt(7)
	v_mul_f32_e32 v69, 0x3f317218, v254
	v_mul_f32_e32 v70, 0x3f317218, v255
	v_cvt_pk_bf16_f32 v69, v69, v70
	ds_read2_b32 v[254:255], v114 offset0:222 offset1:255
	v_or_b32_e32 v70, s2, v111
	v_ashrrev_i32_e32 v71, 31, v70
	v_lshlrev_b64 v[70:71], 13, v[70:71]
	v_lshl_add_u64 v[70:71], v[72:73], 0, v[70:71]
	global_store_dwordx4 v[70:71], v[66:69], off
	s_waitcnt lgkmcnt(7)
	s_nop 0
	v_mul_f32_e32 v66, 0x3f317218, v240
	v_mul_f32_e32 v67, 0x3f317218, v241
	v_cvt_pk_bf16_f32 v66, v66, v67
	s_waitcnt lgkmcnt(6)
	v_mul_f32_e32 v67, 0x3f317218, v242
	v_mul_f32_e32 v68, 0x3f317218, v243
	v_cvt_pk_bf16_f32 v67, v67, v68
	s_waitcnt lgkmcnt(5)
	v_mul_f32_e32 v68, 0x3f317218, v244
	v_mul_f32_e32 v69, 0x3f317218, v245
	v_cvt_pk_bf16_f32 v68, v68, v69
	s_waitcnt lgkmcnt(4)
	v_mul_f32_e32 v69, 0x3f317218, v246
	v_mul_f32_e32 v70, 0x3f317218, v247
	v_cvt_pk_bf16_f32 v69, v69, v70
	v_or_b32_e32 v70, s2, v112
	v_ashrrev_i32_e32 v71, 31, v70
	v_lshlrev_b64 v[70:71], 13, v[70:71]
	v_lshl_add_u64 v[70:71], v[72:73], 0, v[70:71]
	global_store_dwordx4 v[70:71], v[66:69], off
	s_waitcnt lgkmcnt(3)
	s_nop 0
	v_mul_f32_e32 v66, 0x3f317218, v248
	v_mul_f32_e32 v67, 0x3f317218, v249
	v_cvt_pk_bf16_f32 v66, v66, v67
	s_waitcnt lgkmcnt(2)
	v_mul_f32_e32 v67, 0x3f317218, v250
	v_mul_f32_e32 v68, 0x3f317218, v251
	v_cvt_pk_bf16_f32 v67, v67, v68
	s_waitcnt lgkmcnt(1)
	v_mul_f32_e32 v68, 0x3f317218, v252
	v_mul_f32_e32 v69, 0x3f317218, v253
	v_cvt_pk_bf16_f32 v68, v68, v69
	s_waitcnt lgkmcnt(0)
	v_mul_f32_e32 v69, 0x3f317218, v254
	v_mul_f32_e32 v70, 0x3f317218, v255
	v_cvt_pk_bf16_f32 v69, v69, v70
	v_or_b32_e32 v70, s2, v113
	v_ashrrev_i32_e32 v71, 31, v70
	v_lshlrev_b64 v[70:71], 13, v[70:71]
	v_lshl_add_u64 v[70:71], v[72:73], 0, v[70:71]
	global_store_dwordx4 v[70:71], v[66:69], off
	s_waitcnt lgkmcnt(0)
	s_add_i32 s18, s18, -1
	s_cmp_lg_u32 s18, 0
	s_mov_b32 s21, s3
	s_mov_b32 s19, s20
	s_cbranch_scc1 .LBB0_477

; #define LAS __attribute__((address_space(3)))
; __device__ __forceinline__ void p0_item_load(const float* __restrict__ W, int N, int nblk, int nb0, int item, int lane, f32x4 (&v)[8]) {
;     const int kb = item / nblk, nb = nb0 + item % nblk;
;     const float* src = W + (size_t)(64 * kb + (lane >> 3)) * N + 32 * nb + 4 * (lane & 7);
; #pragma unroll
;     for (int i = 0; i < 8; ++i) v[i] = __builtin_nontemporal_load((const f32x4*)(src + (size_t)(8 * i) * N));
; }
; __device__ __forceinline__ void p0_item_store(const f32x4 (&v)[8], int K, int nblk, int nb0, bf16* __restrict__ WT, int mode, LAS float* scr, int item, int lane) {
;     const int kb = item / nblk, nb = nb0 + item % nblk, k0 = 64 * kb, n0 = 32 * nb;
; #pragma unroll
;     for (int i = 0; i < 8; ++i) { LAS float* d = scr + (8 * i + (lane >> 3)) * 33 + 4 * (lane & 7); d[0] = v[i].x; d[1] = v[i].y; d[2] = v[i].z; d[3] = v[i].w; }
;     LDS_WAIT(); asm volatile("" ::: "memory");
;     const int c = lane & 7, r0 = map_row(n0, mode);
;     const float wsc = mode == 1 ? 1.44269504089f : (mode == 2 ? 0.69314718056f : 1.0f);
; #pragma unroll
;     for (int j = 0; j < 4; ++j) { const int n = (lane >> 3) + 8 * j; const LAS float* s = scr + (8 * c) * 33 + n;
;         v4u o; o.x = cvt_pk_bf16(s[0 * 33] * wsc, s[1 * 33] * wsc); o.y = cvt_pk_bf16(s[2 * 33] * wsc, s[3 * 33] * wsc); o.z = cvt_pk_bf16(s[4 * 33] * wsc, s[5 * 33] * wsc); o.w = cvt_pk_bf16(s[6 * 33] * wsc, s[7 * 33] * wsc);
;         *(v4u*)(WT + (size_t)(r0 + n) * K + k0 + 8 * c) = o; }
;     LDS_WAIT(); asm volatile("" ::: "memory");
; }
;     LAS float* scr = (LAS float*)(F.lds + RING_OFF + F.wave * 16384);
;     const int nblk = nbn ? nbn : N / 32, nall = (K / 64) * nblk, nitems = (int)((long)nall * f1 / 16);
;     int it = (int)((long)nall * f0 / 16) + w0; if (it >= nitems) return;
;     f32x4 va[8], vb[8], vc[8];
;     __builtin_amdgcn_s_waitcnt(0x0F70);
;     const int last = nitems - 1, ntri = ((nitems - it + nw - 1) / nw + 2) / 3;
;     int i1 = min(it + nw, last);
;     p0_item_load(W, N, nblk, nb0, it, F.lane, va);
;     p0_item_load(W, N, nblk, nb0, i1, F.lane, vb); __builtin_amdgcn_sched_barrier(0);
;     for (int p = 0; p < ntri; ++p) {
;         const int i2 = min(i1 + nw, last), i3 = min(i2 + nw, last), i4 = min(i3 + nw, last);
;         p0_item_load(W, N, nblk, nb0, i2, F.lane, vc); __builtin_amdgcn_sched_barrier(0);
.LBB0_481:
	s_add_i32 s2, s23, s8
	s_min_i32 s22, s2, 0x1fff
	s_ashr_i32 s2, s22, 31
	s_lshr_b32 s2, s2, 24
	s_add_i32 s2, s22, s2
	s_ashr_i32 s4, s2, 8
	s_and_b32 s2, s2, 0xffffff00
	s_sub_i32 s3, s22, s2
	s_lshl_b32 s2, s4, 6
	v_or_b32_e32 v66, s2, v108
	v_ashrrev_i32_e32 v67, 31, v66
	v_lshlrev_b64 v[66:67], 15, v[66:67]
	s_lshl_b32 s4, s3, 5
	v_lshl_add_u64 v[66:67], s[52:53], 0, v[66:67]
	s_ashr_i32 s5, s4, 31
	v_lshl_add_u64 v[66:67], s[4:5], 2, v[66:67]
	v_lshl_add_u64 v[90:91], v[66:67], 0, v[98:99]
	v_add_co_u32_e32 v70, vcc, s13, v90
	s_add_i32 s22, s22, s8
	s_nop 0
	v_addc_co_u32_e32 v71, vcc, 0, v91, vcc
	v_add_co_u32_e32 v74, vcc, s12, v90
	global_load_dwordx4 v[66:69], v[90:91], off nt
	s_nop 0
	global_load_dwordx4 v[70:73], v[70:71], off nt
	v_addc_co_u32_e32 v75, vcc, 0, v91, vcc
	v_add_co_u32_e32 v78, vcc, s16, v90
	s_min_i32 s5, s22, 0x1fff
	s_nop 0
	v_addc_co_u32_e32 v79, vcc, 0, v91, vcc
	v_add_co_u32_e32 v82, vcc, s17, v90
	global_load_dwordx4 v[74:77], v[74:75], off nt
	s_nop 0
	global_load_dwordx4 v[78:81], v[78:79], off nt
	v_addc_co_u32_e32 v83, vcc, 0, v91, vcc
	v_add_co_u32_e32 v86, vcc, s18, v90
	s_add_i32 s22, s5, s8
	s_nop 0
	v_addc_co_u32_e32 v87, vcc, 0, v91, vcc
	v_add_co_u32_e32 v92, vcc, s19, v90
	global_load_dwordx4 v[82:85], v[82:83], off nt
	s_nop 0
	global_load_dwordx4 v[86:89], v[86:87], off nt
	v_addc_co_u32_e32 v93, vcc, 0, v91, vcc
	v_add_co_u32_e32 v94, vcc, s20, v90
	s_min_i32 s22, s22, 0x1fff
	s_nop 0
	v_addc_co_u32_e32 v95, vcc, 0, v91, vcc
	global_load_dwordx4 v[90:93], v[92:93], off nt
	s_nop 0
	global_load_dwordx4 v[94:97], v[94:95], off nt
	s_ashr_i32 s25, s24, 31
	s_lshr_b32 s25, s25, 24
	s_add_i32 s25, s24, s25
	v_add_u32_e32 v101, v109, v110
	s_ashr_i32 s26, s25, 8
	s_and_b32 s25, s25, 0xffffff00
	v_add_u32_e32 v104, 0x420, v101
	v_add_u32_e32 v105, 0x428, v101
	v_add_u32_e32 v106, 0x840, v101
	v_add_u32_e32 v107, 0x848, v101
	v_add_u32_e32 v115, 0xc60, v101
	v_add_u32_e32 v116, 0xc68, v101
	v_add_u32_e32 v117, 0x1080, v101
	v_add_u32_e32 v118, 0x1088, v101
	v_add_u32_e32 v119, 0x14a0, v101
	v_add_u32_e32 v120, 0x14a8, v101
	v_add_u32_e32 v121, 0x18c0, v101
	v_add_u32_e32 v122, 0x18c8, v101
	v_add_u32_e32 v123, 0x1ce0, v101
	v_add_u32_e32 v124, 0x1ce8, v101
	s_sub_i32 s24, s24, s25
	s_waitcnt vmcnt(0)
	ds_write2_b32 v101, v30, v31 offset1:1
	ds_write2_b32 v101, v32, v33 offset0:2 offset1:3
	ds_write2_b32 v104, v2, v3 offset1:1
	ds_write2_b32 v105, v4, v5 offset1:1
	ds_write2_b32 v106, v6, v7 offset1:1
	ds_write2_b32 v107, v8, v9 offset1:1
	ds_write2_b32 v115, v10, v11 offset1:1
	ds_write2_b32 v116, v12, v13 offset1:1
	ds_write2_b32 v117, v14, v15 offset1:1
	ds_write2_b32 v118, v16, v17 offset1:1
	ds_write2_b32 v119, v26, v27 offset1:1
	ds_write2_b32 v120, v28, v29 offset1:1
	ds_write2_b32 v121, v34, v35 offset1:1
	ds_write2_b32 v122, v36, v37 offset1:1
	ds_write2_b32 v123, v42, v43 offset1:1
	ds_write2_b32 v124, v44, v45 offset1:1
	s_lshl_b32 s25, s24, 5
	s_waitcnt lgkmcnt(0)
	s_cmpk_gt_i32 s24, 0x7f
	s_cselect_b32 s24, 0xfffff000, 0
	ds_read2_b32 v[240:241], v114 offset1:33
	ds_read2_b32 v[242:243], v114 offset0:66 offset1:99
	ds_read2_b32 v[244:245], v114 offset0:132 offset1:165
	ds_read2_b32 v[246:247], v114 offset0:198 offset1:231
	ds_read2_b32 v[248:249], v114 offset0:8 offset1:41
	ds_read2_b32 v[250:251], v114 offset0:74 offset1:107
	ds_read2_b32 v[252:253], v114 offset0:140 offset1:173
	ds_read2_b32 v[254:255], v114 offset0:206 offset1:239
	s_cselect_b32 s27, 0x80, 0
	s_add_i32 s24, s24, s25
	s_waitcnt lgkmcnt(7)
	v_cvt_pk_bf16_f32 v2, v240, v241
	ds_read2_b32 v[240:241], v114 offset0:16 offset1:49
	s_lshl_b32 s24, s24, 1
	s_and_b32 s25, s25, 0x60
	s_waitcnt lgkmcnt(7)
	v_cvt_pk_bf16_f32 v3, v242, v243
	ds_read2_b32 v[242:243], v114 offset0:82 offset1:115
	s_and_b32 s24, s24, 0xffffff00
	s_or_b32 s25, s27, s25
	s_waitcnt lgkmcnt(7)
	v_cvt_pk_bf16_f32 v4, v244, v245
	ds_read2_b32 v[244:245], v114 offset0:148 offset1:181
	s_or_b32 s27, s25, s24
	s_lshl_b32 s24, s26, 6
	s_waitcnt lgkmcnt(7)
	v_cvt_pk_bf16_f32 v5, v246, v247
	ds_read2_b32 v[246:247], v114 offset0:214 offset1:247
	v_or_b32_e32 v6, s27, v108
	s_ashr_i32 s25, s24, 31
	v_ashrrev_i32_e32 v7, 31, v6
	v_lshl_add_u64 v[8:9], s[24:25], 1, v[102:103]
	v_lshlrev_b64 v[6:7], 12, v[6:7]
	v_lshl_add_u64 v[6:7], v[8:9], 0, v[6:7]
	global_store_dwordx4 v[6:7], v[2:5], off
	s_waitcnt lgkmcnt(7)
	s_nop 0
	v_cvt_pk_bf16_f32 v2, v248, v249
	ds_read2_b32 v[248:249], v114 offset0:24 offset1:57
	s_waitcnt lgkmcnt(7)
	v_cvt_pk_bf16_f32 v3, v250, v251
	ds_read2_b32 v[250:251], v114 offset0:90 offset1:123
	s_waitcnt lgkmcnt(7)
	v_cvt_pk_bf16_f32 v4, v252, v253
	ds_read2_b32 v[252:253], v114 offset0:156 offset1:189
	s_waitcnt lgkmcnt(7)
	v_cvt_pk_bf16_f32 v5, v254, v255
	ds_read2_b32 v[254:255], v114 offset0:222 offset1:255
	v_or_b32_e32 v6, s27, v111
	v_ashrrev_i32_e32 v7, 31, v6
	v_lshlrev_b64 v[6:7], 12, v[6:7]
	v_lshl_add_u64 v[6:7], v[8:9], 0, v[6:7]
	global_store_dwordx4 v[6:7], v[2:5], off
	s_waitcnt lgkmcnt(7)
	s_nop 0
	v_cvt_pk_bf16_f32 v2, v240, v241
	s_waitcnt lgkmcnt(6)
	v_cvt_pk_bf16_f32 v3, v242, v243
	s_waitcnt lgkmcnt(5)
	v_cvt_pk_bf16_f32 v4, v244, v245
	s_waitcnt lgkmcnt(4)
	v_cvt_pk_bf16_f32 v5, v246, v247
	v_or_b32_e32 v6, s27, v112
	v_ashrrev_i32_e32 v7, 31, v6
	v_lshlrev_b64 v[6:7], 12, v[6:7]
	v_lshl_add_u64 v[6:7], v[8:9], 0, v[6:7]
	global_store_dwordx4 v[6:7], v[2:5], off
	s_waitcnt lgkmcnt(3)
	s_nop 0
	v_cvt_pk_bf16_f32 v2, v248, v249
	s_waitcnt lgkmcnt(2)
	v_cvt_pk_bf16_f32 v3, v250, v251
	s_waitcnt lgkmcnt(1)
	v_cvt_pk_bf16_f32 v4, v252, v253
	s_waitcnt lgkmcnt(0)
; #define LAS __attribute__((address_space(3)))
; __device__ __forceinline__ void p0_item_load(const float* __restrict__ W, int N, int nblk, int nb0, int item, int lane, f32x4 (&v)[8]) {
;     const int kb = item / nblk, nb = nb0 + item % nblk;
;     const float* src = W + (size_t)(64 * kb + (lane >> 3)) * N + 32 * nb + 4 * (lane & 7);
; #pragma unroll
;     for (int i = 0; i < 8; ++i) v[i] = __builtin_nontemporal_load((const f32x4*)(src + (size_t)(8 * i) * N));
; }
; __device__ __forceinline__ void p0_item_store(const f32x4 (&v)[8], int K, int nblk, int nb0, bf16* __restrict__ WT, int mode, LAS float* scr, int item, int lane) {
;     const int kb = item / nblk, nb = nb0 + item % nblk, k0 = 64 * kb, n0 = 32 * nb;
; #pragma unroll
;     for (int i = 0; i < 8; ++i) { LAS float* d = scr + (8 * i + (lane >> 3)) * 33 + 4 * (lane & 7); d[0] = v[i].x; d[1] = v[i].y; d[2] = v[i].z; d[3] = v[i].w; }
;     LDS_WAIT(); asm volatile("" ::: "memory");
;     const int c = lane & 7, r0 = map_row(n0, mode);
;     const float wsc = mode == 1 ? 1.44269504089f : (mode == 2 ? 0.69314718056f : 1.0f);
; #pragma unroll
;     for (int j = 0; j < 4; ++j) { const int n = (lane >> 3) + 8 * j; const LAS float* s = scr + (8 * c) * 33 + n;
;         v4u o; o.x = cvt_pk_bf16(s[0 * 33] * wsc, s[1 * 33] * wsc); o.y = cvt_pk_bf16(s[2 * 33] * wsc, s[3 * 33] * wsc); o.z = cvt_pk_bf16(s[4 * 33] * wsc, s[5 * 33] * wsc); o.w = cvt_pk_bf16(s[6 * 33] * wsc, s[7 * 33] * wsc);
;         *(v4u*)(WT + (size_t)(r0 + n) * K + k0 + 8 * c) = o; }
;     LDS_WAIT(); asm volatile("" ::: "memory");
; }
;     LAS float* scr = (LAS float*)(F.lds + RING_OFF + F.wave * 16384);
;     const int nblk = nbn ? nbn : N / 32, nall = (K / 64) * nblk, nitems = (int)((long)nall * f1 / 16);
;     int it = (int)((long)nall * f0 / 16) + w0; if (it >= nitems) return;
;     f32x4 va[8], vb[8], vc[8];
;     __builtin_amdgcn_s_waitcnt(0x0F70);
;     const int last = nitems - 1, ntri = ((nitems - it + nw - 1) / nw + 2) / 3;
;     int i1 = min(it + nw, last);
;     p0_item_load(W, N, nblk, nb0, it, F.lane, va);
;     p0_item_load(W, N, nblk, nb0, i1, F.lane, vb); __builtin_amdgcn_sched_barrier(0);
;     for (int p = 0; p < ntri; ++p) {
;         const int i2 = min(i1 + nw, last), i3 = min(i2 + nw, last), i4 = min(i3 + nw, last);
;         p0_item_load(W, N, nblk, nb0, i2, F.lane, vc); __builtin_amdgcn_sched_barrier(0);
	v_cvt_pk_bf16_f32 v5, v254, v255
	v_or_b32_e32 v6, s27, v113
	v_ashrrev_i32_e32 v7, 31, v6
	v_lshlrev_b64 v[6:7], 12, v[6:7]
	v_lshl_add_u64 v[6:7], v[8:9], 0, v[6:7]
	global_store_dwordx4 v[6:7], v[2:5], off
	s_waitcnt lgkmcnt(0)
	s_ashr_i32 s24, s5, 31
	s_lshr_b32 s24, s24, 24
	s_add_i32 s24, s5, s24
	s_ashr_i32 s25, s24, 8
	s_and_b32 s24, s24, 0x7ffff00
	v_lshl_or_b32 v2, s25, 6, v108
	s_sub_i32 s24, s5, s24
	v_ashrrev_i32_e32 v3, 31, v2
	v_lshlrev_b64 v[2:3], 15, v[2:3]
	s_lshl_b32 s24, s24, 5
	v_lshl_add_u64 v[2:3], s[52:53], 0, v[2:3]
	s_ashr_i32 s25, s24, 31
	v_lshl_add_u64 v[2:3], s[24:25], 2, v[2:3]
	v_lshl_add_u64 v[34:35], v[2:3], 0, v[98:99]
	v_add_co_u32_e32 v2, vcc, s13, v34
	s_nop 1
	v_addc_co_u32_e32 v3, vcc, 0, v35, vcc
	v_add_co_u32_e32 v6, vcc, s12, v34
	global_load_dwordx4 v[30:33], v[34:35], off nt
	s_nop 0
	global_load_dwordx4 v[2:5], v[2:3], off nt
	v_addc_co_u32_e32 v7, vcc, 0, v35, vcc
	v_add_co_u32_e32 v10, vcc, s16, v34
	s_nop 1
	v_addc_co_u32_e32 v11, vcc, 0, v35, vcc
	v_add_co_u32_e32 v14, vcc, s17, v34
	global_load_dwordx4 v[6:9], v[6:7], off nt
	s_nop 0
	global_load_dwordx4 v[10:13], v[10:11], off nt
	v_addc_co_u32_e32 v15, vcc, 0, v35, vcc
	v_add_co_u32_e32 v26, vcc, s18, v34
	s_nop 1
	v_addc_co_u32_e32 v27, vcc, 0, v35, vcc
	v_add_co_u32_e32 v36, vcc, s19, v34
	global_load_dwordx4 v[14:17], v[14:15], off nt
	s_nop 0
	global_load_dwordx4 v[26:29], v[26:27], off nt
	v_addc_co_u32_e32 v37, vcc, 0, v35, vcc
	v_add_co_u32_e32 v42, vcc, s20, v34
	s_nop 1
	v_addc_co_u32_e32 v43, vcc, 0, v35, vcc
	global_load_dwordx4 v[34:37], v[36:37], off nt
	s_nop 0
	global_load_dwordx4 v[42:45], v[42:43], off nt
	s_ashr_i32 s24, s23, 31
	s_lshr_b32 s24, s24, 24
	s_add_i32 s24, s23, s24
	s_ashr_i32 s25, s24, 8
	s_and_b32 s24, s24, 0xffffff00
	s_sub_i32 s23, s23, s24
	ds_write2_b32 v101, v18, v19 offset1:1
	ds_write2_b32 v101, v20, v21 offset0:2 offset1:3
	ds_write2_b32 v104, v22, v23 offset1:1
	ds_write2_b32 v105, v24, v25 offset1:1
	ds_write2_b32 v106, v38, v39 offset1:1
	ds_write2_b32 v107, v40, v41 offset1:1
	ds_write2_b32 v115, v46, v47 offset1:1
	ds_write2_b32 v116, v48, v49 offset1:1
	ds_write2_b32 v117, v50, v51 offset1:1
	ds_write2_b32 v118, v52, v53 offset1:1
	ds_write2_b32 v119, v54, v55 offset1:1
	ds_write2_b32 v120, v56, v57 offset1:1
	ds_write2_b32 v121, v58, v59 offset1:1
	ds_write2_b32 v122, v60, v61 offset1:1
	ds_write2_b32 v123, v62, v63 offset1:1
	ds_write2_b32 v124, v64, v65 offset1:1
	s_lshl_b32 s24, s23, 5
	s_waitcnt lgkmcnt(0)
	s_cmpk_gt_i32 s23, 0x7f
	s_cselect_b32 s23, 0xfffff000, 0
	ds_read2_b32 v[240:241], v114 offset1:33
	ds_read2_b32 v[242:243], v114 offset0:66 offset1:99
	ds_read2_b32 v[244:245], v114 offset0:132 offset1:165
	ds_read2_b32 v[246:247], v114 offset0:198 offset1:231
	ds_read2_b32 v[248:249], v114 offset0:8 offset1:41
	ds_read2_b32 v[250:251], v114 offset0:74 offset1:107
	ds_read2_b32 v[252:253], v114 offset0:140 offset1:173
	ds_read2_b32 v[254:255], v114 offset0:206 offset1:239
	s_cselect_b32 s26, 0x80, 0
	s_add_i32 s23, s23, s24
	s_waitcnt lgkmcnt(7)
	v_cvt_pk_bf16_f32 v18, v240, v241
	ds_read2_b32 v[240:241], v114 offset0:16 offset1:49
	s_lshl_b32 s23, s23, 1
	s_and_b32 s24, s24, 0x60
	s_waitcnt lgkmcnt(7)
	v_cvt_pk_bf16_f32 v19, v242, v243
	ds_read2_b32 v[242:243], v114 offset0:82 offset1:115
	s_and_b32 s23, s23, 0xffffff00
	s_or_b32 s24, s26, s24
	s_waitcnt lgkmcnt(7)
	v_cvt_pk_bf16_f32 v20, v244, v245
	ds_read2_b32 v[244:245], v114 offset0:148 offset1:181
	s_or_b32 s23, s24, s23
	s_lshl_b32 s24, s25, 6
	s_waitcnt lgkmcnt(7)
	v_cvt_pk_bf16_f32 v21, v246, v247
	ds_read2_b32 v[246:247], v114 offset0:214 offset1:247
	v_or_b32_e32 v22, s23, v108
	s_ashr_i32 s25, s24, 31
	v_ashrrev_i32_e32 v23, 31, v22
	v_lshl_add_u64 v[24:25], s[24:25], 1, v[102:103]
	v_lshlrev_b64 v[22:23], 12, v[22:23]
	v_lshl_add_u64 v[22:23], v[24:25], 0, v[22:23]
	global_store_dwordx4 v[22:23], v[18:21], off
	s_waitcnt lgkmcnt(7)
	s_nop 0
	v_cvt_pk_bf16_f32 v18, v248, v249
	ds_read2_b32 v[248:249], v114 offset0:24 offset1:57
	s_waitcnt lgkmcnt(7)
	v_cvt_pk_bf16_f32 v19, v250, v251
	ds_read2_b32 v[250:251], v114 offset0:90 offset1:123
	s_waitcnt lgkmcnt(7)
	v_cvt_pk_bf16_f32 v20, v252, v253
	ds_read2_b32 v[252:253], v114 offset0:156 offset1:189
	s_waitcnt lgkmcnt(7)
	v_cvt_pk_bf16_f32 v21, v254, v255
	ds_read2_b32 v[254:255], v114 offset0:222 offset1:255
	v_or_b32_e32 v22, s23, v111
	v_ashrrev_i32_e32 v23, 31, v22
	v_lshlrev_b64 v[22:23], 12, v[22:23]
	v_lshl_add_u64 v[22:23], v[24:25], 0, v[22:23]
	global_store_dwordx4 v[22:23], v[18:21], off
	s_waitcnt lgkmcnt(7)
	s_nop 0
	v_cvt_pk_bf16_f32 v18, v240, v241
	s_waitcnt lgkmcnt(6)
	v_cvt_pk_bf16_f32 v19, v242, v243
	s_waitcnt lgkmcnt(5)
	v_cvt_pk_bf16_f32 v20, v244, v245
	s_waitcnt lgkmcnt(4)
	v_cvt_pk_bf16_f32 v21, v246, v247
	v_or_b32_e32 v22, s23, v112
	v_ashrrev_i32_e32 v23, 31, v22
	v_lshlrev_b64 v[22:23], 12, v[22:23]
	v_lshl_add_u64 v[22:23], v[24:25], 0, v[22:23]
	global_store_dwordx4 v[22:23], v[18:21], off
	s_waitcnt lgkmcnt(3)
	s_nop 0
	v_cvt_pk_bf16_f32 v18, v248, v249
	s_waitcnt lgkmcnt(2)
	v_cvt_pk_bf16_f32 v19, v250, v251
	s_waitcnt lgkmcnt(1)
	v_cvt_pk_bf16_f32 v20, v252, v253
	s_waitcnt lgkmcnt(0)
; #define LAS __attribute__((address_space(3)))
; __device__ __forceinline__ void p0_item_load(const float* __restrict__ W, int N, int nblk, int nb0, int item, int lane, f32x4 (&v)[8]) {
;     const int kb = item / nblk, nb = nb0 + item % nblk;
;     const float* src = W + (size_t)(64 * kb + (lane >> 3)) * N + 32 * nb + 4 * (lane & 7);
; #pragma unroll
;     for (int i = 0; i < 8; ++i) v[i] = __builtin_nontemporal_load((const f32x4*)(src + (size_t)(8 * i) * N));
; }
; __device__ __forceinline__ void p0_item_store(const f32x4 (&v)[8], int K, int nblk, int nb0, bf16* __restrict__ WT, int mode, LAS float* scr, int item, int lane) {
;     const int kb = item / nblk, nb = nb0 + item % nblk, k0 = 64 * kb, n0 = 32 * nb;
; #pragma unroll
;     for (int i = 0; i < 8; ++i) { LAS float* d = scr + (8 * i + (lane >> 3)) * 33 + 4 * (lane & 7); d[0] = v[i].x; d[1] = v[i].y; d[2] = v[i].z; d[3] = v[i].w; }
;     LDS_WAIT(); asm volatile("" ::: "memory");
;     const int c = lane & 7, r0 = map_row(n0, mode);
;     const float wsc = mode == 1 ? 1.44269504089f : (mode == 2 ? 0.69314718056f : 1.0f);
; #pragma unroll
;     for (int j = 0; j < 4; ++j) { const int n = (lane >> 3) + 8 * j; const LAS float* s = scr + (8 * c) * 33 + n;
;         v4u o; o.x = cvt_pk_bf16(s[0 * 33] * wsc, s[1 * 33] * wsc); o.y = cvt_pk_bf16(s[2 * 33] * wsc, s[3 * 33] * wsc); o.z = cvt_pk_bf16(s[4 * 33] * wsc, s[5 * 33] * wsc); o.w = cvt_pk_bf16(s[6 * 33] * wsc, s[7 * 33] * wsc);
;         *(v4u*)(WT + (size_t)(r0 + n) * K + k0 + 8 * c) = o; }
;     LDS_WAIT(); asm volatile("" ::: "memory");
; }
;     LAS float* scr = (LAS float*)(F.lds + RING_OFF + F.wave * 16384);
;     const int nblk = nbn ? nbn : N / 32, nall = (K / 64) * nblk, nitems = (int)((long)nall * f1 / 16);
;     int it = (int)((long)nall * f0 / 16) + w0; if (it >= nitems) return;
;     f32x4 va[8], vb[8], vc[8];
;     __builtin_amdgcn_s_waitcnt(0x0F70);
;     const int last = nitems - 1, ntri = ((nitems - it + nw - 1) / nw + 2) / 3;
;     int i1 = min(it + nw, last);
;     p0_item_load(W, N, nblk, nb0, it, F.lane, va);
;     p0_item_load(W, N, nblk, nb0, i1, F.lane, vb); __builtin_amdgcn_sched_barrier(0);
;     for (int p = 0; p < ntri; ++p) {
;         const int i2 = min(i1 + nw, last), i3 = min(i2 + nw, last), i4 = min(i3 + nw, last);
;         p0_item_load(W, N, nblk, nb0, i2, F.lane, vc); __builtin_amdgcn_sched_barrier(0);
	v_cvt_pk_bf16_f32 v21, v254, v255
	v_or_b32_e32 v22, s23, v113
	v_ashrrev_i32_e32 v23, 31, v22
	v_lshlrev_b64 v[22:23], 12, v[22:23]
	v_lshl_add_u64 v[22:23], v[24:25], 0, v[22:23]
	global_store_dwordx4 v[22:23], v[18:21], off
	s_waitcnt lgkmcnt(0)
	s_ashr_i32 s23, s22, 31
	s_lshr_b32 s23, s23, 24
	s_add_i32 s23, s22, s23
	s_ashr_i32 s24, s23, 8
	s_and_b32 s23, s23, 0x7ffff00
	v_lshl_or_b32 v18, s24, 6, v108
	s_sub_i32 s23, s22, s23
	v_ashrrev_i32_e32 v19, 31, v18
	v_lshlrev_b64 v[18:19], 15, v[18:19]
	s_lshl_b32 s24, s23, 5
	v_lshl_add_u64 v[18:19], s[52:53], 0, v[18:19]
	s_ashr_i32 s25, s24, 31
	v_lshl_add_u64 v[18:19], s[24:25], 2, v[18:19]
	v_lshl_add_u64 v[58:59], v[18:19], 0, v[98:99]
	v_add_co_u32_e32 v22, vcc, s13, v58
	s_nop 1
	v_addc_co_u32_e32 v23, vcc, 0, v59, vcc
	v_add_co_u32_e32 v38, vcc, s12, v58
	global_load_dwordx4 v[18:21], v[58:59], off nt
	s_nop 0
	global_load_dwordx4 v[22:25], v[22:23], off nt
	v_addc_co_u32_e32 v39, vcc, 0, v59, vcc
	v_add_co_u32_e32 v46, vcc, s16, v58
	s_nop 1
	v_addc_co_u32_e32 v47, vcc, 0, v59, vcc
	v_add_co_u32_e32 v50, vcc, s17, v58
	global_load_dwordx4 v[38:41], v[38:39], off nt
	s_nop 0
	global_load_dwordx4 v[46:49], v[46:47], off nt
	v_addc_co_u32_e32 v51, vcc, 0, v59, vcc
	v_add_co_u32_e32 v54, vcc, s18, v58
	s_nop 1
	v_addc_co_u32_e32 v55, vcc, 0, v59, vcc
	v_add_co_u32_e32 v60, vcc, s19, v58
	global_load_dwordx4 v[50:53], v[50:51], off nt
	s_nop 0
	global_load_dwordx4 v[54:57], v[54:55], off nt
	v_addc_co_u32_e32 v61, vcc, 0, v59, vcc
	v_add_co_u32_e32 v62, vcc, s20, v58
	s_nop 1
	v_addc_co_u32_e32 v63, vcc, 0, v59, vcc
	global_load_dwordx4 v[58:61], v[60:61], off nt
	s_nop 0
	global_load_dwordx4 v[62:65], v[62:63], off nt
	ds_write2_b32 v101, v66, v67 offset1:1
	ds_write2_b32 v101, v68, v69 offset0:2 offset1:3
	ds_write2_b32 v104, v70, v71 offset1:1
	ds_write2_b32 v105, v72, v73 offset1:1
	ds_write2_b32 v106, v74, v75 offset1:1
	ds_write2_b32 v107, v76, v77 offset1:1
	ds_write2_b32 v115, v78, v79 offset1:1
	ds_write2_b32 v116, v80, v81 offset1:1
	ds_write2_b32 v117, v82, v83 offset1:1
	ds_write2_b32 v118, v84, v85 offset1:1
	ds_write2_b32 v119, v86, v87 offset1:1
	ds_write2_b32 v120, v88, v89 offset1:1
	ds_write2_b32 v121, v90, v91 offset1:1
	ds_write2_b32 v122, v92, v93 offset1:1
	ds_write2_b32 v123, v94, v95 offset1:1
	ds_write2_b32 v124, v96, v97 offset1:1
	s_waitcnt lgkmcnt(0)
	s_cmpk_gt_i32 s3, 0x7f
	s_cselect_b32 s3, 0xfffff000, 0
	ds_read2_b32 v[240:241], v114 offset1:33
	ds_read2_b32 v[242:243], v114 offset0:66 offset1:99
	ds_read2_b32 v[244:245], v114 offset0:132 offset1:165
	ds_read2_b32 v[246:247], v114 offset0:198 offset1:231
	ds_read2_b32 v[248:249], v114 offset0:8 offset1:41
	ds_read2_b32 v[250:251], v114 offset0:74 offset1:107
	ds_read2_b32 v[252:253], v114 offset0:140 offset1:173
	ds_read2_b32 v[254:255], v114 offset0:206 offset1:239
	s_cselect_b32 s23, 0x80, 0
	s_add_i32 s3, s3, s4
	s_waitcnt lgkmcnt(7)
	v_cvt_pk_bf16_f32 v66, v240, v241
	ds_read2_b32 v[240:241], v114 offset0:16 offset1:49
	s_lshl_b32 s3, s3, 1
	s_and_b32 s4, s4, 0x60
	s_waitcnt lgkmcnt(7)
	v_cvt_pk_bf16_f32 v67, v242, v243
	ds_read2_b32 v[242:243], v114 offset0:82 offset1:115
	s_and_b32 s3, s3, 0xffffff00
	s_or_b32 s4, s23, s4
	s_waitcnt lgkmcnt(7)
	v_cvt_pk_bf16_f32 v68, v244, v245
	ds_read2_b32 v[244:245], v114 offset0:148 offset1:181
	s_or_b32 s4, s4, s3
	s_waitcnt lgkmcnt(7)
	v_cvt_pk_bf16_f32 v69, v246, v247
	ds_read2_b32 v[246:247], v114 offset0:214 offset1:247
	v_or_b32_e32 v70, s4, v108
	s_ashr_i32 s3, s2, 31
	v_ashrrev_i32_e32 v71, 31, v70
	v_lshl_add_u64 v[72:73], s[2:3], 1, v[102:103]
	v_lshlrev_b64 v[70:71], 12, v[70:71]
	v_lshl_add_u64 v[70:71], v[72:73], 0, v[70:71]
	global_store_dwordx4 v[70:71], v[66:69], off
	s_waitcnt lgkmcnt(7)
	s_nop 0
	v_cvt_pk_bf16_f32 v66, v248, v249
	ds_read2_b32 v[248:249], v114 offset0:24 offset1:57
	s_waitcnt lgkmcnt(7)
	v_cvt_pk_bf16_f32 v67, v250, v251
	ds_read2_b32 v[250:251], v114 offset0:90 offset1:123
	s_waitcnt lgkmcnt(7)
	v_cvt_pk_bf16_f32 v68, v252, v253
	ds_read2_b32 v[252:253], v114 offset0:156 offset1:189
	s_waitcnt lgkmcnt(7)
	v_cvt_pk_bf16_f32 v69, v254, v255
	ds_read2_b32 v[254:255], v114 offset0:222 offset1:255
	v_or_b32_e32 v70, s4, v111
	v_ashrrev_i32_e32 v71, 31, v70
	v_lshlrev_b64 v[70:71], 12, v[70:71]
	v_lshl_add_u64 v[70:71], v[72:73], 0, v[70:71]
	global_store_dwordx4 v[70:71], v[66:69], off
	s_waitcnt lgkmcnt(7)
	s_nop 0
	v_cvt_pk_bf16_f32 v66, v240, v241
	v_or_b32_e32 v74, s4, v112
	v_ashrrev_i32_e32 v75, 31, v74
	s_waitcnt lgkmcnt(6)
	v_cvt_pk_bf16_f32 v67, v242, v243
	v_lshlrev_b64 v[74:75], 12, v[74:75]
	s_waitcnt lgkmcnt(5)
	v_cvt_pk_bf16_f32 v68, v244, v245
	s_waitcnt lgkmcnt(4)
	v_cvt_pk_bf16_f32 v69, v246, v247
	v_lshl_add_u64 v[74:75], v[72:73], 0, v[74:75]
	global_store_dwordx4 v[74:75], v[66:69], off
	v_or_b32_e32 v74, s4, v113
	v_ashrrev_i32_e32 v75, 31, v74
	s_waitcnt lgkmcnt(3)
	v_cvt_pk_bf16_f32 v66, v248, v249
	s_waitcnt lgkmcnt(2)
	v_cvt_pk_bf16_f32 v67, v250, v251
	s_waitcnt lgkmcnt(1)
	v_cvt_pk_bf16_f32 v68, v252, v253
	v_lshlrev_b64 v[74:75], 12, v[74:75]
	s_waitcnt lgkmcnt(0)
	v_cvt_pk_bf16_f32 v69, v254, v255
	v_lshl_add_u64 v[70:71], v[72:73], 0, v[74:75]
	global_store_dwordx4 v[70:71], v[66:69], off
	s_waitcnt lgkmcnt(0)
	s_add_i32 s21, s21, -1
	s_cmp_lg_u32 s21, 0
	s_mov_b32 s24, s5
	s_mov_b32 s23, s22
	s_cbranch_scc1 .LBB0_481

; #define LAS __attribute__((address_space(3)))
; __device__ __forceinline__ void p0_item_load(const float* __restrict__ W, int N, int nblk, int nb0, int item, int lane, f32x4 (&v)[8]) {
;     const int kb = item / nblk, nb = nb0 + item % nblk;
;     const float* src = W + (size_t)(64 * kb + (lane >> 3)) * N + 32 * nb + 4 * (lane & 7);
; #pragma unroll
;     for (int i = 0; i < 8; ++i) v[i] = __builtin_nontemporal_load((const f32x4*)(src + (size_t)(8 * i) * N));
; }
; __device__ __forceinline__ void p0_item_store(const f32x4 (&v)[8], int K, int nblk, int nb0, bf16* __restrict__ WT, int mode, LAS float* scr, int item, int lane) {
;     const int kb = item / nblk, nb = nb0 + item % nblk, k0 = 64 * kb, n0 = 32 * nb;
; #pragma unroll
;     for (int i = 0; i < 8; ++i) { LAS float* d = scr + (8 * i + (lane >> 3)) * 33 + 4 * (lane & 7); d[0] = v[i].x; d[1] = v[i].y; d[2] = v[i].z; d[3] = v[i].w; }
;     LDS_WAIT(); asm volatile("" ::: "memory");
;     const int c = lane & 7, r0 = map_row(n0, mode);
;     const float wsc = mode == 1 ? 1.44269504089f : (mode == 2 ? 0.69314718056f : 1.0f);
; #pragma unroll
;     for (int j = 0; j < 4; ++j) { const int n = (lane >> 3) + 8 * j; const LAS float* s = scr + (8 * c) * 33 + n;
;         v4u o; o.x = cvt_pk_bf16(s[0 * 33] * wsc, s[1 * 33] * wsc); o.y = cvt_pk_bf16(s[2 * 33] * wsc, s[3 * 33] * wsc); o.z = cvt_pk_bf16(s[4 * 33] * wsc, s[5 * 33] * wsc); o.w = cvt_pk_bf16(s[6 * 33] * wsc, s[7 * 33] * wsc);
;         *(v4u*)(WT + (size_t)(r0 + n) * K + k0 + 8 * c) = o; }
;     LDS_WAIT(); asm volatile("" ::: "memory");
; }
;     LAS float* scr = (LAS float*)(F.lds + RING_OFF + F.wave * 16384);
;     const int nblk = nbn ? nbn : N / 32, nall = (K / 64) * nblk, nitems = (int)((long)nall * f1 / 16);
;     int it = (int)((long)nall * f0 / 16) + w0; if (it >= nitems) return;
;     f32x4 va[8], vb[8], vc[8];
;     __builtin_amdgcn_s_waitcnt(0x0F70);
;     const int last = nitems - 1, ntri = ((nitems - it + nw - 1) / nw + 2) / 3;
;     int i1 = min(it + nw, last);
;     p0_item_load(W, N, nblk, nb0, it, F.lane, va);
;     p0_item_load(W, N, nblk, nb0, i1, F.lane, vb); __builtin_amdgcn_sched_barrier(0);
;     for (int p = 0; p < ntri; ++p) {
;         const int i2 = min(i1 + nw, last), i3 = min(i2 + nw, last), i4 = min(i3 + nw, last);
;         p0_item_load(W, N, nblk, nb0, i2, F.lane, vc); __builtin_amdgcn_sched_barrier(0);
.LBB0_484:
	s_add_i32 s0, s11, s8
	s_min_i32 s3, s0, 0x1fff
	s_ashr_i32 s0, s3, 31
	s_lshr_b32 s0, s0, 25
	s_add_i32 s0, s3, s0
	s_ashr_i32 s1, s0, 7
	s_lshl_b32 s2, s1, 6
	s_and_b32 s0, s0, 0x7ffff80
	v_or_b32_e32 v66, s2, v108
	s_sub_i32 s0, s3, s0
	v_ashrrev_i32_e32 v67, 31, v66
	v_lshlrev_b64 v[66:67], 14, v[66:67]
	s_lshl_b32 s0, s0, 5
	v_lshl_add_u64 v[66:67], s[62:63], 0, v[66:67]
	s_ashr_i32 s1, s0, 31
	v_lshl_add_u64 v[66:67], s[0:1], 2, v[66:67]
	v_lshl_add_u64 v[90:91], v[66:67], 0, v[98:99]
	v_add_co_u32_e32 v70, vcc, s4, v90
	s_add_i32 s3, s3, s8
	s_nop 0
	v_addc_co_u32_e32 v71, vcc, 0, v91, vcc
	v_add_co_u32_e32 v74, vcc, s12, v90
	global_load_dwordx4 v[66:69], v[90:91], off nt
	s_nop 0
	global_load_dwordx4 v[70:73], v[70:71], off nt
	v_addc_co_u32_e32 v75, vcc, 0, v91, vcc
	v_add_co_u32_e32 v78, vcc, s5, v90
	s_min_i32 s1, s3, 0x1fff
	s_nop 0
	v_addc_co_u32_e32 v79, vcc, 0, v91, vcc
	v_add_co_u32_e32 v82, vcc, s13, v90
	global_load_dwordx4 v[74:77], v[74:75], off nt
	s_nop 0
	global_load_dwordx4 v[78:81], v[78:79], off nt
	v_addc_co_u32_e32 v83, vcc, 0, v91, vcc
	v_add_co_u32_e32 v86, vcc, s14, v90
	s_add_i32 s3, s1, s8
	s_nop 0
	v_addc_co_u32_e32 v87, vcc, 0, v91, vcc
	v_add_co_u32_e32 v92, vcc, s16, v90
	global_load_dwordx4 v[82:85], v[82:83], off nt
	s_nop 0
	global_load_dwordx4 v[86:89], v[86:87], off nt
	v_addc_co_u32_e32 v93, vcc, 0, v91, vcc
	v_add_co_u32_e32 v94, vcc, s15, v90
	s_min_i32 s17, s3, 0x1fff
	s_nop 0
	v_addc_co_u32_e32 v95, vcc, 0, v91, vcc
	global_load_dwordx4 v[90:93], v[92:93], off nt
	s_nop 0
	global_load_dwordx4 v[94:97], v[94:95], off nt
	v_add_u32_e32 v102, v109, v110
	v_add_u32_e32 v103, 0x420, v102
	v_add_u32_e32 v104, 0x428, v102
	v_add_u32_e32 v105, 0x840, v102
	v_add_u32_e32 v106, 0x848, v102
	v_add_u32_e32 v107, 0xc60, v102
	v_add_u32_e32 v115, 0xc68, v102
	v_add_u32_e32 v116, 0x1080, v102
	v_add_u32_e32 v117, 0x1088, v102
	v_add_u32_e32 v118, 0x14a0, v102
	v_add_u32_e32 v119, 0x14a8, v102
	v_add_u32_e32 v120, 0x18c0, v102
	v_add_u32_e32 v121, 0x18c8, v102
	v_add_u32_e32 v122, 0x1ce0, v102
	v_add_u32_e32 v123, 0x1ce8, v102
	s_waitcnt vmcnt(0)
	ds_write2_b32 v102, v30, v31 offset1:1
	ds_write2_b32 v102, v32, v33 offset0:2 offset1:3
	ds_write2_b32 v103, v2, v3 offset1:1
	ds_write2_b32 v104, v4, v5 offset1:1
	ds_write2_b32 v105, v6, v7 offset1:1
	ds_write2_b32 v106, v8, v9 offset1:1
	ds_write2_b32 v107, v10, v11 offset1:1
	ds_write2_b32 v115, v12, v13 offset1:1
	ds_write2_b32 v116, v14, v15 offset1:1
	ds_write2_b32 v117, v16, v17 offset1:1
	ds_write2_b32 v118, v22, v23 offset1:1
	ds_write2_b32 v119, v24, v25 offset1:1
	ds_write2_b32 v120, v34, v35 offset1:1
	ds_write2_b32 v121, v36, v37 offset1:1
	ds_write2_b32 v122, v38, v39 offset1:1
	ds_write2_b32 v123, v40, v41 offset1:1
	s_waitcnt lgkmcnt(0)
	s_ashr_i32 s3, s9, 31
	s_lshr_b32 s3, s3, 25
	ds_read2_b32 v[240:241], v114 offset1:33
	ds_read2_b32 v[242:243], v114 offset0:66 offset1:99
	ds_read2_b32 v[244:245], v114 offset0:132 offset1:165
	ds_read2_b32 v[246:247], v114 offset0:198 offset1:231
	ds_read2_b32 v[248:249], v114 offset0:8 offset1:41
	ds_read2_b32 v[250:251], v114 offset0:74 offset1:107
	ds_read2_b32 v[252:253], v114 offset0:140 offset1:173
	ds_read2_b32 v[254:255], v114 offset0:206 offset1:239
	s_add_i32 s3, s9, s3
	s_waitcnt lgkmcnt(7)
	v_cvt_pk_bf16_f32 v2, v240, v241
	ds_read2_b32 v[240:241], v114 offset0:16 offset1:49
	s_ashr_i32 s18, s3, 7
	s_and_b32 s3, s3, 0x7ffff80
	s_waitcnt lgkmcnt(7)
	v_cvt_pk_bf16_f32 v3, v242, v243
	ds_read2_b32 v[242:243], v114 offset0:82 offset1:115
	s_sub_i32 s3, s9, s3
	s_waitcnt lgkmcnt(7)
	v_cvt_pk_bf16_f32 v4, v244, v245
	ds_read2_b32 v[244:245], v114 offset0:148 offset1:181
	s_lshl_b32 s3, s3, 5
	s_lshl_b32 s18, s18, 6
	s_waitcnt lgkmcnt(7)
	v_cvt_pk_bf16_f32 v5, v246, v247
	ds_read2_b32 v[246:247], v114 offset0:214 offset1:247
	v_or_b32_e32 v6, s3, v108
	s_ashr_i32 s19, s18, 31
	v_ashrrev_i32_e32 v7, 31, v6
	v_lshl_add_u64 v[8:9], s[18:19], 1, v[100:101]
	v_lshlrev_b64 v[6:7], 13, v[6:7]
	v_lshl_add_u64 v[6:7], v[8:9], 0, v[6:7]
	global_store_dwordx4 v[6:7], v[2:5], off
	s_waitcnt lgkmcnt(7)
	s_nop 0
	v_cvt_pk_bf16_f32 v2, v248, v249
	ds_read2_b32 v[248:249], v114 offset0:24 offset1:57
	s_waitcnt lgkmcnt(7)
	v_cvt_pk_bf16_f32 v3, v250, v251
	ds_read2_b32 v[250:251], v114 offset0:90 offset1:123
	s_waitcnt lgkmcnt(7)
	v_cvt_pk_bf16_f32 v4, v252, v253
	ds_read2_b32 v[252:253], v114 offset0:156 offset1:189
	s_waitcnt lgkmcnt(7)
	v_cvt_pk_bf16_f32 v5, v254, v255
	ds_read2_b32 v[254:255], v114 offset0:222 offset1:255
	v_or_b32_e32 v6, s3, v111
	v_ashrrev_i32_e32 v7, 31, v6
	v_lshlrev_b64 v[6:7], 13, v[6:7]
	v_lshl_add_u64 v[6:7], v[8:9], 0, v[6:7]
	global_store_dwordx4 v[6:7], v[2:5], off
	s_waitcnt lgkmcnt(7)
	s_nop 0
	v_cvt_pk_bf16_f32 v2, v240, v241
	s_waitcnt lgkmcnt(6)
	v_cvt_pk_bf16_f32 v3, v242, v243
	s_waitcnt lgkmcnt(5)
	v_cvt_pk_bf16_f32 v4, v244, v245
	s_waitcnt lgkmcnt(4)
	v_cvt_pk_bf16_f32 v5, v246, v247
	v_or_b32_e32 v6, s3, v112
	v_ashrrev_i32_e32 v7, 31, v6
	v_lshlrev_b64 v[6:7], 13, v[6:7]
	v_lshl_add_u64 v[6:7], v[8:9], 0, v[6:7]
	global_store_dwordx4 v[6:7], v[2:5], off
	s_waitcnt lgkmcnt(3)
	s_nop 0
	v_cvt_pk_bf16_f32 v2, v248, v249
	s_waitcnt lgkmcnt(2)
	v_cvt_pk_bf16_f32 v3, v250, v251
	s_waitcnt lgkmcnt(1)
	v_cvt_pk_bf16_f32 v4, v252, v253
	s_waitcnt lgkmcnt(0)
	v_cvt_pk_bf16_f32 v5, v254, v255
	v_or_b32_e32 v6, s3, v113
	v_ashrrev_i32_e32 v7, 31, v6
	v_lshlrev_b64 v[6:7], 13, v[6:7]
	v_lshl_add_u64 v[6:7], v[8:9], 0, v[6:7]
	global_store_dwordx4 v[6:7], v[2:5], off
	s_waitcnt lgkmcnt(0)
; #define LAS __attribute__((address_space(3)))
; __device__ __forceinline__ void p0_item_load(const float* __restrict__ W, int N, int nblk, int nb0, int item, int lane, f32x4 (&v)[8]) {
;     const int kb = item / nblk, nb = nb0 + item % nblk;
;     const float* src = W + (size_t)(64 * kb + (lane >> 3)) * N + 32 * nb + 4 * (lane & 7);
; #pragma unroll
;     for (int i = 0; i < 8; ++i) v[i] = __builtin_nontemporal_load((const f32x4*)(src + (size_t)(8 * i) * N));
; }
; __device__ __forceinline__ void p0_item_store(const f32x4 (&v)[8], int K, int nblk, int nb0, bf16* __restrict__ WT, int mode, LAS float* scr, int item, int lane) {
;     const int kb = item / nblk, nb = nb0 + item % nblk, k0 = 64 * kb, n0 = 32 * nb;
; #pragma unroll
;     for (int i = 0; i < 8; ++i) { LAS float* d = scr + (8 * i + (lane >> 3)) * 33 + 4 * (lane & 7); d[0] = v[i].x; d[1] = v[i].y; d[2] = v[i].z; d[3] = v[i].w; }
;     LDS_WAIT(); asm volatile("" ::: "memory");
;     const int c = lane & 7, r0 = map_row(n0, mode);
;     const float wsc = mode == 1 ? 1.44269504089f : (mode == 2 ? 0.69314718056f : 1.0f);
; #pragma unroll
;     for (int j = 0; j < 4; ++j) { const int n = (lane >> 3) + 8 * j; const LAS float* s = scr + (8 * c) * 33 + n;
;         v4u o; o.x = cvt_pk_bf16(s[0 * 33] * wsc, s[1 * 33] * wsc); o.y = cvt_pk_bf16(s[2 * 33] * wsc, s[3 * 33] * wsc); o.z = cvt_pk_bf16(s[4 * 33] * wsc, s[5 * 33] * wsc); o.w = cvt_pk_bf16(s[6 * 33] * wsc, s[7 * 33] * wsc);
;         *(v4u*)(WT + (size_t)(r0 + n) * K + k0 + 8 * c) = o; }
;     LDS_WAIT(); asm volatile("" ::: "memory");
; }
;     LAS float* scr = (LAS float*)(F.lds + RING_OFF + F.wave * 16384);
;     const int nblk = nbn ? nbn : N / 32, nall = (K / 64) * nblk, nitems = (int)((long)nall * f1 / 16);
;     int it = (int)((long)nall * f0 / 16) + w0; if (it >= nitems) return;
;     f32x4 va[8], vb[8], vc[8];
;     __builtin_amdgcn_s_waitcnt(0x0F70);
;     const int last = nitems - 1, ntri = ((nitems - it + nw - 1) / nw + 2) / 3;
;     int i1 = min(it + nw, last);
;     p0_item_load(W, N, nblk, nb0, it, F.lane, va);
;     p0_item_load(W, N, nblk, nb0, i1, F.lane, vb); __builtin_amdgcn_sched_barrier(0);
;     for (int p = 0; p < ntri; ++p) {
;         const int i2 = min(i1 + nw, last), i3 = min(i2 + nw, last), i4 = min(i3 + nw, last);
;         p0_item_load(W, N, nblk, nb0, i2, F.lane, vc); __builtin_amdgcn_sched_barrier(0);
	s_ashr_i32 s3, s1, 31
	s_lshr_b32 s3, s3, 25
	s_add_i32 s3, s1, s3
	s_ashr_i32 s9, s3, 7
	s_and_b32 s3, s3, 0x7ffff80
	v_lshl_or_b32 v2, s9, 6, v108
	s_sub_i32 s3, s1, s3
	v_ashrrev_i32_e32 v3, 31, v2
	v_lshlrev_b64 v[2:3], 14, v[2:3]
	s_lshl_b32 s18, s3, 5
	v_lshl_add_u64 v[2:3], s[62:63], 0, v[2:3]
	s_ashr_i32 s19, s18, 31
	v_lshl_add_u64 v[2:3], s[18:19], 2, v[2:3]
	v_lshl_add_u64 v[34:35], v[2:3], 0, v[98:99]
	v_add_co_u32_e32 v2, vcc, s4, v34
	s_nop 1
	v_addc_co_u32_e32 v3, vcc, 0, v35, vcc
	v_add_co_u32_e32 v6, vcc, s12, v34
	global_load_dwordx4 v[30:33], v[34:35], off nt
	s_nop 0
	global_load_dwordx4 v[2:5], v[2:3], off nt
	v_addc_co_u32_e32 v7, vcc, 0, v35, vcc
	v_add_co_u32_e32 v10, vcc, s5, v34
	s_nop 1
	v_addc_co_u32_e32 v11, vcc, 0, v35, vcc
	v_add_co_u32_e32 v14, vcc, s13, v34
	global_load_dwordx4 v[6:9], v[6:7], off nt
	s_nop 0
	global_load_dwordx4 v[10:13], v[10:11], off nt
	v_addc_co_u32_e32 v15, vcc, 0, v35, vcc
	v_add_co_u32_e32 v22, vcc, s14, v34
	s_nop 1
	v_addc_co_u32_e32 v23, vcc, 0, v35, vcc
	v_add_co_u32_e32 v36, vcc, s16, v34
	global_load_dwordx4 v[14:17], v[14:15], off nt
	s_nop 0
	global_load_dwordx4 v[22:25], v[22:23], off nt
	v_addc_co_u32_e32 v37, vcc, 0, v35, vcc
	v_add_co_u32_e32 v38, vcc, s15, v34
	s_nop 1
	v_addc_co_u32_e32 v39, vcc, 0, v35, vcc
	global_load_dwordx4 v[34:37], v[36:37], off nt
	s_nop 0
	global_load_dwordx4 v[38:41], v[38:39], off nt
	ds_write2_b32 v102, v18, v19 offset1:1
	ds_write2_b32 v102, v20, v21 offset0:2 offset1:3
	ds_write2_b32 v103, v26, v27 offset1:1
	ds_write2_b32 v104, v28, v29 offset1:1
	ds_write2_b32 v105, v42, v43 offset1:1
	ds_write2_b32 v106, v44, v45 offset1:1
	ds_write2_b32 v107, v46, v47 offset1:1
	ds_write2_b32 v115, v48, v49 offset1:1
	ds_write2_b32 v116, v50, v51 offset1:1
	ds_write2_b32 v117, v52, v53 offset1:1
	ds_write2_b32 v118, v54, v55 offset1:1
	ds_write2_b32 v119, v56, v57 offset1:1
	ds_write2_b32 v120, v58, v59 offset1:1
	ds_write2_b32 v121, v60, v61 offset1:1
	ds_write2_b32 v122, v62, v63 offset1:1
	ds_write2_b32 v123, v64, v65 offset1:1
	s_waitcnt lgkmcnt(0)
	s_ashr_i32 s3, s11, 31
	s_lshr_b32 s3, s3, 25
	ds_read2_b32 v[240:241], v114 offset1:33
	ds_read2_b32 v[242:243], v114 offset0:66 offset1:99
	ds_read2_b32 v[244:245], v114 offset0:132 offset1:165
	ds_read2_b32 v[246:247], v114 offset0:198 offset1:231
	ds_read2_b32 v[248:249], v114 offset0:8 offset1:41
	ds_read2_b32 v[250:251], v114 offset0:74 offset1:107
	ds_read2_b32 v[252:253], v114 offset0:140 offset1:173
	ds_read2_b32 v[254:255], v114 offset0:206 offset1:239
	s_add_i32 s3, s11, s3
	s_waitcnt lgkmcnt(7)
	v_cvt_pk_bf16_f32 v18, v240, v241
	ds_read2_b32 v[240:241], v114 offset0:16 offset1:49
	s_ashr_i32 s9, s3, 7
	s_and_b32 s3, s3, 0x7ffff80
	s_waitcnt lgkmcnt(7)
	v_cvt_pk_bf16_f32 v19, v242, v243
	ds_read2_b32 v[242:243], v114 offset0:82 offset1:115
	s_sub_i32 s3, s11, s3
	s_waitcnt lgkmcnt(7)
	v_cvt_pk_bf16_f32 v20, v244, v245
	ds_read2_b32 v[244:245], v114 offset0:148 offset1:181
	s_lshl_b32 s3, s3, 5
	s_lshl_b32 s18, s9, 6
	s_waitcnt lgkmcnt(7)
	v_cvt_pk_bf16_f32 v21, v246, v247
	ds_read2_b32 v[246:247], v114 offset0:214 offset1:247
	v_or_b32_e32 v26, s3, v108
	s_ashr_i32 s19, s18, 31
	v_ashrrev_i32_e32 v27, 31, v26
	v_lshl_add_u64 v[28:29], s[18:19], 1, v[100:101]
	v_lshlrev_b64 v[26:27], 13, v[26:27]
	v_lshl_add_u64 v[26:27], v[28:29], 0, v[26:27]
	global_store_dwordx4 v[26:27], v[18:21], off
	s_waitcnt lgkmcnt(7)
	s_nop 0
	v_cvt_pk_bf16_f32 v18, v248, v249
	ds_read2_b32 v[248:249], v114 offset0:24 offset1:57
	s_waitcnt lgkmcnt(7)
	v_cvt_pk_bf16_f32 v19, v250, v251
	ds_read2_b32 v[250:251], v114 offset0:90 offset1:123
	s_waitcnt lgkmcnt(7)
	v_cvt_pk_bf16_f32 v20, v252, v253
	ds_read2_b32 v[252:253], v114 offset0:156 offset1:189
	s_waitcnt lgkmcnt(7)
	v_cvt_pk_bf16_f32 v21, v254, v255
	ds_read2_b32 v[254:255], v114 offset0:222 offset1:255
	v_or_b32_e32 v26, s3, v111
	v_ashrrev_i32_e32 v27, 31, v26
	v_lshlrev_b64 v[26:27], 13, v[26:27]
	v_lshl_add_u64 v[26:27], v[28:29], 0, v[26:27]
	global_store_dwordx4 v[26:27], v[18:21], off
	s_waitcnt lgkmcnt(7)
	s_nop 0
	v_cvt_pk_bf16_f32 v18, v240, v241
	v_or_b32_e32 v42, s3, v112
	v_ashrrev_i32_e32 v43, 31, v42
	s_waitcnt lgkmcnt(6)
	v_cvt_pk_bf16_f32 v19, v242, v243
	v_lshlrev_b64 v[42:43], 13, v[42:43]
	s_waitcnt lgkmcnt(5)
	v_cvt_pk_bf16_f32 v20, v244, v245
	s_waitcnt lgkmcnt(4)
	v_cvt_pk_bf16_f32 v21, v246, v247
	v_lshl_add_u64 v[42:43], v[28:29], 0, v[42:43]
	global_store_dwordx4 v[42:43], v[18:21], off
	v_or_b32_e32 v42, s3, v113
	v_ashrrev_i32_e32 v43, 31, v42
	s_waitcnt lgkmcnt(3)
	v_cvt_pk_bf16_f32 v18, v248, v249
	s_waitcnt lgkmcnt(2)
	v_cvt_pk_bf16_f32 v19, v250, v251
	s_waitcnt lgkmcnt(1)
	v_cvt_pk_bf16_f32 v20, v252, v253
	v_lshlrev_b64 v[42:43], 13, v[42:43]
	s_waitcnt lgkmcnt(0)
	v_cvt_pk_bf16_f32 v21, v254, v255
	v_lshl_add_u64 v[26:27], v[28:29], 0, v[42:43]
	global_store_dwordx4 v[26:27], v[18:21], off
	s_waitcnt lgkmcnt(0)
; #define LAS __attribute__((address_space(3)))
; __device__ __forceinline__ void p0_item_load(const float* __restrict__ W, int N, int nblk, int nb0, int item, int lane, f32x4 (&v)[8]) {
;     const int kb = item / nblk, nb = nb0 + item % nblk;
;     const float* src = W + (size_t)(64 * kb + (lane >> 3)) * N + 32 * nb + 4 * (lane & 7);
; #pragma unroll
;     for (int i = 0; i < 8; ++i) v[i] = __builtin_nontemporal_load((const f32x4*)(src + (size_t)(8 * i) * N));
; }
; __device__ __forceinline__ void p0_item_store(const f32x4 (&v)[8], int K, int nblk, int nb0, bf16* __restrict__ WT, int mode, LAS float* scr, int item, int lane) {
;     const int kb = item / nblk, nb = nb0 + item % nblk, k0 = 64 * kb, n0 = 32 * nb;
; #pragma unroll
;     for (int i = 0; i < 8; ++i) { LAS float* d = scr + (8 * i + (lane >> 3)) * 33 + 4 * (lane & 7); d[0] = v[i].x; d[1] = v[i].y; d[2] = v[i].z; d[3] = v[i].w; }
;     LDS_WAIT(); asm volatile("" ::: "memory");
;     const int c = lane & 7, r0 = map_row(n0, mode);
;     const float wsc = mode == 1 ? 1.44269504089f : (mode == 2 ? 0.69314718056f : 1.0f);
; #pragma unroll
;     for (int j = 0; j < 4; ++j) { const int n = (lane >> 3) + 8 * j; const LAS float* s = scr + (8 * c) * 33 + n;
;         v4u o; o.x = cvt_pk_bf16(s[0 * 33] * wsc, s[1 * 33] * wsc); o.y = cvt_pk_bf16(s[2 * 33] * wsc, s[3 * 33] * wsc); o.z = cvt_pk_bf16(s[4 * 33] * wsc, s[5 * 33] * wsc); o.w = cvt_pk_bf16(s[6 * 33] * wsc, s[7 * 33] * wsc);
;         *(v4u*)(WT + (size_t)(r0 + n) * K + k0 + 8 * c) = o; }
;     LDS_WAIT(); asm volatile("" ::: "memory");
; }
;     LAS float* scr = (LAS float*)(F.lds + RING_OFF + F.wave * 16384);
;     const int nblk = nbn ? nbn : N / 32, nall = (K / 64) * nblk, nitems = (int)((long)nall * f1 / 16);
;     int it = (int)((long)nall * f0 / 16) + w0; if (it >= nitems) return;
;     f32x4 va[8], vb[8], vc[8];
;     __builtin_amdgcn_s_waitcnt(0x0F70);
;     const int last = nitems - 1, ntri = ((nitems - it + nw - 1) / nw + 2) / 3;
;     int i1 = min(it + nw, last);
;     p0_item_load(W, N, nblk, nb0, it, F.lane, va);
;     p0_item_load(W, N, nblk, nb0, i1, F.lane, vb); __builtin_amdgcn_sched_barrier(0);
;     for (int p = 0; p < ntri; ++p) {
;         const int i2 = min(i1 + nw, last), i3 = min(i2 + nw, last), i4 = min(i3 + nw, last);
;         p0_item_load(W, N, nblk, nb0, i2, F.lane, vc); __builtin_amdgcn_sched_barrier(0);
	s_ashr_i32 s3, s17, 31
	s_lshr_b32 s3, s3, 25
	s_add_i32 s3, s17, s3
	s_ashr_i32 s9, s3, 7
	s_and_b32 s3, s3, 0x7ffff80
	v_lshl_or_b32 v18, s9, 6, v108
	s_sub_i32 s3, s17, s3
	v_ashrrev_i32_e32 v19, 31, v18
	v_lshlrev_b64 v[18:19], 14, v[18:19]
	s_lshl_b32 s18, s3, 5
	v_lshl_add_u64 v[18:19], s[62:63], 0, v[18:19]
	s_ashr_i32 s19, s18, 31
	v_lshl_add_u64 v[18:19], s[18:19], 2, v[18:19]
	v_lshl_add_u64 v[58:59], v[18:19], 0, v[98:99]
	v_add_co_u32_e32 v26, vcc, s4, v58
	s_nop 1
	v_addc_co_u32_e32 v27, vcc, 0, v59, vcc
	v_add_co_u32_e32 v42, vcc, s12, v58
	global_load_dwordx4 v[18:21], v[58:59], off nt
	s_nop 0
	global_load_dwordx4 v[26:29], v[26:27], off nt
	v_addc_co_u32_e32 v43, vcc, 0, v59, vcc
	v_add_co_u32_e32 v46, vcc, s5, v58
	s_nop 1
	v_addc_co_u32_e32 v47, vcc, 0, v59, vcc
	v_add_co_u32_e32 v50, vcc, s13, v58
	global_load_dwordx4 v[42:45], v[42:43], off nt
	s_nop 0
	global_load_dwordx4 v[46:49], v[46:47], off nt
	v_addc_co_u32_e32 v51, vcc, 0, v59, vcc
	v_add_co_u32_e32 v54, vcc, s14, v58
	s_nop 1
	v_addc_co_u32_e32 v55, vcc, 0, v59, vcc
	v_add_co_u32_e32 v60, vcc, s16, v58
	global_load_dwordx4 v[50:53], v[50:51], off nt
	s_nop 0
	global_load_dwordx4 v[54:57], v[54:55], off nt
	v_addc_co_u32_e32 v61, vcc, 0, v59, vcc
	v_add_co_u32_e32 v62, vcc, s15, v58
	s_nop 1
	v_addc_co_u32_e32 v63, vcc, 0, v59, vcc
	global_load_dwordx4 v[58:61], v[60:61], off nt
	s_nop 0
	global_load_dwordx4 v[62:65], v[62:63], off nt
	ds_write2_b32 v102, v66, v67 offset1:1
	ds_write2_b32 v102, v68, v69 offset0:2 offset1:3
	ds_write2_b32 v103, v70, v71 offset1:1
	ds_write2_b32 v104, v72, v73 offset1:1
	ds_write2_b32 v105, v74, v75 offset1:1
	ds_write2_b32 v106, v76, v77 offset1:1
	ds_write2_b32 v107, v78, v79 offset1:1
	ds_write2_b32 v115, v80, v81 offset1:1
	ds_write2_b32 v116, v82, v83 offset1:1
	ds_write2_b32 v117, v84, v85 offset1:1
	ds_write2_b32 v118, v86, v87 offset1:1
	ds_write2_b32 v119, v88, v89 offset1:1
	ds_write2_b32 v120, v90, v91 offset1:1
	ds_write2_b32 v121, v92, v93 offset1:1
	ds_write2_b32 v122, v94, v95 offset1:1
	ds_write2_b32 v123, v96, v97 offset1:1
	s_waitcnt lgkmcnt(0)
	ds_read2_b32 v[240:241], v114 offset1:33
	ds_read2_b32 v[242:243], v114 offset0:66 offset1:99
	ds_read2_b32 v[244:245], v114 offset0:132 offset1:165
	ds_read2_b32 v[246:247], v114 offset0:198 offset1:231
	ds_read2_b32 v[248:249], v114 offset0:8 offset1:41
	ds_read2_b32 v[250:251], v114 offset0:74 offset1:107
	ds_read2_b32 v[252:253], v114 offset0:140 offset1:173
	ds_read2_b32 v[254:255], v114 offset0:206 offset1:239
	s_waitcnt lgkmcnt(7)
	v_cvt_pk_bf16_f32 v66, v240, v241
	ds_read2_b32 v[240:241], v114 offset0:16 offset1:49
	s_waitcnt lgkmcnt(7)
	v_cvt_pk_bf16_f32 v67, v242, v243
	ds_read2_b32 v[242:243], v114 offset0:82 offset1:115
	s_waitcnt lgkmcnt(7)
	v_cvt_pk_bf16_f32 v68, v244, v245
	ds_read2_b32 v[244:245], v114 offset0:148 offset1:181
	s_waitcnt lgkmcnt(7)
	v_cvt_pk_bf16_f32 v69, v246, v247
	ds_read2_b32 v[246:247], v114 offset0:214 offset1:247
	v_or_b32_e32 v70, s0, v108
	s_ashr_i32 s3, s2, 31
	v_ashrrev_i32_e32 v71, 31, v70
	v_lshl_add_u64 v[72:73], s[2:3], 1, v[100:101]
	v_lshlrev_b64 v[70:71], 13, v[70:71]
	v_lshl_add_u64 v[70:71], v[72:73], 0, v[70:71]
	global_store_dwordx4 v[70:71], v[66:69], off
	s_waitcnt lgkmcnt(7)
	s_nop 0
	v_cvt_pk_bf16_f32 v66, v248, v249
	ds_read2_b32 v[248:249], v114 offset0:24 offset1:57
	v_or_b32_e32 v74, s0, v111
	v_ashrrev_i32_e32 v75, 31, v74
	v_lshlrev_b64 v[74:75], 13, v[74:75]
	s_waitcnt lgkmcnt(7)
	v_cvt_pk_bf16_f32 v67, v250, v251
	ds_read2_b32 v[250:251], v114 offset0:90 offset1:123
	v_lshl_add_u64 v[74:75], v[72:73], 0, v[74:75]
	s_waitcnt lgkmcnt(7)
	v_cvt_pk_bf16_f32 v68, v252, v253
	ds_read2_b32 v[252:253], v114 offset0:156 offset1:189
	s_waitcnt lgkmcnt(7)
	v_cvt_pk_bf16_f32 v69, v254, v255
	ds_read2_b32 v[254:255], v114 offset0:222 offset1:255
	global_store_dwordx4 v[74:75], v[66:69], off
	v_or_b32_e32 v74, s0, v112
	s_waitcnt lgkmcnt(7)
	v_cvt_pk_bf16_f32 v66, v240, v241
	v_ashrrev_i32_e32 v75, 31, v74
	s_waitcnt lgkmcnt(6)
	v_cvt_pk_bf16_f32 v67, v242, v243
	v_lshlrev_b64 v[74:75], 13, v[74:75]
	s_waitcnt lgkmcnt(5)
	v_cvt_pk_bf16_f32 v68, v244, v245
	s_waitcnt lgkmcnt(4)
	v_cvt_pk_bf16_f32 v69, v246, v247
	v_lshl_add_u64 v[74:75], v[72:73], 0, v[74:75]
	global_store_dwordx4 v[74:75], v[66:69], off
	v_or_b32_e32 v74, s0, v113
	v_ashrrev_i32_e32 v75, 31, v74
	s_waitcnt lgkmcnt(3)
	v_cvt_pk_bf16_f32 v66, v248, v249
	s_waitcnt lgkmcnt(2)
	v_cvt_pk_bf16_f32 v67, v250, v251
	s_waitcnt lgkmcnt(1)
	v_cvt_pk_bf16_f32 v68, v252, v253
	v_lshlrev_b64 v[74:75], 13, v[74:75]
	s_waitcnt lgkmcnt(0)
	v_cvt_pk_bf16_f32 v69, v254, v255
	v_lshl_add_u64 v[70:71], v[72:73], 0, v[74:75]
	global_store_dwordx4 v[70:71], v[66:69], off
	s_waitcnt lgkmcnt(0)
	s_add_i32 s10, s10, -1
	s_cmp_lg_u32 s10, 0
	s_mov_b32 s9, s1
	s_mov_b32 s11, s17
	s_cbranch_scc1 .LBB0_484

; #define LAS __attribute__((address_space(3)))
; __device__ __forceinline__ void p0_item_load(const float* __restrict__ W, int N, int nblk, int nb0, int item, int lane, f32x4 (&v)[8]) {
;     const int kb = item / nblk, nb = nb0 + item % nblk;
;     const float* src = W + (size_t)(64 * kb + (lane >> 3)) * N + 32 * nb + 4 * (lane & 7);
; #pragma unroll
;     for (int i = 0; i < 8; ++i) v[i] = __builtin_nontemporal_load((const f32x4*)(src + (size_t)(8 * i) * N));
; }
; __device__ __forceinline__ void p0_item_store(const f32x4 (&v)[8], int K, int nblk, int nb0, bf16* __restrict__ WT, int mode, LAS float* scr, int item, int lane) {
;     const int kb = item / nblk, nb = nb0 + item % nblk, k0 = 64 * kb, n0 = 32 * nb;
; #pragma unroll
;     for (int i = 0; i < 8; ++i) { LAS float* d = scr + (8 * i + (lane >> 3)) * 33 + 4 * (lane & 7); d[0] = v[i].x; d[1] = v[i].y; d[2] = v[i].z; d[3] = v[i].w; }
;     LDS_WAIT(); asm volatile("" ::: "memory");
;     const int c = lane & 7, r0 = map_row(n0, mode);
;     const float wsc = mode == 1 ? 1.44269504089f : (mode == 2 ? 0.69314718056f : 1.0f);
; #pragma unroll
;     for (int j = 0; j < 4; ++j) { const int n = (lane >> 3) + 8 * j; const LAS float* s = scr + (8 * c) * 33 + n;
;         v4u o; o.x = cvt_pk_bf16(s[0 * 33] * wsc, s[1 * 33] * wsc); o.y = cvt_pk_bf16(s[2 * 33] * wsc, s[3 * 33] * wsc); o.z = cvt_pk_bf16(s[4 * 33] * wsc, s[5 * 33] * wsc); o.w = cvt_pk_bf16(s[6 * 33] * wsc, s[7 * 33] * wsc);
;         *(v4u*)(WT + (size_t)(r0 + n) * K + k0 + 8 * c) = o; }
;     LDS_WAIT(); asm volatile("" ::: "memory");
; }
;     LAS float* scr = (LAS float*)(F.lds + RING_OFF + F.wave * 16384);
;     const int nblk = nbn ? nbn : N / 32, nall = (K / 64) * nblk, nitems = (int)((long)nall * f1 / 16);
;     int it = (int)((long)nall * f0 / 16) + w0; if (it >= nitems) return;
;     f32x4 va[8], vb[8], vc[8];
;     __builtin_amdgcn_s_waitcnt(0x0F70);
;     const int last = nitems - 1, ntri = ((nitems - it + nw - 1) / nw + 2) / 3;
;     int i1 = min(it + nw, last);
;     p0_item_load(W, N, nblk, nb0, it, F.lane, va);
;     p0_item_load(W, N, nblk, nb0, i1, F.lane, vb); __builtin_amdgcn_sched_barrier(0);
;     for (int p = 0; p < ntri; ++p) {
;         const int i2 = min(i1 + nw, last), i3 = min(i2 + nw, last), i4 = min(i3 + nw, last);
;         p0_item_load(W, N, nblk, nb0, i2, F.lane, vc); __builtin_amdgcn_sched_barrier(0);
.LBB0_1302:
	s_add_i32 s0, s3, s4
	s_min_i32 s16, s0, 0x55ff
	s_ashr_i32 s0, s16, 31
	s_lshr_b32 s0, s0, 25
	s_add_i32 s0, s16, s0
	s_ashr_i32 s1, s0, 7
	s_lshl_b32 s2, s1, 6
	s_and_b32 s0, s0, 0x7ffff80
	v_or_b32_e32 v66, s2, v102
	s_sub_i32 s0, s16, s0
	v_ashrrev_i32_e32 v67, 31, v66
	v_lshlrev_b64 v[66:67], 14, v[66:67]
	s_lshl_b32 s0, s0, 5
	v_lshl_add_u64 v[66:67], s[6:7], 0, v[66:67]
	s_ashr_i32 s1, s0, 31
	v_lshl_add_u64 v[66:67], s[0:1], 2, v[66:67]
	v_lshl_add_u64 v[90:91], v[66:67], 0, v[98:99]
	v_add_co_u32_e32 v74, vcc, s5, v90
	s_add_i32 s16, s16, s4
	s_nop 0
	v_addc_co_u32_e32 v75, vcc, 0, v91, vcc
	v_add_co_u32_e32 v82, vcc, s8, v90
	global_load_dwordx4 v[66:69], v[90:91], off nt
	global_load_dwordx4 v[70:73], v[74:75], off nt
	v_addc_co_u32_e32 v83, vcc, 0, v91, vcc
	v_add_co_u32_e32 v84, vcc, s9, v90
	s_min_i32 s1, s16, 0x55ff
	s_nop 0
	v_addc_co_u32_e32 v85, vcc, 0, v91, vcc
	v_add_co_u32_e32 v92, vcc, s10, v90
	global_load_dwordx4 v[74:77], v[82:83], off nt
	global_load_dwordx4 v[78:81], v[84:85], off nt
	v_addc_co_u32_e32 v93, vcc, 0, v91, vcc
	v_add_co_u32_e32 v94, vcc, s11, v90
	s_add_i32 s16, s1, s4
	s_nop 0
	v_addc_co_u32_e32 v95, vcc, 0, v91, vcc
	v_add_co_u32_e32 v108, vcc, s12, v90
	global_load_dwordx4 v[82:85], v[92:93], off nt
	global_load_dwordx4 v[86:89], v[94:95], off nt
	v_addc_co_u32_e32 v109, vcc, 0, v91, vcc
	v_add_co_u32_e32 v110, vcc, s13, v90
	s_min_i32 s16, s16, 0x55ff
	s_nop 0
	v_addc_co_u32_e32 v111, vcc, 0, v91, vcc
	global_load_dwordx4 v[90:93], v[108:109], off nt
	global_load_dwordx4 v[94:97], v[110:111], off nt
	s_ashr_i32 s18, s17, 31
	s_lshr_b32 s18, s18, 25
	s_add_i32 s18, s17, s18
	v_add_u32_e32 v112, 0x420, v107
	v_add_u32_e32 v113, 0x428, v107
	v_add_u32_e32 v114, 0x840, v107
	v_add_u32_e32 v115, 0x848, v107
	v_add_u32_e32 v116, 0xc60, v107
	v_add_u32_e32 v117, 0xc68, v107
	v_add_u32_e32 v118, 0x1080, v107
	v_add_u32_e32 v119, 0x1088, v107
	v_add_u32_e32 v120, 0x14a0, v107
	v_add_u32_e32 v121, 0x14a8, v107
	v_add_u32_e32 v122, 0x18c0, v107
	v_add_u32_e32 v123, 0x18c8, v107
	v_add_u32_e32 v124, 0x1ce0, v107
	v_add_u32_e32 v125, 0x1ce8, v107
	s_ashr_i32 s19, s18, 7
	s_and_b32 s18, s18, 0x7ffff80
	s_waitcnt vmcnt(17)
	ds_write2_b32 v107, v30, v31 offset1:1
	ds_write2_b32 v107, v32, v33 offset0:2 offset1:3
	ds_write2_b32 v112, v2, v3 offset1:1
	ds_write2_b32 v113, v4, v5 offset1:1
	ds_write2_b32 v114, v6, v7 offset1:1
	ds_write2_b32 v115, v8, v9 offset1:1
	ds_write2_b32 v116, v10, v11 offset1:1
	ds_write2_b32 v117, v12, v13 offset1:1
	ds_write2_b32 v118, v14, v15 offset1:1
	ds_write2_b32 v119, v16, v17 offset1:1
	ds_write2_b32 v120, v22, v23 offset1:1
	ds_write2_b32 v121, v24, v25 offset1:1
	ds_write2_b32 v122, v34, v35 offset1:1
	ds_write2_b32 v123, v36, v37 offset1:1
	s_waitcnt vmcnt(15)
	ds_write2_b32 v124, v42, v43 offset1:1
	ds_write2_b32 v125, v44, v45 offset1:1
	s_sub_i32 s17, s17, s18
	s_waitcnt lgkmcnt(0)
	s_lshl_b32 s17, s17, 5
	s_lshl_b32 s18, s19, 6
	v_or_b32_e32 v10, s17, v102
	ds_read2_b32 v[240:241], v106 offset1:33
	ds_read2_b32 v[242:243], v106 offset0:66 offset1:99
	ds_read2_b32 v[244:245], v106 offset0:132 offset1:165
	ds_read2_b32 v[246:247], v106 offset0:198 offset1:231
	ds_read2_b32 v[248:249], v106 offset0:8 offset1:41
	ds_read2_b32 v[250:251], v106 offset0:74 offset1:107
	ds_read2_b32 v[252:253], v106 offset0:140 offset1:173
	ds_read2_b32 v[254:255], v106 offset0:206 offset1:239
	s_ashr_i32 s19, s18, 31
	v_mul_lo_u32 v10, v10, s15
	s_waitcnt lgkmcnt(7)
	v_cvt_pk_bf16_f32 v2, v240, v241
	ds_read2_b32 v[240:241], v106 offset0:16 offset1:49
	v_lshl_add_u64 v[8:9], s[18:19], 1, v[100:101]
	v_ashrrev_i32_e32 v11, 31, v10
	s_waitcnt lgkmcnt(7)
	v_cvt_pk_bf16_f32 v3, v242, v243
	ds_read2_b32 v[242:243], v106 offset0:82 offset1:115
	v_lshl_add_u64 v[10:11], v[8:9], 0, v[10:11]
	s_waitcnt lgkmcnt(7)
	v_cvt_pk_bf16_f32 v4, v244, v245
	ds_read2_b32 v[244:245], v106 offset0:148 offset1:181
	s_waitcnt lgkmcnt(7)
	v_cvt_pk_bf16_f32 v5, v246, v247
	ds_read2_b32 v[246:247], v106 offset0:214 offset1:247
	global_store_dwordx4 v[10:11], v[2:5], off
	v_or_b32_e32 v10, s17, v103
	v_mul_lo_u32 v10, v10, s15
	s_waitcnt lgkmcnt(7)
	v_cvt_pk_bf16_f32 v2, v248, v249
	ds_read2_b32 v[248:249], v106 offset0:24 offset1:57
	v_ashrrev_i32_e32 v11, 31, v10
	s_waitcnt lgkmcnt(7)
	v_cvt_pk_bf16_f32 v3, v250, v251
	ds_read2_b32 v[250:251], v106 offset0:90 offset1:123
	v_lshl_add_u64 v[10:11], v[8:9], 0, v[10:11]
	s_waitcnt lgkmcnt(7)
	v_cvt_pk_bf16_f32 v4, v252, v253
	ds_read2_b32 v[252:253], v106 offset0:156 offset1:189
	s_waitcnt lgkmcnt(7)
	v_cvt_pk_bf16_f32 v5, v254, v255
	ds_read2_b32 v[254:255], v106 offset0:222 offset1:255
	global_store_dwordx4 v[10:11], v[2:5], off
	v_or_b32_e32 v10, s17, v104
	s_waitcnt lgkmcnt(7)
	v_cvt_pk_bf16_f32 v2, v240, v241
	v_mul_lo_u32 v10, v10, s15
	s_waitcnt lgkmcnt(6)
	v_cvt_pk_bf16_f32 v3, v242, v243
	v_ashrrev_i32_e32 v11, 31, v10
	s_waitcnt lgkmcnt(5)
	v_cvt_pk_bf16_f32 v4, v244, v245
	s_waitcnt lgkmcnt(4)
	v_cvt_pk_bf16_f32 v5, v246, v247
	v_lshl_add_u64 v[10:11], v[8:9], 0, v[10:11]
	global_store_dwordx4 v[10:11], v[2:5], off
	s_waitcnt lgkmcnt(3)
	s_nop 0
	v_cvt_pk_bf16_f32 v2, v248, v249
	s_waitcnt lgkmcnt(2)
	v_cvt_pk_bf16_f32 v3, v250, v251
	s_waitcnt lgkmcnt(1)
	v_cvt_pk_bf16_f32 v4, v252, v253
	s_waitcnt lgkmcnt(0)
	v_cvt_pk_bf16_f32 v5, v254, v255
	v_or_b32_e32 v6, s17, v105
	v_mul_lo_u32 v6, v6, s15
	v_ashrrev_i32_e32 v7, 31, v6
	v_lshl_add_u64 v[6:7], v[8:9], 0, v[6:7]
	global_store_dwordx4 v[6:7], v[2:5], off
	s_waitcnt lgkmcnt(0)
; #define LAS __attribute__((address_space(3)))
; __device__ __forceinline__ void p0_item_load(const float* __restrict__ W, int N, int nblk, int nb0, int item, int lane, f32x4 (&v)[8]) {
;     const int kb = item / nblk, nb = nb0 + item % nblk;
;     const float* src = W + (size_t)(64 * kb + (lane >> 3)) * N + 32 * nb + 4 * (lane & 7);
; #pragma unroll
;     for (int i = 0; i < 8; ++i) v[i] = __builtin_nontemporal_load((const f32x4*)(src + (size_t)(8 * i) * N));
; }
; __device__ __forceinline__ void p0_item_store(const f32x4 (&v)[8], int K, int nblk, int nb0, bf16* __restrict__ WT, int mode, LAS float* scr, int item, int lane) {
;     const int kb = item / nblk, nb = nb0 + item % nblk, k0 = 64 * kb, n0 = 32 * nb;
; #pragma unroll
;     for (int i = 0; i < 8; ++i) { LAS float* d = scr + (8 * i + (lane >> 3)) * 33 + 4 * (lane & 7); d[0] = v[i].x; d[1] = v[i].y; d[2] = v[i].z; d[3] = v[i].w; }
;     LDS_WAIT(); asm volatile("" ::: "memory");
;     const int c = lane & 7, r0 = map_row(n0, mode);
;     const float wsc = mode == 1 ? 1.44269504089f : (mode == 2 ? 0.69314718056f : 1.0f);
; #pragma unroll
;     for (int j = 0; j < 4; ++j) { const int n = (lane >> 3) + 8 * j; const LAS float* s = scr + (8 * c) * 33 + n;
;         v4u o; o.x = cvt_pk_bf16(s[0 * 33] * wsc, s[1 * 33] * wsc); o.y = cvt_pk_bf16(s[2 * 33] * wsc, s[3 * 33] * wsc); o.z = cvt_pk_bf16(s[4 * 33] * wsc, s[5 * 33] * wsc); o.w = cvt_pk_bf16(s[6 * 33] * wsc, s[7 * 33] * wsc);
;         *(v4u*)(WT + (size_t)(r0 + n) * K + k0 + 8 * c) = o; }
;     LDS_WAIT(); asm volatile("" ::: "memory");
; }
;     LAS float* scr = (LAS float*)(F.lds + RING_OFF + F.wave * 16384);
;     const int nblk = nbn ? nbn : N / 32, nall = (K / 64) * nblk, nitems = (int)((long)nall * f1 / 16);
;     int it = (int)((long)nall * f0 / 16) + w0; if (it >= nitems) return;
;     f32x4 va[8], vb[8], vc[8];
;     __builtin_amdgcn_s_waitcnt(0x0F70);
;     const int last = nitems - 1, ntri = ((nitems - it + nw - 1) / nw + 2) / 3;
;     int i1 = min(it + nw, last);
;     p0_item_load(W, N, nblk, nb0, it, F.lane, va);
;     p0_item_load(W, N, nblk, nb0, i1, F.lane, vb); __builtin_amdgcn_sched_barrier(0);
;     for (int p = 0; p < ntri; ++p) {
;         const int i2 = min(i1 + nw, last), i3 = min(i2 + nw, last), i4 = min(i3 + nw, last);
;         p0_item_load(W, N, nblk, nb0, i2, F.lane, vc); __builtin_amdgcn_sched_barrier(0);
	s_ashr_i32 s17, s1, 31
	s_lshr_b32 s17, s17, 25
	s_add_i32 s17, s1, s17
	s_ashr_i32 s18, s17, 7
	s_and_b32 s17, s17, 0x7ffff80
	v_lshl_or_b32 v2, s18, 6, v102
	s_sub_i32 s17, s1, s17
	v_ashrrev_i32_e32 v3, 31, v2
	v_lshlrev_b64 v[2:3], 14, v[2:3]
	s_lshl_b32 s18, s17, 5
	v_lshl_add_u64 v[2:3], s[6:7], 0, v[2:3]
	s_ashr_i32 s19, s18, 31
	v_lshl_add_u64 v[2:3], s[18:19], 2, v[2:3]
	v_lshl_add_u64 v[34:35], v[2:3], 0, v[98:99]
	v_add_co_u32_e32 v6, vcc, s5, v34
	s_nop 1
	v_addc_co_u32_e32 v7, vcc, 0, v35, vcc
	v_add_co_u32_e32 v14, vcc, s8, v34
	global_load_dwordx4 v[30:33], v[34:35], off nt
	global_load_dwordx4 v[2:5], v[6:7], off nt
	v_addc_co_u32_e32 v15, vcc, 0, v35, vcc
	v_add_co_u32_e32 v16, vcc, s9, v34
	s_nop 1
	v_addc_co_u32_e32 v17, vcc, 0, v35, vcc
	v_add_co_u32_e32 v36, vcc, s10, v34
	global_load_dwordx4 v[6:9], v[14:15], off nt
	global_load_dwordx4 v[10:13], v[16:17], off nt
	v_addc_co_u32_e32 v37, vcc, 0, v35, vcc
	v_add_co_u32_e32 v42, vcc, s11, v34
	s_nop 1
	v_addc_co_u32_e32 v43, vcc, 0, v35, vcc
	v_add_co_u32_e32 v108, vcc, s12, v34
	global_load_dwordx4 v[14:17], v[36:37], off nt
	global_load_dwordx4 v[22:25], v[42:43], off nt
	v_addc_co_u32_e32 v109, vcc, 0, v35, vcc
	v_add_co_u32_e32 v110, vcc, s13, v34
	s_nop 1
	v_addc_co_u32_e32 v111, vcc, 0, v35, vcc
	global_load_dwordx4 v[34:37], v[108:109], off nt
	global_load_dwordx4 v[42:45], v[110:111], off nt
	s_ashr_i32 s17, s3, 31
	s_lshr_b32 s17, s17, 25
	s_add_i32 s17, s3, s17
	s_ashr_i32 s18, s17, 7
	s_and_b32 s17, s17, 0x7ffff80
	ds_write2_b32 v107, v18, v19 offset1:1
	ds_write2_b32 v107, v20, v21 offset0:2 offset1:3
	s_waitcnt vmcnt(26)
	ds_write2_b32 v112, v26, v27 offset1:1
	ds_write2_b32 v113, v28, v29 offset1:1
	s_waitcnt vmcnt(25)
	ds_write2_b32 v114, v38, v39 offset1:1
	ds_write2_b32 v115, v40, v41 offset1:1
	s_waitcnt vmcnt(24)
	ds_write2_b32 v116, v46, v47 offset1:1
	ds_write2_b32 v117, v48, v49 offset1:1
	s_waitcnt vmcnt(23)
	ds_write2_b32 v118, v50, v51 offset1:1
	ds_write2_b32 v119, v52, v53 offset1:1
	s_waitcnt vmcnt(22)
	ds_write2_b32 v120, v54, v55 offset1:1
	ds_write2_b32 v121, v56, v57 offset1:1
	s_waitcnt vmcnt(21)
	ds_write2_b32 v122, v58, v59 offset1:1
	ds_write2_b32 v123, v60, v61 offset1:1
	s_waitcnt vmcnt(20)
	ds_write2_b32 v124, v62, v63 offset1:1
	ds_write2_b32 v125, v64, v65 offset1:1
	s_sub_i32 s3, s3, s17
	s_waitcnt lgkmcnt(0)
	s_lshl_b32 s3, s3, 5
	s_lshl_b32 s18, s18, 6
	v_or_b32_e32 v38, s3, v102
	ds_read2_b32 v[240:241], v106 offset1:33
	ds_read2_b32 v[242:243], v106 offset0:66 offset1:99
	ds_read2_b32 v[244:245], v106 offset0:132 offset1:165
	ds_read2_b32 v[246:247], v106 offset0:198 offset1:231
	ds_read2_b32 v[248:249], v106 offset0:8 offset1:41
	ds_read2_b32 v[250:251], v106 offset0:74 offset1:107
	ds_read2_b32 v[252:253], v106 offset0:140 offset1:173
	ds_read2_b32 v[254:255], v106 offset0:206 offset1:239
	s_ashr_i32 s19, s18, 31
	v_mul_lo_u32 v38, v38, s15
	s_waitcnt lgkmcnt(7)
	v_cvt_pk_bf16_f32 v18, v240, v241
	ds_read2_b32 v[240:241], v106 offset0:16 offset1:49
	v_lshl_add_u64 v[28:29], s[18:19], 1, v[100:101]
	v_ashrrev_i32_e32 v39, 31, v38
	s_waitcnt lgkmcnt(7)
	v_cvt_pk_bf16_f32 v19, v242, v243
	ds_read2_b32 v[242:243], v106 offset0:82 offset1:115
	v_lshl_add_u64 v[38:39], v[28:29], 0, v[38:39]
	s_waitcnt lgkmcnt(7)
	v_cvt_pk_bf16_f32 v20, v244, v245
	ds_read2_b32 v[244:245], v106 offset0:148 offset1:181
	s_waitcnt lgkmcnt(7)
	v_cvt_pk_bf16_f32 v21, v246, v247
	ds_read2_b32 v[246:247], v106 offset0:214 offset1:247
	global_store_dwordx4 v[38:39], v[18:21], off
	v_or_b32_e32 v38, s3, v103
	v_mul_lo_u32 v38, v38, s15
	s_waitcnt lgkmcnt(7)
	v_cvt_pk_bf16_f32 v18, v248, v249
	ds_read2_b32 v[248:249], v106 offset0:24 offset1:57
	v_ashrrev_i32_e32 v39, 31, v38
	s_waitcnt lgkmcnt(7)
	v_cvt_pk_bf16_f32 v19, v250, v251
	ds_read2_b32 v[250:251], v106 offset0:90 offset1:123
	v_lshl_add_u64 v[38:39], v[28:29], 0, v[38:39]
	s_waitcnt lgkmcnt(7)
	v_cvt_pk_bf16_f32 v20, v252, v253
	ds_read2_b32 v[252:253], v106 offset0:156 offset1:189
	s_waitcnt lgkmcnt(7)
	v_cvt_pk_bf16_f32 v21, v254, v255
	ds_read2_b32 v[254:255], v106 offset0:222 offset1:255
	global_store_dwordx4 v[38:39], v[18:21], off
	v_or_b32_e32 v38, s3, v104
	s_waitcnt lgkmcnt(7)
	v_cvt_pk_bf16_f32 v18, v240, v241
	v_mul_lo_u32 v38, v38, s15
	s_waitcnt lgkmcnt(6)
	v_cvt_pk_bf16_f32 v19, v242, v243
	v_ashrrev_i32_e32 v39, 31, v38
	s_waitcnt lgkmcnt(5)
	v_cvt_pk_bf16_f32 v20, v244, v245
	s_waitcnt lgkmcnt(4)
	v_cvt_pk_bf16_f32 v21, v246, v247
	v_lshl_add_u64 v[38:39], v[28:29], 0, v[38:39]
	global_store_dwordx4 v[38:39], v[18:21], off
	s_waitcnt lgkmcnt(3)
	s_nop 0
	v_cvt_pk_bf16_f32 v18, v248, v249
	s_waitcnt lgkmcnt(2)
	v_cvt_pk_bf16_f32 v19, v250, v251
	s_waitcnt lgkmcnt(1)
	v_cvt_pk_bf16_f32 v20, v252, v253
	v_or_b32_e32 v21, s3, v105
	v_mul_lo_u32 v38, v21, s15
	v_ashrrev_i32_e32 v39, 31, v38
	s_waitcnt lgkmcnt(0)
	v_cvt_pk_bf16_f32 v21, v254, v255
	v_lshl_add_u64 v[26:27], v[28:29], 0, v[38:39]
	global_store_dwordx4 v[26:27], v[18:21], off
	s_waitcnt lgkmcnt(0)
; #define LAS __attribute__((address_space(3)))
; __device__ __forceinline__ void p0_item_load(const float* __restrict__ W, int N, int nblk, int nb0, int item, int lane, f32x4 (&v)[8]) {
;     const int kb = item / nblk, nb = nb0 + item % nblk;
;     const float* src = W + (size_t)(64 * kb + (lane >> 3)) * N + 32 * nb + 4 * (lane & 7);
; #pragma unroll
;     for (int i = 0; i < 8; ++i) v[i] = __builtin_nontemporal_load((const f32x4*)(src + (size_t)(8 * i) * N));
; }
; __device__ __forceinline__ void p0_item_store(const f32x4 (&v)[8], int K, int nblk, int nb0, bf16* __restrict__ WT, int mode, LAS float* scr, int item, int lane) {
;     const int kb = item / nblk, nb = nb0 + item % nblk, k0 = 64 * kb, n0 = 32 * nb;
; #pragma unroll
;     for (int i = 0; i < 8; ++i) { LAS float* d = scr + (8 * i + (lane >> 3)) * 33 + 4 * (lane & 7); d[0] = v[i].x; d[1] = v[i].y; d[2] = v[i].z; d[3] = v[i].w; }
;     LDS_WAIT(); asm volatile("" ::: "memory");
;     const int c = lane & 7, r0 = map_row(n0, mode);
;     const float wsc = mode == 1 ? 1.44269504089f : (mode == 2 ? 0.69314718056f : 1.0f);
; #pragma unroll
;     for (int j = 0; j < 4; ++j) { const int n = (lane >> 3) + 8 * j; const LAS float* s = scr + (8 * c) * 33 + n;
;         v4u o; o.x = cvt_pk_bf16(s[0 * 33] * wsc, s[1 * 33] * wsc); o.y = cvt_pk_bf16(s[2 * 33] * wsc, s[3 * 33] * wsc); o.z = cvt_pk_bf16(s[4 * 33] * wsc, s[5 * 33] * wsc); o.w = cvt_pk_bf16(s[6 * 33] * wsc, s[7 * 33] * wsc);
;         *(v4u*)(WT + (size_t)(r0 + n) * K + k0 + 8 * c) = o; }
;     LDS_WAIT(); asm volatile("" ::: "memory");
; }
;     LAS float* scr = (LAS float*)(F.lds + RING_OFF + F.wave * 16384);
;     const int nblk = nbn ? nbn : N / 32, nall = (K / 64) * nblk, nitems = (int)((long)nall * f1 / 16);
;     int it = (int)((long)nall * f0 / 16) + w0; if (it >= nitems) return;
;     f32x4 va[8], vb[8], vc[8];
;     __builtin_amdgcn_s_waitcnt(0x0F70);
;     const int last = nitems - 1, ntri = ((nitems - it + nw - 1) / nw + 2) / 3;
;     int i1 = min(it + nw, last);
;     p0_item_load(W, N, nblk, nb0, it, F.lane, va);
;     p0_item_load(W, N, nblk, nb0, i1, F.lane, vb); __builtin_amdgcn_sched_barrier(0);
;     for (int p = 0; p < ntri; ++p) {
;         const int i2 = min(i1 + nw, last), i3 = min(i2 + nw, last), i4 = min(i3 + nw, last);
;         p0_item_load(W, N, nblk, nb0, i2, F.lane, vc); __builtin_amdgcn_sched_barrier(0);
	s_ashr_i32 s3, s16, 31
	s_lshr_b32 s3, s3, 25
	s_add_i32 s3, s16, s3
	s_ashr_i32 s17, s3, 7
	s_and_b32 s3, s3, 0x7ffff80
	v_lshl_or_b32 v18, s17, 6, v102
	s_sub_i32 s3, s16, s3
	v_ashrrev_i32_e32 v19, 31, v18
	v_lshlrev_b64 v[18:19], 14, v[18:19]
	s_lshl_b32 s18, s3, 5
	v_lshl_add_u64 v[18:19], s[6:7], 0, v[18:19]
	s_ashr_i32 s19, s18, 31
	v_lshl_add_u64 v[18:19], s[18:19], 2, v[18:19]
	v_lshl_add_u64 v[58:59], v[18:19], 0, v[98:99]
	v_add_co_u32_e32 v38, vcc, s5, v58
	s_nop 1
	v_addc_co_u32_e32 v39, vcc, 0, v59, vcc
	v_add_co_u32_e32 v50, vcc, s8, v58
	global_load_dwordx4 v[18:21], v[58:59], off nt
	global_load_dwordx4 v[26:29], v[38:39], off nt
	v_addc_co_u32_e32 v51, vcc, 0, v59, vcc
	v_add_co_u32_e32 v52, vcc, s9, v58
	s_nop 1
	v_addc_co_u32_e32 v53, vcc, 0, v59, vcc
	v_add_co_u32_e32 v60, vcc, s10, v58
	global_load_dwordx4 v[38:41], v[50:51], off nt
	global_load_dwordx4 v[46:49], v[52:53], off nt
	v_addc_co_u32_e32 v61, vcc, 0, v59, vcc
	v_add_co_u32_e32 v62, vcc, s11, v58
	s_nop 1
	v_addc_co_u32_e32 v63, vcc, 0, v59, vcc
	v_add_co_u32_e32 v108, vcc, s12, v58
	global_load_dwordx4 v[50:53], v[60:61], off nt
	global_load_dwordx4 v[54:57], v[62:63], off nt
	v_addc_co_u32_e32 v109, vcc, 0, v59, vcc
	v_add_co_u32_e32 v110, vcc, s13, v58
	s_nop 1
	v_addc_co_u32_e32 v111, vcc, 0, v59, vcc
	global_load_dwordx4 v[58:61], v[108:109], off nt
	global_load_dwordx4 v[62:65], v[110:111], off nt
	s_waitcnt vmcnt(31)
	ds_write2_b32 v107, v66, v67 offset1:1
	ds_write2_b32 v107, v68, v69 offset0:2 offset1:3
	s_waitcnt vmcnt(30)
	ds_write2_b32 v112, v70, v71 offset1:1
	ds_write2_b32 v113, v72, v73 offset1:1
	s_waitcnt vmcnt(29)
	ds_write2_b32 v114, v74, v75 offset1:1
	ds_write2_b32 v115, v76, v77 offset1:1
	s_waitcnt vmcnt(28)
	ds_write2_b32 v116, v78, v79 offset1:1
	ds_write2_b32 v117, v80, v81 offset1:1
	s_waitcnt vmcnt(27)
	ds_write2_b32 v118, v82, v83 offset1:1
	ds_write2_b32 v119, v84, v85 offset1:1
	s_waitcnt vmcnt(26)
	ds_write2_b32 v120, v86, v87 offset1:1
	ds_write2_b32 v121, v88, v89 offset1:1
	s_waitcnt vmcnt(25)
	ds_write2_b32 v122, v90, v91 offset1:1
	ds_write2_b32 v123, v92, v93 offset1:1
	s_waitcnt vmcnt(24)
	ds_write2_b32 v124, v94, v95 offset1:1
	ds_write2_b32 v125, v96, v97 offset1:1
	s_waitcnt lgkmcnt(0)
	v_or_b32_e32 v74, s0, v102
	ds_read2_b32 v[240:241], v106 offset1:33
	ds_read2_b32 v[242:243], v106 offset0:66 offset1:99
	ds_read2_b32 v[244:245], v106 offset0:132 offset1:165
	ds_read2_b32 v[246:247], v106 offset0:198 offset1:231
	ds_read2_b32 v[248:249], v106 offset0:8 offset1:41
	ds_read2_b32 v[250:251], v106 offset0:74 offset1:107
	ds_read2_b32 v[252:253], v106 offset0:140 offset1:173
	ds_read2_b32 v[254:255], v106 offset0:206 offset1:239
	s_ashr_i32 s3, s2, 31
	v_mul_lo_u32 v74, v74, s15
	s_waitcnt lgkmcnt(7)
	v_cvt_pk_bf16_f32 v66, v240, v241
	ds_read2_b32 v[240:241], v106 offset0:16 offset1:49
	v_lshl_add_u64 v[72:73], s[2:3], 1, v[100:101]
	v_ashrrev_i32_e32 v75, 31, v74
	s_waitcnt lgkmcnt(7)
	v_cvt_pk_bf16_f32 v67, v242, v243
	ds_read2_b32 v[242:243], v106 offset0:82 offset1:115
	v_lshl_add_u64 v[74:75], v[72:73], 0, v[74:75]
	s_waitcnt lgkmcnt(7)
	v_cvt_pk_bf16_f32 v68, v244, v245
	ds_read2_b32 v[244:245], v106 offset0:148 offset1:181
	s_waitcnt lgkmcnt(7)
	v_cvt_pk_bf16_f32 v69, v246, v247
	ds_read2_b32 v[246:247], v106 offset0:214 offset1:247
	global_store_dwordx4 v[74:75], v[66:69], off
	v_or_b32_e32 v74, s0, v103
	v_mul_lo_u32 v74, v74, s15
	s_waitcnt lgkmcnt(7)
	v_cvt_pk_bf16_f32 v66, v248, v249
	ds_read2_b32 v[248:249], v106 offset0:24 offset1:57
	v_ashrrev_i32_e32 v75, 31, v74
	s_waitcnt lgkmcnt(7)
	v_cvt_pk_bf16_f32 v67, v250, v251
	ds_read2_b32 v[250:251], v106 offset0:90 offset1:123
	v_lshl_add_u64 v[74:75], v[72:73], 0, v[74:75]
	s_waitcnt lgkmcnt(7)
	v_cvt_pk_bf16_f32 v68, v252, v253
	ds_read2_b32 v[252:253], v106 offset0:156 offset1:189
	s_waitcnt lgkmcnt(7)
	v_cvt_pk_bf16_f32 v69, v254, v255
	ds_read2_b32 v[254:255], v106 offset0:222 offset1:255
	global_store_dwordx4 v[74:75], v[66:69], off
	v_or_b32_e32 v74, s0, v104
	s_waitcnt lgkmcnt(7)
	v_cvt_pk_bf16_f32 v66, v240, v241
	v_mul_lo_u32 v74, v74, s15
	s_waitcnt lgkmcnt(6)
	v_cvt_pk_bf16_f32 v67, v242, v243
	v_ashrrev_i32_e32 v75, 31, v74
	s_waitcnt lgkmcnt(5)
	v_cvt_pk_bf16_f32 v68, v244, v245
	s_waitcnt lgkmcnt(4)
	v_cvt_pk_bf16_f32 v69, v246, v247
	v_lshl_add_u64 v[74:75], v[72:73], 0, v[74:75]
	global_store_dwordx4 v[74:75], v[66:69], off
	s_waitcnt lgkmcnt(3)
	s_nop 0
	v_cvt_pk_bf16_f32 v66, v248, v249
	s_waitcnt lgkmcnt(2)
	v_cvt_pk_bf16_f32 v67, v250, v251
	s_waitcnt lgkmcnt(1)
	v_cvt_pk_bf16_f32 v68, v252, v253
	v_or_b32_e32 v69, s0, v105
	v_mul_lo_u32 v74, v69, s15
	v_ashrrev_i32_e32 v75, 31, v74
	s_waitcnt lgkmcnt(0)
	v_cvt_pk_bf16_f32 v69, v254, v255
	v_lshl_add_u64 v[70:71], v[72:73], 0, v[74:75]
	global_store_dwordx4 v[70:71], v[66:69], off
	s_waitcnt lgkmcnt(0)
	s_add_i32 s14, s14, -1
	s_cmp_lg_u32 s14, 0
	s_mov_b32 s17, s1
	s_mov_b32 s3, s16
	s_cbranch_scc1 .LBB0_1302

; __global__ void __launch_bounds__(NWAVES * 64, 2) mk_fwd(Args args) {
	.amdhsa_kernel _Z6mk_fwd4Args
		.amdhsa_group_segment_fixed_size 0
		.amdhsa_private_segment_fixed_size 0
		.amdhsa_kernarg_size 512
		.amdhsa_user_sgpr_count 2
		.amdhsa_user_sgpr_dispatch_ptr 0
		.amdhsa_user_sgpr_queue_ptr 0
		.amdhsa_user_sgpr_kernarg_segment_ptr 1
		.amdhsa_user_sgpr_dispatch_id 0
		.amdhsa_user_sgpr_kernarg_preload_length 0
		.amdhsa_user_sgpr_kernarg_preload_offset 0
		.amdhsa_user_sgpr_private_segment_size 0
		.amdhsa_uses_dynamic_stack 0
		.amdhsa_enable_private_segment 0
		.amdhsa_system_sgpr_workgroup_id_x 1
		.amdhsa_system_sgpr_workgroup_id_y 0
		.amdhsa_system_sgpr_workgroup_id_z 0
		.amdhsa_system_sgpr_workgroup_info 0
		.amdhsa_system_vgpr_workitem_id 0
		.amdhsa_next_free_vgpr 256
		.amdhsa_next_free_sgpr 102
		.amdhsa_accum_offset 256
		.amdhsa_reserve_vcc 1
		.amdhsa_float_round_mode_32 0
		.amdhsa_float_round_mode_16_64 0
		.amdhsa_float_denorm_mode_32 3
		.amdhsa_float_denorm_mode_16_64 3
		.amdhsa_dx10_clamp 1
		.amdhsa_ieee_mode 1
		.amdhsa_fp16_overflow 0
		.amdhsa_tg_split 0
		.amdhsa_exception_fp_ieee_invalid_op 0
		.amdhsa_exception_fp_denorm_src 0
		.amdhsa_exception_fp_ieee_div_zero 0
		.amdhsa_exception_fp_ieee_overflow 0
		.amdhsa_exception_fp_ieee_underflow 0
		.amdhsa_exception_fp_ieee_inexact 0
		.amdhsa_exception_int_div_zero 0
	.end_amdhsa_kernel

; __global__ void __launch_bounds__(NWAVES * 64, 2) mk_fwd(Args args) {
amdhsa.kernels:
  - .agpr_count:     0
    .args:
      - .offset:         0
        .size:           256
        .value_kind:     by_value
      - .offset:         256
        .size:           4
        .value_kind:     hidden_block_count_x
      - .offset:         260
        .size:           4
        .value_kind:     hidden_block_count_y
      - .offset:         264
        .size:           4
        .value_kind:     hidden_block_count_z
      - .offset:         268
        .size:           2
        .value_kind:     hidden_group_size_x
      - .offset:         270
        .size:           2
        .value_kind:     hidden_group_size_y
      - .offset:         272
        .size:           2
        .value_kind:     hidden_group_size_z
      - .offset:         274
        .size:           2
        .value_kind:     hidden_remainder_x
      - .offset:         276
        .size:           2
        .value_kind:     hidden_remainder_y
      - .offset:         278
        .size:           2
        .value_kind:     hidden_remainder_z
      - .offset:         296
        .size:           8
        .value_kind:     hidden_global_offset_x
      - .offset:         304
        .size:           8
        .value_kind:     hidden_global_offset_y
      - .offset:         312
        .size:           8
        .value_kind:     hidden_global_offset_z
      - .offset:         320
        .size:           2
        .value_kind:     hidden_grid_dims
      - .offset:         376
        .size:           4
        .value_kind:     hidden_dynamic_lds_size
    .group_segment_fixed_size: 0
    .kernarg_segment_align: 8
    .kernarg_segment_size: 512
    .language:       OpenCL C
    .language_version:
      - 2
      - 0
    .max_flat_workgroup_size: 512
    .name:           _Z6mk_fwd4Args
    .private_segment_fixed_size: 0
    .sgpr_count:     104
    .sgpr_spill_count: 86
    .symbol:         _Z6mk_fwd4Args.kd
    .uniform_work_group_size: 1
    .uses_dynamic_stack: false
    .vgpr_count:     256
    .vgpr_spill_count: 0
    .wavefront_size: 64
